# hand-written LayerNorm row routine for latent rows (deep prefetch, hoisted gain/bias, rsq+Newton); k_rope loads batched; G4 stats batched
# speedup vs baseline: 1.0547x; 1.0238x over previous
; DI const float* modp(const Frame& F, int l, int mr, int which) { return (const float*)(F.ws + WS_MOD) + ((size_t)(l * 9 + mr) * 6 + which) * 1024; }
; DI void ln_row_v(const Frame& F, f32x4 (&v)[4], float* xout, const float* g, const float* b, const float* sh, const float* sc, bf16_t* hout, const float* slab, const float* gres, float* stat = nullptr) {
;     ...
;     if (g) {
;         float s = 0.f, s2 = 0.f;
; #pragma unroll
;         for (int j = 0; j < 4; ++j) { s += (v[j][0] + v[j][1]) + (v[j][2] + v[j][3]); s2 += (v[j][0] * v[j][0] + v[j][1] * v[j][1]) + (v[j][2] * v[j][2] + v[j][3] * v[j][3]); }
;         wave_sum2(s, s2, F.lane);
;         const float mean = s * (1.f / D); const float rstd = 1.f / sqrtf(fmaxf(s2 * (1.f / D) - mean * mean, 0.f) + EPS);
; DI void ln_phase(const Frame& F, int which) {
;     const int gw = F.vcu * 8 + F.wave, NGW = F.G * 8; const int l = F.l;
;     const int nrows = (l == NL - 1) ? ML : MT;
;     bf16_t* H = (bf16_t*)(F.ws + WS_HB);
;     const float* g = pin(F, which == 0 ? I_LN1G : I_LN2G) + l * 1024; const float* b = pin(F, which == 0 ? I_LN1B : I_LN2B) + l * 1024;
;     const bool wh = !(which == 1 && l == NL - 1);
;     f32x4 vc[4], vn[4];
;     if (gw < nrows) ln_load(F, xrow_ptr(F, gw), vc);
;     for (int row = gw; row < nrows; row += NGW) {
;         if (row + NGW < nrows) ln_load(F, xrow_ptr(F, row + NGW), vn);
;         const int mr = row < ML ? (row >> 11) : 8;
;         const float* sh = which == 0 ? modp(F, l, mr, 3) : modp(F, l + 1 < NL ? l + 1 : l, mr, 0);
;         const float* sc = which == 0 ? modp(F, l, mr, 4) : modp(F, l + 1 < NL ? l + 1 : l, mr, 1);
;         const bool sl = (which == 1 && row >= ML);
;         const bool st_only = row < ML && !(which == 1 && l == NL - 1);
;         float* stp = st_only ? (float*)(F.ws + (which == 0 ? WS_ST1 : WS_ST2)) + 2 * (size_t)row : nullptr;
;         ln_row_v(F, vc, st_only ? nullptr : xrow_ptr(F, row), g, b, sh, sc, wh ? H + (size_t)row * D : nullptr, sl ? (const float*)(F.ws + WS_KN) + (size_t)(row - ML) * 1024 : nullptr, modp(F, l, mr, 5), stp);
.LBB0_107:
	s_cmp_gt_i32 s28, 4
	s_mov_b64 s[2:3], -1
	s_cbranch_scc0 .LBB0_125
	v_readlane_b32 s2, v255, 29
	s_lshl_b32 s2, s2, 3
	v_readlane_b32 s3, v255, 31
	s_add_i32 s16, s3, s2
	v_lshlrev_b32_e32 v0, 4, v186
	v_lshlrev_b32_e32 v1, 3, v186
	v_lshlrev_b32_e32 v96, 2, v186
	v_xor_b32_e32 v3, 4, v96
	v_xor_b32_e32 v4, 8, v96
	v_xor_b32_e32 v5, 16, v96
	v_xor_b32_e32 v6, 32, v96
	v_xor_b32_e32 v7, 64, v96
	v_xor_b32_e32 v8, 128, v96
	s_load_dwordx4 s[4:7], s[62:63], 0x98
	v_readlane_b32 s22, v255, 35
	v_readlane_b32 s8, v255, 17
	v_readlane_b32 s9, v255, 18
	s_lshl_b32 s2, s16, 12
	s_add_u32 s8, s8, s2
	s_addc_u32 s9, s9, 0
	s_lshl_b32 s2, s16, 11
	s_add_u32 s10, s94, s2
	s_addc_u32 s11, s95, 0
	s_add_u32 s10, s10, 0x3e00000
	s_addc_u32 s11, s11, 0
	s_lshl_b32 s2, s16, 3
	s_add_u32 s12, s94, s2
	s_addc_u32 s13, s95, 0
	s_add_u32 s12, s12, 0x480000
	s_addc_u32 s13, s13, 0
	s_mov_b32 s3, s22
	s_mul_i32 s3, s3, 0x36000
	s_add_u32 s14, s94, s3
	s_addc_u32 s15, s95, 0
	s_add_u32 s14, s14, 0x103000
	s_addc_u32 s15, s15, 0
	s_add_u32 s18, s14, 0x1000
	s_addc_u32 s19, s15, 0
	s_lshl_b32 s2, s22, 12
	s_waitcnt lgkmcnt(0)
	s_add_u32 s4, s4, s2
	s_addc_u32 s5, s5, 0
	s_add_u32 s6, s6, s2
	s_addc_u32 s7, s7, 0
	global_load_dwordx4 v[10:13], v0, s[4:5]
	global_load_dwordx4 v[14:17], v0, s[4:5] offset:1024
	global_load_dwordx4 v[18:21], v0, s[4:5] offset:2048
	global_load_dwordx4 v[22:25], v0, s[4:5] offset:3072
	global_load_dwordx4 v[26:29], v0, s[6:7]
	global_load_dwordx4 v[30:33], v0, s[6:7] offset:1024
	global_load_dwordx4 v[34:37], v0, s[6:7] offset:2048
	global_load_dwordx4 v[38:41], v0, s[6:7] offset:3072
	s_add_u32 s2, s8, 0x0
	s_addc_u32 s3, s9, 0
	global_load_dwordx4 v[42:45], v0, s[2:3]
	global_load_dwordx4 v[46:49], v0, s[2:3] offset:1024
	global_load_dwordx4 v[50:53], v0, s[2:3] offset:2048
	global_load_dwordx4 v[54:57], v0, s[2:3] offset:3072
	s_add_u32 s2, s14, 0x0
	s_addc_u32 s3, s15, 0
	global_load_dwordx4 v[114:117], v0, s[2:3]
	global_load_dwordx4 v[118:121], v0, s[2:3] offset:1024
	global_load_dwordx4 v[122:125], v0, s[2:3] offset:2048
	global_load_dwordx4 v[126:129], v0, s[2:3] offset:3072
	s_add_u32 s2, s18, 0x0
	s_addc_u32 s3, s19, 0
	global_load_dwordx4 v[130:133], v0, s[2:3]
	global_load_dwordx4 v[134:137], v0, s[2:3] offset:1024
	global_load_dwordx4 v[138:141], v0, s[2:3] offset:2048
	global_load_dwordx4 v[142:145], v0, s[2:3] offset:3072
	s_add_u32 s2, s8, 0x800000
	s_addc_u32 s3, s9, 0
	global_load_dwordx4 v[58:61], v0, s[2:3]
	global_load_dwordx4 v[62:65], v0, s[2:3] offset:1024
	global_load_dwordx4 v[66:69], v0, s[2:3] offset:2048
	global_load_dwordx4 v[70:73], v0, s[2:3] offset:3072
	s_add_u32 s2, s14, 0x6000
	s_addc_u32 s3, s15, 0
	global_load_dwordx4 v[146:149], v0, s[2:3]
	global_load_dwordx4 v[150:153], v0, s[2:3] offset:1024
	global_load_dwordx4 v[154:157], v0, s[2:3] offset:2048
	global_load_dwordx4 v[158:161], v0, s[2:3] offset:3072
	s_add_u32 s2, s18, 0x6000
	s_addc_u32 s3, s19, 0
	global_load_dwordx4 v[162:165], v0, s[2:3]
	global_load_dwordx4 v[166:169], v0, s[2:3] offset:1024
	global_load_dwordx4 v[170:173], v0, s[2:3] offset:2048
	global_load_dwordx4 v[174:177], v0, s[2:3] offset:3072
	s_add_u32 s2, s8, 0x1000000
	s_addc_u32 s3, s9, 0
	global_load_dwordx4 v[74:77], v0, s[2:3]
	global_load_dwordx4 v[78:81], v0, s[2:3] offset:1024
	global_load_dwordx4 v[82:85], v0, s[2:3] offset:2048
	global_load_dwordx4 v[86:89], v0, s[2:3] offset:3072
	s_add_u32 s2, s8, 0x1800000
	s_addc_u32 s3, s9, 0
	global_load_dwordx4 v[98:101], v0, s[2:3]
	global_load_dwordx4 v[102:105], v0, s[2:3] offset:1024
	global_load_dwordx4 v[106:109], v0, s[2:3] offset:2048
	global_load_dwordx4 v[110:113], v0, s[2:3] offset:3072
	s_waitcnt vmcnt(28)
	v_add_f32_e32 v9, v42, v43
	v_add_f32_e32 v91, v44, v45
	v_mul_f32_e32 v90, v42, v42
	v_mul_f32_e32 v92, v43, v43
	v_add_f32_e32 v9, v9, v46
	v_add_f32_e32 v91, v91, v47
	v_add_f32_e32 v9, v9, v48
	v_add_f32_e32 v91, v91, v49
	v_add_f32_e32 v9, v9, v50
	v_add_f32_e32 v91, v91, v51
	v_add_f32_e32 v9, v9, v52
	v_add_f32_e32 v91, v91, v53
	v_add_f32_e32 v9, v9, v54
	v_add_f32_e32 v91, v91, v55
	v_add_f32_e32 v9, v9, v56
	v_add_f32_e32 v91, v91, v57
	v_fmac_f32_e32 v90, v44, v44
	v_fmac_f32_e32 v92, v45, v45
	v_fmac_f32_e32 v90, v46, v46
	v_fmac_f32_e32 v92, v47, v47
	v_fmac_f32_e32 v90, v48, v48
	v_fmac_f32_e32 v92, v49, v49
	v_fmac_f32_e32 v90, v50, v50
	v_fmac_f32_e32 v92, v51, v51
	v_fmac_f32_e32 v90, v52, v52
	v_fmac_f32_e32 v92, v53, v53
	v_fmac_f32_e32 v90, v54, v54
	v_fmac_f32_e32 v92, v55, v55
	v_fmac_f32_e32 v90, v56, v56
	v_fmac_f32_e32 v92, v57, v57
	v_add_f32_e32 v9, v9, v91
	v_add_f32_e32 v90, v90, v92
	ds_bpermute_b32 v91, v3, v9
	ds_bpermute_b32 v92, v3, v90
	s_waitcnt lgkmcnt(0)
	v_add_f32_e32 v9, v9, v91
	v_add_f32_e32 v90, v90, v92
	ds_bpermute_b32 v91, v4, v9
	ds_bpermute_b32 v92, v4, v90
	s_waitcnt lgkmcnt(0)
	v_add_f32_e32 v9, v9, v91
	v_add_f32_e32 v90, v90, v92
	ds_bpermute_b32 v91, v5, v9
	ds_bpermute_b32 v92, v5, v90
	s_waitcnt lgkmcnt(0)
	v_add_f32_e32 v9, v9, v91
	v_add_f32_e32 v90, v90, v92
	ds_bpermute_b32 v91, v6, v9
	ds_bpermute_b32 v92, v6, v90
	s_waitcnt lgkmcnt(0)
	v_add_f32_e32 v9, v9, v91
	v_add_f32_e32 v90, v90, v92
	ds_bpermute_b32 v91, v7, v9
	ds_bpermute_b32 v92, v7, v90
	s_waitcnt lgkmcnt(0)
	v_add_f32_e32 v9, v9, v91
	v_add_f32_e32 v90, v90, v92
	ds_bpermute_b32 v91, v8, v9
	ds_bpermute_b32 v92, v8, v90
	s_waitcnt lgkmcnt(0)
; DI unsigned pk2(float lo, float hi) { f32x2 v = {lo, hi}; bf16x2_t b = __builtin_convertvector(v, bf16x2_t); return __builtin_bit_cast(unsigned, b); }
; DI void ln_row_v(const Frame& F, f32x4 (&v)[4], float* xout, const float* g, const float* b, const float* sh, const float* sc, bf16_t* hout, const float* slab, const float* gres, float* stat = nullptr) {
;     ...
;     if (g) {
;         float s = 0.f, s2 = 0.f;
; #pragma unroll
;         for (int j = 0; j < 4; ++j) { s += (v[j][0] + v[j][1]) + (v[j][2] + v[j][3]); s2 += (v[j][0] * v[j][0] + v[j][1] * v[j][1]) + (v[j][2] * v[j][2] + v[j][3] * v[j][3]); }
;         wave_sum2(s, s2, F.lane);
;         const float mean = s * (1.f / D); const float rstd = 1.f / sqrtf(fmaxf(s2 * (1.f / D) - mean * mean, 0.f) + EPS);
;         if (stat && F.lane == 0) { f32x2 sv = {mean, rstd}; *(f32x2*)stat = sv; }
; #pragma unroll
;         for (int j = 0; j < 4; ++j) { const f32x4 gg = ((const f32x4*)g)[F.lane + 64 * j], bb = ((const f32x4*)b)[F.lane + 64 * j];
;             v[j] = (v[j] - mean) * rstd * gg + bb; if (xout) ((f32x4*)xout)[F.lane + 64 * j] = v[j]; }
;     }
;     if (hout) {
;         float s = 0.f, s2 = 0.f;
; #pragma unroll
;         for (int j = 0; j < 4; ++j) { s += (v[j][0] + v[j][1]) + (v[j][2] + v[j][3]); s2 += (v[j][0] * v[j][0] + v[j][1] * v[j][1]) + (v[j][2] * v[j][2] + v[j][3] * v[j][3]); }
;         wave_sum2(s, s2, F.lane);
;         const float mean = s * (1.f / D); const float rstd = 1.f / sqrtf(fmaxf(s2 * (1.f / D) - mean * mean, 0.f) + EPS);
; #pragma unroll
;         for (int j = 0; j < 4; ++j) { const f32x4 hh = ((const f32x4*)sh)[F.lane + 64 * j], cc = ((const f32x4*)sc)[F.lane + 64 * j];
;             const f32x4 o = (v[j] - mean) * rstd * (cc + 1.f) + hh; u32x2 wv; wv.x = pk2(o[0], o[1]); wv.y = pk2(o[2], o[3]);
;             ((u32x2*)hout)[F.lane + 64 * j] = wv; }
;     }
	v_add_f32_e32 v9, v9, v91
	v_add_f32_e32 v90, v90, v92
	v_mul_f32_e32 v93, 0x3a800000, v9
	v_mul_f32_e32 v91, 0x3a800000, v90
	v_fma_f32 v91, -v93, v93, v91
	v_max_f32_e32 v91, 0, v91
	v_add_f32_e32 v91, 0x358637bd, v91
	v_rsq_f32_e32 v94, v91
	v_mul_f32_e32 v91, 0.5, v91
	v_mul_f32_e32 v92, v94, v94
	v_fma_f32 v92, -v91, v92, 0.5
	v_fma_f32 v94, v94, v92, v94
	s_add_u32 s2, s12, 0x0
	s_addc_u32 s3, s13, 0
	v_mov_b32_e32 v188, v93
	v_mov_b32_e32 v189, v94
	s_mov_b64 exec, 1
	global_store_dwordx2 v97, v[188:189], s[2:3]
	s_mov_b64 exec, -1
	v_sub_f32_e32 v42, v42, v93
	v_sub_f32_e32 v43, v43, v93
	v_sub_f32_e32 v44, v44, v93
	v_sub_f32_e32 v45, v45, v93
	v_sub_f32_e32 v46, v46, v93
	v_sub_f32_e32 v47, v47, v93
	v_sub_f32_e32 v48, v48, v93
	v_sub_f32_e32 v49, v49, v93
	v_sub_f32_e32 v50, v50, v93
	v_sub_f32_e32 v51, v51, v93
	v_sub_f32_e32 v52, v52, v93
	v_sub_f32_e32 v53, v53, v93
	v_sub_f32_e32 v54, v54, v93
	v_sub_f32_e32 v55, v55, v93
	v_sub_f32_e32 v56, v56, v93
	v_sub_f32_e32 v57, v57, v93
	v_mul_f32_e32 v42, v94, v42
	v_mul_f32_e32 v43, v94, v43
	v_mul_f32_e32 v44, v94, v44
	v_mul_f32_e32 v45, v94, v45
	v_mul_f32_e32 v46, v94, v46
	v_mul_f32_e32 v47, v94, v47
	v_mul_f32_e32 v48, v94, v48
	v_mul_f32_e32 v49, v94, v49
	v_mul_f32_e32 v50, v94, v50
	v_mul_f32_e32 v51, v94, v51
	v_mul_f32_e32 v52, v94, v52
	v_mul_f32_e32 v53, v94, v53
	v_mul_f32_e32 v54, v94, v54
	v_mul_f32_e32 v55, v94, v55
	v_mul_f32_e32 v56, v94, v56
	v_mul_f32_e32 v57, v94, v57
	v_fma_f32 v42, v42, v10, v26
	v_fma_f32 v43, v43, v11, v27
	v_fma_f32 v44, v44, v12, v28
	v_fma_f32 v45, v45, v13, v29
	v_fma_f32 v46, v46, v14, v30
	v_fma_f32 v47, v47, v15, v31
	v_fma_f32 v48, v48, v16, v32
	v_fma_f32 v49, v49, v17, v33
	v_fma_f32 v50, v50, v18, v34
	v_fma_f32 v51, v51, v19, v35
	v_fma_f32 v52, v52, v20, v36
	v_fma_f32 v53, v53, v21, v37
	v_fma_f32 v54, v54, v22, v38
	v_fma_f32 v55, v55, v23, v39
	v_fma_f32 v56, v56, v24, v40
	v_fma_f32 v57, v57, v25, v41
	v_add_f32_e32 v9, v42, v43
	v_add_f32_e32 v91, v44, v45
	v_mul_f32_e32 v90, v42, v42
	v_mul_f32_e32 v92, v43, v43
	v_add_f32_e32 v9, v9, v46
	v_add_f32_e32 v91, v91, v47
	v_add_f32_e32 v9, v9, v48
	v_add_f32_e32 v91, v91, v49
	v_add_f32_e32 v9, v9, v50
	v_add_f32_e32 v91, v91, v51
	v_add_f32_e32 v9, v9, v52
	v_add_f32_e32 v91, v91, v53
	v_add_f32_e32 v9, v9, v54
	v_add_f32_e32 v91, v91, v55
	v_add_f32_e32 v9, v9, v56
	v_add_f32_e32 v91, v91, v57
	v_fmac_f32_e32 v90, v44, v44
	v_fmac_f32_e32 v92, v45, v45
	v_fmac_f32_e32 v90, v46, v46
	v_fmac_f32_e32 v92, v47, v47
	v_fmac_f32_e32 v90, v48, v48
	v_fmac_f32_e32 v92, v49, v49
	v_fmac_f32_e32 v90, v50, v50
	v_fmac_f32_e32 v92, v51, v51
	v_fmac_f32_e32 v90, v52, v52
	v_fmac_f32_e32 v92, v53, v53
	v_fmac_f32_e32 v90, v54, v54
	v_fmac_f32_e32 v92, v55, v55
	v_fmac_f32_e32 v90, v56, v56
	v_fmac_f32_e32 v92, v57, v57
	v_add_f32_e32 v9, v9, v91
	v_add_f32_e32 v90, v90, v92
	ds_bpermute_b32 v91, v3, v9
	ds_bpermute_b32 v92, v3, v90
	s_waitcnt lgkmcnt(0)
	v_add_f32_e32 v9, v9, v91
	v_add_f32_e32 v90, v90, v92
	ds_bpermute_b32 v91, v4, v9
	ds_bpermute_b32 v92, v4, v90
	s_waitcnt lgkmcnt(0)
	v_add_f32_e32 v9, v9, v91
	v_add_f32_e32 v90, v90, v92
	ds_bpermute_b32 v91, v5, v9
	ds_bpermute_b32 v92, v5, v90
	s_waitcnt lgkmcnt(0)
	v_add_f32_e32 v9, v9, v91
	v_add_f32_e32 v90, v90, v92
	ds_bpermute_b32 v91, v6, v9
	ds_bpermute_b32 v92, v6, v90
	s_waitcnt lgkmcnt(0)
	v_add_f32_e32 v9, v9, v91
	v_add_f32_e32 v90, v90, v92
	ds_bpermute_b32 v91, v7, v9
	ds_bpermute_b32 v92, v7, v90
	s_waitcnt lgkmcnt(0)
	v_add_f32_e32 v9, v9, v91
	v_add_f32_e32 v90, v90, v92
	ds_bpermute_b32 v91, v8, v9
	ds_bpermute_b32 v92, v8, v90
	s_waitcnt lgkmcnt(0)
	v_add_f32_e32 v9, v9, v91
	v_add_f32_e32 v90, v90, v92
	v_mul_f32_e32 v93, 0x3a800000, v9
	v_mul_f32_e32 v91, 0x3a800000, v90
	v_fma_f32 v91, -v93, v93, v91
	v_max_f32_e32 v91, 0, v91
	v_add_f32_e32 v91, 0x358637bd, v91
	v_rsq_f32_e32 v94, v91
	v_mul_f32_e32 v91, 0.5, v91
	v_mul_f32_e32 v92, v94, v94
	v_fma_f32 v92, -v91, v92, 0.5
	v_fma_f32 v94, v94, v92, v94
	s_waitcnt vmcnt(21)
	v_sub_f32_e32 v42, v42, v93
	v_sub_f32_e32 v43, v43, v93
	v_sub_f32_e32 v44, v44, v93
	v_sub_f32_e32 v45, v45, v93
	v_sub_f32_e32 v46, v46, v93
	v_sub_f32_e32 v47, v47, v93
	v_sub_f32_e32 v48, v48, v93
	v_sub_f32_e32 v49, v49, v93
	v_sub_f32_e32 v50, v50, v93
	v_sub_f32_e32 v51, v51, v93
	v_sub_f32_e32 v52, v52, v93
	v_sub_f32_e32 v53, v53, v93
	v_sub_f32_e32 v54, v54, v93
	v_sub_f32_e32 v55, v55, v93
	v_sub_f32_e32 v56, v56, v93
	v_sub_f32_e32 v57, v57, v93
	v_add_f32_e32 v130, 1.0, v130
	v_add_f32_e32 v131, 1.0, v131
	v_add_f32_e32 v132, 1.0, v132
	v_add_f32_e32 v133, 1.0, v133
	v_add_f32_e32 v134, 1.0, v134
	v_add_f32_e32 v135, 1.0, v135
	v_add_f32_e32 v136, 1.0, v136
	v_add_f32_e32 v137, 1.0, v137
	v_add_f32_e32 v138, 1.0, v138
	v_add_f32_e32 v139, 1.0, v139
	v_add_f32_e32 v140, 1.0, v140
	v_add_f32_e32 v141, 1.0, v141
	v_add_f32_e32 v142, 1.0, v142
	v_add_f32_e32 v143, 1.0, v143
	v_add_f32_e32 v144, 1.0, v144
	v_add_f32_e32 v145, 1.0, v145
	v_mul_f32_e32 v42, v94, v42
	v_mul_f32_e32 v43, v94, v43
	v_mul_f32_e32 v44, v94, v44
	v_mul_f32_e32 v45, v94, v45
	v_mul_f32_e32 v46, v94, v46
	v_mul_f32_e32 v47, v94, v47
	v_mul_f32_e32 v48, v94, v48
	v_mul_f32_e32 v49, v94, v49
	v_mul_f32_e32 v50, v94, v50
	v_mul_f32_e32 v51, v94, v51
	v_mul_f32_e32 v52, v94, v52
	v_mul_f32_e32 v53, v94, v53
	v_mul_f32_e32 v54, v94, v54
	v_mul_f32_e32 v55, v94, v55
	v_mul_f32_e32 v56, v94, v56
	v_mul_f32_e32 v57, v94, v57
	v_fma_f32 v42, v42, v130, v114
	v_fma_f32 v43, v43, v131, v115
	v_fma_f32 v44, v44, v132, v116
	v_fma_f32 v45, v45, v133, v117
	v_fma_f32 v46, v46, v134, v118
	v_fma_f32 v47, v47, v135, v119
; DI unsigned pk2(float lo, float hi) { f32x2 v = {lo, hi}; bf16x2_t b = __builtin_convertvector(v, bf16x2_t); return __builtin_bit_cast(unsigned, b); }
; DI void ln_row_v(const Frame& F, f32x4 (&v)[4], float* xout, const float* g, const float* b, const float* sh, const float* sc, bf16_t* hout, const float* slab, const float* gres, float* stat = nullptr) {
;     ...
;     if (g) {
;         float s = 0.f, s2 = 0.f;
; #pragma unroll
;         for (int j = 0; j < 4; ++j) { s += (v[j][0] + v[j][1]) + (v[j][2] + v[j][3]); s2 += (v[j][0] * v[j][0] + v[j][1] * v[j][1]) + (v[j][2] * v[j][2] + v[j][3] * v[j][3]); }
;         wave_sum2(s, s2, F.lane);
;         const float mean = s * (1.f / D); const float rstd = 1.f / sqrtf(fmaxf(s2 * (1.f / D) - mean * mean, 0.f) + EPS);
;         if (stat && F.lane == 0) { f32x2 sv = {mean, rstd}; *(f32x2*)stat = sv; }
; #pragma unroll
;         for (int j = 0; j < 4; ++j) { const f32x4 gg = ((const f32x4*)g)[F.lane + 64 * j], bb = ((const f32x4*)b)[F.lane + 64 * j];
;             v[j] = (v[j] - mean) * rstd * gg + bb; if (xout) ((f32x4*)xout)[F.lane + 64 * j] = v[j]; }
;     }
;     if (hout) {
;         float s = 0.f, s2 = 0.f;
; #pragma unroll
;         for (int j = 0; j < 4; ++j) { s += (v[j][0] + v[j][1]) + (v[j][2] + v[j][3]); s2 += (v[j][0] * v[j][0] + v[j][1] * v[j][1]) + (v[j][2] * v[j][2] + v[j][3] * v[j][3]); }
;         wave_sum2(s, s2, F.lane);
;         const float mean = s * (1.f / D); const float rstd = 1.f / sqrtf(fmaxf(s2 * (1.f / D) - mean * mean, 0.f) + EPS);
; #pragma unroll
;         for (int j = 0; j < 4; ++j) { const f32x4 hh = ((const f32x4*)sh)[F.lane + 64 * j], cc = ((const f32x4*)sc)[F.lane + 64 * j];
;             const f32x4 o = (v[j] - mean) * rstd * (cc + 1.f) + hh; u32x2 wv; wv.x = pk2(o[0], o[1]); wv.y = pk2(o[2], o[3]);
;             ((u32x2*)hout)[F.lane + 64 * j] = wv; }
;     }
	v_fma_f32 v48, v48, v136, v120
	v_fma_f32 v49, v49, v137, v121
	v_fma_f32 v50, v50, v138, v122
	v_fma_f32 v51, v51, v139, v123
	v_fma_f32 v52, v52, v140, v124
	v_fma_f32 v53, v53, v141, v125
	v_fma_f32 v54, v54, v142, v126
	v_fma_f32 v55, v55, v143, v127
	v_fma_f32 v56, v56, v144, v128
	v_fma_f32 v57, v57, v145, v129
	v_cvt_pk_bf16_f32 v190, v42, v43
	v_cvt_pk_bf16_f32 v191, v44, v45
	v_cvt_pk_bf16_f32 v192, v46, v47
	v_cvt_pk_bf16_f32 v193, v48, v49
	v_cvt_pk_bf16_f32 v194, v50, v51
	v_cvt_pk_bf16_f32 v195, v52, v53
	v_cvt_pk_bf16_f32 v196, v54, v55
	v_cvt_pk_bf16_f32 v197, v56, v57
	s_add_u32 s2, s10, 0x0
	s_addc_u32 s3, s11, 0
	global_store_dwordx2 v1, v[190:191], s[2:3]
	global_store_dwordx2 v1, v[192:193], s[2:3] offset:512
	global_store_dwordx2 v1, v[194:195], s[2:3] offset:1024
	global_store_dwordx2 v1, v[196:197], s[2:3] offset:1536
	s_add_u32 s2, s8, 0x2000000
	s_addc_u32 s3, s9, 0
	global_load_dwordx4 v[42:45], v0, s[2:3]
	global_load_dwordx4 v[46:49], v0, s[2:3] offset:1024
	global_load_dwordx4 v[50:53], v0, s[2:3] offset:2048
	global_load_dwordx4 v[54:57], v0, s[2:3] offset:3072
	s_add_u32 s2, s14, 0xc000
	s_addc_u32 s3, s15, 0
	global_load_dwordx4 v[114:117], v0, s[2:3]
	global_load_dwordx4 v[118:121], v0, s[2:3] offset:1024
	global_load_dwordx4 v[122:125], v0, s[2:3] offset:2048
	global_load_dwordx4 v[126:129], v0, s[2:3] offset:3072
	s_add_u32 s2, s18, 0xc000
	s_addc_u32 s3, s19, 0
	global_load_dwordx4 v[130:133], v0, s[2:3]
	global_load_dwordx4 v[134:137], v0, s[2:3] offset:1024
	global_load_dwordx4 v[138:141], v0, s[2:3] offset:2048
	global_load_dwordx4 v[142:145], v0, s[2:3] offset:3072
	s_waitcnt vmcnt(33)
	v_add_f32_e32 v9, v58, v59
	v_add_f32_e32 v91, v60, v61
	v_mul_f32_e32 v90, v58, v58
	v_mul_f32_e32 v92, v59, v59
	v_add_f32_e32 v9, v9, v62
	v_add_f32_e32 v91, v91, v63
	v_add_f32_e32 v9, v9, v64
	v_add_f32_e32 v91, v91, v65
	v_add_f32_e32 v9, v9, v66
	v_add_f32_e32 v91, v91, v67
	v_add_f32_e32 v9, v9, v68
	v_add_f32_e32 v91, v91, v69
	v_add_f32_e32 v9, v9, v70
	v_add_f32_e32 v91, v91, v71
	v_add_f32_e32 v9, v9, v72
	v_add_f32_e32 v91, v91, v73
	v_fmac_f32_e32 v90, v60, v60
	v_fmac_f32_e32 v92, v61, v61
	v_fmac_f32_e32 v90, v62, v62
	v_fmac_f32_e32 v92, v63, v63
	v_fmac_f32_e32 v90, v64, v64
	v_fmac_f32_e32 v92, v65, v65
	v_fmac_f32_e32 v90, v66, v66
	v_fmac_f32_e32 v92, v67, v67
	v_fmac_f32_e32 v90, v68, v68
	v_fmac_f32_e32 v92, v69, v69
	v_fmac_f32_e32 v90, v70, v70
	v_fmac_f32_e32 v92, v71, v71
	v_fmac_f32_e32 v90, v72, v72
	v_fmac_f32_e32 v92, v73, v73
	v_add_f32_e32 v9, v9, v91
	v_add_f32_e32 v90, v90, v92
	ds_bpermute_b32 v91, v3, v9
	ds_bpermute_b32 v92, v3, v90
	s_waitcnt lgkmcnt(0)
	v_add_f32_e32 v9, v9, v91
	v_add_f32_e32 v90, v90, v92
	ds_bpermute_b32 v91, v4, v9
	ds_bpermute_b32 v92, v4, v90
	s_waitcnt lgkmcnt(0)
	v_add_f32_e32 v9, v9, v91
	v_add_f32_e32 v90, v90, v92
	ds_bpermute_b32 v91, v5, v9
	ds_bpermute_b32 v92, v5, v90
	s_waitcnt lgkmcnt(0)
	v_add_f32_e32 v9, v9, v91
	v_add_f32_e32 v90, v90, v92
	ds_bpermute_b32 v91, v6, v9
	ds_bpermute_b32 v92, v6, v90
	s_waitcnt lgkmcnt(0)
	v_add_f32_e32 v9, v9, v91
	v_add_f32_e32 v90, v90, v92
	ds_bpermute_b32 v91, v7, v9
	ds_bpermute_b32 v92, v7, v90
	s_waitcnt lgkmcnt(0)
	v_add_f32_e32 v9, v9, v91
	v_add_f32_e32 v90, v90, v92
	ds_bpermute_b32 v91, v8, v9
	ds_bpermute_b32 v92, v8, v90
	s_waitcnt lgkmcnt(0)
	v_add_f32_e32 v9, v9, v91
	v_add_f32_e32 v90, v90, v92
	v_mul_f32_e32 v93, 0x3a800000, v9
	v_mul_f32_e32 v91, 0x3a800000, v90
	v_fma_f32 v91, -v93, v93, v91
	v_max_f32_e32 v91, 0, v91
	v_add_f32_e32 v91, 0x358637bd, v91
	v_rsq_f32_e32 v94, v91
	v_mul_f32_e32 v91, 0.5, v91
	v_mul_f32_e32 v92, v94, v94
	v_fma_f32 v92, -v91, v92, 0.5
	v_fma_f32 v94, v94, v92, v94
	s_add_u32 s2, s12, 0x4000
	s_addc_u32 s3, s13, 0
	v_mov_b32_e32 v188, v93
	v_mov_b32_e32 v189, v94
	s_mov_b64 exec, 1
	global_store_dwordx2 v97, v[188:189], s[2:3]
	s_mov_b64 exec, -1
	v_sub_f32_e32 v58, v58, v93
	v_sub_f32_e32 v59, v59, v93
	v_sub_f32_e32 v60, v60, v93
	v_sub_f32_e32 v61, v61, v93
	v_sub_f32_e32 v62, v62, v93
	v_sub_f32_e32 v63, v63, v93
	v_sub_f32_e32 v64, v64, v93
	v_sub_f32_e32 v65, v65, v93
	v_sub_f32_e32 v66, v66, v93
	v_sub_f32_e32 v67, v67, v93
	v_sub_f32_e32 v68, v68, v93
	v_sub_f32_e32 v69, v69, v93
	v_sub_f32_e32 v70, v70, v93
	v_sub_f32_e32 v71, v71, v93
	v_sub_f32_e32 v72, v72, v93
	v_sub_f32_e32 v73, v73, v93
	v_mul_f32_e32 v58, v94, v58
	v_mul_f32_e32 v59, v94, v59
	v_mul_f32_e32 v60, v94, v60
	v_mul_f32_e32 v61, v94, v61
	v_mul_f32_e32 v62, v94, v62
	v_mul_f32_e32 v63, v94, v63
	v_mul_f32_e32 v64, v94, v64
	v_mul_f32_e32 v65, v94, v65
	v_mul_f32_e32 v66, v94, v66
	v_mul_f32_e32 v67, v94, v67
	v_mul_f32_e32 v68, v94, v68
	v_mul_f32_e32 v69, v94, v69
	v_mul_f32_e32 v70, v94, v70
	v_mul_f32_e32 v71, v94, v71
	v_mul_f32_e32 v72, v94, v72
	v_mul_f32_e32 v73, v94, v73
	v_fma_f32 v58, v58, v10, v26
	v_fma_f32 v59, v59, v11, v27
	v_fma_f32 v60, v60, v12, v28
	v_fma_f32 v61, v61, v13, v29
	v_fma_f32 v62, v62, v14, v30
	v_fma_f32 v63, v63, v15, v31
	v_fma_f32 v64, v64, v16, v32
	v_fma_f32 v65, v65, v17, v33
	v_fma_f32 v66, v66, v18, v34
	v_fma_f32 v67, v67, v19, v35
	v_fma_f32 v68, v68, v20, v36
	v_fma_f32 v69, v69, v21, v37
	v_fma_f32 v70, v70, v22, v38
	v_fma_f32 v71, v71, v23, v39
	v_fma_f32 v72, v72, v24, v40
	v_fma_f32 v73, v73, v25, v41
	v_add_f32_e32 v9, v58, v59
	v_add_f32_e32 v91, v60, v61
	v_mul_f32_e32 v90, v58, v58
	v_mul_f32_e32 v92, v59, v59
	v_add_f32_e32 v9, v9, v62
	v_add_f32_e32 v91, v91, v63
	v_add_f32_e32 v9, v9, v64
	v_add_f32_e32 v91, v91, v65
	v_add_f32_e32 v9, v9, v66
	v_add_f32_e32 v91, v91, v67
	v_add_f32_e32 v9, v9, v68
	v_add_f32_e32 v91, v91, v69
	v_add_f32_e32 v9, v9, v70
	v_add_f32_e32 v91, v91, v71
	v_add_f32_e32 v9, v9, v72
	v_add_f32_e32 v91, v91, v73
	v_fmac_f32_e32 v90, v60, v60
	v_fmac_f32_e32 v92, v61, v61
	v_fmac_f32_e32 v90, v62, v62
	v_fmac_f32_e32 v92, v63, v63
	v_fmac_f32_e32 v90, v64, v64
	v_fmac_f32_e32 v92, v65, v65
	v_fmac_f32_e32 v90, v66, v66
	v_fmac_f32_e32 v92, v67, v67
	v_fmac_f32_e32 v90, v68, v68
	v_fmac_f32_e32 v92, v69, v69
	v_fmac_f32_e32 v90, v70, v70
	v_fmac_f32_e32 v92, v71, v71
	v_fmac_f32_e32 v90, v72, v72
	v_fmac_f32_e32 v92, v73, v73
	v_add_f32_e32 v9, v9, v91
	v_add_f32_e32 v90, v90, v92
	ds_bpermute_b32 v91, v3, v9
	ds_bpermute_b32 v92, v3, v90
	s_waitcnt lgkmcnt(0)
; DI unsigned pk2(float lo, float hi) { f32x2 v = {lo, hi}; bf16x2_t b = __builtin_convertvector(v, bf16x2_t); return __builtin_bit_cast(unsigned, b); }
; DI void ln_row_v(const Frame& F, f32x4 (&v)[4], float* xout, const float* g, const float* b, const float* sh, const float* sc, bf16_t* hout, const float* slab, const float* gres, float* stat = nullptr) {
;     ...
;     if (g) {
;         float s = 0.f, s2 = 0.f;
; #pragma unroll
;         for (int j = 0; j < 4; ++j) { s += (v[j][0] + v[j][1]) + (v[j][2] + v[j][3]); s2 += (v[j][0] * v[j][0] + v[j][1] * v[j][1]) + (v[j][2] * v[j][2] + v[j][3] * v[j][3]); }
;         wave_sum2(s, s2, F.lane);
;         const float mean = s * (1.f / D); const float rstd = 1.f / sqrtf(fmaxf(s2 * (1.f / D) - mean * mean, 0.f) + EPS);
;         if (stat && F.lane == 0) { f32x2 sv = {mean, rstd}; *(f32x2*)stat = sv; }
; #pragma unroll
;         for (int j = 0; j < 4; ++j) { const f32x4 gg = ((const f32x4*)g)[F.lane + 64 * j], bb = ((const f32x4*)b)[F.lane + 64 * j];
;             v[j] = (v[j] - mean) * rstd * gg + bb; if (xout) ((f32x4*)xout)[F.lane + 64 * j] = v[j]; }
;     }
;     if (hout) {
;         float s = 0.f, s2 = 0.f;
; #pragma unroll
;         for (int j = 0; j < 4; ++j) { s += (v[j][0] + v[j][1]) + (v[j][2] + v[j][3]); s2 += (v[j][0] * v[j][0] + v[j][1] * v[j][1]) + (v[j][2] * v[j][2] + v[j][3] * v[j][3]); }
;         wave_sum2(s, s2, F.lane);
;         const float mean = s * (1.f / D); const float rstd = 1.f / sqrtf(fmaxf(s2 * (1.f / D) - mean * mean, 0.f) + EPS);
; #pragma unroll
;         for (int j = 0; j < 4; ++j) { const f32x4 hh = ((const f32x4*)sh)[F.lane + 64 * j], cc = ((const f32x4*)sc)[F.lane + 64 * j];
;             const f32x4 o = (v[j] - mean) * rstd * (cc + 1.f) + hh; u32x2 wv; wv.x = pk2(o[0], o[1]); wv.y = pk2(o[2], o[3]);
;             ((u32x2*)hout)[F.lane + 64 * j] = wv; }
;     }
	v_add_f32_e32 v9, v9, v91
	v_add_f32_e32 v90, v90, v92
	ds_bpermute_b32 v91, v4, v9
	ds_bpermute_b32 v92, v4, v90
	s_waitcnt lgkmcnt(0)
	v_add_f32_e32 v9, v9, v91
	v_add_f32_e32 v90, v90, v92
	ds_bpermute_b32 v91, v5, v9
	ds_bpermute_b32 v92, v5, v90
	s_waitcnt lgkmcnt(0)
	v_add_f32_e32 v9, v9, v91
	v_add_f32_e32 v90, v90, v92
	ds_bpermute_b32 v91, v6, v9
	ds_bpermute_b32 v92, v6, v90
	s_waitcnt lgkmcnt(0)
	v_add_f32_e32 v9, v9, v91
	v_add_f32_e32 v90, v90, v92
	ds_bpermute_b32 v91, v7, v9
	ds_bpermute_b32 v92, v7, v90
	s_waitcnt lgkmcnt(0)
	v_add_f32_e32 v9, v9, v91
	v_add_f32_e32 v90, v90, v92
	ds_bpermute_b32 v91, v8, v9
	ds_bpermute_b32 v92, v8, v90
	s_waitcnt lgkmcnt(0)
	v_add_f32_e32 v9, v9, v91
	v_add_f32_e32 v90, v90, v92
	v_mul_f32_e32 v93, 0x3a800000, v9
	v_mul_f32_e32 v91, 0x3a800000, v90
	v_fma_f32 v91, -v93, v93, v91
	v_max_f32_e32 v91, 0, v91
	v_add_f32_e32 v91, 0x358637bd, v91
	v_rsq_f32_e32 v94, v91
	v_mul_f32_e32 v91, 0.5, v91
	v_mul_f32_e32 v92, v94, v94
	v_fma_f32 v92, -v91, v92, 0.5
	v_fma_f32 v94, v94, v92, v94
	s_waitcnt vmcnt(26)
	v_sub_f32_e32 v58, v58, v93
	v_sub_f32_e32 v59, v59, v93
	v_sub_f32_e32 v60, v60, v93
	v_sub_f32_e32 v61, v61, v93
	v_sub_f32_e32 v62, v62, v93
	v_sub_f32_e32 v63, v63, v93
	v_sub_f32_e32 v64, v64, v93
	v_sub_f32_e32 v65, v65, v93
	v_sub_f32_e32 v66, v66, v93
	v_sub_f32_e32 v67, v67, v93
	v_sub_f32_e32 v68, v68, v93
	v_sub_f32_e32 v69, v69, v93
	v_sub_f32_e32 v70, v70, v93
	v_sub_f32_e32 v71, v71, v93
	v_sub_f32_e32 v72, v72, v93
	v_sub_f32_e32 v73, v73, v93
	v_add_f32_e32 v162, 1.0, v162
	v_add_f32_e32 v163, 1.0, v163
	v_add_f32_e32 v164, 1.0, v164
	v_add_f32_e32 v165, 1.0, v165
	v_add_f32_e32 v166, 1.0, v166
	v_add_f32_e32 v167, 1.0, v167
	v_add_f32_e32 v168, 1.0, v168
	v_add_f32_e32 v169, 1.0, v169
	v_add_f32_e32 v170, 1.0, v170
	v_add_f32_e32 v171, 1.0, v171
	v_add_f32_e32 v172, 1.0, v172
	v_add_f32_e32 v173, 1.0, v173
	v_add_f32_e32 v174, 1.0, v174
	v_add_f32_e32 v175, 1.0, v175
	v_add_f32_e32 v176, 1.0, v176
	v_add_f32_e32 v177, 1.0, v177
	v_mul_f32_e32 v58, v94, v58
	v_mul_f32_e32 v59, v94, v59
	v_mul_f32_e32 v60, v94, v60
	v_mul_f32_e32 v61, v94, v61
	v_mul_f32_e32 v62, v94, v62
	v_mul_f32_e32 v63, v94, v63
	v_mul_f32_e32 v64, v94, v64
	v_mul_f32_e32 v65, v94, v65
	v_mul_f32_e32 v66, v94, v66
	v_mul_f32_e32 v67, v94, v67
	v_mul_f32_e32 v68, v94, v68
	v_mul_f32_e32 v69, v94, v69
	v_mul_f32_e32 v70, v94, v70
	v_mul_f32_e32 v71, v94, v71
	v_mul_f32_e32 v72, v94, v72
	v_mul_f32_e32 v73, v94, v73
	v_fma_f32 v58, v58, v162, v146
	v_fma_f32 v59, v59, v163, v147
	v_fma_f32 v60, v60, v164, v148
	v_fma_f32 v61, v61, v165, v149
	v_fma_f32 v62, v62, v166, v150
	v_fma_f32 v63, v63, v167, v151
	v_fma_f32 v64, v64, v168, v152
	v_fma_f32 v65, v65, v169, v153
	v_fma_f32 v66, v66, v170, v154
	v_fma_f32 v67, v67, v171, v155
	v_fma_f32 v68, v68, v172, v156
	v_fma_f32 v69, v69, v173, v157
	v_fma_f32 v70, v70, v174, v158
	v_fma_f32 v71, v71, v175, v159
	v_fma_f32 v72, v72, v176, v160
	v_fma_f32 v73, v73, v177, v161
	v_cvt_pk_bf16_f32 v190, v58, v59
	v_cvt_pk_bf16_f32 v191, v60, v61
	v_cvt_pk_bf16_f32 v192, v62, v63
	v_cvt_pk_bf16_f32 v193, v64, v65
	v_cvt_pk_bf16_f32 v194, v66, v67
	v_cvt_pk_bf16_f32 v195, v68, v69
	v_cvt_pk_bf16_f32 v196, v70, v71
	v_cvt_pk_bf16_f32 v197, v72, v73
	s_add_u32 s2, s10, 0x400000
	s_addc_u32 s3, s11, 0
	global_store_dwordx2 v1, v[190:191], s[2:3]
	global_store_dwordx2 v1, v[192:193], s[2:3] offset:512
	global_store_dwordx2 v1, v[194:195], s[2:3] offset:1024
	global_store_dwordx2 v1, v[196:197], s[2:3] offset:1536
	s_add_u32 s2, s8, 0x2800000
	s_addc_u32 s3, s9, 0
	global_load_dwordx4 v[58:61], v0, s[2:3]
	global_load_dwordx4 v[62:65], v0, s[2:3] offset:1024
	global_load_dwordx4 v[66:69], v0, s[2:3] offset:2048
	global_load_dwordx4 v[70:73], v0, s[2:3] offset:3072
	s_add_u32 s2, s14, 0x12000
	s_addc_u32 s3, s15, 0
	global_load_dwordx4 v[146:149], v0, s[2:3]
	global_load_dwordx4 v[150:153], v0, s[2:3] offset:1024
	global_load_dwordx4 v[154:157], v0, s[2:3] offset:2048
	global_load_dwordx4 v[158:161], v0, s[2:3] offset:3072
	s_add_u32 s2, s18, 0x12000
	s_addc_u32 s3, s19, 0
	global_load_dwordx4 v[162:165], v0, s[2:3]
	global_load_dwordx4 v[166:169], v0, s[2:3] offset:1024
	global_load_dwordx4 v[170:173], v0, s[2:3] offset:2048
	global_load_dwordx4 v[174:177], v0, s[2:3] offset:3072
	s_waitcnt vmcnt(38)
	v_add_f32_e32 v9, v74, v75
	v_add_f32_e32 v91, v76, v77
	v_mul_f32_e32 v90, v74, v74
	v_mul_f32_e32 v92, v75, v75
	v_add_f32_e32 v9, v9, v78
	v_add_f32_e32 v91, v91, v79
	v_add_f32_e32 v9, v9, v80
	v_add_f32_e32 v91, v91, v81
	v_add_f32_e32 v9, v9, v82
	v_add_f32_e32 v91, v91, v83
	v_add_f32_e32 v9, v9, v84
	v_add_f32_e32 v91, v91, v85
	v_add_f32_e32 v9, v9, v86
	v_add_f32_e32 v91, v91, v87
	v_add_f32_e32 v9, v9, v88
	v_add_f32_e32 v91, v91, v89
	v_fmac_f32_e32 v90, v76, v76
	v_fmac_f32_e32 v92, v77, v77
	v_fmac_f32_e32 v90, v78, v78
	v_fmac_f32_e32 v92, v79, v79
	v_fmac_f32_e32 v90, v80, v80
	v_fmac_f32_e32 v92, v81, v81
	v_fmac_f32_e32 v90, v82, v82
	v_fmac_f32_e32 v92, v83, v83
	v_fmac_f32_e32 v90, v84, v84
	v_fmac_f32_e32 v92, v85, v85
	v_fmac_f32_e32 v90, v86, v86
	v_fmac_f32_e32 v92, v87, v87
	v_fmac_f32_e32 v90, v88, v88
	v_fmac_f32_e32 v92, v89, v89
	v_add_f32_e32 v9, v9, v91
	v_add_f32_e32 v90, v90, v92
	ds_bpermute_b32 v91, v3, v9
	ds_bpermute_b32 v92, v3, v90
	s_waitcnt lgkmcnt(0)
	v_add_f32_e32 v9, v9, v91
	v_add_f32_e32 v90, v90, v92
	ds_bpermute_b32 v91, v4, v9
	ds_bpermute_b32 v92, v4, v90
	s_waitcnt lgkmcnt(0)
	v_add_f32_e32 v9, v9, v91
	v_add_f32_e32 v90, v90, v92
	ds_bpermute_b32 v91, v5, v9
	ds_bpermute_b32 v92, v5, v90
	s_waitcnt lgkmcnt(0)
; DI unsigned pk2(float lo, float hi) { f32x2 v = {lo, hi}; bf16x2_t b = __builtin_convertvector(v, bf16x2_t); return __builtin_bit_cast(unsigned, b); }
; DI void ln_row_v(const Frame& F, f32x4 (&v)[4], float* xout, const float* g, const float* b, const float* sh, const float* sc, bf16_t* hout, const float* slab, const float* gres, float* stat = nullptr) {
;     ...
;     if (g) {
;         float s = 0.f, s2 = 0.f;
; #pragma unroll
;         for (int j = 0; j < 4; ++j) { s += (v[j][0] + v[j][1]) + (v[j][2] + v[j][3]); s2 += (v[j][0] * v[j][0] + v[j][1] * v[j][1]) + (v[j][2] * v[j][2] + v[j][3] * v[j][3]); }
;         wave_sum2(s, s2, F.lane);
;         const float mean = s * (1.f / D); const float rstd = 1.f / sqrtf(fmaxf(s2 * (1.f / D) - mean * mean, 0.f) + EPS);
;         if (stat && F.lane == 0) { f32x2 sv = {mean, rstd}; *(f32x2*)stat = sv; }
; #pragma unroll
;         for (int j = 0; j < 4; ++j) { const f32x4 gg = ((const f32x4*)g)[F.lane + 64 * j], bb = ((const f32x4*)b)[F.lane + 64 * j];
;             v[j] = (v[j] - mean) * rstd * gg + bb; if (xout) ((f32x4*)xout)[F.lane + 64 * j] = v[j]; }
;     }
;     if (hout) {
;         float s = 0.f, s2 = 0.f;
; #pragma unroll
;         for (int j = 0; j < 4; ++j) { s += (v[j][0] + v[j][1]) + (v[j][2] + v[j][3]); s2 += (v[j][0] * v[j][0] + v[j][1] * v[j][1]) + (v[j][2] * v[j][2] + v[j][3] * v[j][3]); }
;         wave_sum2(s, s2, F.lane);
;         const float mean = s * (1.f / D); const float rstd = 1.f / sqrtf(fmaxf(s2 * (1.f / D) - mean * mean, 0.f) + EPS);
; #pragma unroll
;         for (int j = 0; j < 4; ++j) { const f32x4 hh = ((const f32x4*)sh)[F.lane + 64 * j], cc = ((const f32x4*)sc)[F.lane + 64 * j];
;             const f32x4 o = (v[j] - mean) * rstd * (cc + 1.f) + hh; u32x2 wv; wv.x = pk2(o[0], o[1]); wv.y = pk2(o[2], o[3]);
;             ((u32x2*)hout)[F.lane + 64 * j] = wv; }
;     }
	v_add_f32_e32 v9, v9, v91
	v_add_f32_e32 v90, v90, v92
	ds_bpermute_b32 v91, v6, v9
	ds_bpermute_b32 v92, v6, v90
	s_waitcnt lgkmcnt(0)
	v_add_f32_e32 v9, v9, v91
	v_add_f32_e32 v90, v90, v92
	ds_bpermute_b32 v91, v7, v9
	ds_bpermute_b32 v92, v7, v90
	s_waitcnt lgkmcnt(0)
	v_add_f32_e32 v9, v9, v91
	v_add_f32_e32 v90, v90, v92
	ds_bpermute_b32 v91, v8, v9
	ds_bpermute_b32 v92, v8, v90
	s_waitcnt lgkmcnt(0)
	v_add_f32_e32 v9, v9, v91
	v_add_f32_e32 v90, v90, v92
	v_mul_f32_e32 v93, 0x3a800000, v9
	v_mul_f32_e32 v91, 0x3a800000, v90
	v_fma_f32 v91, -v93, v93, v91
	v_max_f32_e32 v91, 0, v91
	v_add_f32_e32 v91, 0x358637bd, v91
	v_rsq_f32_e32 v94, v91
	v_mul_f32_e32 v91, 0.5, v91
	v_mul_f32_e32 v92, v94, v94
	v_fma_f32 v92, -v91, v92, 0.5
	v_fma_f32 v94, v94, v92, v94
	s_add_u32 s2, s12, 0x8000
	s_addc_u32 s3, s13, 0
	v_mov_b32_e32 v188, v93
	v_mov_b32_e32 v189, v94
	s_mov_b64 exec, 1
	global_store_dwordx2 v97, v[188:189], s[2:3]
	s_mov_b64 exec, -1
	v_sub_f32_e32 v74, v74, v93
	v_sub_f32_e32 v75, v75, v93
	v_sub_f32_e32 v76, v76, v93
	v_sub_f32_e32 v77, v77, v93
	v_sub_f32_e32 v78, v78, v93
	v_sub_f32_e32 v79, v79, v93
	v_sub_f32_e32 v80, v80, v93
	v_sub_f32_e32 v81, v81, v93
	v_sub_f32_e32 v82, v82, v93
	v_sub_f32_e32 v83, v83, v93
	v_sub_f32_e32 v84, v84, v93
	v_sub_f32_e32 v85, v85, v93
	v_sub_f32_e32 v86, v86, v93
	v_sub_f32_e32 v87, v87, v93
	v_sub_f32_e32 v88, v88, v93
	v_sub_f32_e32 v89, v89, v93
	v_mul_f32_e32 v74, v94, v74
	v_mul_f32_e32 v75, v94, v75
	v_mul_f32_e32 v76, v94, v76
	v_mul_f32_e32 v77, v94, v77
	v_mul_f32_e32 v78, v94, v78
	v_mul_f32_e32 v79, v94, v79
	v_mul_f32_e32 v80, v94, v80
	v_mul_f32_e32 v81, v94, v81
	v_mul_f32_e32 v82, v94, v82
	v_mul_f32_e32 v83, v94, v83
	v_mul_f32_e32 v84, v94, v84
	v_mul_f32_e32 v85, v94, v85
	v_mul_f32_e32 v86, v94, v86
	v_mul_f32_e32 v87, v94, v87
	v_mul_f32_e32 v88, v94, v88
	v_mul_f32_e32 v89, v94, v89
	v_fma_f32 v74, v74, v10, v26
	v_fma_f32 v75, v75, v11, v27
	v_fma_f32 v76, v76, v12, v28
	v_fma_f32 v77, v77, v13, v29
	v_fma_f32 v78, v78, v14, v30
	v_fma_f32 v79, v79, v15, v31
	v_fma_f32 v80, v80, v16, v32
	v_fma_f32 v81, v81, v17, v33
	v_fma_f32 v82, v82, v18, v34
	v_fma_f32 v83, v83, v19, v35
	v_fma_f32 v84, v84, v20, v36
	v_fma_f32 v85, v85, v21, v37
	v_fma_f32 v86, v86, v22, v38
	v_fma_f32 v87, v87, v23, v39
	v_fma_f32 v88, v88, v24, v40
	v_fma_f32 v89, v89, v25, v41
	v_add_f32_e32 v9, v74, v75
	v_add_f32_e32 v91, v76, v77
	v_mul_f32_e32 v90, v74, v74
	v_mul_f32_e32 v92, v75, v75
	v_add_f32_e32 v9, v9, v78
	v_add_f32_e32 v91, v91, v79
	v_add_f32_e32 v9, v9, v80
	v_add_f32_e32 v91, v91, v81
	v_add_f32_e32 v9, v9, v82
	v_add_f32_e32 v91, v91, v83
	v_add_f32_e32 v9, v9, v84
	v_add_f32_e32 v91, v91, v85
	v_add_f32_e32 v9, v9, v86
	v_add_f32_e32 v91, v91, v87
	v_add_f32_e32 v9, v9, v88
	v_add_f32_e32 v91, v91, v89
	v_fmac_f32_e32 v90, v76, v76
	v_fmac_f32_e32 v92, v77, v77
	v_fmac_f32_e32 v90, v78, v78
	v_fmac_f32_e32 v92, v79, v79
	v_fmac_f32_e32 v90, v80, v80
	v_fmac_f32_e32 v92, v81, v81
	v_fmac_f32_e32 v90, v82, v82
	v_fmac_f32_e32 v92, v83, v83
	v_fmac_f32_e32 v90, v84, v84
	v_fmac_f32_e32 v92, v85, v85
	v_fmac_f32_e32 v90, v86, v86
	v_fmac_f32_e32 v92, v87, v87
	v_fmac_f32_e32 v90, v88, v88
	v_fmac_f32_e32 v92, v89, v89
	v_add_f32_e32 v9, v9, v91
	v_add_f32_e32 v90, v90, v92
	ds_bpermute_b32 v91, v3, v9
	ds_bpermute_b32 v92, v3, v90
	s_waitcnt lgkmcnt(0)
	v_add_f32_e32 v9, v9, v91
	v_add_f32_e32 v90, v90, v92
	ds_bpermute_b32 v91, v4, v9
	ds_bpermute_b32 v92, v4, v90
	s_waitcnt lgkmcnt(0)
	v_add_f32_e32 v9, v9, v91
	v_add_f32_e32 v90, v90, v92
	ds_bpermute_b32 v91, v5, v9
	ds_bpermute_b32 v92, v5, v90
	s_waitcnt lgkmcnt(0)
	v_add_f32_e32 v9, v9, v91
	v_add_f32_e32 v90, v90, v92
	ds_bpermute_b32 v91, v6, v9
	ds_bpermute_b32 v92, v6, v90
	s_waitcnt lgkmcnt(0)
	v_add_f32_e32 v9, v9, v91
	v_add_f32_e32 v90, v90, v92
	ds_bpermute_b32 v91, v7, v9
	ds_bpermute_b32 v92, v7, v90
	s_waitcnt lgkmcnt(0)
	v_add_f32_e32 v9, v9, v91
	v_add_f32_e32 v90, v90, v92
	ds_bpermute_b32 v91, v8, v9
	ds_bpermute_b32 v92, v8, v90
	s_waitcnt lgkmcnt(0)
	v_add_f32_e32 v9, v9, v91
	v_add_f32_e32 v90, v90, v92
	v_mul_f32_e32 v93, 0x3a800000, v9
	v_mul_f32_e32 v91, 0x3a800000, v90
	v_fma_f32 v91, -v93, v93, v91
	v_max_f32_e32 v91, 0, v91
	v_add_f32_e32 v91, 0x358637bd, v91
	v_rsq_f32_e32 v94, v91
	v_mul_f32_e32 v91, 0.5, v91
	v_mul_f32_e32 v92, v94, v94
	v_fma_f32 v92, -v91, v92, 0.5
	v_fma_f32 v94, v94, v92, v94
	s_waitcnt vmcnt(18)
; DI unsigned pk2(float lo, float hi) { f32x2 v = {lo, hi}; bf16x2_t b = __builtin_convertvector(v, bf16x2_t); return __builtin_bit_cast(unsigned, b); }
; DI void ln_row_v(const Frame& F, f32x4 (&v)[4], float* xout, const float* g, const float* b, const float* sh, const float* sc, bf16_t* hout, const float* slab, const float* gres, float* stat = nullptr) {
;     ...
;     if (g) {
;         float s = 0.f, s2 = 0.f;
; #pragma unroll
;         for (int j = 0; j < 4; ++j) { s += (v[j][0] + v[j][1]) + (v[j][2] + v[j][3]); s2 += (v[j][0] * v[j][0] + v[j][1] * v[j][1]) + (v[j][2] * v[j][2] + v[j][3] * v[j][3]); }
;         wave_sum2(s, s2, F.lane);
;         const float mean = s * (1.f / D); const float rstd = 1.f / sqrtf(fmaxf(s2 * (1.f / D) - mean * mean, 0.f) + EPS);
;         if (stat && F.lane == 0) { f32x2 sv = {mean, rstd}; *(f32x2*)stat = sv; }
; #pragma unroll
;         for (int j = 0; j < 4; ++j) { const f32x4 gg = ((const f32x4*)g)[F.lane + 64 * j], bb = ((const f32x4*)b)[F.lane + 64 * j];
;             v[j] = (v[j] - mean) * rstd * gg + bb; if (xout) ((f32x4*)xout)[F.lane + 64 * j] = v[j]; }
;     }
;     if (hout) {
;         float s = 0.f, s2 = 0.f;
; #pragma unroll
;         for (int j = 0; j < 4; ++j) { s += (v[j][0] + v[j][1]) + (v[j][2] + v[j][3]); s2 += (v[j][0] * v[j][0] + v[j][1] * v[j][1]) + (v[j][2] * v[j][2] + v[j][3] * v[j][3]); }
;         wave_sum2(s, s2, F.lane);
;         const float mean = s * (1.f / D); const float rstd = 1.f / sqrtf(fmaxf(s2 * (1.f / D) - mean * mean, 0.f) + EPS);
; #pragma unroll
;         for (int j = 0; j < 4; ++j) { const f32x4 hh = ((const f32x4*)sh)[F.lane + 64 * j], cc = ((const f32x4*)sc)[F.lane + 64 * j];
;             const f32x4 o = (v[j] - mean) * rstd * (cc + 1.f) + hh; u32x2 wv; wv.x = pk2(o[0], o[1]); wv.y = pk2(o[2], o[3]);
;             ((u32x2*)hout)[F.lane + 64 * j] = wv; }
;     }
	v_sub_f32_e32 v74, v74, v93
	v_sub_f32_e32 v75, v75, v93
	v_sub_f32_e32 v76, v76, v93
	v_sub_f32_e32 v77, v77, v93
	v_sub_f32_e32 v78, v78, v93
	v_sub_f32_e32 v79, v79, v93
	v_sub_f32_e32 v80, v80, v93
	v_sub_f32_e32 v81, v81, v93
	v_sub_f32_e32 v82, v82, v93
	v_sub_f32_e32 v83, v83, v93
	v_sub_f32_e32 v84, v84, v93
	v_sub_f32_e32 v85, v85, v93
	v_sub_f32_e32 v86, v86, v93
	v_sub_f32_e32 v87, v87, v93
	v_sub_f32_e32 v88, v88, v93
	v_sub_f32_e32 v89, v89, v93
	v_add_f32_e32 v130, 1.0, v130
	v_add_f32_e32 v131, 1.0, v131
	v_add_f32_e32 v132, 1.0, v132
	v_add_f32_e32 v133, 1.0, v133
	v_add_f32_e32 v134, 1.0, v134
	v_add_f32_e32 v135, 1.0, v135
	v_add_f32_e32 v136, 1.0, v136
	v_add_f32_e32 v137, 1.0, v137
	v_add_f32_e32 v138, 1.0, v138
	v_add_f32_e32 v139, 1.0, v139
	v_add_f32_e32 v140, 1.0, v140
	v_add_f32_e32 v141, 1.0, v141
	v_add_f32_e32 v142, 1.0, v142
	v_add_f32_e32 v143, 1.0, v143
	v_add_f32_e32 v144, 1.0, v144
	v_add_f32_e32 v145, 1.0, v145
	v_mul_f32_e32 v74, v94, v74
	v_mul_f32_e32 v75, v94, v75
	v_mul_f32_e32 v76, v94, v76
	v_mul_f32_e32 v77, v94, v77
	v_mul_f32_e32 v78, v94, v78
	v_mul_f32_e32 v79, v94, v79
	v_mul_f32_e32 v80, v94, v80
	v_mul_f32_e32 v81, v94, v81
	v_mul_f32_e32 v82, v94, v82
	v_mul_f32_e32 v83, v94, v83
	v_mul_f32_e32 v84, v94, v84
	v_mul_f32_e32 v85, v94, v85
	v_mul_f32_e32 v86, v94, v86
	v_mul_f32_e32 v87, v94, v87
	v_mul_f32_e32 v88, v94, v88
	v_mul_f32_e32 v89, v94, v89
	v_fma_f32 v74, v74, v130, v114
	v_fma_f32 v75, v75, v131, v115
	v_fma_f32 v76, v76, v132, v116
	v_fma_f32 v77, v77, v133, v117
	v_fma_f32 v78, v78, v134, v118
	v_fma_f32 v79, v79, v135, v119
	v_fma_f32 v80, v80, v136, v120
	v_fma_f32 v81, v81, v137, v121
	v_fma_f32 v82, v82, v138, v122
	v_fma_f32 v83, v83, v139, v123
	v_fma_f32 v84, v84, v140, v124
	v_fma_f32 v85, v85, v141, v125
	v_fma_f32 v86, v86, v142, v126
	v_fma_f32 v87, v87, v143, v127
	v_fma_f32 v88, v88, v144, v128
	v_fma_f32 v89, v89, v145, v129
	v_cvt_pk_bf16_f32 v190, v74, v75
	v_cvt_pk_bf16_f32 v191, v76, v77
	v_cvt_pk_bf16_f32 v192, v78, v79
	v_cvt_pk_bf16_f32 v193, v80, v81
	v_cvt_pk_bf16_f32 v194, v82, v83
	v_cvt_pk_bf16_f32 v195, v84, v85
	v_cvt_pk_bf16_f32 v196, v86, v87
	v_cvt_pk_bf16_f32 v197, v88, v89
	s_add_u32 s2, s10, 0x800000
	s_addc_u32 s3, s11, 0
	global_store_dwordx2 v1, v[190:191], s[2:3]
	global_store_dwordx2 v1, v[192:193], s[2:3] offset:512
	global_store_dwordx2 v1, v[194:195], s[2:3] offset:1024
	global_store_dwordx2 v1, v[196:197], s[2:3] offset:1536
	s_add_u32 s2, s8, 0x3000000
	s_addc_u32 s3, s9, 0
	global_load_dwordx4 v[74:77], v0, s[2:3]
	global_load_dwordx4 v[78:81], v0, s[2:3] offset:1024
	global_load_dwordx4 v[82:85], v0, s[2:3] offset:2048
	global_load_dwordx4 v[86:89], v0, s[2:3] offset:3072
	s_add_u32 s2, s14, 0x18000
	s_addc_u32 s3, s15, 0
	global_load_dwordx4 v[114:117], v0, s[2:3]
	global_load_dwordx4 v[118:121], v0, s[2:3] offset:1024
	global_load_dwordx4 v[122:125], v0, s[2:3] offset:2048
	global_load_dwordx4 v[126:129], v0, s[2:3] offset:3072
	s_add_u32 s2, s18, 0x18000
	s_addc_u32 s3, s19, 0
	global_load_dwordx4 v[130:133], v0, s[2:3]
	global_load_dwordx4 v[134:137], v0, s[2:3] offset:1024
	global_load_dwordx4 v[138:141], v0, s[2:3] offset:2048
	global_load_dwordx4 v[142:145], v0, s[2:3] offset:3072
	v_add_f32_e32 v9, v98, v99
	v_add_f32_e32 v91, v100, v101
	v_mul_f32_e32 v90, v98, v98
	v_mul_f32_e32 v92, v99, v99
	v_add_f32_e32 v9, v9, v102
	v_add_f32_e32 v91, v91, v103
	v_add_f32_e32 v9, v9, v104
	v_add_f32_e32 v91, v91, v105
	v_add_f32_e32 v9, v9, v106
	v_add_f32_e32 v91, v91, v107
	v_add_f32_e32 v9, v9, v108
	v_add_f32_e32 v91, v91, v109
	v_add_f32_e32 v9, v9, v110
	v_add_f32_e32 v91, v91, v111
	v_add_f32_e32 v9, v9, v112
	v_add_f32_e32 v91, v91, v113
	v_fmac_f32_e32 v90, v100, v100
	v_fmac_f32_e32 v92, v101, v101
	v_fmac_f32_e32 v90, v102, v102
	v_fmac_f32_e32 v92, v103, v103
	v_fmac_f32_e32 v90, v104, v104
	v_fmac_f32_e32 v92, v105, v105
	v_fmac_f32_e32 v90, v106, v106
	v_fmac_f32_e32 v92, v107, v107
	v_fmac_f32_e32 v90, v108, v108
	v_fmac_f32_e32 v92, v109, v109
	v_fmac_f32_e32 v90, v110, v110
	v_fmac_f32_e32 v92, v111, v111
	v_fmac_f32_e32 v90, v112, v112
	v_fmac_f32_e32 v92, v113, v113
	v_add_f32_e32 v9, v9, v91
	v_add_f32_e32 v90, v90, v92
	ds_bpermute_b32 v91, v3, v9
	ds_bpermute_b32 v92, v3, v90
	s_waitcnt lgkmcnt(0)
	v_add_f32_e32 v9, v9, v91
	v_add_f32_e32 v90, v90, v92
	ds_bpermute_b32 v91, v4, v9
	ds_bpermute_b32 v92, v4, v90
	s_waitcnt lgkmcnt(0)
	v_add_f32_e32 v9, v9, v91
	v_add_f32_e32 v90, v90, v92
	ds_bpermute_b32 v91, v5, v9
	ds_bpermute_b32 v92, v5, v90
	s_waitcnt lgkmcnt(0)
	v_add_f32_e32 v9, v9, v91
	v_add_f32_e32 v90, v90, v92
	ds_bpermute_b32 v91, v6, v9
	ds_bpermute_b32 v92, v6, v90
	s_waitcnt lgkmcnt(0)
	v_add_f32_e32 v9, v9, v91
	v_add_f32_e32 v90, v90, v92
	ds_bpermute_b32 v91, v7, v9
	ds_bpermute_b32 v92, v7, v90
	s_waitcnt lgkmcnt(0)
	v_add_f32_e32 v9, v9, v91
	v_add_f32_e32 v90, v90, v92
	ds_bpermute_b32 v91, v8, v9
	ds_bpermute_b32 v92, v8, v90
	s_waitcnt lgkmcnt(0)
; DI unsigned pk2(float lo, float hi) { f32x2 v = {lo, hi}; bf16x2_t b = __builtin_convertvector(v, bf16x2_t); return __builtin_bit_cast(unsigned, b); }
; DI void ln_row_v(const Frame& F, f32x4 (&v)[4], float* xout, const float* g, const float* b, const float* sh, const float* sc, bf16_t* hout, const float* slab, const float* gres, float* stat = nullptr) {
;     ...
;     if (g) {
;         float s = 0.f, s2 = 0.f;
; #pragma unroll
;         for (int j = 0; j < 4; ++j) { s += (v[j][0] + v[j][1]) + (v[j][2] + v[j][3]); s2 += (v[j][0] * v[j][0] + v[j][1] * v[j][1]) + (v[j][2] * v[j][2] + v[j][3] * v[j][3]); }
;         wave_sum2(s, s2, F.lane);
;         const float mean = s * (1.f / D); const float rstd = 1.f / sqrtf(fmaxf(s2 * (1.f / D) - mean * mean, 0.f) + EPS);
;         if (stat && F.lane == 0) { f32x2 sv = {mean, rstd}; *(f32x2*)stat = sv; }
; #pragma unroll
;         for (int j = 0; j < 4; ++j) { const f32x4 gg = ((const f32x4*)g)[F.lane + 64 * j], bb = ((const f32x4*)b)[F.lane + 64 * j];
;             v[j] = (v[j] - mean) * rstd * gg + bb; if (xout) ((f32x4*)xout)[F.lane + 64 * j] = v[j]; }
;     }
;     if (hout) {
;         float s = 0.f, s2 = 0.f;
; #pragma unroll
;         for (int j = 0; j < 4; ++j) { s += (v[j][0] + v[j][1]) + (v[j][2] + v[j][3]); s2 += (v[j][0] * v[j][0] + v[j][1] * v[j][1]) + (v[j][2] * v[j][2] + v[j][3] * v[j][3]); }
;         wave_sum2(s, s2, F.lane);
;         const float mean = s * (1.f / D); const float rstd = 1.f / sqrtf(fmaxf(s2 * (1.f / D) - mean * mean, 0.f) + EPS);
; #pragma unroll
;         for (int j = 0; j < 4; ++j) { const f32x4 hh = ((const f32x4*)sh)[F.lane + 64 * j], cc = ((const f32x4*)sc)[F.lane + 64 * j];
;             const f32x4 o = (v[j] - mean) * rstd * (cc + 1.f) + hh; u32x2 wv; wv.x = pk2(o[0], o[1]); wv.y = pk2(o[2], o[3]);
;             ((u32x2*)hout)[F.lane + 64 * j] = wv; }
;     }
	v_add_f32_e32 v9, v9, v91
	v_add_f32_e32 v90, v90, v92
	v_mul_f32_e32 v93, 0x3a800000, v9
	v_mul_f32_e32 v91, 0x3a800000, v90
	v_fma_f32 v91, -v93, v93, v91
	v_max_f32_e32 v91, 0, v91
	v_add_f32_e32 v91, 0x358637bd, v91
	v_rsq_f32_e32 v94, v91
	v_mul_f32_e32 v91, 0.5, v91
	v_mul_f32_e32 v92, v94, v94
	v_fma_f32 v92, -v91, v92, 0.5
	v_fma_f32 v94, v94, v92, v94
	s_add_u32 s2, s12, 0xc000
	s_addc_u32 s3, s13, 0
	v_mov_b32_e32 v188, v93
	v_mov_b32_e32 v189, v94
	s_mov_b64 exec, 1
	global_store_dwordx2 v97, v[188:189], s[2:3]
	s_mov_b64 exec, -1
	v_sub_f32_e32 v98, v98, v93
	v_sub_f32_e32 v99, v99, v93
	v_sub_f32_e32 v100, v100, v93
	v_sub_f32_e32 v101, v101, v93
	v_sub_f32_e32 v102, v102, v93
	v_sub_f32_e32 v103, v103, v93
	v_sub_f32_e32 v104, v104, v93
	v_sub_f32_e32 v105, v105, v93
	v_sub_f32_e32 v106, v106, v93
	v_sub_f32_e32 v107, v107, v93
	v_sub_f32_e32 v108, v108, v93
	v_sub_f32_e32 v109, v109, v93
	v_sub_f32_e32 v110, v110, v93
	v_sub_f32_e32 v111, v111, v93
	v_sub_f32_e32 v112, v112, v93
	v_sub_f32_e32 v113, v113, v93
	v_mul_f32_e32 v98, v94, v98
	v_mul_f32_e32 v99, v94, v99
	v_mul_f32_e32 v100, v94, v100
	v_mul_f32_e32 v101, v94, v101
	v_mul_f32_e32 v102, v94, v102
	v_mul_f32_e32 v103, v94, v103
	v_mul_f32_e32 v104, v94, v104
	v_mul_f32_e32 v105, v94, v105
	v_mul_f32_e32 v106, v94, v106
	v_mul_f32_e32 v107, v94, v107
	v_mul_f32_e32 v108, v94, v108
	v_mul_f32_e32 v109, v94, v109
	v_mul_f32_e32 v110, v94, v110
	v_mul_f32_e32 v111, v94, v111
	v_mul_f32_e32 v112, v94, v112
	v_mul_f32_e32 v113, v94, v113
	v_fma_f32 v98, v98, v10, v26
	v_fma_f32 v99, v99, v11, v27
	v_fma_f32 v100, v100, v12, v28
	v_fma_f32 v101, v101, v13, v29
	v_fma_f32 v102, v102, v14, v30
	v_fma_f32 v103, v103, v15, v31
	v_fma_f32 v104, v104, v16, v32
	v_fma_f32 v105, v105, v17, v33
	v_fma_f32 v106, v106, v18, v34
	v_fma_f32 v107, v107, v19, v35
	v_fma_f32 v108, v108, v20, v36
	v_fma_f32 v109, v109, v21, v37
	v_fma_f32 v110, v110, v22, v38
	v_fma_f32 v111, v111, v23, v39
	v_fma_f32 v112, v112, v24, v40
	v_fma_f32 v113, v113, v25, v41
	v_add_f32_e32 v9, v98, v99
	v_add_f32_e32 v91, v100, v101
	v_mul_f32_e32 v90, v98, v98
	v_mul_f32_e32 v92, v99, v99
	v_add_f32_e32 v9, v9, v102
	v_add_f32_e32 v91, v91, v103
	v_add_f32_e32 v9, v9, v104
	v_add_f32_e32 v91, v91, v105
	v_add_f32_e32 v9, v9, v106
	v_add_f32_e32 v91, v91, v107
	v_add_f32_e32 v9, v9, v108
	v_add_f32_e32 v91, v91, v109
	v_add_f32_e32 v9, v9, v110
	v_add_f32_e32 v91, v91, v111
	v_add_f32_e32 v9, v9, v112
	v_add_f32_e32 v91, v91, v113
	v_fmac_f32_e32 v90, v100, v100
	v_fmac_f32_e32 v92, v101, v101
	v_fmac_f32_e32 v90, v102, v102
	v_fmac_f32_e32 v92, v103, v103
	v_fmac_f32_e32 v90, v104, v104
	v_fmac_f32_e32 v92, v105, v105
	v_fmac_f32_e32 v90, v106, v106
	v_fmac_f32_e32 v92, v107, v107
	v_fmac_f32_e32 v90, v108, v108
	v_fmac_f32_e32 v92, v109, v109
	v_fmac_f32_e32 v90, v110, v110
	v_fmac_f32_e32 v92, v111, v111
	v_fmac_f32_e32 v90, v112, v112
	v_fmac_f32_e32 v92, v113, v113
	v_add_f32_e32 v9, v9, v91
	v_add_f32_e32 v90, v90, v92
	ds_bpermute_b32 v91, v3, v9
	ds_bpermute_b32 v92, v3, v90
	s_waitcnt lgkmcnt(0)
	v_add_f32_e32 v9, v9, v91
	v_add_f32_e32 v90, v90, v92
	ds_bpermute_b32 v91, v4, v9
	ds_bpermute_b32 v92, v4, v90
	s_waitcnt lgkmcnt(0)
	v_add_f32_e32 v9, v9, v91
	v_add_f32_e32 v90, v90, v92
	ds_bpermute_b32 v91, v5, v9
	ds_bpermute_b32 v92, v5, v90
	s_waitcnt lgkmcnt(0)
	v_add_f32_e32 v9, v9, v91
	v_add_f32_e32 v90, v90, v92
	ds_bpermute_b32 v91, v6, v9
	ds_bpermute_b32 v92, v6, v90
	s_waitcnt lgkmcnt(0)
	v_add_f32_e32 v9, v9, v91
	v_add_f32_e32 v90, v90, v92
	ds_bpermute_b32 v91, v7, v9
	ds_bpermute_b32 v92, v7, v90
	s_waitcnt lgkmcnt(0)
	v_add_f32_e32 v9, v9, v91
	v_add_f32_e32 v90, v90, v92
	ds_bpermute_b32 v91, v8, v9
	ds_bpermute_b32 v92, v8, v90
	s_waitcnt lgkmcnt(0)
	v_add_f32_e32 v9, v9, v91
	v_add_f32_e32 v90, v90, v92
	v_mul_f32_e32 v93, 0x3a800000, v9
	v_mul_f32_e32 v91, 0x3a800000, v90
	v_fma_f32 v91, -v93, v93, v91
	v_max_f32_e32 v91, 0, v91
	v_add_f32_e32 v91, 0x358637bd, v91
	v_rsq_f32_e32 v94, v91
	v_mul_f32_e32 v91, 0.5, v91
	v_mul_f32_e32 v92, v94, v94
	v_fma_f32 v92, -v91, v92, 0.5
	v_fma_f32 v94, v94, v92, v94
	s_waitcnt vmcnt(18)
	v_sub_f32_e32 v98, v98, v93
	v_sub_f32_e32 v99, v99, v93
	v_sub_f32_e32 v100, v100, v93
	v_sub_f32_e32 v101, v101, v93
	v_sub_f32_e32 v102, v102, v93
	v_sub_f32_e32 v103, v103, v93
	v_sub_f32_e32 v104, v104, v93
	v_sub_f32_e32 v105, v105, v93
	v_sub_f32_e32 v106, v106, v93
	v_sub_f32_e32 v107, v107, v93
	v_sub_f32_e32 v108, v108, v93
	v_sub_f32_e32 v109, v109, v93
	v_sub_f32_e32 v110, v110, v93
	v_sub_f32_e32 v111, v111, v93
	v_sub_f32_e32 v112, v112, v93
	v_sub_f32_e32 v113, v113, v93
	v_add_f32_e32 v162, 1.0, v162
	v_add_f32_e32 v163, 1.0, v163
	v_add_f32_e32 v164, 1.0, v164
	v_add_f32_e32 v165, 1.0, v165
	v_add_f32_e32 v166, 1.0, v166
	v_add_f32_e32 v167, 1.0, v167
	v_add_f32_e32 v168, 1.0, v168
	v_add_f32_e32 v169, 1.0, v169
	v_add_f32_e32 v170, 1.0, v170
	v_add_f32_e32 v171, 1.0, v171
	v_add_f32_e32 v172, 1.0, v172
	v_add_f32_e32 v173, 1.0, v173
	v_add_f32_e32 v174, 1.0, v174
	v_add_f32_e32 v175, 1.0, v175
	v_add_f32_e32 v176, 1.0, v176
	v_add_f32_e32 v177, 1.0, v177
	v_mul_f32_e32 v98, v94, v98
	v_mul_f32_e32 v99, v94, v99
	v_mul_f32_e32 v100, v94, v100
	v_mul_f32_e32 v101, v94, v101
	v_mul_f32_e32 v102, v94, v102
	v_mul_f32_e32 v103, v94, v103
	v_mul_f32_e32 v104, v94, v104
	v_mul_f32_e32 v105, v94, v105
	v_mul_f32_e32 v106, v94, v106
	v_mul_f32_e32 v107, v94, v107
	v_mul_f32_e32 v108, v94, v108
	v_mul_f32_e32 v109, v94, v109
	v_mul_f32_e32 v110, v94, v110
	v_mul_f32_e32 v111, v94, v111
	v_mul_f32_e32 v112, v94, v112
	v_mul_f32_e32 v113, v94, v113
; DI unsigned pk2(float lo, float hi) { f32x2 v = {lo, hi}; bf16x2_t b = __builtin_convertvector(v, bf16x2_t); return __builtin_bit_cast(unsigned, b); }
; DI void ln_row_v(const Frame& F, f32x4 (&v)[4], float* xout, const float* g, const float* b, const float* sh, const float* sc, bf16_t* hout, const float* slab, const float* gres, float* stat = nullptr) {
;     ...
;     if (g) {
;         float s = 0.f, s2 = 0.f;
; #pragma unroll
;         for (int j = 0; j < 4; ++j) { s += (v[j][0] + v[j][1]) + (v[j][2] + v[j][3]); s2 += (v[j][0] * v[j][0] + v[j][1] * v[j][1]) + (v[j][2] * v[j][2] + v[j][3] * v[j][3]); }
;         wave_sum2(s, s2, F.lane);
;         const float mean = s * (1.f / D); const float rstd = 1.f / sqrtf(fmaxf(s2 * (1.f / D) - mean * mean, 0.f) + EPS);
;         if (stat && F.lane == 0) { f32x2 sv = {mean, rstd}; *(f32x2*)stat = sv; }
; #pragma unroll
;         for (int j = 0; j < 4; ++j) { const f32x4 gg = ((const f32x4*)g)[F.lane + 64 * j], bb = ((const f32x4*)b)[F.lane + 64 * j];
;             v[j] = (v[j] - mean) * rstd * gg + bb; if (xout) ((f32x4*)xout)[F.lane + 64 * j] = v[j]; }
;     }
;     if (hout) {
;         float s = 0.f, s2 = 0.f;
; #pragma unroll
;         for (int j = 0; j < 4; ++j) { s += (v[j][0] + v[j][1]) + (v[j][2] + v[j][3]); s2 += (v[j][0] * v[j][0] + v[j][1] * v[j][1]) + (v[j][2] * v[j][2] + v[j][3] * v[j][3]); }
;         wave_sum2(s, s2, F.lane);
;         const float mean = s * (1.f / D); const float rstd = 1.f / sqrtf(fmaxf(s2 * (1.f / D) - mean * mean, 0.f) + EPS);
; #pragma unroll
;         for (int j = 0; j < 4; ++j) { const f32x4 hh = ((const f32x4*)sh)[F.lane + 64 * j], cc = ((const f32x4*)sc)[F.lane + 64 * j];
;             const f32x4 o = (v[j] - mean) * rstd * (cc + 1.f) + hh; u32x2 wv; wv.x = pk2(o[0], o[1]); wv.y = pk2(o[2], o[3]);
;             ((u32x2*)hout)[F.lane + 64 * j] = wv; }
;     }
	v_fma_f32 v98, v98, v162, v146
	v_fma_f32 v99, v99, v163, v147
	v_fma_f32 v100, v100, v164, v148
	v_fma_f32 v101, v101, v165, v149
	v_fma_f32 v102, v102, v166, v150
	v_fma_f32 v103, v103, v167, v151
	v_fma_f32 v104, v104, v168, v152
	v_fma_f32 v105, v105, v169, v153
	v_fma_f32 v106, v106, v170, v154
	v_fma_f32 v107, v107, v171, v155
	v_fma_f32 v108, v108, v172, v156
	v_fma_f32 v109, v109, v173, v157
	v_fma_f32 v110, v110, v174, v158
	v_fma_f32 v111, v111, v175, v159
	v_fma_f32 v112, v112, v176, v160
	v_fma_f32 v113, v113, v177, v161
	v_cvt_pk_bf16_f32 v190, v98, v99
	v_cvt_pk_bf16_f32 v191, v100, v101
	v_cvt_pk_bf16_f32 v192, v102, v103
	v_cvt_pk_bf16_f32 v193, v104, v105
	v_cvt_pk_bf16_f32 v194, v106, v107
	v_cvt_pk_bf16_f32 v195, v108, v109
	v_cvt_pk_bf16_f32 v196, v110, v111
	v_cvt_pk_bf16_f32 v197, v112, v113
	s_add_u32 s2, s10, 0xc00000
	s_addc_u32 s3, s11, 0
	global_store_dwordx2 v1, v[190:191], s[2:3]
	global_store_dwordx2 v1, v[192:193], s[2:3] offset:512
	global_store_dwordx2 v1, v[194:195], s[2:3] offset:1024
	global_store_dwordx2 v1, v[196:197], s[2:3] offset:1536
	s_add_u32 s2, s8, 0x3800000
	s_addc_u32 s3, s9, 0
	global_load_dwordx4 v[98:101], v0, s[2:3]
	global_load_dwordx4 v[102:105], v0, s[2:3] offset:1024
	global_load_dwordx4 v[106:109], v0, s[2:3] offset:2048
	global_load_dwordx4 v[110:113], v0, s[2:3] offset:3072
	s_add_u32 s2, s14, 0x1e000
	s_addc_u32 s3, s15, 0
	global_load_dwordx4 v[146:149], v0, s[2:3]
	global_load_dwordx4 v[150:153], v0, s[2:3] offset:1024
	global_load_dwordx4 v[154:157], v0, s[2:3] offset:2048
	global_load_dwordx4 v[158:161], v0, s[2:3] offset:3072
	s_add_u32 s2, s18, 0x1e000
	s_addc_u32 s3, s19, 0
	global_load_dwordx4 v[162:165], v0, s[2:3]
	global_load_dwordx4 v[166:169], v0, s[2:3] offset:1024
	global_load_dwordx4 v[170:173], v0, s[2:3] offset:2048
	global_load_dwordx4 v[174:177], v0, s[2:3] offset:3072
	v_add_f32_e32 v9, v42, v43
	v_add_f32_e32 v91, v44, v45
	v_mul_f32_e32 v90, v42, v42
	v_mul_f32_e32 v92, v43, v43
	v_add_f32_e32 v9, v9, v46
	v_add_f32_e32 v91, v91, v47
	v_add_f32_e32 v9, v9, v48
	v_add_f32_e32 v91, v91, v49
	v_add_f32_e32 v9, v9, v50
	v_add_f32_e32 v91, v91, v51
	v_add_f32_e32 v9, v9, v52
	v_add_f32_e32 v91, v91, v53
	v_add_f32_e32 v9, v9, v54
	v_add_f32_e32 v91, v91, v55
	v_add_f32_e32 v9, v9, v56
	v_add_f32_e32 v91, v91, v57
	v_fmac_f32_e32 v90, v44, v44
	v_fmac_f32_e32 v92, v45, v45
	v_fmac_f32_e32 v90, v46, v46
	v_fmac_f32_e32 v92, v47, v47
	v_fmac_f32_e32 v90, v48, v48
	v_fmac_f32_e32 v92, v49, v49
	v_fmac_f32_e32 v90, v50, v50
	v_fmac_f32_e32 v92, v51, v51
	v_fmac_f32_e32 v90, v52, v52
	v_fmac_f32_e32 v92, v53, v53
	v_fmac_f32_e32 v90, v54, v54
	v_fmac_f32_e32 v92, v55, v55
	v_fmac_f32_e32 v90, v56, v56
	v_fmac_f32_e32 v92, v57, v57
	v_add_f32_e32 v9, v9, v91
	v_add_f32_e32 v90, v90, v92
	ds_bpermute_b32 v91, v3, v9
	ds_bpermute_b32 v92, v3, v90
	s_waitcnt lgkmcnt(0)
	v_add_f32_e32 v9, v9, v91
	v_add_f32_e32 v90, v90, v92
	ds_bpermute_b32 v91, v4, v9
	ds_bpermute_b32 v92, v4, v90
	s_waitcnt lgkmcnt(0)
	v_add_f32_e32 v9, v9, v91
	v_add_f32_e32 v90, v90, v92
	ds_bpermute_b32 v91, v5, v9
	ds_bpermute_b32 v92, v5, v90
	s_waitcnt lgkmcnt(0)
	v_add_f32_e32 v9, v9, v91
	v_add_f32_e32 v90, v90, v92
	ds_bpermute_b32 v91, v6, v9
	ds_bpermute_b32 v92, v6, v90
	s_waitcnt lgkmcnt(0)
	v_add_f32_e32 v9, v9, v91
	v_add_f32_e32 v90, v90, v92
	ds_bpermute_b32 v91, v7, v9
	ds_bpermute_b32 v92, v7, v90
	s_waitcnt lgkmcnt(0)
	v_add_f32_e32 v9, v9, v91
	v_add_f32_e32 v90, v90, v92
	ds_bpermute_b32 v91, v8, v9
	ds_bpermute_b32 v92, v8, v90
	s_waitcnt lgkmcnt(0)
	v_add_f32_e32 v9, v9, v91
	v_add_f32_e32 v90, v90, v92
	v_mul_f32_e32 v93, 0x3a800000, v9
	v_mul_f32_e32 v91, 0x3a800000, v90
	v_fma_f32 v91, -v93, v93, v91
	v_max_f32_e32 v91, 0, v91
	v_add_f32_e32 v91, 0x358637bd, v91
	v_rsq_f32_e32 v94, v91
	v_mul_f32_e32 v91, 0.5, v91
	v_mul_f32_e32 v92, v94, v94
	v_fma_f32 v92, -v91, v92, 0.5
	v_fma_f32 v94, v94, v92, v94
	s_add_u32 s2, s12, 0x10000
	s_addc_u32 s3, s13, 0
	v_mov_b32_e32 v188, v93
	v_mov_b32_e32 v189, v94
	s_mov_b64 exec, 1
	global_store_dwordx2 v97, v[188:189], s[2:3]
	s_mov_b64 exec, -1
	v_sub_f32_e32 v42, v42, v93
	v_sub_f32_e32 v43, v43, v93
	v_sub_f32_e32 v44, v44, v93
	v_sub_f32_e32 v45, v45, v93
	v_sub_f32_e32 v46, v46, v93
	v_sub_f32_e32 v47, v47, v93
	v_sub_f32_e32 v48, v48, v93
	v_sub_f32_e32 v49, v49, v93
	v_sub_f32_e32 v50, v50, v93
	v_sub_f32_e32 v51, v51, v93
	v_sub_f32_e32 v52, v52, v93
	v_sub_f32_e32 v53, v53, v93
	v_sub_f32_e32 v54, v54, v93
	v_sub_f32_e32 v55, v55, v93
	v_sub_f32_e32 v56, v56, v93
	v_sub_f32_e32 v57, v57, v93
	v_mul_f32_e32 v42, v94, v42
	v_mul_f32_e32 v43, v94, v43
	v_mul_f32_e32 v44, v94, v44
	v_mul_f32_e32 v45, v94, v45
	v_mul_f32_e32 v46, v94, v46
	v_mul_f32_e32 v47, v94, v47
	v_mul_f32_e32 v48, v94, v48
	v_mul_f32_e32 v49, v94, v49
	v_mul_f32_e32 v50, v94, v50
	v_mul_f32_e32 v51, v94, v51
	v_mul_f32_e32 v52, v94, v52
	v_mul_f32_e32 v53, v94, v53
	v_mul_f32_e32 v54, v94, v54
	v_mul_f32_e32 v55, v94, v55
	v_mul_f32_e32 v56, v94, v56
	v_mul_f32_e32 v57, v94, v57
	v_fma_f32 v42, v42, v10, v26
	v_fma_f32 v43, v43, v11, v27
	v_fma_f32 v44, v44, v12, v28
	v_fma_f32 v45, v45, v13, v29
	v_fma_f32 v46, v46, v14, v30
	v_fma_f32 v47, v47, v15, v31
	v_fma_f32 v48, v48, v16, v32
	v_fma_f32 v49, v49, v17, v33
	v_fma_f32 v50, v50, v18, v34
	v_fma_f32 v51, v51, v19, v35
	v_fma_f32 v52, v52, v20, v36
	v_fma_f32 v53, v53, v21, v37
	v_fma_f32 v54, v54, v22, v38
	v_fma_f32 v55, v55, v23, v39
	v_fma_f32 v56, v56, v24, v40
	v_fma_f32 v57, v57, v25, v41
	v_add_f32_e32 v9, v42, v43
	v_add_f32_e32 v91, v44, v45
	v_mul_f32_e32 v90, v42, v42
	v_mul_f32_e32 v92, v43, v43
	v_add_f32_e32 v9, v9, v46
	v_add_f32_e32 v91, v91, v47
	v_add_f32_e32 v9, v9, v48
	v_add_f32_e32 v91, v91, v49
	v_add_f32_e32 v9, v9, v50
	v_add_f32_e32 v91, v91, v51
	v_add_f32_e32 v9, v9, v52
	v_add_f32_e32 v91, v91, v53
	v_add_f32_e32 v9, v9, v54
	v_add_f32_e32 v91, v91, v55
	v_add_f32_e32 v9, v9, v56
	v_add_f32_e32 v91, v91, v57
	v_fmac_f32_e32 v90, v44, v44
	v_fmac_f32_e32 v92, v45, v45
	v_fmac_f32_e32 v90, v46, v46
	v_fmac_f32_e32 v92, v47, v47
	v_fmac_f32_e32 v90, v48, v48
	v_fmac_f32_e32 v92, v49, v49
	v_fmac_f32_e32 v90, v50, v50
	v_fmac_f32_e32 v92, v51, v51
	v_fmac_f32_e32 v90, v52, v52
	v_fmac_f32_e32 v92, v53, v53
	v_fmac_f32_e32 v90, v54, v54
	v_fmac_f32_e32 v92, v55, v55
	v_fmac_f32_e32 v90, v56, v56
	v_fmac_f32_e32 v92, v57, v57
	v_add_f32_e32 v9, v9, v91
	v_add_f32_e32 v90, v90, v92
	ds_bpermute_b32 v91, v3, v9
	ds_bpermute_b32 v92, v3, v90
	s_waitcnt lgkmcnt(0)
; DI unsigned pk2(float lo, float hi) { f32x2 v = {lo, hi}; bf16x2_t b = __builtin_convertvector(v, bf16x2_t); return __builtin_bit_cast(unsigned, b); }
; DI void ln_row_v(const Frame& F, f32x4 (&v)[4], float* xout, const float* g, const float* b, const float* sh, const float* sc, bf16_t* hout, const float* slab, const float* gres, float* stat = nullptr) {
;     ...
;     if (g) {
;         float s = 0.f, s2 = 0.f;
; #pragma unroll
;         for (int j = 0; j < 4; ++j) { s += (v[j][0] + v[j][1]) + (v[j][2] + v[j][3]); s2 += (v[j][0] * v[j][0] + v[j][1] * v[j][1]) + (v[j][2] * v[j][2] + v[j][3] * v[j][3]); }
;         wave_sum2(s, s2, F.lane);
;         const float mean = s * (1.f / D); const float rstd = 1.f / sqrtf(fmaxf(s2 * (1.f / D) - mean * mean, 0.f) + EPS);
;         if (stat && F.lane == 0) { f32x2 sv = {mean, rstd}; *(f32x2*)stat = sv; }
; #pragma unroll
;         for (int j = 0; j < 4; ++j) { const f32x4 gg = ((const f32x4*)g)[F.lane + 64 * j], bb = ((const f32x4*)b)[F.lane + 64 * j];
;             v[j] = (v[j] - mean) * rstd * gg + bb; if (xout) ((f32x4*)xout)[F.lane + 64 * j] = v[j]; }
;     }
;     if (hout) {
;         float s = 0.f, s2 = 0.f;
; #pragma unroll
;         for (int j = 0; j < 4; ++j) { s += (v[j][0] + v[j][1]) + (v[j][2] + v[j][3]); s2 += (v[j][0] * v[j][0] + v[j][1] * v[j][1]) + (v[j][2] * v[j][2] + v[j][3] * v[j][3]); }
;         wave_sum2(s, s2, F.lane);
;         const float mean = s * (1.f / D); const float rstd = 1.f / sqrtf(fmaxf(s2 * (1.f / D) - mean * mean, 0.f) + EPS);
; #pragma unroll
;         for (int j = 0; j < 4; ++j) { const f32x4 hh = ((const f32x4*)sh)[F.lane + 64 * j], cc = ((const f32x4*)sc)[F.lane + 64 * j];
;             const f32x4 o = (v[j] - mean) * rstd * (cc + 1.f) + hh; u32x2 wv; wv.x = pk2(o[0], o[1]); wv.y = pk2(o[2], o[3]);
;             ((u32x2*)hout)[F.lane + 64 * j] = wv; }
;     }
	v_add_f32_e32 v9, v9, v91
	v_add_f32_e32 v90, v90, v92
	ds_bpermute_b32 v91, v4, v9
	ds_bpermute_b32 v92, v4, v90
	s_waitcnt lgkmcnt(0)
	v_add_f32_e32 v9, v9, v91
	v_add_f32_e32 v90, v90, v92
	ds_bpermute_b32 v91, v5, v9
	ds_bpermute_b32 v92, v5, v90
	s_waitcnt lgkmcnt(0)
	v_add_f32_e32 v9, v9, v91
	v_add_f32_e32 v90, v90, v92
	ds_bpermute_b32 v91, v6, v9
	ds_bpermute_b32 v92, v6, v90
	s_waitcnt lgkmcnt(0)
	v_add_f32_e32 v9, v9, v91
	v_add_f32_e32 v90, v90, v92
	ds_bpermute_b32 v91, v7, v9
	ds_bpermute_b32 v92, v7, v90
	s_waitcnt lgkmcnt(0)
	v_add_f32_e32 v9, v9, v91
	v_add_f32_e32 v90, v90, v92
	ds_bpermute_b32 v91, v8, v9
	ds_bpermute_b32 v92, v8, v90
	s_waitcnt lgkmcnt(0)
	v_add_f32_e32 v9, v9, v91
	v_add_f32_e32 v90, v90, v92
	v_mul_f32_e32 v93, 0x3a800000, v9
	v_mul_f32_e32 v91, 0x3a800000, v90
	v_fma_f32 v91, -v93, v93, v91
	v_max_f32_e32 v91, 0, v91
	v_add_f32_e32 v91, 0x358637bd, v91
	v_rsq_f32_e32 v94, v91
	v_mul_f32_e32 v91, 0.5, v91
	v_mul_f32_e32 v92, v94, v94
	v_fma_f32 v92, -v91, v92, 0.5
	v_fma_f32 v94, v94, v92, v94
	s_waitcnt vmcnt(18)
	v_sub_f32_e32 v42, v42, v93
	v_sub_f32_e32 v43, v43, v93
	v_sub_f32_e32 v44, v44, v93
	v_sub_f32_e32 v45, v45, v93
	v_sub_f32_e32 v46, v46, v93
	v_sub_f32_e32 v47, v47, v93
	v_sub_f32_e32 v48, v48, v93
	v_sub_f32_e32 v49, v49, v93
	v_sub_f32_e32 v50, v50, v93
	v_sub_f32_e32 v51, v51, v93
	v_sub_f32_e32 v52, v52, v93
	v_sub_f32_e32 v53, v53, v93
	v_sub_f32_e32 v54, v54, v93
	v_sub_f32_e32 v55, v55, v93
	v_sub_f32_e32 v56, v56, v93
	v_sub_f32_e32 v57, v57, v93
	v_add_f32_e32 v130, 1.0, v130
	v_add_f32_e32 v131, 1.0, v131
	v_add_f32_e32 v132, 1.0, v132
	v_add_f32_e32 v133, 1.0, v133
	v_add_f32_e32 v134, 1.0, v134
	v_add_f32_e32 v135, 1.0, v135
	v_add_f32_e32 v136, 1.0, v136
	v_add_f32_e32 v137, 1.0, v137
	v_add_f32_e32 v138, 1.0, v138
	v_add_f32_e32 v139, 1.0, v139
	v_add_f32_e32 v140, 1.0, v140
	v_add_f32_e32 v141, 1.0, v141
	v_add_f32_e32 v142, 1.0, v142
	v_add_f32_e32 v143, 1.0, v143
	v_add_f32_e32 v144, 1.0, v144
	v_add_f32_e32 v145, 1.0, v145
	v_mul_f32_e32 v42, v94, v42
	v_mul_f32_e32 v43, v94, v43
	v_mul_f32_e32 v44, v94, v44
	v_mul_f32_e32 v45, v94, v45
	v_mul_f32_e32 v46, v94, v46
	v_mul_f32_e32 v47, v94, v47
	v_mul_f32_e32 v48, v94, v48
	v_mul_f32_e32 v49, v94, v49
	v_mul_f32_e32 v50, v94, v50
	v_mul_f32_e32 v51, v94, v51
	v_mul_f32_e32 v52, v94, v52
	v_mul_f32_e32 v53, v94, v53
	v_mul_f32_e32 v54, v94, v54
	v_mul_f32_e32 v55, v94, v55
	v_mul_f32_e32 v56, v94, v56
	v_mul_f32_e32 v57, v94, v57
	v_fma_f32 v42, v42, v130, v114
	v_fma_f32 v43, v43, v131, v115
	v_fma_f32 v44, v44, v132, v116
	v_fma_f32 v45, v45, v133, v117
	v_fma_f32 v46, v46, v134, v118
	v_fma_f32 v47, v47, v135, v119
	v_fma_f32 v48, v48, v136, v120
	v_fma_f32 v49, v49, v137, v121
	v_fma_f32 v50, v50, v138, v122
	v_fma_f32 v51, v51, v139, v123
	v_fma_f32 v52, v52, v140, v124
	v_fma_f32 v53, v53, v141, v125
	v_fma_f32 v54, v54, v142, v126
	v_fma_f32 v55, v55, v143, v127
	v_fma_f32 v56, v56, v144, v128
	v_fma_f32 v57, v57, v145, v129
	v_cvt_pk_bf16_f32 v190, v42, v43
	v_cvt_pk_bf16_f32 v191, v44, v45
	v_cvt_pk_bf16_f32 v192, v46, v47
	v_cvt_pk_bf16_f32 v193, v48, v49
	v_cvt_pk_bf16_f32 v194, v50, v51
	v_cvt_pk_bf16_f32 v195, v52, v53
	v_cvt_pk_bf16_f32 v196, v54, v55
	v_cvt_pk_bf16_f32 v197, v56, v57
	s_add_u32 s2, s10, 0x1000000
	s_addc_u32 s3, s11, 0
	global_store_dwordx2 v1, v[190:191], s[2:3]
	global_store_dwordx2 v1, v[192:193], s[2:3] offset:512
	global_store_dwordx2 v1, v[194:195], s[2:3] offset:1024
	global_store_dwordx2 v1, v[196:197], s[2:3] offset:1536
	s_add_u32 s2, s14, 0x24000
	s_addc_u32 s3, s15, 0
	global_load_dwordx4 v[114:117], v0, s[2:3]
	global_load_dwordx4 v[118:121], v0, s[2:3] offset:1024
	global_load_dwordx4 v[122:125], v0, s[2:3] offset:2048
	global_load_dwordx4 v[126:129], v0, s[2:3] offset:3072
	s_add_u32 s2, s18, 0x24000
	s_addc_u32 s3, s19, 0
	global_load_dwordx4 v[130:133], v0, s[2:3]
	global_load_dwordx4 v[134:137], v0, s[2:3] offset:1024
	global_load_dwordx4 v[138:141], v0, s[2:3] offset:2048
	global_load_dwordx4 v[142:145], v0, s[2:3] offset:3072
	v_add_f32_e32 v9, v58, v59
	v_add_f32_e32 v91, v60, v61
	v_mul_f32_e32 v90, v58, v58
	v_mul_f32_e32 v92, v59, v59
	v_add_f32_e32 v9, v9, v62
	v_add_f32_e32 v91, v91, v63
	v_add_f32_e32 v9, v9, v64
	v_add_f32_e32 v91, v91, v65
	v_add_f32_e32 v9, v9, v66
	v_add_f32_e32 v91, v91, v67
	v_add_f32_e32 v9, v9, v68
	v_add_f32_e32 v91, v91, v69
	v_add_f32_e32 v9, v9, v70
	v_add_f32_e32 v91, v91, v71
	v_add_f32_e32 v9, v9, v72
	v_add_f32_e32 v91, v91, v73
	v_fmac_f32_e32 v90, v60, v60
	v_fmac_f32_e32 v92, v61, v61
	v_fmac_f32_e32 v90, v62, v62
	v_fmac_f32_e32 v92, v63, v63
	v_fmac_f32_e32 v90, v64, v64
	v_fmac_f32_e32 v92, v65, v65
	v_fmac_f32_e32 v90, v66, v66
	v_fmac_f32_e32 v92, v67, v67
	v_fmac_f32_e32 v90, v68, v68
	v_fmac_f32_e32 v92, v69, v69
	v_fmac_f32_e32 v90, v70, v70
	v_fmac_f32_e32 v92, v71, v71
	v_fmac_f32_e32 v90, v72, v72
	v_fmac_f32_e32 v92, v73, v73
	v_add_f32_e32 v9, v9, v91
	v_add_f32_e32 v90, v90, v92
	ds_bpermute_b32 v91, v3, v9
	ds_bpermute_b32 v92, v3, v90
	s_waitcnt lgkmcnt(0)
	v_add_f32_e32 v9, v9, v91
	v_add_f32_e32 v90, v90, v92
	ds_bpermute_b32 v91, v4, v9
	ds_bpermute_b32 v92, v4, v90
	s_waitcnt lgkmcnt(0)
	v_add_f32_e32 v9, v9, v91
	v_add_f32_e32 v90, v90, v92
	ds_bpermute_b32 v91, v5, v9
	ds_bpermute_b32 v92, v5, v90
	s_waitcnt lgkmcnt(0)
	v_add_f32_e32 v9, v9, v91
	v_add_f32_e32 v90, v90, v92
	ds_bpermute_b32 v91, v6, v9
	ds_bpermute_b32 v92, v6, v90
	s_waitcnt lgkmcnt(0)
	v_add_f32_e32 v9, v9, v91
	v_add_f32_e32 v90, v90, v92
	ds_bpermute_b32 v91, v7, v9
	ds_bpermute_b32 v92, v7, v90
	s_waitcnt lgkmcnt(0)
; DI unsigned pk2(float lo, float hi) { f32x2 v = {lo, hi}; bf16x2_t b = __builtin_convertvector(v, bf16x2_t); return __builtin_bit_cast(unsigned, b); }
; DI void ln_row_v(const Frame& F, f32x4 (&v)[4], float* xout, const float* g, const float* b, const float* sh, const float* sc, bf16_t* hout, const float* slab, const float* gres, float* stat = nullptr) {
;     ...
;     if (g) {
;         float s = 0.f, s2 = 0.f;
; #pragma unroll
;         for (int j = 0; j < 4; ++j) { s += (v[j][0] + v[j][1]) + (v[j][2] + v[j][3]); s2 += (v[j][0] * v[j][0] + v[j][1] * v[j][1]) + (v[j][2] * v[j][2] + v[j][3] * v[j][3]); }
;         wave_sum2(s, s2, F.lane);
;         const float mean = s * (1.f / D); const float rstd = 1.f / sqrtf(fmaxf(s2 * (1.f / D) - mean * mean, 0.f) + EPS);
;         if (stat && F.lane == 0) { f32x2 sv = {mean, rstd}; *(f32x2*)stat = sv; }
; #pragma unroll
;         for (int j = 0; j < 4; ++j) { const f32x4 gg = ((const f32x4*)g)[F.lane + 64 * j], bb = ((const f32x4*)b)[F.lane + 64 * j];
;             v[j] = (v[j] - mean) * rstd * gg + bb; if (xout) ((f32x4*)xout)[F.lane + 64 * j] = v[j]; }
;     }
;     if (hout) {
;         float s = 0.f, s2 = 0.f;
; #pragma unroll
;         for (int j = 0; j < 4; ++j) { s += (v[j][0] + v[j][1]) + (v[j][2] + v[j][3]); s2 += (v[j][0] * v[j][0] + v[j][1] * v[j][1]) + (v[j][2] * v[j][2] + v[j][3] * v[j][3]); }
;         wave_sum2(s, s2, F.lane);
;         const float mean = s * (1.f / D); const float rstd = 1.f / sqrtf(fmaxf(s2 * (1.f / D) - mean * mean, 0.f) + EPS);
; #pragma unroll
;         for (int j = 0; j < 4; ++j) { const f32x4 hh = ((const f32x4*)sh)[F.lane + 64 * j], cc = ((const f32x4*)sc)[F.lane + 64 * j];
;             const f32x4 o = (v[j] - mean) * rstd * (cc + 1.f) + hh; u32x2 wv; wv.x = pk2(o[0], o[1]); wv.y = pk2(o[2], o[3]);
;             ((u32x2*)hout)[F.lane + 64 * j] = wv; }
;     }
	v_add_f32_e32 v9, v9, v91
	v_add_f32_e32 v90, v90, v92
	ds_bpermute_b32 v91, v8, v9
	ds_bpermute_b32 v92, v8, v90
	s_waitcnt lgkmcnt(0)
	v_add_f32_e32 v9, v9, v91
	v_add_f32_e32 v90, v90, v92
	v_mul_f32_e32 v93, 0x3a800000, v9
	v_mul_f32_e32 v91, 0x3a800000, v90
	v_fma_f32 v91, -v93, v93, v91
	v_max_f32_e32 v91, 0, v91
	v_add_f32_e32 v91, 0x358637bd, v91
	v_rsq_f32_e32 v94, v91
	v_mul_f32_e32 v91, 0.5, v91
	v_mul_f32_e32 v92, v94, v94
	v_fma_f32 v92, -v91, v92, 0.5
	v_fma_f32 v94, v94, v92, v94
	s_add_u32 s2, s12, 0x14000
	s_addc_u32 s3, s13, 0
	v_mov_b32_e32 v188, v93
	v_mov_b32_e32 v189, v94
	s_mov_b64 exec, 1
	global_store_dwordx2 v97, v[188:189], s[2:3]
	s_mov_b64 exec, -1
	v_sub_f32_e32 v58, v58, v93
	v_sub_f32_e32 v59, v59, v93
	v_sub_f32_e32 v60, v60, v93
	v_sub_f32_e32 v61, v61, v93
	v_sub_f32_e32 v62, v62, v93
	v_sub_f32_e32 v63, v63, v93
	v_sub_f32_e32 v64, v64, v93
	v_sub_f32_e32 v65, v65, v93
	v_sub_f32_e32 v66, v66, v93
	v_sub_f32_e32 v67, v67, v93
	v_sub_f32_e32 v68, v68, v93
	v_sub_f32_e32 v69, v69, v93
	v_sub_f32_e32 v70, v70, v93
	v_sub_f32_e32 v71, v71, v93
	v_sub_f32_e32 v72, v72, v93
	v_sub_f32_e32 v73, v73, v93
	v_mul_f32_e32 v58, v94, v58
	v_mul_f32_e32 v59, v94, v59
	v_mul_f32_e32 v60, v94, v60
	v_mul_f32_e32 v61, v94, v61
	v_mul_f32_e32 v62, v94, v62
	v_mul_f32_e32 v63, v94, v63
	v_mul_f32_e32 v64, v94, v64
	v_mul_f32_e32 v65, v94, v65
	v_mul_f32_e32 v66, v94, v66
	v_mul_f32_e32 v67, v94, v67
	v_mul_f32_e32 v68, v94, v68
	v_mul_f32_e32 v69, v94, v69
	v_mul_f32_e32 v70, v94, v70
	v_mul_f32_e32 v71, v94, v71
	v_mul_f32_e32 v72, v94, v72
	v_mul_f32_e32 v73, v94, v73
	v_fma_f32 v58, v58, v10, v26
	v_fma_f32 v59, v59, v11, v27
	v_fma_f32 v60, v60, v12, v28
	v_fma_f32 v61, v61, v13, v29
	v_fma_f32 v62, v62, v14, v30
	v_fma_f32 v63, v63, v15, v31
	v_fma_f32 v64, v64, v16, v32
	v_fma_f32 v65, v65, v17, v33
	v_fma_f32 v66, v66, v18, v34
	v_fma_f32 v67, v67, v19, v35
	v_fma_f32 v68, v68, v20, v36
	v_fma_f32 v69, v69, v21, v37
	v_fma_f32 v70, v70, v22, v38
	v_fma_f32 v71, v71, v23, v39
	v_fma_f32 v72, v72, v24, v40
	v_fma_f32 v73, v73, v25, v41
	v_add_f32_e32 v9, v58, v59
	v_add_f32_e32 v91, v60, v61
	v_mul_f32_e32 v90, v58, v58
	v_mul_f32_e32 v92, v59, v59
	v_add_f32_e32 v9, v9, v62
	v_add_f32_e32 v91, v91, v63
	v_add_f32_e32 v9, v9, v64
	v_add_f32_e32 v91, v91, v65
	v_add_f32_e32 v9, v9, v66
	v_add_f32_e32 v91, v91, v67
	v_add_f32_e32 v9, v9, v68
	v_add_f32_e32 v91, v91, v69
	v_add_f32_e32 v9, v9, v70
	v_add_f32_e32 v91, v91, v71
	v_add_f32_e32 v9, v9, v72
	v_add_f32_e32 v91, v91, v73
	v_fmac_f32_e32 v90, v60, v60
	v_fmac_f32_e32 v92, v61, v61
	v_fmac_f32_e32 v90, v62, v62
	v_fmac_f32_e32 v92, v63, v63
	v_fmac_f32_e32 v90, v64, v64
	v_fmac_f32_e32 v92, v65, v65
	v_fmac_f32_e32 v90, v66, v66
	v_fmac_f32_e32 v92, v67, v67
	v_fmac_f32_e32 v90, v68, v68
	v_fmac_f32_e32 v92, v69, v69
	v_fmac_f32_e32 v90, v70, v70
	v_fmac_f32_e32 v92, v71, v71
	v_fmac_f32_e32 v90, v72, v72
	v_fmac_f32_e32 v92, v73, v73
	v_add_f32_e32 v9, v9, v91
	v_add_f32_e32 v90, v90, v92
	ds_bpermute_b32 v91, v3, v9
	ds_bpermute_b32 v92, v3, v90
	s_waitcnt lgkmcnt(0)
	v_add_f32_e32 v9, v9, v91
	v_add_f32_e32 v90, v90, v92
	ds_bpermute_b32 v91, v4, v9
	ds_bpermute_b32 v92, v4, v90
	s_waitcnt lgkmcnt(0)
	v_add_f32_e32 v9, v9, v91
	v_add_f32_e32 v90, v90, v92
	ds_bpermute_b32 v91, v5, v9
	ds_bpermute_b32 v92, v5, v90
	s_waitcnt lgkmcnt(0)
	v_add_f32_e32 v9, v9, v91
	v_add_f32_e32 v90, v90, v92
	ds_bpermute_b32 v91, v6, v9
	ds_bpermute_b32 v92, v6, v90
	s_waitcnt lgkmcnt(0)
	v_add_f32_e32 v9, v9, v91
	v_add_f32_e32 v90, v90, v92
	ds_bpermute_b32 v91, v7, v9
	ds_bpermute_b32 v92, v7, v90
	s_waitcnt lgkmcnt(0)
	v_add_f32_e32 v9, v9, v91
	v_add_f32_e32 v90, v90, v92
	ds_bpermute_b32 v91, v8, v9
	ds_bpermute_b32 v92, v8, v90
	s_waitcnt lgkmcnt(0)
	v_add_f32_e32 v9, v9, v91
	v_add_f32_e32 v90, v90, v92
	v_mul_f32_e32 v93, 0x3a800000, v9
	v_mul_f32_e32 v91, 0x3a800000, v90
	v_fma_f32 v91, -v93, v93, v91
	v_max_f32_e32 v91, 0, v91
	v_add_f32_e32 v91, 0x358637bd, v91
	v_rsq_f32_e32 v94, v91
	v_mul_f32_e32 v91, 0.5, v91
	v_mul_f32_e32 v92, v94, v94
	v_fma_f32 v92, -v91, v92, 0.5
	v_fma_f32 v94, v94, v92, v94
	s_waitcnt vmcnt(14)
	v_sub_f32_e32 v58, v58, v93
	v_sub_f32_e32 v59, v59, v93
	v_sub_f32_e32 v60, v60, v93
	v_sub_f32_e32 v61, v61, v93
	v_sub_f32_e32 v62, v62, v93
	v_sub_f32_e32 v63, v63, v93
	v_sub_f32_e32 v64, v64, v93
	v_sub_f32_e32 v65, v65, v93
	v_sub_f32_e32 v66, v66, v93
	v_sub_f32_e32 v67, v67, v93
	v_sub_f32_e32 v68, v68, v93
	v_sub_f32_e32 v69, v69, v93
	v_sub_f32_e32 v70, v70, v93
	v_sub_f32_e32 v71, v71, v93
	v_sub_f32_e32 v72, v72, v93
	v_sub_f32_e32 v73, v73, v93
	v_add_f32_e32 v162, 1.0, v162
	v_add_f32_e32 v163, 1.0, v163
	v_add_f32_e32 v164, 1.0, v164
	v_add_f32_e32 v165, 1.0, v165
	v_add_f32_e32 v166, 1.0, v166
	v_add_f32_e32 v167, 1.0, v167
	v_add_f32_e32 v168, 1.0, v168
	v_add_f32_e32 v169, 1.0, v169
	v_add_f32_e32 v170, 1.0, v170
	v_add_f32_e32 v171, 1.0, v171
	v_add_f32_e32 v172, 1.0, v172
	v_add_f32_e32 v173, 1.0, v173
	v_add_f32_e32 v174, 1.0, v174
	v_add_f32_e32 v175, 1.0, v175
	v_add_f32_e32 v176, 1.0, v176
	v_add_f32_e32 v177, 1.0, v177
	v_mul_f32_e32 v58, v94, v58
	v_mul_f32_e32 v59, v94, v59
	v_mul_f32_e32 v60, v94, v60
	v_mul_f32_e32 v61, v94, v61
	v_mul_f32_e32 v62, v94, v62
	v_mul_f32_e32 v63, v94, v63
	v_mul_f32_e32 v64, v94, v64
	v_mul_f32_e32 v65, v94, v65
	v_mul_f32_e32 v66, v94, v66
	v_mul_f32_e32 v67, v94, v67
	v_mul_f32_e32 v68, v94, v68
	v_mul_f32_e32 v69, v94, v69
	v_mul_f32_e32 v70, v94, v70
	v_mul_f32_e32 v71, v94, v71
	v_mul_f32_e32 v72, v94, v72
	v_mul_f32_e32 v73, v94, v73
	v_fma_f32 v58, v58, v162, v146
; DI unsigned pk2(float lo, float hi) { f32x2 v = {lo, hi}; bf16x2_t b = __builtin_convertvector(v, bf16x2_t); return __builtin_bit_cast(unsigned, b); }
; DI void ln_row_v(const Frame& F, f32x4 (&v)[4], float* xout, const float* g, const float* b, const float* sh, const float* sc, bf16_t* hout, const float* slab, const float* gres, float* stat = nullptr) {
;     ...
;     if (g) {
;         float s = 0.f, s2 = 0.f;
; #pragma unroll
;         for (int j = 0; j < 4; ++j) { s += (v[j][0] + v[j][1]) + (v[j][2] + v[j][3]); s2 += (v[j][0] * v[j][0] + v[j][1] * v[j][1]) + (v[j][2] * v[j][2] + v[j][3] * v[j][3]); }
;         wave_sum2(s, s2, F.lane);
;         const float mean = s * (1.f / D); const float rstd = 1.f / sqrtf(fmaxf(s2 * (1.f / D) - mean * mean, 0.f) + EPS);
;         if (stat && F.lane == 0) { f32x2 sv = {mean, rstd}; *(f32x2*)stat = sv; }
; #pragma unroll
;         for (int j = 0; j < 4; ++j) { const f32x4 gg = ((const f32x4*)g)[F.lane + 64 * j], bb = ((const f32x4*)b)[F.lane + 64 * j];
;             v[j] = (v[j] - mean) * rstd * gg + bb; if (xout) ((f32x4*)xout)[F.lane + 64 * j] = v[j]; }
;     }
;     if (hout) {
;         float s = 0.f, s2 = 0.f;
; #pragma unroll
;         for (int j = 0; j < 4; ++j) { s += (v[j][0] + v[j][1]) + (v[j][2] + v[j][3]); s2 += (v[j][0] * v[j][0] + v[j][1] * v[j][1]) + (v[j][2] * v[j][2] + v[j][3] * v[j][3]); }
;         wave_sum2(s, s2, F.lane);
;         const float mean = s * (1.f / D); const float rstd = 1.f / sqrtf(fmaxf(s2 * (1.f / D) - mean * mean, 0.f) + EPS);
; #pragma unroll
;         for (int j = 0; j < 4; ++j) { const f32x4 hh = ((const f32x4*)sh)[F.lane + 64 * j], cc = ((const f32x4*)sc)[F.lane + 64 * j];
;             const f32x4 o = (v[j] - mean) * rstd * (cc + 1.f) + hh; u32x2 wv; wv.x = pk2(o[0], o[1]); wv.y = pk2(o[2], o[3]);
;             ((u32x2*)hout)[F.lane + 64 * j] = wv; }
;     }
	v_fma_f32 v59, v59, v163, v147
	v_fma_f32 v60, v60, v164, v148
	v_fma_f32 v61, v61, v165, v149
	v_fma_f32 v62, v62, v166, v150
	v_fma_f32 v63, v63, v167, v151
	v_fma_f32 v64, v64, v168, v152
	v_fma_f32 v65, v65, v169, v153
	v_fma_f32 v66, v66, v170, v154
	v_fma_f32 v67, v67, v171, v155
	v_fma_f32 v68, v68, v172, v156
	v_fma_f32 v69, v69, v173, v157
	v_fma_f32 v70, v70, v174, v158
	v_fma_f32 v71, v71, v175, v159
	v_fma_f32 v72, v72, v176, v160
	v_fma_f32 v73, v73, v177, v161
	v_cvt_pk_bf16_f32 v190, v58, v59
	v_cvt_pk_bf16_f32 v191, v60, v61
	v_cvt_pk_bf16_f32 v192, v62, v63
	v_cvt_pk_bf16_f32 v193, v64, v65
	v_cvt_pk_bf16_f32 v194, v66, v67
	v_cvt_pk_bf16_f32 v195, v68, v69
	v_cvt_pk_bf16_f32 v196, v70, v71
	v_cvt_pk_bf16_f32 v197, v72, v73
	s_add_u32 s2, s10, 0x1400000
	s_addc_u32 s3, s11, 0
	global_store_dwordx2 v1, v[190:191], s[2:3]
	global_store_dwordx2 v1, v[192:193], s[2:3] offset:512
	global_store_dwordx2 v1, v[194:195], s[2:3] offset:1024
	global_store_dwordx2 v1, v[196:197], s[2:3] offset:1536
	s_add_u32 s2, s14, 0x2a000
	s_addc_u32 s3, s15, 0
	global_load_dwordx4 v[146:149], v0, s[2:3]
	global_load_dwordx4 v[150:153], v0, s[2:3] offset:1024
	global_load_dwordx4 v[154:157], v0, s[2:3] offset:2048
	global_load_dwordx4 v[158:161], v0, s[2:3] offset:3072
	s_add_u32 s2, s18, 0x2a000
	s_addc_u32 s3, s19, 0
	global_load_dwordx4 v[162:165], v0, s[2:3]
	global_load_dwordx4 v[166:169], v0, s[2:3] offset:1024
	global_load_dwordx4 v[170:173], v0, s[2:3] offset:2048
	global_load_dwordx4 v[174:177], v0, s[2:3] offset:3072
	v_add_f32_e32 v9, v74, v75
	v_add_f32_e32 v91, v76, v77
	v_mul_f32_e32 v90, v74, v74
	v_mul_f32_e32 v92, v75, v75
	v_add_f32_e32 v9, v9, v78
	v_add_f32_e32 v91, v91, v79
	v_add_f32_e32 v9, v9, v80
	v_add_f32_e32 v91, v91, v81
	v_add_f32_e32 v9, v9, v82
	v_add_f32_e32 v91, v91, v83
	v_add_f32_e32 v9, v9, v84
	v_add_f32_e32 v91, v91, v85
	v_add_f32_e32 v9, v9, v86
	v_add_f32_e32 v91, v91, v87
	v_add_f32_e32 v9, v9, v88
	v_add_f32_e32 v91, v91, v89
	v_fmac_f32_e32 v90, v76, v76
	v_fmac_f32_e32 v92, v77, v77
	v_fmac_f32_e32 v90, v78, v78
	v_fmac_f32_e32 v92, v79, v79
	v_fmac_f32_e32 v90, v80, v80
	v_fmac_f32_e32 v92, v81, v81
	v_fmac_f32_e32 v90, v82, v82
	v_fmac_f32_e32 v92, v83, v83
	v_fmac_f32_e32 v90, v84, v84
	v_fmac_f32_e32 v92, v85, v85
	v_fmac_f32_e32 v90, v86, v86
	v_fmac_f32_e32 v92, v87, v87
	v_fmac_f32_e32 v90, v88, v88
	v_fmac_f32_e32 v92, v89, v89
	v_add_f32_e32 v9, v9, v91
	v_add_f32_e32 v90, v90, v92
	ds_bpermute_b32 v91, v3, v9
	ds_bpermute_b32 v92, v3, v90
	s_waitcnt lgkmcnt(0)
	v_add_f32_e32 v9, v9, v91
	v_add_f32_e32 v90, v90, v92
	ds_bpermute_b32 v91, v4, v9
	ds_bpermute_b32 v92, v4, v90
	s_waitcnt lgkmcnt(0)
	v_add_f32_e32 v9, v9, v91
	v_add_f32_e32 v90, v90, v92
	ds_bpermute_b32 v91, v5, v9
	ds_bpermute_b32 v92, v5, v90
	s_waitcnt lgkmcnt(0)
	v_add_f32_e32 v9, v9, v91
	v_add_f32_e32 v90, v90, v92
	ds_bpermute_b32 v91, v6, v9
	ds_bpermute_b32 v92, v6, v90
	s_waitcnt lgkmcnt(0)
	v_add_f32_e32 v9, v9, v91
	v_add_f32_e32 v90, v90, v92
	ds_bpermute_b32 v91, v7, v9
	ds_bpermute_b32 v92, v7, v90
	s_waitcnt lgkmcnt(0)
	v_add_f32_e32 v9, v9, v91
	v_add_f32_e32 v90, v90, v92
	ds_bpermute_b32 v91, v8, v9
	ds_bpermute_b32 v92, v8, v90
	s_waitcnt lgkmcnt(0)
	v_add_f32_e32 v9, v9, v91
	v_add_f32_e32 v90, v90, v92
	v_mul_f32_e32 v93, 0x3a800000, v9
	v_mul_f32_e32 v91, 0x3a800000, v90
	v_fma_f32 v91, -v93, v93, v91
	v_max_f32_e32 v91, 0, v91
	v_add_f32_e32 v91, 0x358637bd, v91
	v_rsq_f32_e32 v94, v91
	v_mul_f32_e32 v91, 0.5, v91
	v_mul_f32_e32 v92, v94, v94
	v_fma_f32 v92, -v91, v92, 0.5
	v_fma_f32 v94, v94, v92, v94
	s_add_u32 s2, s12, 0x18000
	s_addc_u32 s3, s13, 0
	v_mov_b32_e32 v188, v93
	v_mov_b32_e32 v189, v94
	s_mov_b64 exec, 1
	global_store_dwordx2 v97, v[188:189], s[2:3]
	s_mov_b64 exec, -1
	v_sub_f32_e32 v74, v74, v93
	v_sub_f32_e32 v75, v75, v93
	v_sub_f32_e32 v76, v76, v93
	v_sub_f32_e32 v77, v77, v93
	v_sub_f32_e32 v78, v78, v93
	v_sub_f32_e32 v79, v79, v93
	v_sub_f32_e32 v80, v80, v93
	v_sub_f32_e32 v81, v81, v93
	v_sub_f32_e32 v82, v82, v93
	v_sub_f32_e32 v83, v83, v93
	v_sub_f32_e32 v84, v84, v93
	v_sub_f32_e32 v85, v85, v93
	v_sub_f32_e32 v86, v86, v93
	v_sub_f32_e32 v87, v87, v93
	v_sub_f32_e32 v88, v88, v93
	v_sub_f32_e32 v89, v89, v93
	v_mul_f32_e32 v74, v94, v74
	v_mul_f32_e32 v75, v94, v75
	v_mul_f32_e32 v76, v94, v76
	v_mul_f32_e32 v77, v94, v77
	v_mul_f32_e32 v78, v94, v78
	v_mul_f32_e32 v79, v94, v79
	v_mul_f32_e32 v80, v94, v80
	v_mul_f32_e32 v81, v94, v81
	v_mul_f32_e32 v82, v94, v82
	v_mul_f32_e32 v83, v94, v83
	v_mul_f32_e32 v84, v94, v84
	v_mul_f32_e32 v85, v94, v85
	v_mul_f32_e32 v86, v94, v86
	v_mul_f32_e32 v87, v94, v87
	v_mul_f32_e32 v88, v94, v88
	v_mul_f32_e32 v89, v94, v89
	v_fma_f32 v74, v74, v10, v26
	v_fma_f32 v75, v75, v11, v27
	v_fma_f32 v76, v76, v12, v28
	v_fma_f32 v77, v77, v13, v29
	v_fma_f32 v78, v78, v14, v30
	v_fma_f32 v79, v79, v15, v31
	v_fma_f32 v80, v80, v16, v32
	v_fma_f32 v81, v81, v17, v33
	v_fma_f32 v82, v82, v18, v34
	v_fma_f32 v83, v83, v19, v35
	v_fma_f32 v84, v84, v20, v36
	v_fma_f32 v85, v85, v21, v37
	v_fma_f32 v86, v86, v22, v38
	v_fma_f32 v87, v87, v23, v39
	v_fma_f32 v88, v88, v24, v40
	v_fma_f32 v89, v89, v25, v41
	v_add_f32_e32 v9, v74, v75
	v_add_f32_e32 v91, v76, v77
	v_mul_f32_e32 v90, v74, v74
	v_mul_f32_e32 v92, v75, v75
	v_add_f32_e32 v9, v9, v78
	v_add_f32_e32 v91, v91, v79
	v_add_f32_e32 v9, v9, v80
	v_add_f32_e32 v91, v91, v81
	v_add_f32_e32 v9, v9, v82
	v_add_f32_e32 v91, v91, v83
	v_add_f32_e32 v9, v9, v84
	v_add_f32_e32 v91, v91, v85
	v_add_f32_e32 v9, v9, v86
	v_add_f32_e32 v91, v91, v87
	v_add_f32_e32 v9, v9, v88
	v_add_f32_e32 v91, v91, v89
	v_fmac_f32_e32 v90, v76, v76
	v_fmac_f32_e32 v92, v77, v77
	v_fmac_f32_e32 v90, v78, v78
	v_fmac_f32_e32 v92, v79, v79
	v_fmac_f32_e32 v90, v80, v80
	v_fmac_f32_e32 v92, v81, v81
	v_fmac_f32_e32 v90, v82, v82
	v_fmac_f32_e32 v92, v83, v83
	v_fmac_f32_e32 v90, v84, v84
	v_fmac_f32_e32 v92, v85, v85
	v_fmac_f32_e32 v90, v86, v86
	v_fmac_f32_e32 v92, v87, v87
	v_fmac_f32_e32 v90, v88, v88
	v_fmac_f32_e32 v92, v89, v89
	v_add_f32_e32 v9, v9, v91
	v_add_f32_e32 v90, v90, v92
	ds_bpermute_b32 v91, v3, v9
	ds_bpermute_b32 v92, v3, v90
	s_waitcnt lgkmcnt(0)
; DI unsigned pk2(float lo, float hi) { f32x2 v = {lo, hi}; bf16x2_t b = __builtin_convertvector(v, bf16x2_t); return __builtin_bit_cast(unsigned, b); }
; DI void ln_row_v(const Frame& F, f32x4 (&v)[4], float* xout, const float* g, const float* b, const float* sh, const float* sc, bf16_t* hout, const float* slab, const float* gres, float* stat = nullptr) {
;     ...
;     if (g) {
;         float s = 0.f, s2 = 0.f;
; #pragma unroll
;         for (int j = 0; j < 4; ++j) { s += (v[j][0] + v[j][1]) + (v[j][2] + v[j][3]); s2 += (v[j][0] * v[j][0] + v[j][1] * v[j][1]) + (v[j][2] * v[j][2] + v[j][3] * v[j][3]); }
;         wave_sum2(s, s2, F.lane);
;         const float mean = s * (1.f / D); const float rstd = 1.f / sqrtf(fmaxf(s2 * (1.f / D) - mean * mean, 0.f) + EPS);
;         if (stat && F.lane == 0) { f32x2 sv = {mean, rstd}; *(f32x2*)stat = sv; }
; #pragma unroll
;         for (int j = 0; j < 4; ++j) { const f32x4 gg = ((const f32x4*)g)[F.lane + 64 * j], bb = ((const f32x4*)b)[F.lane + 64 * j];
;             v[j] = (v[j] - mean) * rstd * gg + bb; if (xout) ((f32x4*)xout)[F.lane + 64 * j] = v[j]; }
;     }
;     if (hout) {
;         float s = 0.f, s2 = 0.f;
; #pragma unroll
;         for (int j = 0; j < 4; ++j) { s += (v[j][0] + v[j][1]) + (v[j][2] + v[j][3]); s2 += (v[j][0] * v[j][0] + v[j][1] * v[j][1]) + (v[j][2] * v[j][2] + v[j][3] * v[j][3]); }
;         wave_sum2(s, s2, F.lane);
;         const float mean = s * (1.f / D); const float rstd = 1.f / sqrtf(fmaxf(s2 * (1.f / D) - mean * mean, 0.f) + EPS);
; #pragma unroll
;         for (int j = 0; j < 4; ++j) { const f32x4 hh = ((const f32x4*)sh)[F.lane + 64 * j], cc = ((const f32x4*)sc)[F.lane + 64 * j];
;             const f32x4 o = (v[j] - mean) * rstd * (cc + 1.f) + hh; u32x2 wv; wv.x = pk2(o[0], o[1]); wv.y = pk2(o[2], o[3]);
;             ((u32x2*)hout)[F.lane + 64 * j] = wv; }
;     }
	v_add_f32_e32 v9, v9, v91
	v_add_f32_e32 v90, v90, v92
	ds_bpermute_b32 v91, v4, v9
	ds_bpermute_b32 v92, v4, v90
	s_waitcnt lgkmcnt(0)
	v_add_f32_e32 v9, v9, v91
	v_add_f32_e32 v90, v90, v92
	ds_bpermute_b32 v91, v5, v9
	ds_bpermute_b32 v92, v5, v90
	s_waitcnt lgkmcnt(0)
	v_add_f32_e32 v9, v9, v91
	v_add_f32_e32 v90, v90, v92
	ds_bpermute_b32 v91, v6, v9
	ds_bpermute_b32 v92, v6, v90
	s_waitcnt lgkmcnt(0)
	v_add_f32_e32 v9, v9, v91
	v_add_f32_e32 v90, v90, v92
	ds_bpermute_b32 v91, v7, v9
	ds_bpermute_b32 v92, v7, v90
	s_waitcnt lgkmcnt(0)
	v_add_f32_e32 v9, v9, v91
	v_add_f32_e32 v90, v90, v92
	ds_bpermute_b32 v91, v8, v9
	ds_bpermute_b32 v92, v8, v90
	s_waitcnt lgkmcnt(0)
	v_add_f32_e32 v9, v9, v91
	v_add_f32_e32 v90, v90, v92
	v_mul_f32_e32 v93, 0x3a800000, v9
	v_mul_f32_e32 v91, 0x3a800000, v90
	v_fma_f32 v91, -v93, v93, v91
	v_max_f32_e32 v91, 0, v91
	v_add_f32_e32 v91, 0x358637bd, v91
	v_rsq_f32_e32 v94, v91
	v_mul_f32_e32 v91, 0.5, v91
	v_mul_f32_e32 v92, v94, v94
	v_fma_f32 v92, -v91, v92, 0.5
	v_fma_f32 v94, v94, v92, v94
	s_waitcnt vmcnt(14)
	v_sub_f32_e32 v74, v74, v93
	v_sub_f32_e32 v75, v75, v93
	v_sub_f32_e32 v76, v76, v93
	v_sub_f32_e32 v77, v77, v93
	v_sub_f32_e32 v78, v78, v93
	v_sub_f32_e32 v79, v79, v93
	v_sub_f32_e32 v80, v80, v93
	v_sub_f32_e32 v81, v81, v93
	v_sub_f32_e32 v82, v82, v93
	v_sub_f32_e32 v83, v83, v93
	v_sub_f32_e32 v84, v84, v93
	v_sub_f32_e32 v85, v85, v93
	v_sub_f32_e32 v86, v86, v93
	v_sub_f32_e32 v87, v87, v93
	v_sub_f32_e32 v88, v88, v93
	v_sub_f32_e32 v89, v89, v93
	v_add_f32_e32 v130, 1.0, v130
	v_add_f32_e32 v131, 1.0, v131
	v_add_f32_e32 v132, 1.0, v132
	v_add_f32_e32 v133, 1.0, v133
	v_add_f32_e32 v134, 1.0, v134
	v_add_f32_e32 v135, 1.0, v135
	v_add_f32_e32 v136, 1.0, v136
	v_add_f32_e32 v137, 1.0, v137
	v_add_f32_e32 v138, 1.0, v138
	v_add_f32_e32 v139, 1.0, v139
	v_add_f32_e32 v140, 1.0, v140
	v_add_f32_e32 v141, 1.0, v141
	v_add_f32_e32 v142, 1.0, v142
	v_add_f32_e32 v143, 1.0, v143
	v_add_f32_e32 v144, 1.0, v144
	v_add_f32_e32 v145, 1.0, v145
	v_mul_f32_e32 v74, v94, v74
	v_mul_f32_e32 v75, v94, v75
	v_mul_f32_e32 v76, v94, v76
	v_mul_f32_e32 v77, v94, v77
	v_mul_f32_e32 v78, v94, v78
	v_mul_f32_e32 v79, v94, v79
	v_mul_f32_e32 v80, v94, v80
	v_mul_f32_e32 v81, v94, v81
	v_mul_f32_e32 v82, v94, v82
	v_mul_f32_e32 v83, v94, v83
	v_mul_f32_e32 v84, v94, v84
	v_mul_f32_e32 v85, v94, v85
	v_mul_f32_e32 v86, v94, v86
	v_mul_f32_e32 v87, v94, v87
	v_mul_f32_e32 v88, v94, v88
	v_mul_f32_e32 v89, v94, v89
	v_fma_f32 v74, v74, v130, v114
	v_fma_f32 v75, v75, v131, v115
	v_fma_f32 v76, v76, v132, v116
	v_fma_f32 v77, v77, v133, v117
	v_fma_f32 v78, v78, v134, v118
	v_fma_f32 v79, v79, v135, v119
	v_fma_f32 v80, v80, v136, v120
	v_fma_f32 v81, v81, v137, v121
	v_fma_f32 v82, v82, v138, v122
	v_fma_f32 v83, v83, v139, v123
	v_fma_f32 v84, v84, v140, v124
	v_fma_f32 v85, v85, v141, v125
	v_fma_f32 v86, v86, v142, v126
	v_fma_f32 v87, v87, v143, v127
	v_fma_f32 v88, v88, v144, v128
	v_fma_f32 v89, v89, v145, v129
	v_cvt_pk_bf16_f32 v190, v74, v75
	v_cvt_pk_bf16_f32 v191, v76, v77
	v_cvt_pk_bf16_f32 v192, v78, v79
	v_cvt_pk_bf16_f32 v193, v80, v81
	v_cvt_pk_bf16_f32 v194, v82, v83
	v_cvt_pk_bf16_f32 v195, v84, v85
	v_cvt_pk_bf16_f32 v196, v86, v87
	v_cvt_pk_bf16_f32 v197, v88, v89
	s_add_u32 s2, s10, 0x1800000
	s_addc_u32 s3, s11, 0
	global_store_dwordx2 v1, v[190:191], s[2:3]
	global_store_dwordx2 v1, v[192:193], s[2:3] offset:512
	global_store_dwordx2 v1, v[194:195], s[2:3] offset:1024
	global_store_dwordx2 v1, v[196:197], s[2:3] offset:1536
	v_add_f32_e32 v9, v98, v99
	v_add_f32_e32 v91, v100, v101
	v_mul_f32_e32 v90, v98, v98
	v_mul_f32_e32 v92, v99, v99
	v_add_f32_e32 v9, v9, v102
	v_add_f32_e32 v91, v91, v103
	v_add_f32_e32 v9, v9, v104
	v_add_f32_e32 v91, v91, v105
	v_add_f32_e32 v9, v9, v106
	v_add_f32_e32 v91, v91, v107
	v_add_f32_e32 v9, v9, v108
	v_add_f32_e32 v91, v91, v109
	v_add_f32_e32 v9, v9, v110
	v_add_f32_e32 v91, v91, v111
	v_add_f32_e32 v9, v9, v112
	v_add_f32_e32 v91, v91, v113
	v_fmac_f32_e32 v90, v100, v100
	v_fmac_f32_e32 v92, v101, v101
	v_fmac_f32_e32 v90, v102, v102
	v_fmac_f32_e32 v92, v103, v103
	v_fmac_f32_e32 v90, v104, v104
	v_fmac_f32_e32 v92, v105, v105
	v_fmac_f32_e32 v90, v106, v106
	v_fmac_f32_e32 v92, v107, v107
	v_fmac_f32_e32 v90, v108, v108
	v_fmac_f32_e32 v92, v109, v109
	v_fmac_f32_e32 v90, v110, v110
	v_fmac_f32_e32 v92, v111, v111
	v_fmac_f32_e32 v90, v112, v112
	v_fmac_f32_e32 v92, v113, v113
	v_add_f32_e32 v9, v9, v91
	v_add_f32_e32 v90, v90, v92
	ds_bpermute_b32 v91, v3, v9
	ds_bpermute_b32 v92, v3, v90
	s_waitcnt lgkmcnt(0)
	v_add_f32_e32 v9, v9, v91
	v_add_f32_e32 v90, v90, v92
	ds_bpermute_b32 v91, v4, v9
	ds_bpermute_b32 v92, v4, v90
	s_waitcnt lgkmcnt(0)
	v_add_f32_e32 v9, v9, v91
	v_add_f32_e32 v90, v90, v92
	ds_bpermute_b32 v91, v5, v9
	ds_bpermute_b32 v92, v5, v90
	s_waitcnt lgkmcnt(0)
	v_add_f32_e32 v9, v9, v91
	v_add_f32_e32 v90, v90, v92
	ds_bpermute_b32 v91, v6, v9
	ds_bpermute_b32 v92, v6, v90
	s_waitcnt lgkmcnt(0)
	v_add_f32_e32 v9, v9, v91
	v_add_f32_e32 v90, v90, v92
	ds_bpermute_b32 v91, v7, v9
	ds_bpermute_b32 v92, v7, v90
	s_waitcnt lgkmcnt(0)
	v_add_f32_e32 v9, v9, v91
	v_add_f32_e32 v90, v90, v92
	ds_bpermute_b32 v91, v8, v9
	ds_bpermute_b32 v92, v8, v90
	s_waitcnt lgkmcnt(0)
; DI unsigned pk2(float lo, float hi) { f32x2 v = {lo, hi}; bf16x2_t b = __builtin_convertvector(v, bf16x2_t); return __builtin_bit_cast(unsigned, b); }
; DI void ln_row_v(const Frame& F, f32x4 (&v)[4], float* xout, const float* g, const float* b, const float* sh, const float* sc, bf16_t* hout, const float* slab, const float* gres, float* stat = nullptr) {
;     ...
;     if (g) {
;         float s = 0.f, s2 = 0.f;
; #pragma unroll
;         for (int j = 0; j < 4; ++j) { s += (v[j][0] + v[j][1]) + (v[j][2] + v[j][3]); s2 += (v[j][0] * v[j][0] + v[j][1] * v[j][1]) + (v[j][2] * v[j][2] + v[j][3] * v[j][3]); }
;         wave_sum2(s, s2, F.lane);
;         const float mean = s * (1.f / D); const float rstd = 1.f / sqrtf(fmaxf(s2 * (1.f / D) - mean * mean, 0.f) + EPS);
;         if (stat && F.lane == 0) { f32x2 sv = {mean, rstd}; *(f32x2*)stat = sv; }
; #pragma unroll
;         for (int j = 0; j < 4; ++j) { const f32x4 gg = ((const f32x4*)g)[F.lane + 64 * j], bb = ((const f32x4*)b)[F.lane + 64 * j];
;             v[j] = (v[j] - mean) * rstd * gg + bb; if (xout) ((f32x4*)xout)[F.lane + 64 * j] = v[j]; }
;     }
;     if (hout) {
;         float s = 0.f, s2 = 0.f;
; #pragma unroll
;         for (int j = 0; j < 4; ++j) { s += (v[j][0] + v[j][1]) + (v[j][2] + v[j][3]); s2 += (v[j][0] * v[j][0] + v[j][1] * v[j][1]) + (v[j][2] * v[j][2] + v[j][3] * v[j][3]); }
;         wave_sum2(s, s2, F.lane);
;         const float mean = s * (1.f / D); const float rstd = 1.f / sqrtf(fmaxf(s2 * (1.f / D) - mean * mean, 0.f) + EPS);
; #pragma unroll
;         for (int j = 0; j < 4; ++j) { const f32x4 hh = ((const f32x4*)sh)[F.lane + 64 * j], cc = ((const f32x4*)sc)[F.lane + 64 * j];
;             const f32x4 o = (v[j] - mean) * rstd * (cc + 1.f) + hh; u32x2 wv; wv.x = pk2(o[0], o[1]); wv.y = pk2(o[2], o[3]);
;             ((u32x2*)hout)[F.lane + 64 * j] = wv; }
;     }
; DI void ln_phase(const Frame& F, int which) {
;     ...
;     for (int row = gw; row < nrows; row += NGW) {
	v_add_f32_e32 v9, v9, v91
	v_add_f32_e32 v90, v90, v92
	v_mul_f32_e32 v93, 0x3a800000, v9
	v_mul_f32_e32 v91, 0x3a800000, v90
	v_fma_f32 v91, -v93, v93, v91
	v_max_f32_e32 v91, 0, v91
	v_add_f32_e32 v91, 0x358637bd, v91
	v_rsq_f32_e32 v94, v91
	v_mul_f32_e32 v91, 0.5, v91
	v_mul_f32_e32 v92, v94, v94
	v_fma_f32 v92, -v91, v92, 0.5
	v_fma_f32 v94, v94, v92, v94
	s_add_u32 s2, s12, 0x1c000
	s_addc_u32 s3, s13, 0
	v_mov_b32_e32 v188, v93
	v_mov_b32_e32 v189, v94
	s_mov_b64 exec, 1
	global_store_dwordx2 v97, v[188:189], s[2:3]
	s_mov_b64 exec, -1
	v_sub_f32_e32 v98, v98, v93
	v_sub_f32_e32 v99, v99, v93
	v_sub_f32_e32 v100, v100, v93
	v_sub_f32_e32 v101, v101, v93
	v_sub_f32_e32 v102, v102, v93
	v_sub_f32_e32 v103, v103, v93
	v_sub_f32_e32 v104, v104, v93
	v_sub_f32_e32 v105, v105, v93
	v_sub_f32_e32 v106, v106, v93
	v_sub_f32_e32 v107, v107, v93
	v_sub_f32_e32 v108, v108, v93
	v_sub_f32_e32 v109, v109, v93
	v_sub_f32_e32 v110, v110, v93
	v_sub_f32_e32 v111, v111, v93
	v_sub_f32_e32 v112, v112, v93
	v_sub_f32_e32 v113, v113, v93
	v_mul_f32_e32 v98, v94, v98
	v_mul_f32_e32 v99, v94, v99
	v_mul_f32_e32 v100, v94, v100
	v_mul_f32_e32 v101, v94, v101
	v_mul_f32_e32 v102, v94, v102
	v_mul_f32_e32 v103, v94, v103
	v_mul_f32_e32 v104, v94, v104
	v_mul_f32_e32 v105, v94, v105
	v_mul_f32_e32 v106, v94, v106
	v_mul_f32_e32 v107, v94, v107
	v_mul_f32_e32 v108, v94, v108
	v_mul_f32_e32 v109, v94, v109
	v_mul_f32_e32 v110, v94, v110
	v_mul_f32_e32 v111, v94, v111
	v_mul_f32_e32 v112, v94, v112
	v_mul_f32_e32 v113, v94, v113
	v_fma_f32 v98, v98, v10, v26
	v_fma_f32 v99, v99, v11, v27
	v_fma_f32 v100, v100, v12, v28
	v_fma_f32 v101, v101, v13, v29
	v_fma_f32 v102, v102, v14, v30
	v_fma_f32 v103, v103, v15, v31
	v_fma_f32 v104, v104, v16, v32
	v_fma_f32 v105, v105, v17, v33
	v_fma_f32 v106, v106, v18, v34
	v_fma_f32 v107, v107, v19, v35
	v_fma_f32 v108, v108, v20, v36
	v_fma_f32 v109, v109, v21, v37
	v_fma_f32 v110, v110, v22, v38
	v_fma_f32 v111, v111, v23, v39
	v_fma_f32 v112, v112, v24, v40
	v_fma_f32 v113, v113, v25, v41
	v_add_f32_e32 v9, v98, v99
	v_add_f32_e32 v91, v100, v101
	v_mul_f32_e32 v90, v98, v98
	v_mul_f32_e32 v92, v99, v99
	v_add_f32_e32 v9, v9, v102
	v_add_f32_e32 v91, v91, v103
	v_add_f32_e32 v9, v9, v104
	v_add_f32_e32 v91, v91, v105
	v_add_f32_e32 v9, v9, v106
	v_add_f32_e32 v91, v91, v107
	v_add_f32_e32 v9, v9, v108
	v_add_f32_e32 v91, v91, v109
	v_add_f32_e32 v9, v9, v110
	v_add_f32_e32 v91, v91, v111
	v_add_f32_e32 v9, v9, v112
	v_add_f32_e32 v91, v91, v113
	v_fmac_f32_e32 v90, v100, v100
	v_fmac_f32_e32 v92, v101, v101
	v_fmac_f32_e32 v90, v102, v102
	v_fmac_f32_e32 v92, v103, v103
	v_fmac_f32_e32 v90, v104, v104
	v_fmac_f32_e32 v92, v105, v105
	v_fmac_f32_e32 v90, v106, v106
	v_fmac_f32_e32 v92, v107, v107
	v_fmac_f32_e32 v90, v108, v108
	v_fmac_f32_e32 v92, v109, v109
	v_fmac_f32_e32 v90, v110, v110
	v_fmac_f32_e32 v92, v111, v111
	v_fmac_f32_e32 v90, v112, v112
	v_fmac_f32_e32 v92, v113, v113
	v_add_f32_e32 v9, v9, v91
	v_add_f32_e32 v90, v90, v92
	ds_bpermute_b32 v91, v3, v9
	ds_bpermute_b32 v92, v3, v90
	s_waitcnt lgkmcnt(0)
	v_add_f32_e32 v9, v9, v91
	v_add_f32_e32 v90, v90, v92
	ds_bpermute_b32 v91, v4, v9
	ds_bpermute_b32 v92, v4, v90
	s_waitcnt lgkmcnt(0)
	v_add_f32_e32 v9, v9, v91
	v_add_f32_e32 v90, v90, v92
	ds_bpermute_b32 v91, v5, v9
	ds_bpermute_b32 v92, v5, v90
	s_waitcnt lgkmcnt(0)
	v_add_f32_e32 v9, v9, v91
	v_add_f32_e32 v90, v90, v92
	ds_bpermute_b32 v91, v6, v9
	ds_bpermute_b32 v92, v6, v90
	s_waitcnt lgkmcnt(0)
	v_add_f32_e32 v9, v9, v91
	v_add_f32_e32 v90, v90, v92
	ds_bpermute_b32 v91, v7, v9
	ds_bpermute_b32 v92, v7, v90
	s_waitcnt lgkmcnt(0)
	v_add_f32_e32 v9, v9, v91
	v_add_f32_e32 v90, v90, v92
	ds_bpermute_b32 v91, v8, v9
	ds_bpermute_b32 v92, v8, v90
	s_waitcnt lgkmcnt(0)
	v_add_f32_e32 v9, v9, v91
	v_add_f32_e32 v90, v90, v92
	v_mul_f32_e32 v93, 0x3a800000, v9
	v_mul_f32_e32 v91, 0x3a800000, v90
	v_fma_f32 v91, -v93, v93, v91
	v_max_f32_e32 v91, 0, v91
	v_add_f32_e32 v91, 0x358637bd, v91
	v_rsq_f32_e32 v94, v91
	v_mul_f32_e32 v91, 0.5, v91
	v_mul_f32_e32 v92, v94, v94
	v_fma_f32 v92, -v91, v92, 0.5
	v_fma_f32 v94, v94, v92, v94
	s_waitcnt vmcnt(6)
	v_sub_f32_e32 v98, v98, v93
	v_sub_f32_e32 v99, v99, v93
	v_sub_f32_e32 v100, v100, v93
	v_sub_f32_e32 v101, v101, v93
	v_sub_f32_e32 v102, v102, v93
	v_sub_f32_e32 v103, v103, v93
	v_sub_f32_e32 v104, v104, v93
	v_sub_f32_e32 v105, v105, v93
	v_sub_f32_e32 v106, v106, v93
	v_sub_f32_e32 v107, v107, v93
	v_sub_f32_e32 v108, v108, v93
	v_sub_f32_e32 v109, v109, v93
	v_sub_f32_e32 v110, v110, v93
	v_sub_f32_e32 v111, v111, v93
	v_sub_f32_e32 v112, v112, v93
	v_sub_f32_e32 v113, v113, v93
	v_add_f32_e32 v162, 1.0, v162
	v_add_f32_e32 v163, 1.0, v163
	v_add_f32_e32 v164, 1.0, v164
	v_add_f32_e32 v165, 1.0, v165
	v_add_f32_e32 v166, 1.0, v166
	v_add_f32_e32 v167, 1.0, v167
	v_add_f32_e32 v168, 1.0, v168
	v_add_f32_e32 v169, 1.0, v169
	v_add_f32_e32 v170, 1.0, v170
	v_add_f32_e32 v171, 1.0, v171
	v_add_f32_e32 v172, 1.0, v172
	v_add_f32_e32 v173, 1.0, v173
	v_add_f32_e32 v174, 1.0, v174
	v_add_f32_e32 v175, 1.0, v175
	v_add_f32_e32 v176, 1.0, v176
	v_add_f32_e32 v177, 1.0, v177
	v_mul_f32_e32 v98, v94, v98
	v_mul_f32_e32 v99, v94, v99
	v_mul_f32_e32 v100, v94, v100
	v_mul_f32_e32 v101, v94, v101
	v_mul_f32_e32 v102, v94, v102
	v_mul_f32_e32 v103, v94, v103
	v_mul_f32_e32 v104, v94, v104
	v_mul_f32_e32 v105, v94, v105
	v_mul_f32_e32 v106, v94, v106
	v_mul_f32_e32 v107, v94, v107
	v_mul_f32_e32 v108, v94, v108
	v_mul_f32_e32 v109, v94, v109
	v_mul_f32_e32 v110, v94, v110
	v_mul_f32_e32 v111, v94, v111
	v_mul_f32_e32 v112, v94, v112
	v_mul_f32_e32 v113, v94, v113
	v_fma_f32 v98, v98, v162, v146
	v_fma_f32 v99, v99, v163, v147
	v_fma_f32 v100, v100, v164, v148
	v_fma_f32 v101, v101, v165, v149
	v_fma_f32 v102, v102, v166, v150
	v_fma_f32 v103, v103, v167, v151
	v_fma_f32 v104, v104, v168, v152
	v_fma_f32 v105, v105, v169, v153
	v_fma_f32 v106, v106, v170, v154
	v_fma_f32 v107, v107, v171, v155
	v_fma_f32 v108, v108, v172, v156
	v_fma_f32 v109, v109, v173, v157
	v_fma_f32 v110, v110, v174, v158
	v_fma_f32 v111, v111, v175, v159
	v_fma_f32 v112, v112, v176, v160
	v_fma_f32 v113, v113, v177, v161
	v_cvt_pk_bf16_f32 v190, v98, v99
	v_cvt_pk_bf16_f32 v191, v100, v101
	v_cvt_pk_bf16_f32 v192, v102, v103
	v_cvt_pk_bf16_f32 v193, v104, v105
	v_cvt_pk_bf16_f32 v194, v106, v107
	v_cvt_pk_bf16_f32 v195, v108, v109
	v_cvt_pk_bf16_f32 v196, v110, v111
	v_cvt_pk_bf16_f32 v197, v112, v113
	s_add_u32 s2, s10, 0x1c00000
	s_addc_u32 s3, s11, 0
	global_store_dwordx2 v1, v[190:191], s[2:3]
	global_store_dwordx2 v1, v[192:193], s[2:3] offset:512
	global_store_dwordx2 v1, v[194:195], s[2:3] offset:1024
	global_store_dwordx2 v1, v[196:197], s[2:3] offset:1536
	s_waitcnt vmcnt(0)
	s_add_i32 s16, s16, 0x4000
	s_add_i32 s2, s70, 0xffe5
	s_and_b32 s2, s2, 0xff
	s_cmp_lt_u32 s2, 9
	s_movk_i32 s2, 0x4800
	s_cselect_b32 s8, 0x4000, s2
	s_cmp_ge_u32 s16, s8
	s_cbranch_scc1 .LBB0_124
; DI void ln_phase(const Frame& F, int which) {
;     const int gw = F.vcu * 8 + F.wave, NGW = F.G * 8; const int l = F.l;
;     const int nrows = (l == NL - 1) ? ML : MT;
;     bf16_t* H = (bf16_t*)(F.ws + WS_HB);
;     const float* g = pin(F, which == 0 ? I_LN1G : I_LN2G) + l * 1024; const float* b = pin(F, which == 0 ? I_LN1B : I_LN2B) + l * 1024;
;     const bool wh = !(which == 1 && l == NL - 1);
;     f32x4 vc[4], vn[4];
;     if (gw < nrows) ln_load(F, xrow_ptr(F, gw), vc);
;     for (int row = gw; row < nrows; row += NGW) {
;         if (row + NGW < nrows) ln_load(F, xrow_ptr(F, row + NGW), vn);
	s_lshl_b32 s9, s93, 3
	s_lshl_b64 s[2:3], s[44:45], 3
	s_add_u32 s2, s62, s2
	s_addc_u32 s3, s63, s3
	s_load_dwordx4 s[4:7], s[2:3], 0x98
	v_readlane_b32 s2, v255, 35
	s_lshl_b32 s2, s2, 12
	v_mov_b32_e32 v0, s16
	v_sub_co_u32_e32 v1, vcc, s16, v217
	s_waitcnt lgkmcnt(0)
	s_add_u32 s10, s6, s2
	s_addc_u32 s11, s7, 0
	s_add_u32 s12, s4, s2
	s_addc_u32 s13, s5, 0
	s_add_u32 s18, s94, 0x3600000
	s_addc_u32 s19, s95, 0
	v_readlane_b32 s20, v255, 17
	v_cndmask_b32_e32 v0, v1, v0, vcc
	v_mov_b32_e32 v1, v97
	s_and_b64 s[2:3], vcc, exec
	v_readlane_b32 s21, v255, 18
	s_cselect_b32 s3, s21, s19
	s_cselect_b32 s2, s20, s18
	v_lshlrev_b64 v[0:1], 12, v[0:1]
	v_lshl_add_u64 v[0:1], s[2:3], 0, v[0:1]
	v_lshlrev_b32_e32 v8, 4, v186
	v_readfirstlane_b32 s2, v0
	v_readfirstlane_b32 s3, v1
	s_nop 4
	global_load_dwordx4 v[16:19], v8, s[2:3]
	global_load_dwordx4 v[12:15], v8, s[2:3] offset:1024
	global_load_dwordx4 v[4:7], v8, s[2:3] offset:2048
	global_load_dwordx4 v[0:3], v8, s[2:3] offset:3072
	v_mov_b32_e32 v9, v97
	s_cmp_lg_u64 s[4:5], 0
	v_lshl_add_u64 v[32:33], s[12:13], 0, v[8:9]
	v_lshl_add_u64 v[34:35], s[10:11], 0, v[8:9]
	v_lshl_add_u64 v[8:9], s[94:95], 0, v[8:9]
	s_mov_b64 s[4:5], 0x103000
	v_lshl_add_u64 v[36:37], v[8:9], 0, s[4:5]
	s_mov_b64 s[4:5], 0x104000
	s_cselect_b64 s[6:7], -1, 0
	v_lshl_add_u64 v[38:39], v[8:9], 0, s[4:5]
	s_lshl_b32 s4, s16, 3
	s_add_u32 s4, s4, s44
	s_addc_u32 s5, 0, s45
	v_readlane_b32 s10, v255, 4
	s_add_u32 s12, s10, s4
	v_readlane_b32 s4, v255, 5
	s_addc_u32 s13, s4, s5
	s_lshl_b32 s24, s93, 6
	s_add_i32 s10, s16, 0xffffc000
	s_lshl_b64 s[4:5], s[16:17], 11
	v_readlane_b32 s11, v255, 6
	s_add_u32 s11, s11, s44
	v_readlane_b32 s14, v255, 7
	s_addc_u32 s14, s14, s45
	s_add_u32 s4, s11, s4
	v_lshlrev_b32_e32 v8, 3, v186
	v_mov_b32_e32 v9, v97
	s_addc_u32 s5, s14, s5
	v_lshlrev_b32_e32 v10, 2, v186
	v_lshl_add_u64 v[40:41], s[4:5], 0, v[8:9]
	v_mov_b32_e32 v8, 0
	v_xor_b32_e32 v48, 4, v10
	v_xor_b32_e32 v49, 8, v10
	v_xor_b32_e32 v50, 16, v10
	v_xor_b32_e32 v51, 32, v10
	v_xor_b32_e32 v52, 64, v10
	v_xor_b32_e32 v53, 0x80, v10
	v_cmp_ne_u32_e64 s[2:3], 0, v186
	s_lshl_b32 s14, s93, 14
	s_mov_b32 s15, s17
	s_mov_b32 s16, s10
	v_mov_b32_e32 v9, v8
	v_mov_b32_e32 v10, v8
	v_mov_b32_e32 v11, v8
	v_mov_b32_e32 v20, v8
	v_mov_b32_e32 v21, v8
	v_mov_b32_e32 v22, v8
	v_mov_b32_e32 v23, v8
	v_mov_b32_e32 v24, v8
	v_mov_b32_e32 v25, v8
	v_mov_b32_e32 v26, v8
	v_mov_b32_e32 v27, v8
	v_mov_b32_e32 v28, v8
	v_mov_b32_e32 v29, v8
	v_mov_b32_e32 v30, v8
	v_mov_b32_e32 v31, v8
	v_readlane_b32 s22, v255, 19
	v_readlane_b32 s23, v255, 20
	s_branch .LBB0_111

;     DI void operator()(Acc& acc, const Unit& u, int wr, int wc, int fr, int fq) const {
;     ...
;         for (int aim = 0; aim < 8; ++aim) { const int ai = aim >> 2, m = aim & 3;
;             f32x4 xa[2][2]; f32x2 sv = {0.f, 1.f};
;             if (ln) sv = *(const f32x2*)(st + 2 * (size_t)(row0 + EPI_ROWS(ai, m) + oz_));
; #pragma unroll
;             for (int bj = 0; bj < 2; ++bj) { const float* p = xib + (size_t)(EPI_ROWS(ai, m) + oz_) * D + EPI_COL8(bj); xa[bj][0] = *(const f32x4*)p; xa[bj][1] = *(const f32x4*)(p + 4); }
; #pragma unroll
;             for (int bj = 0; bj < 2; ++bj) { float* p = xob + (size_t)(EPI_ROWS(ai, m) + oz_) * D + EPI_COL8(bj);
;                 *(f32x4*)p = ((xa[bj][0] - sv[0]) * sv[1]) * la[bj][0] + acc[ai][bj][m][0];
;                 *(f32x4*)(p + 4) = ((xa[bj][1] - sv[0]) * sv[1]) * la[bj][1] + acc[ai][bj][m][1]; }
.LBB0_161:
	v_mov_b32_e32 v200, v97
	v_mov_b32_e32 v206, 1.0
	v_add3_u32 v202, s56, v207, v200
	v_mov_b32_e32 v204, 0
	s_and_b64 vcc, exec, s[4:5]
	v_mov_b32_e32 v210, 0
	v_mov_b32_e32 v208, 1.0
	s_cbranch_vccnz .LBB0_163
	v_ashrrev_i32_e32 v203, 31, v202
	v_lshl_add_u64 v[210:211], v[202:203], 3, s[28:29]
	global_load_dwordx2 v[248:249], v[210:211], off offset:128
	global_load_dwordx2 v[250:251], v[210:211], off offset:256
	global_load_dwordx2 v[252:253], v[210:211], off offset:384
	global_load_dwordx2 v[210:211], v[210:211], off
	s_waitcnt vmcnt(0)
	v_mov_b32_e32 v208, v211
.LBB0_163:
	s_lshl_b64 s[8:9], s[14:15], 12
	s_waitcnt lgkmcnt(0)
	s_add_u32 s8, s12, s8
	s_addc_u32 s9, s13, s9
	v_add_u32_e32 v200, v200, v207
	s_add_u32 s12, s8, s34
	v_ashrrev_i32_e32 v201, 31, v200
	s_addc_u32 s13, s9, s35
	v_lshlrev_b64 v[214:215], 12, v[200:201]
	v_lshl_add_u64 v[228:229], s[12:13], 0, v[214:215]
	v_lshl_add_u64 v[240:241], v[228:229], 0, v[96:97]
	global_load_dwordx4 v[228:231], v[240:241], off
	global_load_dwordx4 v[232:235], v[240:241], off offset:16
	global_load_dwordx4 v[236:239], v[240:241], off offset:512
	s_nop 0
	global_load_dwordx4 v[240:243], v[240:241], off offset:528
	s_add_i32 s10, s56, 0xffffc000
	s_ashr_i32 s11, s56, 31
	s_and_b64 s[8:9], s[40:41], exec
	v_readlane_b32 s24, v255, 17
	s_cselect_b32 s9, s11, 0
	s_cselect_b32 s8, s56, s10
	v_readlane_b32 s25, v255, 18
	s_cselect_b32 s10, s25, s55
	s_cselect_b32 s11, s24, s54
	s_lshl_b64 s[8:9], s[8:9], 12
	s_add_u32 s8, s11, s8
	s_addc_u32 s9, s10, s9
	s_add_u32 s14, s8, s34
	s_addc_u32 s15, s9, s35
	s_waitcnt vmcnt(0)
	v_pk_fma_f32 v[244:245], v[138:139], v[72:73], v[176:177]
	v_pk_fma_f32 v[138:139], v[130:131], v[64:65], v[174:175]
	v_lshl_add_u64 v[130:131], s[14:15], 0, v[214:215]
	v_pk_fma_f32 v[246:247], v[140:141], v[74:75], v[194:195]
	v_pk_fma_f32 v[140:141], v[132:133], v[66:67], v[188:189]
	v_lshl_add_u64 v[214:215], v[130:131], 0, v[96:97]
	v_pk_fma_f32 v[136:137], v[136:137], v[70:71], v[192:193]
	v_pk_fma_f32 v[134:135], v[134:135], v[68:69], v[190:191]
	v_pk_fma_f32 v[144:145], v[144:145], v[78:79], v[198:199]
	v_pk_fma_f32 v[142:143], v[142:143], v[76:77], v[196:197]
	s_and_b64 vcc, exec, s[4:5]
	v_readlane_b32 s26, v255, 19
	v_readlane_b32 s27, v255, 20
	v_sub_f32_e32 v131, v231, v210
	v_sub_f32_e32 v130, v230, v210
	v_sub_f32_e32 v133, v229, v210
	v_sub_f32_e32 v132, v228, v210
	v_sub_f32_e32 v229, v235, v210
	v_sub_f32_e32 v228, v234, v210
	v_sub_f32_e32 v231, v233, v210
	v_sub_f32_e32 v230, v232, v210
	v_sub_f32_e32 v233, v239, v210
	v_sub_f32_e32 v232, v238, v210
	v_sub_f32_e32 v235, v237, v210
	v_sub_f32_e32 v234, v236, v210
	v_sub_f32_e32 v237, v243, v210
	v_sub_f32_e32 v236, v242, v210
	v_sub_f32_e32 v211, v241, v210
	v_sub_f32_e32 v210, v240, v210
	v_pk_mul_f32 v[238:239], v[208:209], v[132:133] op_sel_hi:[0,1]
	v_pk_mul_f32 v[130:131], v[208:209], v[130:131] op_sel_hi:[0,1]
	v_pk_mul_f32 v[230:231], v[208:209], v[230:231] op_sel_hi:[0,1]
	v_pk_mul_f32 v[228:229], v[208:209], v[228:229] op_sel_hi:[0,1]
	v_pk_mul_f32 v[234:235], v[208:209], v[234:235] op_sel_hi:[0,1]
	v_pk_mul_f32 v[232:233], v[208:209], v[232:233] op_sel_hi:[0,1]
	v_pk_mul_f32 v[210:211], v[208:209], v[210:211] op_sel_hi:[0,1]
	v_pk_mul_f32 v[236:237], v[208:209], v[236:237] op_sel_hi:[0,1]
	v_pk_fma_f32 v[132:133], v[172:173], v[130:131], v[136:137]
	v_pk_fma_f32 v[130:131], v[170:171], v[238:239], v[134:135]
	v_pk_fma_f32 v[136:137], v[164:165], v[228:229], v[140:141]
	v_pk_fma_f32 v[134:135], v[162:163], v[230:231], v[138:139]
	v_pk_fma_f32 v[140:141], v[168:169], v[232:233], v[144:145]
	v_pk_fma_f32 v[138:139], v[166:167], v[234:235], v[142:143]
	v_pk_fma_f32 v[144:145], v[160:161], v[236:237], v[246:247]
	v_pk_fma_f32 v[142:143], v[158:159], v[210:211], v[244:245]
	global_store_dwordx4 v[214:215], v[130:133], off
	global_store_dwordx4 v[214:215], v[134:137], off offset:16
	global_store_dwordx4 v[214:215], v[138:141], off offset:512
	global_store_dwordx4 v[214:215], v[142:145], off offset:528
	s_cbranch_vccnz .LBB0_165
	v_mov_b32_e32 v204, v248
	v_mov_b32_e32 v206, v249
.LBB0_165:
	s_nop 0
	v_pk_fma_f32 v[144:145], v[114:115], v[64:65], v[174:175]
	v_add_u32_e32 v114, 16, v200
	v_ashrrev_i32_e32 v115, 31, v114
	v_lshlrev_b64 v[210:211], 12, v[114:115]
	v_lshl_add_u64 v[114:115], s[12:13], 0, v[210:211]
	v_pk_fma_f32 v[132:133], v[126:127], v[76:77], v[196:197]
	v_lshl_add_u64 v[126:127], v[114:115], 0, v[96:97]
	v_pk_fma_f32 v[130:131], v[128:129], v[78:79], v[198:199]
	v_pk_fma_f32 v[134:135], v[124:125], v[74:75], v[194:195]
	v_pk_fma_f32 v[136:137], v[122:123], v[72:73], v[176:177]
	v_pk_fma_f32 v[138:139], v[120:121], v[70:71], v[192:193]
	v_pk_fma_f32 v[140:141], v[118:119], v[68:69], v[190:191]
	v_pk_fma_f32 v[142:143], v[116:117], v[66:67], v[188:189]
	global_load_dwordx4 v[114:117], v[126:127], off offset:16
	global_load_dwordx4 v[118:121], v[126:127], off
	global_load_dwordx4 v[122:125], v[126:127], off offset:528
	s_nop 0
	global_load_dwordx4 v[126:129], v[126:127], off offset:512
	v_lshl_add_u64 v[210:211], s[14:15], 0, v[210:211]
	v_lshl_add_u64 v[210:211], v[210:211], 0, v[96:97]
	s_and_b64 vcc, exec, s[4:5]
	s_waitcnt vmcnt(3)
	v_sub_f32_e32 v117, v117, v204
	v_sub_f32_e32 v116, v116, v204
	v_sub_f32_e32 v115, v115, v204
	v_sub_f32_e32 v114, v114, v204
	s_waitcnt vmcnt(2)
; #define ROW_FENCE asm volatile("" ::: "memory")
;     DI void operator()(Acc& acc, const Unit& u, int wr, int wc, int fr, int fq) const {
;     ...
;         for (int aim = 0; aim < 8; ++aim) { const int ai = aim >> 2, m = aim & 3;
;             f32x4 xa[2][2]; f32x2 sv = {0.f, 1.f};
;             if (ln) sv = *(const f32x2*)(st + 2 * (size_t)(row0 + EPI_ROWS(ai, m) + oz_));
; #pragma unroll
;             for (int bj = 0; bj < 2; ++bj) { const float* p = xib + (size_t)(EPI_ROWS(ai, m) + oz_) * D + EPI_COL8(bj); xa[bj][0] = *(const f32x4*)p; xa[bj][1] = *(const f32x4*)(p + 4); }
; #pragma unroll
;             for (int bj = 0; bj < 2; ++bj) { float* p = xob + (size_t)(EPI_ROWS(ai, m) + oz_) * D + EPI_COL8(bj);
;                 *(f32x4*)p = ((xa[bj][0] - sv[0]) * sv[1]) * la[bj][0] + acc[ai][bj][m][0];
;                 *(f32x4*)(p + 4) = ((xa[bj][1] - sv[0]) * sv[1]) * la[bj][1] + acc[ai][bj][m][1]; }
;             if (m & 1) ROW_FENCE;
	v_sub_f32_e32 v121, v121, v204
	v_sub_f32_e32 v120, v120, v204
	v_sub_f32_e32 v119, v119, v204
	v_sub_f32_e32 v118, v118, v204
	v_pk_mul_f32 v[114:115], v[206:207], v[114:115] op_sel_hi:[0,1]
	v_pk_mul_f32 v[116:117], v[206:207], v[116:117] op_sel_hi:[0,1]
	v_pk_mul_f32 v[118:119], v[206:207], v[118:119] op_sel_hi:[0,1]
	v_pk_mul_f32 v[120:121], v[206:207], v[120:121] op_sel_hi:[0,1]
	v_pk_fma_f32 v[116:117], v[164:165], v[116:117], v[142:143]
	v_pk_fma_f32 v[114:115], v[162:163], v[114:115], v[144:145]
	v_pk_fma_f32 v[120:121], v[172:173], v[120:121], v[138:139]
	v_pk_fma_f32 v[118:119], v[170:171], v[118:119], v[140:141]
	global_store_dwordx4 v[210:211], v[114:117], off offset:16
	global_store_dwordx4 v[210:211], v[118:121], off
	s_waitcnt vmcnt(2)
	v_sub_f32_e32 v115, v129, v204
	v_sub_f32_e32 v114, v128, v204
	v_sub_f32_e32 v117, v127, v204
	v_sub_f32_e32 v116, v126, v204
	v_pk_mul_f32 v[118:119], v[206:207], v[116:117] op_sel_hi:[0,1]
	v_pk_mul_f32 v[114:115], v[206:207], v[114:115] op_sel_hi:[0,1]
	v_pk_fma_f32 v[116:117], v[168:169], v[114:115], v[130:131]
	v_pk_fma_f32 v[114:115], v[166:167], v[118:119], v[132:133]
	global_store_dwordx4 v[210:211], v[114:117], off offset:512
	v_mov_b32_e32 v120, 0
	s_nop 0
	v_sub_f32_e32 v115, v125, v204
	v_sub_f32_e32 v114, v124, v204
	v_sub_f32_e32 v117, v123, v204
	v_sub_f32_e32 v116, v122, v204
	v_pk_mul_f32 v[118:119], v[206:207], v[116:117] op_sel_hi:[0,1]
	v_pk_mul_f32 v[114:115], v[206:207], v[114:115] op_sel_hi:[0,1]
	v_pk_fma_f32 v[116:117], v[160:161], v[114:115], v[134:135]
	v_pk_fma_f32 v[114:115], v[158:159], v[118:119], v[136:137]
	global_store_dwordx4 v[210:211], v[114:117], off offset:528
	v_mov_b32_e32 v118, 1.0
	s_nop 0
	v_mov_b32_e32 v114, 1.0
	v_mov_b32_e32 v116, 0
	s_cbranch_vccnz .LBB0_167
	v_mov_b32_e32 v120, v250
	v_mov_b32_e32 v118, v251
.LBB0_167:
	v_add_u32_e32 v122, 32, v200
	v_ashrrev_i32_e32 v123, 31, v122
	v_lshlrev_b64 v[138:139], 12, v[122:123]
	v_lshl_add_u64 v[122:123], s[12:13], 0, v[138:139]
	v_lshl_add_u64 v[134:135], v[122:123], 0, v[96:97]
	global_load_dwordx4 v[122:125], v[134:135], off
	global_load_dwordx4 v[126:129], v[134:135], off offset:16
	global_load_dwordx4 v[130:133], v[134:135], off offset:512
	s_nop 0
	global_load_dwordx4 v[134:137], v[134:135], off offset:528
	v_pk_fma_f32 v[140:141], v[108:109], v[74:75], v[194:195]
	v_pk_fma_f32 v[108:109], v[98:99], v[64:65], v[174:175]
	v_lshl_add_u64 v[98:99], s[14:15], 0, v[138:139]
	v_pk_fma_f32 v[142:143], v[106:107], v[72:73], v[176:177]
	v_pk_fma_f32 v[106:107], v[100:101], v[66:67], v[188:189]
	v_lshl_add_u64 v[138:139], v[98:99], 0, v[96:97]
	v_pk_fma_f32 v[104:105], v[104:105], v[70:71], v[192:193]
	v_pk_fma_f32 v[102:103], v[102:103], v[68:69], v[190:191]
	v_pk_fma_f32 v[112:113], v[112:113], v[78:79], v[198:199]
	v_pk_fma_f32 v[110:111], v[110:111], v[76:77], v[196:197]
	s_and_b64 vcc, exec, s[4:5]
	s_waitcnt vmcnt(3)
	v_sub_f32_e32 v99, v125, v120
	v_sub_f32_e32 v98, v124, v120
	v_sub_f32_e32 v101, v123, v120
	v_sub_f32_e32 v100, v122, v120
	s_waitcnt vmcnt(2)
	v_sub_f32_e32 v123, v129, v120
	v_sub_f32_e32 v122, v128, v120
	v_sub_f32_e32 v125, v127, v120
	v_sub_f32_e32 v124, v126, v120
	s_waitcnt vmcnt(1)
	v_sub_f32_e32 v127, v133, v120
	v_sub_f32_e32 v126, v132, v120
	v_sub_f32_e32 v129, v131, v120
	v_sub_f32_e32 v128, v130, v120
	s_waitcnt vmcnt(0)
	v_sub_f32_e32 v131, v137, v120
	v_sub_f32_e32 v130, v136, v120
	v_sub_f32_e32 v121, v135, v120
	v_sub_f32_e32 v120, v134, v120
	v_pk_mul_f32 v[132:133], v[118:119], v[100:101] op_sel_hi:[0,1]
	v_pk_mul_f32 v[98:99], v[118:119], v[98:99] op_sel_hi:[0,1]
	v_pk_mul_f32 v[124:125], v[118:119], v[124:125] op_sel_hi:[0,1]
	v_pk_mul_f32 v[122:123], v[118:119], v[122:123] op_sel_hi:[0,1]
	v_pk_mul_f32 v[128:129], v[118:119], v[128:129] op_sel_hi:[0,1]
	v_pk_mul_f32 v[126:127], v[118:119], v[126:127] op_sel_hi:[0,1]
	v_pk_mul_f32 v[120:121], v[118:119], v[120:121] op_sel_hi:[0,1]
	v_pk_mul_f32 v[118:119], v[118:119], v[130:131] op_sel_hi:[0,1]
	v_pk_fma_f32 v[100:101], v[172:173], v[98:99], v[104:105]
	v_pk_fma_f32 v[98:99], v[170:171], v[132:133], v[102:103]
	v_pk_fma_f32 v[104:105], v[164:165], v[122:123], v[106:107]
	v_pk_fma_f32 v[102:103], v[162:163], v[124:125], v[108:109]
	v_pk_fma_f32 v[108:109], v[168:169], v[126:127], v[112:113]
	v_pk_fma_f32 v[106:107], v[166:167], v[128:129], v[110:111]
	v_pk_fma_f32 v[112:113], v[160:161], v[118:119], v[140:141]
	v_pk_fma_f32 v[110:111], v[158:159], v[120:121], v[142:143]
	global_store_dwordx4 v[138:139], v[98:101], off
	global_store_dwordx4 v[138:139], v[102:105], off offset:16
	global_store_dwordx4 v[138:139], v[106:109], off offset:512
	global_store_dwordx4 v[138:139], v[110:113], off offset:528
	s_cbranch_vccnz .LBB0_169
	v_mov_b32_e32 v116, v252
	v_mov_b32_e32 v114, v253
; #define ROW_FENCE asm volatile("" ::: "memory")
;     DI void operator()(Acc& acc, const Unit& u, int wr, int wc, int fr, int fq) const {
;     ...
;         for (int aim = 0; aim < 8; ++aim) { const int ai = aim >> 2, m = aim & 3;
;             f32x4 xa[2][2]; f32x2 sv = {0.f, 1.f};
;             if (ln) sv = *(const f32x2*)(st + 2 * (size_t)(row0 + EPI_ROWS(ai, m) + oz_));
; #pragma unroll
;             for (int bj = 0; bj < 2; ++bj) { const float* p = xib + (size_t)(EPI_ROWS(ai, m) + oz_) * D + EPI_COL8(bj); xa[bj][0] = *(const f32x4*)p; xa[bj][1] = *(const f32x4*)(p + 4); }
; #pragma unroll
;             for (int bj = 0; bj < 2; ++bj) { float* p = xob + (size_t)(EPI_ROWS(ai, m) + oz_) * D + EPI_COL8(bj);
;                 *(f32x4*)p = ((xa[bj][0] - sv[0]) * sv[1]) * la[bj][0] + acc[ai][bj][m][0];
;                 *(f32x4*)(p + 4) = ((xa[bj][1] - sv[0]) * sv[1]) * la[bj][1] + acc[ai][bj][m][1]; }
;             if (m & 1) ROW_FENCE;
.LBB0_169:
	s_nop 0
	v_pk_fma_f32 v[112:113], v[80:81], v[64:65], v[174:175]
	v_add_u32_e32 v80, 48, v200
	v_ashrrev_i32_e32 v81, 31, v80
	v_lshlrev_b64 v[118:119], 12, v[80:81]
	v_lshl_add_u64 v[80:81], s[12:13], 0, v[118:119]
	v_pk_fma_f32 v[100:101], v[92:93], v[76:77], v[196:197]
	v_lshl_add_u64 v[92:93], v[80:81], 0, v[96:97]
	v_pk_fma_f32 v[98:99], v[94:95], v[78:79], v[198:199]
	v_pk_fma_f32 v[102:103], v[90:91], v[74:75], v[194:195]
	v_pk_fma_f32 v[104:105], v[88:89], v[72:73], v[176:177]
	v_pk_fma_f32 v[106:107], v[86:87], v[70:71], v[192:193]
	v_pk_fma_f32 v[108:109], v[84:85], v[68:69], v[190:191]
	v_pk_fma_f32 v[110:111], v[82:83], v[66:67], v[188:189]
	global_load_dwordx4 v[80:83], v[92:93], off offset:16
	global_load_dwordx4 v[84:87], v[92:93], off
	global_load_dwordx4 v[88:91], v[92:93], off offset:528
	s_nop 0
	global_load_dwordx4 v[92:95], v[92:93], off offset:512
	v_lshl_add_u64 v[118:119], s[14:15], 0, v[118:119]
	v_lshl_add_u64 v[118:119], v[118:119], 0, v[96:97]
	s_and_b64 vcc, exec, s[4:5]
	s_waitcnt vmcnt(3)
	v_sub_f32_e32 v83, v83, v116
	v_sub_f32_e32 v82, v82, v116
	v_sub_f32_e32 v81, v81, v116
	v_sub_f32_e32 v80, v80, v116
	s_waitcnt vmcnt(2)
	v_sub_f32_e32 v87, v87, v116
	v_sub_f32_e32 v86, v86, v116
	v_sub_f32_e32 v85, v85, v116
	v_sub_f32_e32 v84, v84, v116
	v_pk_mul_f32 v[80:81], v[114:115], v[80:81] op_sel_hi:[0,1]
	v_pk_mul_f32 v[82:83], v[114:115], v[82:83] op_sel_hi:[0,1]
	v_pk_mul_f32 v[84:85], v[114:115], v[84:85] op_sel_hi:[0,1]
	v_pk_mul_f32 v[86:87], v[114:115], v[86:87] op_sel_hi:[0,1]
	v_pk_fma_f32 v[82:83], v[164:165], v[82:83], v[110:111]
	v_pk_fma_f32 v[80:81], v[162:163], v[80:81], v[112:113]
	v_pk_fma_f32 v[86:87], v[172:173], v[86:87], v[106:107]
	v_pk_fma_f32 v[84:85], v[170:171], v[84:85], v[108:109]
	global_store_dwordx4 v[118:119], v[80:83], off offset:16
	global_store_dwordx4 v[118:119], v[84:87], off
	s_waitcnt vmcnt(2)
	v_sub_f32_e32 v81, v95, v116
	v_sub_f32_e32 v80, v94, v116
	v_sub_f32_e32 v83, v93, v116
	v_sub_f32_e32 v82, v92, v116
	v_pk_mul_f32 v[84:85], v[114:115], v[82:83] op_sel_hi:[0,1]
	v_pk_mul_f32 v[80:81], v[114:115], v[80:81] op_sel_hi:[0,1]
	v_pk_fma_f32 v[82:83], v[168:169], v[80:81], v[98:99]
	v_pk_fma_f32 v[80:81], v[166:167], v[84:85], v[100:101]
	global_store_dwordx4 v[118:119], v[80:83], off offset:512
	v_mov_b32_e32 v86, 0
	s_nop 0
	v_sub_f32_e32 v81, v91, v116
	v_sub_f32_e32 v80, v90, v116
	v_sub_f32_e32 v83, v89, v116
	v_sub_f32_e32 v82, v88, v116
	v_pk_mul_f32 v[84:85], v[114:115], v[82:83] op_sel_hi:[0,1]
	v_pk_mul_f32 v[80:81], v[114:115], v[80:81] op_sel_hi:[0,1]
	v_pk_fma_f32 v[82:83], v[160:161], v[80:81], v[102:103]
	v_pk_fma_f32 v[80:81], v[158:159], v[84:85], v[104:105]
	global_store_dwordx4 v[118:119], v[80:83], off offset:528
	v_mov_b32_e32 v84, 1.0
	s_nop 0
	v_mov_b32_e32 v80, 1.0
	v_mov_b32_e32 v82, 0
	s_cbranch_vccnz .LBB0_171
	v_add_u32_e32 v84, 0x80, v202
	v_ashrrev_i32_e32 v85, 31, v84
	v_lshl_add_u64 v[84:85], v[84:85], 3, s[28:29]
	global_load_dwordx2 v[248:249], v[84:85], off offset:128
	global_load_dwordx2 v[250:251], v[84:85], off offset:256
	global_load_dwordx2 v[252:253], v[84:85], off offset:384
	global_load_dwordx2 v[86:87], v[84:85], off
	s_waitcnt vmcnt(0)
	v_mov_b32_e32 v84, v87
.LBB0_171:
	v_add_u32_e32 v88, 0x80, v200
	v_ashrrev_i32_e32 v89, 31, v88
	v_lshlrev_b64 v[106:107], 12, v[88:89]
	v_lshl_add_u64 v[88:89], s[12:13], 0, v[106:107]
	v_lshl_add_u64 v[102:103], v[88:89], 0, v[96:97]
	global_load_dwordx4 v[88:91], v[102:103], off
	global_load_dwordx4 v[92:95], v[102:103], off offset:16
	global_load_dwordx4 v[98:101], v[102:103], off offset:512
	s_nop 0
	global_load_dwordx4 v[102:105], v[102:103], off offset:528
	v_pk_fma_f32 v[108:109], v[58:59], v[74:75], v[194:195]
	v_pk_fma_f32 v[58:59], v[48:49], v[64:65], v[174:175]
	v_lshl_add_u64 v[48:49], s[14:15], 0, v[106:107]
	v_pk_fma_f32 v[110:111], v[56:57], v[72:73], v[176:177]
	v_pk_fma_f32 v[56:57], v[50:51], v[66:67], v[188:189]
	v_lshl_add_u64 v[106:107], v[48:49], 0, v[96:97]
	v_pk_fma_f32 v[54:55], v[54:55], v[70:71], v[192:193]
	v_pk_fma_f32 v[52:53], v[52:53], v[68:69], v[190:191]
	v_pk_fma_f32 v[62:63], v[62:63], v[78:79], v[198:199]
	v_pk_fma_f32 v[60:61], v[60:61], v[76:77], v[196:197]
	s_and_b64 vcc, exec, s[4:5]
	s_waitcnt vmcnt(3)
	v_sub_f32_e32 v49, v91, v86
	v_sub_f32_e32 v48, v90, v86
	v_sub_f32_e32 v51, v89, v86
	v_sub_f32_e32 v50, v88, v86
	s_waitcnt vmcnt(2)
	v_sub_f32_e32 v89, v95, v86
	v_sub_f32_e32 v88, v94, v86
	v_sub_f32_e32 v91, v93, v86
	v_sub_f32_e32 v90, v92, v86
	s_waitcnt vmcnt(1)
	v_sub_f32_e32 v93, v101, v86
	v_sub_f32_e32 v92, v100, v86
	v_sub_f32_e32 v95, v99, v86
	v_sub_f32_e32 v94, v98, v86
	s_waitcnt vmcnt(0)
	v_sub_f32_e32 v99, v105, v86
	v_sub_f32_e32 v98, v104, v86
	v_sub_f32_e32 v87, v103, v86
	v_sub_f32_e32 v86, v102, v86
	v_pk_mul_f32 v[100:101], v[84:85], v[50:51] op_sel_hi:[0,1]
	v_pk_mul_f32 v[48:49], v[84:85], v[48:49] op_sel_hi:[0,1]
	v_pk_mul_f32 v[90:91], v[84:85], v[90:91] op_sel_hi:[0,1]
	v_pk_mul_f32 v[88:89], v[84:85], v[88:89] op_sel_hi:[0,1]
	v_pk_mul_f32 v[94:95], v[84:85], v[94:95] op_sel_hi:[0,1]
	v_pk_mul_f32 v[92:93], v[84:85], v[92:93] op_sel_hi:[0,1]
	v_pk_mul_f32 v[86:87], v[84:85], v[86:87] op_sel_hi:[0,1]
	v_pk_mul_f32 v[84:85], v[84:85], v[98:99] op_sel_hi:[0,1]
	v_pk_fma_f32 v[50:51], v[172:173], v[48:49], v[54:55]
	v_pk_fma_f32 v[48:49], v[170:171], v[100:101], v[52:53]
	v_pk_fma_f32 v[54:55], v[164:165], v[88:89], v[56:57]
	v_pk_fma_f32 v[52:53], v[162:163], v[90:91], v[58:59]
	v_pk_fma_f32 v[58:59], v[168:169], v[92:93], v[62:63]
	v_pk_fma_f32 v[56:57], v[166:167], v[94:95], v[60:61]
	v_pk_fma_f32 v[62:63], v[160:161], v[84:85], v[108:109]
	v_pk_fma_f32 v[60:61], v[158:159], v[86:87], v[110:111]
	global_store_dwordx4 v[106:107], v[48:51], off
	global_store_dwordx4 v[106:107], v[52:55], off offset:16
	global_store_dwordx4 v[106:107], v[56:59], off offset:512
	global_store_dwordx4 v[106:107], v[60:63], off offset:528
	s_cbranch_vccnz .LBB0_173
	v_mov_b32_e32 v82, v248
	v_mov_b32_e32 v80, v249
; #define ROW_FENCE asm volatile("" ::: "memory")
;     DI void operator()(Acc& acc, const Unit& u, int wr, int wc, int fr, int fq) const {
;     ...
;         for (int aim = 0; aim < 8; ++aim) { const int ai = aim >> 2, m = aim & 3;
;             f32x4 xa[2][2]; f32x2 sv = {0.f, 1.f};
;             if (ln) sv = *(const f32x2*)(st + 2 * (size_t)(row0 + EPI_ROWS(ai, m) + oz_));
; #pragma unroll
;             for (int bj = 0; bj < 2; ++bj) { const float* p = xib + (size_t)(EPI_ROWS(ai, m) + oz_) * D + EPI_COL8(bj); xa[bj][0] = *(const f32x4*)p; xa[bj][1] = *(const f32x4*)(p + 4); }
; #pragma unroll
;             for (int bj = 0; bj < 2; ++bj) { float* p = xob + (size_t)(EPI_ROWS(ai, m) + oz_) * D + EPI_COL8(bj);
;                 *(f32x4*)p = ((xa[bj][0] - sv[0]) * sv[1]) * la[bj][0] + acc[ai][bj][m][0];
;                 *(f32x4*)(p + 4) = ((xa[bj][1] - sv[0]) * sv[1]) * la[bj][1] + acc[ai][bj][m][1]; }
;             if (m & 1) ROW_FENCE;
.LBB0_173:
	s_nop 0
	v_pk_fma_f32 v[62:63], v[32:33], v[64:65], v[174:175]
	v_add_u32_e32 v32, 0x90, v200
	v_ashrrev_i32_e32 v33, 31, v32
	v_lshlrev_b64 v[84:85], 12, v[32:33]
	v_lshl_add_u64 v[32:33], s[12:13], 0, v[84:85]
	v_pk_fma_f32 v[50:51], v[44:45], v[76:77], v[196:197]
	v_lshl_add_u64 v[44:45], v[32:33], 0, v[96:97]
	v_pk_fma_f32 v[48:49], v[46:47], v[78:79], v[198:199]
	v_pk_fma_f32 v[52:53], v[42:43], v[74:75], v[194:195]
	v_pk_fma_f32 v[54:55], v[40:41], v[72:73], v[176:177]
	v_pk_fma_f32 v[56:57], v[38:39], v[70:71], v[192:193]
	v_pk_fma_f32 v[58:59], v[36:37], v[68:69], v[190:191]
	v_pk_fma_f32 v[60:61], v[34:35], v[66:67], v[188:189]
	global_load_dwordx4 v[32:35], v[44:45], off offset:16
	global_load_dwordx4 v[36:39], v[44:45], off
	global_load_dwordx4 v[40:43], v[44:45], off offset:528
	s_nop 0
	global_load_dwordx4 v[44:47], v[44:45], off offset:512
	v_lshl_add_u64 v[84:85], s[14:15], 0, v[84:85]
	v_lshl_add_u64 v[84:85], v[84:85], 0, v[96:97]
	s_and_b64 vcc, exec, s[4:5]
	s_waitcnt vmcnt(3)
	v_sub_f32_e32 v35, v35, v82
	v_sub_f32_e32 v34, v34, v82
	v_sub_f32_e32 v33, v33, v82
	v_sub_f32_e32 v32, v32, v82
	s_waitcnt vmcnt(2)
	v_sub_f32_e32 v39, v39, v82
	v_sub_f32_e32 v38, v38, v82
	v_sub_f32_e32 v37, v37, v82
	v_sub_f32_e32 v36, v36, v82
	v_pk_mul_f32 v[32:33], v[80:81], v[32:33] op_sel_hi:[0,1]
	v_pk_mul_f32 v[34:35], v[80:81], v[34:35] op_sel_hi:[0,1]
	v_pk_mul_f32 v[36:37], v[80:81], v[36:37] op_sel_hi:[0,1]
	v_pk_mul_f32 v[38:39], v[80:81], v[38:39] op_sel_hi:[0,1]
	v_pk_fma_f32 v[34:35], v[164:165], v[34:35], v[60:61]
	v_pk_fma_f32 v[32:33], v[162:163], v[32:33], v[62:63]
	v_pk_fma_f32 v[38:39], v[172:173], v[38:39], v[56:57]
	v_pk_fma_f32 v[36:37], v[170:171], v[36:37], v[58:59]
	global_store_dwordx4 v[84:85], v[32:35], off offset:16
	global_store_dwordx4 v[84:85], v[36:39], off
	s_waitcnt vmcnt(2)
	v_sub_f32_e32 v33, v47, v82
	v_sub_f32_e32 v32, v46, v82
	v_sub_f32_e32 v35, v45, v82
	v_sub_f32_e32 v34, v44, v82
	v_pk_mul_f32 v[36:37], v[80:81], v[34:35] op_sel_hi:[0,1]
	v_pk_mul_f32 v[32:33], v[80:81], v[32:33] op_sel_hi:[0,1]
	v_pk_fma_f32 v[34:35], v[168:169], v[32:33], v[48:49]
	v_pk_fma_f32 v[32:33], v[166:167], v[36:37], v[50:51]
	global_store_dwordx4 v[84:85], v[32:35], off offset:512
	v_mov_b32_e32 v38, 0
	s_nop 0
	v_sub_f32_e32 v33, v43, v82
	v_sub_f32_e32 v32, v42, v82
	v_sub_f32_e32 v35, v41, v82
	v_sub_f32_e32 v34, v40, v82
	v_pk_mul_f32 v[36:37], v[80:81], v[34:35] op_sel_hi:[0,1]
	v_pk_mul_f32 v[32:33], v[80:81], v[32:33] op_sel_hi:[0,1]
	v_pk_fma_f32 v[34:35], v[160:161], v[32:33], v[52:53]
	v_pk_fma_f32 v[32:33], v[158:159], v[36:37], v[54:55]
	global_store_dwordx4 v[84:85], v[32:35], off offset:528
	v_mov_b32_e32 v36, 1.0
	s_nop 0
	v_mov_b32_e32 v32, 1.0
	v_mov_b32_e32 v34, 0
	s_cbranch_vccnz .LBB0_175
	v_mov_b32_e32 v38, v250
	v_mov_b32_e32 v36, v251
.LBB0_175:
	v_add_u32_e32 v40, 0xa0, v200
	v_ashrrev_i32_e32 v41, 31, v40
	v_lshlrev_b64 v[56:57], 12, v[40:41]
	v_lshl_add_u64 v[40:41], s[12:13], 0, v[56:57]
	v_lshl_add_u64 v[52:53], v[40:41], 0, v[96:97]
	global_load_dwordx4 v[40:43], v[52:53], off
	global_load_dwordx4 v[44:47], v[52:53], off offset:16
	global_load_dwordx4 v[48:51], v[52:53], off offset:512
	s_nop 0
	global_load_dwordx4 v[52:55], v[52:53], off offset:528
	v_pk_fma_f32 v[58:59], v[26:27], v[74:75], v[194:195]
	v_pk_fma_f32 v[26:27], v[16:17], v[64:65], v[174:175]
	v_lshl_add_u64 v[16:17], s[14:15], 0, v[56:57]
	v_pk_fma_f32 v[60:61], v[24:25], v[72:73], v[176:177]
	v_pk_fma_f32 v[24:25], v[18:19], v[66:67], v[188:189]
	v_lshl_add_u64 v[56:57], v[16:17], 0, v[96:97]
	v_pk_fma_f32 v[22:23], v[22:23], v[70:71], v[192:193]
	v_pk_fma_f32 v[20:21], v[20:21], v[68:69], v[190:191]
	v_pk_fma_f32 v[30:31], v[30:31], v[78:79], v[198:199]
	v_pk_fma_f32 v[28:29], v[28:29], v[76:77], v[196:197]
	s_and_b64 vcc, exec, s[4:5]
	s_waitcnt vmcnt(3)
	v_sub_f32_e32 v17, v43, v38
	v_sub_f32_e32 v16, v42, v38
	v_sub_f32_e32 v19, v41, v38
	v_sub_f32_e32 v18, v40, v38
	s_waitcnt vmcnt(2)
	v_sub_f32_e32 v41, v47, v38
	v_sub_f32_e32 v40, v46, v38
	v_sub_f32_e32 v43, v45, v38
	v_sub_f32_e32 v42, v44, v38
	s_waitcnt vmcnt(1)
	v_sub_f32_e32 v45, v51, v38
	v_sub_f32_e32 v44, v50, v38
	v_sub_f32_e32 v47, v49, v38
	v_sub_f32_e32 v46, v48, v38
	s_waitcnt vmcnt(0)
	v_sub_f32_e32 v49, v55, v38
	v_sub_f32_e32 v48, v54, v38
	v_sub_f32_e32 v39, v53, v38
	v_sub_f32_e32 v38, v52, v38
	v_pk_mul_f32 v[50:51], v[36:37], v[18:19] op_sel_hi:[0,1]
	v_pk_mul_f32 v[16:17], v[36:37], v[16:17] op_sel_hi:[0,1]
	v_pk_mul_f32 v[42:43], v[36:37], v[42:43] op_sel_hi:[0,1]
	v_pk_mul_f32 v[40:41], v[36:37], v[40:41] op_sel_hi:[0,1]
	v_pk_mul_f32 v[46:47], v[36:37], v[46:47] op_sel_hi:[0,1]
	v_pk_mul_f32 v[44:45], v[36:37], v[44:45] op_sel_hi:[0,1]
	v_pk_mul_f32 v[38:39], v[36:37], v[38:39] op_sel_hi:[0,1]
	v_pk_mul_f32 v[36:37], v[36:37], v[48:49] op_sel_hi:[0,1]
	v_pk_fma_f32 v[18:19], v[172:173], v[16:17], v[22:23]
	v_pk_fma_f32 v[16:17], v[170:171], v[50:51], v[20:21]
	v_pk_fma_f32 v[22:23], v[164:165], v[40:41], v[24:25]
	v_pk_fma_f32 v[20:21], v[162:163], v[42:43], v[26:27]
	v_pk_fma_f32 v[26:27], v[168:169], v[44:45], v[30:31]
	v_pk_fma_f32 v[24:25], v[166:167], v[46:47], v[28:29]
	v_pk_fma_f32 v[30:31], v[160:161], v[36:37], v[58:59]
	v_pk_fma_f32 v[28:29], v[158:159], v[38:39], v[60:61]
	global_store_dwordx4 v[56:57], v[16:19], off
	global_store_dwordx4 v[56:57], v[20:23], off offset:16
	global_store_dwordx4 v[56:57], v[24:27], off offset:512
	global_store_dwordx4 v[56:57], v[28:31], off offset:528
	s_cbranch_vccnz .LBB0_177
	v_mov_b32_e32 v34, v252
	v_mov_b32_e32 v32, v253

; DI const float* modp(const Frame& F, int l, int mr, int which) { return (const float*)(F.ws + WS_MOD) + ((size_t)(l * 9 + mr) * 6 + which) * 1024; }
; DI void ln_row_v(const Frame& F, f32x4 (&v)[4], float* xout, const float* g, const float* b, const float* sh, const float* sc, bf16_t* hout, const float* slab, const float* gres, float* stat = nullptr) {
;     ...
;     if (g) {
;         float s = 0.f, s2 = 0.f;
; #pragma unroll
;         for (int j = 0; j < 4; ++j) { s += (v[j][0] + v[j][1]) + (v[j][2] + v[j][3]); s2 += (v[j][0] * v[j][0] + v[j][1] * v[j][1]) + (v[j][2] * v[j][2] + v[j][3] * v[j][3]); }
;         wave_sum2(s, s2, F.lane);
; DI void ln_phase(const Frame& F, int which) {
;     const int gw = F.vcu * 8 + F.wave, NGW = F.G * 8; const int l = F.l;
;     const int nrows = (l == NL - 1) ? ML : MT;
;     bf16_t* H = (bf16_t*)(F.ws + WS_HB);
;     const float* g = pin(F, which == 0 ? I_LN1G : I_LN2G) + l * 1024; const float* b = pin(F, which == 0 ? I_LN1B : I_LN2B) + l * 1024;
;     const bool wh = !(which == 1 && l == NL - 1);
;     f32x4 vc[4], vn[4];
;     if (gw < nrows) ln_load(F, xrow_ptr(F, gw), vc);
;     for (int row = gw; row < nrows; row += NGW) {
;         if (row + NGW < nrows) ln_load(F, xrow_ptr(F, row + NGW), vn);
;         const int mr = row < ML ? (row >> 11) : 8;
;         const float* sh = which == 0 ? modp(F, l, mr, 3) : modp(F, l + 1 < NL ? l + 1 : l, mr, 0);
;         const float* sc = which == 0 ? modp(F, l, mr, 4) : modp(F, l + 1 < NL ? l + 1 : l, mr, 1);
;         const bool sl = (which == 1 && row >= ML);
;         const bool st_only = row < ML && !(which == 1 && l == NL - 1);
;         float* stp = st_only ? (float*)(F.ws + (which == 0 ? WS_ST1 : WS_ST2)) + 2 * (size_t)row : nullptr;
;         ln_row_v(F, vc, st_only ? nullptr : xrow_ptr(F, row), g, b, sh, sc, wh ? H + (size_t)row * D : nullptr, sl ? (const float*)(F.ws + WS_KN) + (size_t)(row - ML) * 1024 : nullptr, modp(F, l, mr, 5), stp);
.LBB0_513:
	s_and_b64 vcc, exec, s[2:3]
	s_cbranch_vccz .LBB0_537
	v_readlane_b32 s2, v255, 29
	s_lshl_b32 s2, s2, 3
	v_readlane_b32 s3, v255, 31
	s_add_i32 s16, s3, s2
	v_lshlrev_b32_e32 v0, 4, v186
	v_lshlrev_b32_e32 v1, 3, v186
	v_lshlrev_b32_e32 v96, 2, v186
	v_xor_b32_e32 v3, 4, v96
	v_xor_b32_e32 v4, 8, v96
	v_xor_b32_e32 v5, 16, v96
	v_xor_b32_e32 v6, 32, v96
	v_xor_b32_e32 v7, 64, v96
	v_xor_b32_e32 v8, 128, v96
	s_load_dwordx4 s[4:7], s[62:63], 0xb8
	v_readlane_b32 s22, v255, 35
	v_readlane_b32 s8, v255, 17
	v_readlane_b32 s9, v255, 18
	s_lshl_b32 s2, s16, 12
	s_add_u32 s8, s8, s2
	s_addc_u32 s9, s9, 0
	s_lshl_b32 s2, s16, 11
	s_add_u32 s10, s94, s2
	s_addc_u32 s11, s95, 0
	s_add_u32 s10, s10, 0x3e00000
	s_addc_u32 s11, s11, 0
	s_lshl_b32 s2, s16, 3
	s_add_u32 s12, s94, s2
	s_addc_u32 s13, s95, 0
	s_add_u32 s12, s12, 0x4c0000
	s_addc_u32 s13, s13, 0
	s_add_i32 s3, s22, 1
	s_min_u32 s3, s3, 3
	s_mul_i32 s3, s3, 0x36000
	s_add_u32 s14, s94, s3
	s_addc_u32 s15, s95, 0
	s_add_u32 s14, s14, 0x100000
	s_addc_u32 s15, s15, 0
	s_add_u32 s18, s14, 0x1000
	s_addc_u32 s19, s15, 0
	s_lshl_b32 s2, s22, 12
	s_waitcnt lgkmcnt(0)
	s_add_u32 s4, s4, s2
	s_addc_u32 s5, s5, 0
	s_add_u32 s6, s6, s2
	s_addc_u32 s7, s7, 0
	s_cmp_eq_u32 s22, 3
	s_cbranch_scc1 .Lln_b_final
	global_load_dwordx4 v[10:13], v0, s[4:5]
	global_load_dwordx4 v[14:17], v0, s[4:5] offset:1024
	global_load_dwordx4 v[18:21], v0, s[4:5] offset:2048
	global_load_dwordx4 v[22:25], v0, s[4:5] offset:3072
	global_load_dwordx4 v[26:29], v0, s[6:7]
	global_load_dwordx4 v[30:33], v0, s[6:7] offset:1024
	global_load_dwordx4 v[34:37], v0, s[6:7] offset:2048
	global_load_dwordx4 v[38:41], v0, s[6:7] offset:3072
	s_add_u32 s2, s8, 0x0
	s_addc_u32 s3, s9, 0
	global_load_dwordx4 v[42:45], v0, s[2:3]
	global_load_dwordx4 v[46:49], v0, s[2:3] offset:1024
	global_load_dwordx4 v[50:53], v0, s[2:3] offset:2048
	global_load_dwordx4 v[54:57], v0, s[2:3] offset:3072
	s_add_u32 s2, s14, 0x0
	s_addc_u32 s3, s15, 0
	global_load_dwordx4 v[114:117], v0, s[2:3]
	global_load_dwordx4 v[118:121], v0, s[2:3] offset:1024
	global_load_dwordx4 v[122:125], v0, s[2:3] offset:2048
	global_load_dwordx4 v[126:129], v0, s[2:3] offset:3072
	s_add_u32 s2, s18, 0x0
	s_addc_u32 s3, s19, 0
	global_load_dwordx4 v[130:133], v0, s[2:3]
	global_load_dwordx4 v[134:137], v0, s[2:3] offset:1024
	global_load_dwordx4 v[138:141], v0, s[2:3] offset:2048
	global_load_dwordx4 v[142:145], v0, s[2:3] offset:3072
	s_add_u32 s2, s8, 0x800000
	s_addc_u32 s3, s9, 0
	global_load_dwordx4 v[58:61], v0, s[2:3]
	global_load_dwordx4 v[62:65], v0, s[2:3] offset:1024
	global_load_dwordx4 v[66:69], v0, s[2:3] offset:2048
	global_load_dwordx4 v[70:73], v0, s[2:3] offset:3072
	s_add_u32 s2, s14, 0x6000
	s_addc_u32 s3, s15, 0
	global_load_dwordx4 v[146:149], v0, s[2:3]
	global_load_dwordx4 v[150:153], v0, s[2:3] offset:1024
	global_load_dwordx4 v[154:157], v0, s[2:3] offset:2048
	global_load_dwordx4 v[158:161], v0, s[2:3] offset:3072
	s_add_u32 s2, s18, 0x6000
	s_addc_u32 s3, s19, 0
	global_load_dwordx4 v[162:165], v0, s[2:3]
	global_load_dwordx4 v[166:169], v0, s[2:3] offset:1024
	global_load_dwordx4 v[170:173], v0, s[2:3] offset:2048
	global_load_dwordx4 v[174:177], v0, s[2:3] offset:3072
	s_add_u32 s2, s8, 0x1000000
	s_addc_u32 s3, s9, 0
	global_load_dwordx4 v[74:77], v0, s[2:3]
	global_load_dwordx4 v[78:81], v0, s[2:3] offset:1024
	global_load_dwordx4 v[82:85], v0, s[2:3] offset:2048
	global_load_dwordx4 v[86:89], v0, s[2:3] offset:3072
	s_add_u32 s2, s8, 0x1800000
	s_addc_u32 s3, s9, 0
	global_load_dwordx4 v[98:101], v0, s[2:3]
	global_load_dwordx4 v[102:105], v0, s[2:3] offset:1024
	global_load_dwordx4 v[106:109], v0, s[2:3] offset:2048
	global_load_dwordx4 v[110:113], v0, s[2:3] offset:3072
	s_waitcnt vmcnt(28)
	v_add_f32_e32 v9, v42, v43
	v_add_f32_e32 v91, v44, v45
	v_mul_f32_e32 v90, v42, v42
	v_mul_f32_e32 v92, v43, v43
	v_add_f32_e32 v9, v9, v46
	v_add_f32_e32 v91, v91, v47
	v_add_f32_e32 v9, v9, v48
	v_add_f32_e32 v91, v91, v49
	v_add_f32_e32 v9, v9, v50
	v_add_f32_e32 v91, v91, v51
	v_add_f32_e32 v9, v9, v52
	v_add_f32_e32 v91, v91, v53
	v_add_f32_e32 v9, v9, v54
	v_add_f32_e32 v91, v91, v55
	v_add_f32_e32 v9, v9, v56
	v_add_f32_e32 v91, v91, v57
	v_fmac_f32_e32 v90, v44, v44
	v_fmac_f32_e32 v92, v45, v45
	v_fmac_f32_e32 v90, v46, v46
	v_fmac_f32_e32 v92, v47, v47
	v_fmac_f32_e32 v90, v48, v48
	v_fmac_f32_e32 v92, v49, v49
	v_fmac_f32_e32 v90, v50, v50
	v_fmac_f32_e32 v92, v51, v51
	v_fmac_f32_e32 v90, v52, v52
	v_fmac_f32_e32 v92, v53, v53
	v_fmac_f32_e32 v90, v54, v54
	v_fmac_f32_e32 v92, v55, v55
	v_fmac_f32_e32 v90, v56, v56
	v_fmac_f32_e32 v92, v57, v57
	v_add_f32_e32 v9, v9, v91
	v_add_f32_e32 v90, v90, v92
	ds_bpermute_b32 v91, v3, v9
	ds_bpermute_b32 v92, v3, v90
	s_waitcnt lgkmcnt(0)
	v_add_f32_e32 v9, v9, v91
	v_add_f32_e32 v90, v90, v92
	ds_bpermute_b32 v91, v4, v9
	ds_bpermute_b32 v92, v4, v90
	s_waitcnt lgkmcnt(0)
	v_add_f32_e32 v9, v9, v91
	v_add_f32_e32 v90, v90, v92
	ds_bpermute_b32 v91, v5, v9
	ds_bpermute_b32 v92, v5, v90
	s_waitcnt lgkmcnt(0)
	v_add_f32_e32 v9, v9, v91
	v_add_f32_e32 v90, v90, v92
	ds_bpermute_b32 v91, v6, v9
	ds_bpermute_b32 v92, v6, v90
	s_waitcnt lgkmcnt(0)
	v_add_f32_e32 v9, v9, v91
	v_add_f32_e32 v90, v90, v92
	ds_bpermute_b32 v91, v7, v9
	ds_bpermute_b32 v92, v7, v90
	s_waitcnt lgkmcnt(0)
	v_add_f32_e32 v9, v9, v91
	v_add_f32_e32 v90, v90, v92
	ds_bpermute_b32 v91, v8, v9
	ds_bpermute_b32 v92, v8, v90
	s_waitcnt lgkmcnt(0)
; DI unsigned pk2(float lo, float hi) { f32x2 v = {lo, hi}; bf16x2_t b = __builtin_convertvector(v, bf16x2_t); return __builtin_bit_cast(unsigned, b); }
; DI void ln_row_v(const Frame& F, f32x4 (&v)[4], float* xout, const float* g, const float* b, const float* sh, const float* sc, bf16_t* hout, const float* slab, const float* gres, float* stat = nullptr) {
;     ...
;         float s = 0.f, s2 = 0.f;
; #pragma unroll
;         for (int j = 0; j < 4; ++j) { s += (v[j][0] + v[j][1]) + (v[j][2] + v[j][3]); s2 += (v[j][0] * v[j][0] + v[j][1] * v[j][1]) + (v[j][2] * v[j][2] + v[j][3] * v[j][3]); }
;         wave_sum2(s, s2, F.lane);
;         const float mean = s * (1.f / D); const float rstd = 1.f / sqrtf(fmaxf(s2 * (1.f / D) - mean * mean, 0.f) + EPS);
;         if (stat && F.lane == 0) { f32x2 sv = {mean, rstd}; *(f32x2*)stat = sv; }
; #pragma unroll
;         for (int j = 0; j < 4; ++j) { const f32x4 gg = ((const f32x4*)g)[F.lane + 64 * j], bb = ((const f32x4*)b)[F.lane + 64 * j];
;             v[j] = (v[j] - mean) * rstd * gg + bb; if (xout) ((f32x4*)xout)[F.lane + 64 * j] = v[j]; }
;     }
;     if (hout) {
;         float s = 0.f, s2 = 0.f;
; #pragma unroll
;         for (int j = 0; j < 4; ++j) { s += (v[j][0] + v[j][1]) + (v[j][2] + v[j][3]); s2 += (v[j][0] * v[j][0] + v[j][1] * v[j][1]) + (v[j][2] * v[j][2] + v[j][3] * v[j][3]); }
;         wave_sum2(s, s2, F.lane);
;         const float mean = s * (1.f / D); const float rstd = 1.f / sqrtf(fmaxf(s2 * (1.f / D) - mean * mean, 0.f) + EPS);
; #pragma unroll
;         for (int j = 0; j < 4; ++j) { const f32x4 hh = ((const f32x4*)sh)[F.lane + 64 * j], cc = ((const f32x4*)sc)[F.lane + 64 * j];
;             const f32x4 o = (v[j] - mean) * rstd * (cc + 1.f) + hh; u32x2 wv; wv.x = pk2(o[0], o[1]); wv.y = pk2(o[2], o[3]);
	v_add_f32_e32 v9, v9, v91
	v_add_f32_e32 v90, v90, v92
	v_mul_f32_e32 v93, 0x3a800000, v9
	v_mul_f32_e32 v91, 0x3a800000, v90
	v_fma_f32 v91, -v93, v93, v91
	v_max_f32_e32 v91, 0, v91
	v_add_f32_e32 v91, 0x358637bd, v91
	v_rsq_f32_e32 v94, v91
	v_mul_f32_e32 v91, 0.5, v91
	v_mul_f32_e32 v92, v94, v94
	v_fma_f32 v92, -v91, v92, 0.5
	v_fma_f32 v94, v94, v92, v94
	s_add_u32 s2, s12, 0x0
	s_addc_u32 s3, s13, 0
	v_mov_b32_e32 v188, v93
	v_mov_b32_e32 v189, v94
	s_mov_b64 exec, 1
	global_store_dwordx2 v97, v[188:189], s[2:3]
	s_mov_b64 exec, -1
	v_sub_f32_e32 v42, v42, v93
	v_sub_f32_e32 v43, v43, v93
	v_sub_f32_e32 v44, v44, v93
	v_sub_f32_e32 v45, v45, v93
	v_sub_f32_e32 v46, v46, v93
	v_sub_f32_e32 v47, v47, v93
	v_sub_f32_e32 v48, v48, v93
	v_sub_f32_e32 v49, v49, v93
	v_sub_f32_e32 v50, v50, v93
	v_sub_f32_e32 v51, v51, v93
	v_sub_f32_e32 v52, v52, v93
	v_sub_f32_e32 v53, v53, v93
	v_sub_f32_e32 v54, v54, v93
	v_sub_f32_e32 v55, v55, v93
	v_sub_f32_e32 v56, v56, v93
	v_sub_f32_e32 v57, v57, v93
	v_mul_f32_e32 v42, v94, v42
	v_mul_f32_e32 v43, v94, v43
	v_mul_f32_e32 v44, v94, v44
	v_mul_f32_e32 v45, v94, v45
	v_mul_f32_e32 v46, v94, v46
	v_mul_f32_e32 v47, v94, v47
	v_mul_f32_e32 v48, v94, v48
	v_mul_f32_e32 v49, v94, v49
	v_mul_f32_e32 v50, v94, v50
	v_mul_f32_e32 v51, v94, v51
	v_mul_f32_e32 v52, v94, v52
	v_mul_f32_e32 v53, v94, v53
	v_mul_f32_e32 v54, v94, v54
	v_mul_f32_e32 v55, v94, v55
	v_mul_f32_e32 v56, v94, v56
	v_mul_f32_e32 v57, v94, v57
	v_fma_f32 v42, v42, v10, v26
	v_fma_f32 v43, v43, v11, v27
	v_fma_f32 v44, v44, v12, v28
	v_fma_f32 v45, v45, v13, v29
	v_fma_f32 v46, v46, v14, v30
	v_fma_f32 v47, v47, v15, v31
	v_fma_f32 v48, v48, v16, v32
	v_fma_f32 v49, v49, v17, v33
	v_fma_f32 v50, v50, v18, v34
	v_fma_f32 v51, v51, v19, v35
	v_fma_f32 v52, v52, v20, v36
	v_fma_f32 v53, v53, v21, v37
	v_fma_f32 v54, v54, v22, v38
	v_fma_f32 v55, v55, v23, v39
	v_fma_f32 v56, v56, v24, v40
	v_fma_f32 v57, v57, v25, v41
	v_add_f32_e32 v9, v42, v43
	v_add_f32_e32 v91, v44, v45
	v_mul_f32_e32 v90, v42, v42
	v_mul_f32_e32 v92, v43, v43
	v_add_f32_e32 v9, v9, v46
	v_add_f32_e32 v91, v91, v47
	v_add_f32_e32 v9, v9, v48
	v_add_f32_e32 v91, v91, v49
	v_add_f32_e32 v9, v9, v50
	v_add_f32_e32 v91, v91, v51
	v_add_f32_e32 v9, v9, v52
	v_add_f32_e32 v91, v91, v53
	v_add_f32_e32 v9, v9, v54
	v_add_f32_e32 v91, v91, v55
	v_add_f32_e32 v9, v9, v56
	v_add_f32_e32 v91, v91, v57
	v_fmac_f32_e32 v90, v44, v44
	v_fmac_f32_e32 v92, v45, v45
	v_fmac_f32_e32 v90, v46, v46
	v_fmac_f32_e32 v92, v47, v47
	v_fmac_f32_e32 v90, v48, v48
	v_fmac_f32_e32 v92, v49, v49
	v_fmac_f32_e32 v90, v50, v50
	v_fmac_f32_e32 v92, v51, v51
	v_fmac_f32_e32 v90, v52, v52
	v_fmac_f32_e32 v92, v53, v53
	v_fmac_f32_e32 v90, v54, v54
	v_fmac_f32_e32 v92, v55, v55
	v_fmac_f32_e32 v90, v56, v56
	v_fmac_f32_e32 v92, v57, v57
	v_add_f32_e32 v9, v9, v91
	v_add_f32_e32 v90, v90, v92
	ds_bpermute_b32 v91, v3, v9
	ds_bpermute_b32 v92, v3, v90
	s_waitcnt lgkmcnt(0)
	v_add_f32_e32 v9, v9, v91
	v_add_f32_e32 v90, v90, v92
	ds_bpermute_b32 v91, v4, v9
	ds_bpermute_b32 v92, v4, v90
	s_waitcnt lgkmcnt(0)
	v_add_f32_e32 v9, v9, v91
	v_add_f32_e32 v90, v90, v92
	ds_bpermute_b32 v91, v5, v9
	ds_bpermute_b32 v92, v5, v90
	s_waitcnt lgkmcnt(0)
	v_add_f32_e32 v9, v9, v91
	v_add_f32_e32 v90, v90, v92
	ds_bpermute_b32 v91, v6, v9
	ds_bpermute_b32 v92, v6, v90
	s_waitcnt lgkmcnt(0)
	v_add_f32_e32 v9, v9, v91
	v_add_f32_e32 v90, v90, v92
	ds_bpermute_b32 v91, v7, v9
	ds_bpermute_b32 v92, v7, v90
	s_waitcnt lgkmcnt(0)
	v_add_f32_e32 v9, v9, v91
	v_add_f32_e32 v90, v90, v92
	ds_bpermute_b32 v91, v8, v9
	ds_bpermute_b32 v92, v8, v90
	s_waitcnt lgkmcnt(0)
	v_add_f32_e32 v9, v9, v91
	v_add_f32_e32 v90, v90, v92
	v_mul_f32_e32 v93, 0x3a800000, v9
	v_mul_f32_e32 v91, 0x3a800000, v90
	v_fma_f32 v91, -v93, v93, v91
	v_max_f32_e32 v91, 0, v91
	v_add_f32_e32 v91, 0x358637bd, v91
	v_rsq_f32_e32 v94, v91
	v_mul_f32_e32 v91, 0.5, v91
	v_mul_f32_e32 v92, v94, v94
	v_fma_f32 v92, -v91, v92, 0.5
	v_fma_f32 v94, v94, v92, v94
	s_waitcnt vmcnt(21)
	v_sub_f32_e32 v42, v42, v93
	v_sub_f32_e32 v43, v43, v93
	v_sub_f32_e32 v44, v44, v93
	v_sub_f32_e32 v45, v45, v93
	v_sub_f32_e32 v46, v46, v93
	v_sub_f32_e32 v47, v47, v93
	v_sub_f32_e32 v48, v48, v93
	v_sub_f32_e32 v49, v49, v93
	v_sub_f32_e32 v50, v50, v93
	v_sub_f32_e32 v51, v51, v93
	v_sub_f32_e32 v52, v52, v93
	v_sub_f32_e32 v53, v53, v93
	v_sub_f32_e32 v54, v54, v93
	v_sub_f32_e32 v55, v55, v93
	v_sub_f32_e32 v56, v56, v93
	v_sub_f32_e32 v57, v57, v93
	v_add_f32_e32 v130, 1.0, v130
	v_add_f32_e32 v131, 1.0, v131
	v_add_f32_e32 v132, 1.0, v132
	v_add_f32_e32 v133, 1.0, v133
	v_add_f32_e32 v134, 1.0, v134
	v_add_f32_e32 v135, 1.0, v135
	v_add_f32_e32 v136, 1.0, v136
	v_add_f32_e32 v137, 1.0, v137
	v_add_f32_e32 v138, 1.0, v138
	v_add_f32_e32 v139, 1.0, v139
	v_add_f32_e32 v140, 1.0, v140
	v_add_f32_e32 v141, 1.0, v141
	v_add_f32_e32 v142, 1.0, v142
	v_add_f32_e32 v143, 1.0, v143
	v_add_f32_e32 v144, 1.0, v144
	v_add_f32_e32 v145, 1.0, v145
	v_mul_f32_e32 v42, v94, v42
	v_mul_f32_e32 v43, v94, v43
	v_mul_f32_e32 v44, v94, v44
	v_mul_f32_e32 v45, v94, v45
	v_mul_f32_e32 v46, v94, v46
	v_mul_f32_e32 v47, v94, v47
	v_mul_f32_e32 v48, v94, v48
	v_mul_f32_e32 v49, v94, v49
	v_mul_f32_e32 v50, v94, v50
	v_mul_f32_e32 v51, v94, v51
	v_mul_f32_e32 v52, v94, v52
	v_mul_f32_e32 v53, v94, v53
	v_mul_f32_e32 v54, v94, v54
	v_mul_f32_e32 v55, v94, v55
	v_mul_f32_e32 v56, v94, v56
	v_mul_f32_e32 v57, v94, v57
	v_fma_f32 v42, v42, v130, v114
	v_fma_f32 v43, v43, v131, v115
	v_fma_f32 v44, v44, v132, v116
	v_fma_f32 v45, v45, v133, v117
	v_fma_f32 v46, v46, v134, v118
	v_fma_f32 v47, v47, v135, v119
; DI unsigned pk2(float lo, float hi) { f32x2 v = {lo, hi}; bf16x2_t b = __builtin_convertvector(v, bf16x2_t); return __builtin_bit_cast(unsigned, b); }
; DI const float* modp(const Frame& F, int l, int mr, int which) { return (const float*)(F.ws + WS_MOD) + ((size_t)(l * 9 + mr) * 6 + which) * 1024; }
; DI void ln_row_v(const Frame& F, f32x4 (&v)[4], float* xout, const float* g, const float* b, const float* sh, const float* sc, bf16_t* hout, const float* slab, const float* gres, float* stat = nullptr) {
;     ...
;         for (int j = 0; j < 4; ++j) { const f32x4 gg = ((const f32x4*)g)[F.lane + 64 * j], bb = ((const f32x4*)b)[F.lane + 64 * j];
;             v[j] = (v[j] - mean) * rstd * gg + bb; if (xout) ((f32x4*)xout)[F.lane + 64 * j] = v[j]; }
;     }
;     if (hout) {
;         float s = 0.f, s2 = 0.f;
; #pragma unroll
;         for (int j = 0; j < 4; ++j) { s += (v[j][0] + v[j][1]) + (v[j][2] + v[j][3]); s2 += (v[j][0] * v[j][0] + v[j][1] * v[j][1]) + (v[j][2] * v[j][2] + v[j][3] * v[j][3]); }
;         wave_sum2(s, s2, F.lane);
;         const float mean = s * (1.f / D); const float rstd = 1.f / sqrtf(fmaxf(s2 * (1.f / D) - mean * mean, 0.f) + EPS);
; #pragma unroll
;         for (int j = 0; j < 4; ++j) { const f32x4 hh = ((const f32x4*)sh)[F.lane + 64 * j], cc = ((const f32x4*)sc)[F.lane + 64 * j];
;             const f32x4 o = (v[j] - mean) * rstd * (cc + 1.f) + hh; u32x2 wv; wv.x = pk2(o[0], o[1]); wv.y = pk2(o[2], o[3]);
;             ((u32x2*)hout)[F.lane + 64 * j] = wv; }
; DI void ln_phase(const Frame& F, int which) {
;     ...
;     for (int row = gw; row < nrows; row += NGW) {
;         if (row + NGW < nrows) ln_load(F, xrow_ptr(F, row + NGW), vn);
;         const int mr = row < ML ? (row >> 11) : 8;
;         const float* sh = which == 0 ? modp(F, l, mr, 3) : modp(F, l + 1 < NL ? l + 1 : l, mr, 0);
;         const float* sc = which == 0 ? modp(F, l, mr, 4) : modp(F, l + 1 < NL ? l + 1 : l, mr, 1);
;         const bool sl = (which == 1 && row >= ML);
;         const bool st_only = row < ML && !(which == 1 && l == NL - 1);
;         float* stp = st_only ? (float*)(F.ws + (which == 0 ? WS_ST1 : WS_ST2)) + 2 * (size_t)row : nullptr;
;         ln_row_v(F, vc, st_only ? nullptr : xrow_ptr(F, row), g, b, sh, sc, wh ? H + (size_t)row * D : nullptr, sl ? (const float*)(F.ws + WS_KN) + (size_t)(row - ML) * 1024 : nullptr, modp(F, l, mr, 5), stp);
	v_fma_f32 v48, v48, v136, v120
	v_fma_f32 v49, v49, v137, v121
	v_fma_f32 v50, v50, v138, v122
	v_fma_f32 v51, v51, v139, v123
	v_fma_f32 v52, v52, v140, v124
	v_fma_f32 v53, v53, v141, v125
	v_fma_f32 v54, v54, v142, v126
	v_fma_f32 v55, v55, v143, v127
	v_fma_f32 v56, v56, v144, v128
	v_fma_f32 v57, v57, v145, v129
	v_cvt_pk_bf16_f32 v190, v42, v43
	v_cvt_pk_bf16_f32 v191, v44, v45
	v_cvt_pk_bf16_f32 v192, v46, v47
	v_cvt_pk_bf16_f32 v193, v48, v49
	v_cvt_pk_bf16_f32 v194, v50, v51
	v_cvt_pk_bf16_f32 v195, v52, v53
	v_cvt_pk_bf16_f32 v196, v54, v55
	v_cvt_pk_bf16_f32 v197, v56, v57
	s_add_u32 s2, s10, 0x0
	s_addc_u32 s3, s11, 0
	global_store_dwordx2 v1, v[190:191], s[2:3]
	global_store_dwordx2 v1, v[192:193], s[2:3] offset:512
	global_store_dwordx2 v1, v[194:195], s[2:3] offset:1024
	global_store_dwordx2 v1, v[196:197], s[2:3] offset:1536
	s_add_u32 s2, s8, 0x2000000
	s_addc_u32 s3, s9, 0
	global_load_dwordx4 v[42:45], v0, s[2:3]
	global_load_dwordx4 v[46:49], v0, s[2:3] offset:1024
	global_load_dwordx4 v[50:53], v0, s[2:3] offset:2048
	global_load_dwordx4 v[54:57], v0, s[2:3] offset:3072
	s_add_u32 s2, s14, 0xc000
	s_addc_u32 s3, s15, 0
	global_load_dwordx4 v[114:117], v0, s[2:3]
	global_load_dwordx4 v[118:121], v0, s[2:3] offset:1024
	global_load_dwordx4 v[122:125], v0, s[2:3] offset:2048
	global_load_dwordx4 v[126:129], v0, s[2:3] offset:3072
	s_add_u32 s2, s18, 0xc000
	s_addc_u32 s3, s19, 0
	global_load_dwordx4 v[130:133], v0, s[2:3]
	global_load_dwordx4 v[134:137], v0, s[2:3] offset:1024
	global_load_dwordx4 v[138:141], v0, s[2:3] offset:2048
	global_load_dwordx4 v[142:145], v0, s[2:3] offset:3072
	s_waitcnt vmcnt(33)
	v_add_f32_e32 v9, v58, v59
	v_add_f32_e32 v91, v60, v61
	v_mul_f32_e32 v90, v58, v58
	v_mul_f32_e32 v92, v59, v59
	v_add_f32_e32 v9, v9, v62
	v_add_f32_e32 v91, v91, v63
	v_add_f32_e32 v9, v9, v64
	v_add_f32_e32 v91, v91, v65
	v_add_f32_e32 v9, v9, v66
	v_add_f32_e32 v91, v91, v67
	v_add_f32_e32 v9, v9, v68
	v_add_f32_e32 v91, v91, v69
	v_add_f32_e32 v9, v9, v70
	v_add_f32_e32 v91, v91, v71
	v_add_f32_e32 v9, v9, v72
	v_add_f32_e32 v91, v91, v73
	v_fmac_f32_e32 v90, v60, v60
	v_fmac_f32_e32 v92, v61, v61
	v_fmac_f32_e32 v90, v62, v62
	v_fmac_f32_e32 v92, v63, v63
	v_fmac_f32_e32 v90, v64, v64
	v_fmac_f32_e32 v92, v65, v65
	v_fmac_f32_e32 v90, v66, v66
	v_fmac_f32_e32 v92, v67, v67
	v_fmac_f32_e32 v90, v68, v68
	v_fmac_f32_e32 v92, v69, v69
	v_fmac_f32_e32 v90, v70, v70
	v_fmac_f32_e32 v92, v71, v71
	v_fmac_f32_e32 v90, v72, v72
	v_fmac_f32_e32 v92, v73, v73
	v_add_f32_e32 v9, v9, v91
	v_add_f32_e32 v90, v90, v92
	ds_bpermute_b32 v91, v3, v9
	ds_bpermute_b32 v92, v3, v90
	s_waitcnt lgkmcnt(0)
	v_add_f32_e32 v9, v9, v91
	v_add_f32_e32 v90, v90, v92
	ds_bpermute_b32 v91, v4, v9
	ds_bpermute_b32 v92, v4, v90
	s_waitcnt lgkmcnt(0)
	v_add_f32_e32 v9, v9, v91
	v_add_f32_e32 v90, v90, v92
	ds_bpermute_b32 v91, v5, v9
	ds_bpermute_b32 v92, v5, v90
	s_waitcnt lgkmcnt(0)
	v_add_f32_e32 v9, v9, v91
	v_add_f32_e32 v90, v90, v92
	ds_bpermute_b32 v91, v6, v9
	ds_bpermute_b32 v92, v6, v90
	s_waitcnt lgkmcnt(0)
	v_add_f32_e32 v9, v9, v91
	v_add_f32_e32 v90, v90, v92
	ds_bpermute_b32 v91, v7, v9
	ds_bpermute_b32 v92, v7, v90
	s_waitcnt lgkmcnt(0)
	v_add_f32_e32 v9, v9, v91
	v_add_f32_e32 v90, v90, v92
	ds_bpermute_b32 v91, v8, v9
	ds_bpermute_b32 v92, v8, v90
	s_waitcnt lgkmcnt(0)
	v_add_f32_e32 v9, v9, v91
	v_add_f32_e32 v90, v90, v92
	v_mul_f32_e32 v93, 0x3a800000, v9
	v_mul_f32_e32 v91, 0x3a800000, v90
	v_fma_f32 v91, -v93, v93, v91
	v_max_f32_e32 v91, 0, v91
	v_add_f32_e32 v91, 0x358637bd, v91
	v_rsq_f32_e32 v94, v91
	v_mul_f32_e32 v91, 0.5, v91
	v_mul_f32_e32 v92, v94, v94
	v_fma_f32 v92, -v91, v92, 0.5
	v_fma_f32 v94, v94, v92, v94
	s_add_u32 s2, s12, 0x4000
	s_addc_u32 s3, s13, 0
	v_mov_b32_e32 v188, v93
	v_mov_b32_e32 v189, v94
	s_mov_b64 exec, 1
	global_store_dwordx2 v97, v[188:189], s[2:3]
	s_mov_b64 exec, -1
	v_sub_f32_e32 v58, v58, v93
	v_sub_f32_e32 v59, v59, v93
	v_sub_f32_e32 v60, v60, v93
	v_sub_f32_e32 v61, v61, v93
	v_sub_f32_e32 v62, v62, v93
	v_sub_f32_e32 v63, v63, v93
	v_sub_f32_e32 v64, v64, v93
	v_sub_f32_e32 v65, v65, v93
	v_sub_f32_e32 v66, v66, v93
	v_sub_f32_e32 v67, v67, v93
	v_sub_f32_e32 v68, v68, v93
	v_sub_f32_e32 v69, v69, v93
	v_sub_f32_e32 v70, v70, v93
	v_sub_f32_e32 v71, v71, v93
	v_sub_f32_e32 v72, v72, v93
	v_sub_f32_e32 v73, v73, v93
	v_mul_f32_e32 v58, v94, v58
	v_mul_f32_e32 v59, v94, v59
	v_mul_f32_e32 v60, v94, v60
	v_mul_f32_e32 v61, v94, v61
	v_mul_f32_e32 v62, v94, v62
	v_mul_f32_e32 v63, v94, v63
	v_mul_f32_e32 v64, v94, v64
	v_mul_f32_e32 v65, v94, v65
	v_mul_f32_e32 v66, v94, v66
	v_mul_f32_e32 v67, v94, v67
	v_mul_f32_e32 v68, v94, v68
	v_mul_f32_e32 v69, v94, v69
	v_mul_f32_e32 v70, v94, v70
	v_mul_f32_e32 v71, v94, v71
	v_mul_f32_e32 v72, v94, v72
	v_mul_f32_e32 v73, v94, v73
	v_fma_f32 v58, v58, v10, v26
	v_fma_f32 v59, v59, v11, v27
	v_fma_f32 v60, v60, v12, v28
	v_fma_f32 v61, v61, v13, v29
	v_fma_f32 v62, v62, v14, v30
	v_fma_f32 v63, v63, v15, v31
	v_fma_f32 v64, v64, v16, v32
	v_fma_f32 v65, v65, v17, v33
	v_fma_f32 v66, v66, v18, v34
	v_fma_f32 v67, v67, v19, v35
	v_fma_f32 v68, v68, v20, v36
	v_fma_f32 v69, v69, v21, v37
	v_fma_f32 v70, v70, v22, v38
	v_fma_f32 v71, v71, v23, v39
	v_fma_f32 v72, v72, v24, v40
	v_fma_f32 v73, v73, v25, v41
	v_add_f32_e32 v9, v58, v59
	v_add_f32_e32 v91, v60, v61
	v_mul_f32_e32 v90, v58, v58
	v_mul_f32_e32 v92, v59, v59
	v_add_f32_e32 v9, v9, v62
	v_add_f32_e32 v91, v91, v63
	v_add_f32_e32 v9, v9, v64
	v_add_f32_e32 v91, v91, v65
	v_add_f32_e32 v9, v9, v66
	v_add_f32_e32 v91, v91, v67
	v_add_f32_e32 v9, v9, v68
	v_add_f32_e32 v91, v91, v69
	v_add_f32_e32 v9, v9, v70
	v_add_f32_e32 v91, v91, v71
	v_add_f32_e32 v9, v9, v72
	v_add_f32_e32 v91, v91, v73
	v_fmac_f32_e32 v90, v60, v60
	v_fmac_f32_e32 v92, v61, v61
	v_fmac_f32_e32 v90, v62, v62
	v_fmac_f32_e32 v92, v63, v63
	v_fmac_f32_e32 v90, v64, v64
	v_fmac_f32_e32 v92, v65, v65
	v_fmac_f32_e32 v90, v66, v66
	v_fmac_f32_e32 v92, v67, v67
	v_fmac_f32_e32 v90, v68, v68
	v_fmac_f32_e32 v92, v69, v69
	v_fmac_f32_e32 v90, v70, v70
	v_fmac_f32_e32 v92, v71, v71
	v_fmac_f32_e32 v90, v72, v72
	v_fmac_f32_e32 v92, v73, v73
	v_add_f32_e32 v9, v9, v91
	v_add_f32_e32 v90, v90, v92
	ds_bpermute_b32 v91, v3, v9
	ds_bpermute_b32 v92, v3, v90
	s_waitcnt lgkmcnt(0)
; DI unsigned pk2(float lo, float hi) { f32x2 v = {lo, hi}; bf16x2_t b = __builtin_convertvector(v, bf16x2_t); return __builtin_bit_cast(unsigned, b); }
; DI const float* modp(const Frame& F, int l, int mr, int which) { return (const float*)(F.ws + WS_MOD) + ((size_t)(l * 9 + mr) * 6 + which) * 1024; }
; DI void ln_row_v(const Frame& F, f32x4 (&v)[4], float* xout, const float* g, const float* b, const float* sh, const float* sc, bf16_t* hout, const float* slab, const float* gres, float* stat = nullptr) {
;     ...
;         float s = 0.f, s2 = 0.f;
; #pragma unroll
;         for (int j = 0; j < 4; ++j) { s += (v[j][0] + v[j][1]) + (v[j][2] + v[j][3]); s2 += (v[j][0] * v[j][0] + v[j][1] * v[j][1]) + (v[j][2] * v[j][2] + v[j][3] * v[j][3]); }
;         wave_sum2(s, s2, F.lane);
;         const float mean = s * (1.f / D); const float rstd = 1.f / sqrtf(fmaxf(s2 * (1.f / D) - mean * mean, 0.f) + EPS);
; #pragma unroll
;         for (int j = 0; j < 4; ++j) { const f32x4 hh = ((const f32x4*)sh)[F.lane + 64 * j], cc = ((const f32x4*)sc)[F.lane + 64 * j];
;             const f32x4 o = (v[j] - mean) * rstd * (cc + 1.f) + hh; u32x2 wv; wv.x = pk2(o[0], o[1]); wv.y = pk2(o[2], o[3]);
;             ((u32x2*)hout)[F.lane + 64 * j] = wv; }
; DI void ln_phase(const Frame& F, int which) {
;     ...
;     for (int row = gw; row < nrows; row += NGW) {
;         if (row + NGW < nrows) ln_load(F, xrow_ptr(F, row + NGW), vn);
;         const int mr = row < ML ? (row >> 11) : 8;
;         const float* sh = which == 0 ? modp(F, l, mr, 3) : modp(F, l + 1 < NL ? l + 1 : l, mr, 0);
;         const float* sc = which == 0 ? modp(F, l, mr, 4) : modp(F, l + 1 < NL ? l + 1 : l, mr, 1);
	v_add_f32_e32 v9, v9, v91
	v_add_f32_e32 v90, v90, v92
	ds_bpermute_b32 v91, v4, v9
	ds_bpermute_b32 v92, v4, v90
	s_waitcnt lgkmcnt(0)
	v_add_f32_e32 v9, v9, v91
	v_add_f32_e32 v90, v90, v92
	ds_bpermute_b32 v91, v5, v9
	ds_bpermute_b32 v92, v5, v90
	s_waitcnt lgkmcnt(0)
	v_add_f32_e32 v9, v9, v91
	v_add_f32_e32 v90, v90, v92
	ds_bpermute_b32 v91, v6, v9
	ds_bpermute_b32 v92, v6, v90
	s_waitcnt lgkmcnt(0)
	v_add_f32_e32 v9, v9, v91
	v_add_f32_e32 v90, v90, v92
	ds_bpermute_b32 v91, v7, v9
	ds_bpermute_b32 v92, v7, v90
	s_waitcnt lgkmcnt(0)
	v_add_f32_e32 v9, v9, v91
	v_add_f32_e32 v90, v90, v92
	ds_bpermute_b32 v91, v8, v9
	ds_bpermute_b32 v92, v8, v90
	s_waitcnt lgkmcnt(0)
	v_add_f32_e32 v9, v9, v91
	v_add_f32_e32 v90, v90, v92
	v_mul_f32_e32 v93, 0x3a800000, v9
	v_mul_f32_e32 v91, 0x3a800000, v90
	v_fma_f32 v91, -v93, v93, v91
	v_max_f32_e32 v91, 0, v91
	v_add_f32_e32 v91, 0x358637bd, v91
	v_rsq_f32_e32 v94, v91
	v_mul_f32_e32 v91, 0.5, v91
	v_mul_f32_e32 v92, v94, v94
	v_fma_f32 v92, -v91, v92, 0.5
	v_fma_f32 v94, v94, v92, v94
	s_waitcnt vmcnt(26)
	v_sub_f32_e32 v58, v58, v93
	v_sub_f32_e32 v59, v59, v93
	v_sub_f32_e32 v60, v60, v93
	v_sub_f32_e32 v61, v61, v93
	v_sub_f32_e32 v62, v62, v93
	v_sub_f32_e32 v63, v63, v93
	v_sub_f32_e32 v64, v64, v93
	v_sub_f32_e32 v65, v65, v93
	v_sub_f32_e32 v66, v66, v93
	v_sub_f32_e32 v67, v67, v93
	v_sub_f32_e32 v68, v68, v93
	v_sub_f32_e32 v69, v69, v93
	v_sub_f32_e32 v70, v70, v93
	v_sub_f32_e32 v71, v71, v93
	v_sub_f32_e32 v72, v72, v93
	v_sub_f32_e32 v73, v73, v93
	v_add_f32_e32 v162, 1.0, v162
	v_add_f32_e32 v163, 1.0, v163
	v_add_f32_e32 v164, 1.0, v164
	v_add_f32_e32 v165, 1.0, v165
	v_add_f32_e32 v166, 1.0, v166
	v_add_f32_e32 v167, 1.0, v167
	v_add_f32_e32 v168, 1.0, v168
	v_add_f32_e32 v169, 1.0, v169
	v_add_f32_e32 v170, 1.0, v170
	v_add_f32_e32 v171, 1.0, v171
	v_add_f32_e32 v172, 1.0, v172
	v_add_f32_e32 v173, 1.0, v173
	v_add_f32_e32 v174, 1.0, v174
	v_add_f32_e32 v175, 1.0, v175
	v_add_f32_e32 v176, 1.0, v176
	v_add_f32_e32 v177, 1.0, v177
	v_mul_f32_e32 v58, v94, v58
	v_mul_f32_e32 v59, v94, v59
	v_mul_f32_e32 v60, v94, v60
	v_mul_f32_e32 v61, v94, v61
	v_mul_f32_e32 v62, v94, v62
	v_mul_f32_e32 v63, v94, v63
	v_mul_f32_e32 v64, v94, v64
	v_mul_f32_e32 v65, v94, v65
	v_mul_f32_e32 v66, v94, v66
	v_mul_f32_e32 v67, v94, v67
	v_mul_f32_e32 v68, v94, v68
	v_mul_f32_e32 v69, v94, v69
	v_mul_f32_e32 v70, v94, v70
	v_mul_f32_e32 v71, v94, v71
	v_mul_f32_e32 v72, v94, v72
	v_mul_f32_e32 v73, v94, v73
	v_fma_f32 v58, v58, v162, v146
	v_fma_f32 v59, v59, v163, v147
	v_fma_f32 v60, v60, v164, v148
	v_fma_f32 v61, v61, v165, v149
	v_fma_f32 v62, v62, v166, v150
	v_fma_f32 v63, v63, v167, v151
	v_fma_f32 v64, v64, v168, v152
	v_fma_f32 v65, v65, v169, v153
	v_fma_f32 v66, v66, v170, v154
	v_fma_f32 v67, v67, v171, v155
	v_fma_f32 v68, v68, v172, v156
	v_fma_f32 v69, v69, v173, v157
	v_fma_f32 v70, v70, v174, v158
	v_fma_f32 v71, v71, v175, v159
	v_fma_f32 v72, v72, v176, v160
	v_fma_f32 v73, v73, v177, v161
	v_cvt_pk_bf16_f32 v190, v58, v59
	v_cvt_pk_bf16_f32 v191, v60, v61
	v_cvt_pk_bf16_f32 v192, v62, v63
	v_cvt_pk_bf16_f32 v193, v64, v65
	v_cvt_pk_bf16_f32 v194, v66, v67
	v_cvt_pk_bf16_f32 v195, v68, v69
	v_cvt_pk_bf16_f32 v196, v70, v71
	v_cvt_pk_bf16_f32 v197, v72, v73
	s_add_u32 s2, s10, 0x400000
	s_addc_u32 s3, s11, 0
	global_store_dwordx2 v1, v[190:191], s[2:3]
	global_store_dwordx2 v1, v[192:193], s[2:3] offset:512
	global_store_dwordx2 v1, v[194:195], s[2:3] offset:1024
	global_store_dwordx2 v1, v[196:197], s[2:3] offset:1536
	s_add_u32 s2, s8, 0x2800000
	s_addc_u32 s3, s9, 0
	global_load_dwordx4 v[58:61], v0, s[2:3]
	global_load_dwordx4 v[62:65], v0, s[2:3] offset:1024
	global_load_dwordx4 v[66:69], v0, s[2:3] offset:2048
	global_load_dwordx4 v[70:73], v0, s[2:3] offset:3072
	s_add_u32 s2, s14, 0x12000
	s_addc_u32 s3, s15, 0
	global_load_dwordx4 v[146:149], v0, s[2:3]
	global_load_dwordx4 v[150:153], v0, s[2:3] offset:1024
	global_load_dwordx4 v[154:157], v0, s[2:3] offset:2048
	global_load_dwordx4 v[158:161], v0, s[2:3] offset:3072
	s_add_u32 s2, s18, 0x12000
	s_addc_u32 s3, s19, 0
	global_load_dwordx4 v[162:165], v0, s[2:3]
	global_load_dwordx4 v[166:169], v0, s[2:3] offset:1024
	global_load_dwordx4 v[170:173], v0, s[2:3] offset:2048
	global_load_dwordx4 v[174:177], v0, s[2:3] offset:3072
	s_waitcnt vmcnt(38)
	v_add_f32_e32 v9, v74, v75
	v_add_f32_e32 v91, v76, v77
	v_mul_f32_e32 v90, v74, v74
	v_mul_f32_e32 v92, v75, v75
	v_add_f32_e32 v9, v9, v78
	v_add_f32_e32 v91, v91, v79
	v_add_f32_e32 v9, v9, v80
	v_add_f32_e32 v91, v91, v81
	v_add_f32_e32 v9, v9, v82
	v_add_f32_e32 v91, v91, v83
	v_add_f32_e32 v9, v9, v84
	v_add_f32_e32 v91, v91, v85
	v_add_f32_e32 v9, v9, v86
	v_add_f32_e32 v91, v91, v87
	v_add_f32_e32 v9, v9, v88
	v_add_f32_e32 v91, v91, v89
	v_fmac_f32_e32 v90, v76, v76
	v_fmac_f32_e32 v92, v77, v77
	v_fmac_f32_e32 v90, v78, v78
	v_fmac_f32_e32 v92, v79, v79
	v_fmac_f32_e32 v90, v80, v80
	v_fmac_f32_e32 v92, v81, v81
	v_fmac_f32_e32 v90, v82, v82
	v_fmac_f32_e32 v92, v83, v83
	v_fmac_f32_e32 v90, v84, v84
	v_fmac_f32_e32 v92, v85, v85
	v_fmac_f32_e32 v90, v86, v86
	v_fmac_f32_e32 v92, v87, v87
	v_fmac_f32_e32 v90, v88, v88
	v_fmac_f32_e32 v92, v89, v89
	v_add_f32_e32 v9, v9, v91
	v_add_f32_e32 v90, v90, v92
	ds_bpermute_b32 v91, v3, v9
	ds_bpermute_b32 v92, v3, v90
	s_waitcnt lgkmcnt(0)
	v_add_f32_e32 v9, v9, v91
	v_add_f32_e32 v90, v90, v92
	ds_bpermute_b32 v91, v4, v9
	ds_bpermute_b32 v92, v4, v90
	s_waitcnt lgkmcnt(0)
	v_add_f32_e32 v9, v9, v91
	v_add_f32_e32 v90, v90, v92
	ds_bpermute_b32 v91, v5, v9
	ds_bpermute_b32 v92, v5, v90
	s_waitcnt lgkmcnt(0)
; DI void ln_row_v(const Frame& F, f32x4 (&v)[4], float* xout, const float* g, const float* b, const float* sh, const float* sc, bf16_t* hout, const float* slab, const float* gres, float* stat = nullptr) {
;     ...
;         float s = 0.f, s2 = 0.f;
; #pragma unroll
;         for (int j = 0; j < 4; ++j) { s += (v[j][0] + v[j][1]) + (v[j][2] + v[j][3]); s2 += (v[j][0] * v[j][0] + v[j][1] * v[j][1]) + (v[j][2] * v[j][2] + v[j][3] * v[j][3]); }
;         wave_sum2(s, s2, F.lane);
;         const float mean = s * (1.f / D); const float rstd = 1.f / sqrtf(fmaxf(s2 * (1.f / D) - mean * mean, 0.f) + EPS);
;         if (stat && F.lane == 0) { f32x2 sv = {mean, rstd}; *(f32x2*)stat = sv; }
; #pragma unroll
;         for (int j = 0; j < 4; ++j) { const f32x4 gg = ((const f32x4*)g)[F.lane + 64 * j], bb = ((const f32x4*)b)[F.lane + 64 * j];
;             v[j] = (v[j] - mean) * rstd * gg + bb; if (xout) ((f32x4*)xout)[F.lane + 64 * j] = v[j]; }
;     }
;     if (hout) {
;         float s = 0.f, s2 = 0.f;
; #pragma unroll
;         for (int j = 0; j < 4; ++j) { s += (v[j][0] + v[j][1]) + (v[j][2] + v[j][3]); s2 += (v[j][0] * v[j][0] + v[j][1] * v[j][1]) + (v[j][2] * v[j][2] + v[j][3] * v[j][3]); }
;         wave_sum2(s, s2, F.lane);
;         const float mean = s * (1.f / D); const float rstd = 1.f / sqrtf(fmaxf(s2 * (1.f / D) - mean * mean, 0.f) + EPS);
	v_add_f32_e32 v9, v9, v91
	v_add_f32_e32 v90, v90, v92
	ds_bpermute_b32 v91, v6, v9
	ds_bpermute_b32 v92, v6, v90
	s_waitcnt lgkmcnt(0)
	v_add_f32_e32 v9, v9, v91
	v_add_f32_e32 v90, v90, v92
	ds_bpermute_b32 v91, v7, v9
	ds_bpermute_b32 v92, v7, v90
	s_waitcnt lgkmcnt(0)
	v_add_f32_e32 v9, v9, v91
	v_add_f32_e32 v90, v90, v92
	ds_bpermute_b32 v91, v8, v9
	ds_bpermute_b32 v92, v8, v90
	s_waitcnt lgkmcnt(0)
	v_add_f32_e32 v9, v9, v91
	v_add_f32_e32 v90, v90, v92
	v_mul_f32_e32 v93, 0x3a800000, v9
	v_mul_f32_e32 v91, 0x3a800000, v90
	v_fma_f32 v91, -v93, v93, v91
	v_max_f32_e32 v91, 0, v91
	v_add_f32_e32 v91, 0x358637bd, v91
	v_rsq_f32_e32 v94, v91
	v_mul_f32_e32 v91, 0.5, v91
	v_mul_f32_e32 v92, v94, v94
	v_fma_f32 v92, -v91, v92, 0.5
	v_fma_f32 v94, v94, v92, v94
	s_add_u32 s2, s12, 0x8000
	s_addc_u32 s3, s13, 0
	v_mov_b32_e32 v188, v93
	v_mov_b32_e32 v189, v94
	s_mov_b64 exec, 1
	global_store_dwordx2 v97, v[188:189], s[2:3]
	s_mov_b64 exec, -1
	v_sub_f32_e32 v74, v74, v93
	v_sub_f32_e32 v75, v75, v93
	v_sub_f32_e32 v76, v76, v93
	v_sub_f32_e32 v77, v77, v93
	v_sub_f32_e32 v78, v78, v93
	v_sub_f32_e32 v79, v79, v93
	v_sub_f32_e32 v80, v80, v93
	v_sub_f32_e32 v81, v81, v93
	v_sub_f32_e32 v82, v82, v93
	v_sub_f32_e32 v83, v83, v93
	v_sub_f32_e32 v84, v84, v93
	v_sub_f32_e32 v85, v85, v93
	v_sub_f32_e32 v86, v86, v93
	v_sub_f32_e32 v87, v87, v93
	v_sub_f32_e32 v88, v88, v93
	v_sub_f32_e32 v89, v89, v93
	v_mul_f32_e32 v74, v94, v74
	v_mul_f32_e32 v75, v94, v75
	v_mul_f32_e32 v76, v94, v76
	v_mul_f32_e32 v77, v94, v77
	v_mul_f32_e32 v78, v94, v78
	v_mul_f32_e32 v79, v94, v79
	v_mul_f32_e32 v80, v94, v80
	v_mul_f32_e32 v81, v94, v81
	v_mul_f32_e32 v82, v94, v82
	v_mul_f32_e32 v83, v94, v83
	v_mul_f32_e32 v84, v94, v84
	v_mul_f32_e32 v85, v94, v85
	v_mul_f32_e32 v86, v94, v86
	v_mul_f32_e32 v87, v94, v87
	v_mul_f32_e32 v88, v94, v88
	v_mul_f32_e32 v89, v94, v89
	v_fma_f32 v74, v74, v10, v26
	v_fma_f32 v75, v75, v11, v27
	v_fma_f32 v76, v76, v12, v28
	v_fma_f32 v77, v77, v13, v29
	v_fma_f32 v78, v78, v14, v30
	v_fma_f32 v79, v79, v15, v31
	v_fma_f32 v80, v80, v16, v32
	v_fma_f32 v81, v81, v17, v33
	v_fma_f32 v82, v82, v18, v34
	v_fma_f32 v83, v83, v19, v35
	v_fma_f32 v84, v84, v20, v36
	v_fma_f32 v85, v85, v21, v37
	v_fma_f32 v86, v86, v22, v38
	v_fma_f32 v87, v87, v23, v39
	v_fma_f32 v88, v88, v24, v40
	v_fma_f32 v89, v89, v25, v41
	v_add_f32_e32 v9, v74, v75
	v_add_f32_e32 v91, v76, v77
	v_mul_f32_e32 v90, v74, v74
	v_mul_f32_e32 v92, v75, v75
	v_add_f32_e32 v9, v9, v78
	v_add_f32_e32 v91, v91, v79
	v_add_f32_e32 v9, v9, v80
	v_add_f32_e32 v91, v91, v81
	v_add_f32_e32 v9, v9, v82
	v_add_f32_e32 v91, v91, v83
	v_add_f32_e32 v9, v9, v84
	v_add_f32_e32 v91, v91, v85
	v_add_f32_e32 v9, v9, v86
	v_add_f32_e32 v91, v91, v87
	v_add_f32_e32 v9, v9, v88
	v_add_f32_e32 v91, v91, v89
	v_fmac_f32_e32 v90, v76, v76
	v_fmac_f32_e32 v92, v77, v77
	v_fmac_f32_e32 v90, v78, v78
	v_fmac_f32_e32 v92, v79, v79
	v_fmac_f32_e32 v90, v80, v80
	v_fmac_f32_e32 v92, v81, v81
	v_fmac_f32_e32 v90, v82, v82
	v_fmac_f32_e32 v92, v83, v83
	v_fmac_f32_e32 v90, v84, v84
	v_fmac_f32_e32 v92, v85, v85
	v_fmac_f32_e32 v90, v86, v86
	v_fmac_f32_e32 v92, v87, v87
	v_fmac_f32_e32 v90, v88, v88
	v_fmac_f32_e32 v92, v89, v89
	v_add_f32_e32 v9, v9, v91
	v_add_f32_e32 v90, v90, v92
	ds_bpermute_b32 v91, v3, v9
	ds_bpermute_b32 v92, v3, v90
	s_waitcnt lgkmcnt(0)
	v_add_f32_e32 v9, v9, v91
	v_add_f32_e32 v90, v90, v92
	ds_bpermute_b32 v91, v4, v9
	ds_bpermute_b32 v92, v4, v90
	s_waitcnt lgkmcnt(0)
	v_add_f32_e32 v9, v9, v91
	v_add_f32_e32 v90, v90, v92
	ds_bpermute_b32 v91, v5, v9
	ds_bpermute_b32 v92, v5, v90
	s_waitcnt lgkmcnt(0)
	v_add_f32_e32 v9, v9, v91
	v_add_f32_e32 v90, v90, v92
	ds_bpermute_b32 v91, v6, v9
	ds_bpermute_b32 v92, v6, v90
	s_waitcnt lgkmcnt(0)
	v_add_f32_e32 v9, v9, v91
	v_add_f32_e32 v90, v90, v92
	ds_bpermute_b32 v91, v7, v9
	ds_bpermute_b32 v92, v7, v90
	s_waitcnt lgkmcnt(0)
	v_add_f32_e32 v9, v9, v91
	v_add_f32_e32 v90, v90, v92
	ds_bpermute_b32 v91, v8, v9
	ds_bpermute_b32 v92, v8, v90
	s_waitcnt lgkmcnt(0)
	v_add_f32_e32 v9, v9, v91
	v_add_f32_e32 v90, v90, v92
	v_mul_f32_e32 v93, 0x3a800000, v9
	v_mul_f32_e32 v91, 0x3a800000, v90
	v_fma_f32 v91, -v93, v93, v91
	v_max_f32_e32 v91, 0, v91
	v_add_f32_e32 v91, 0x358637bd, v91
	v_rsq_f32_e32 v94, v91
	v_mul_f32_e32 v91, 0.5, v91
	v_mul_f32_e32 v92, v94, v94
	v_fma_f32 v92, -v91, v92, 0.5
	v_fma_f32 v94, v94, v92, v94
	s_waitcnt vmcnt(18)
; DI unsigned pk2(float lo, float hi) { f32x2 v = {lo, hi}; bf16x2_t b = __builtin_convertvector(v, bf16x2_t); return __builtin_bit_cast(unsigned, b); }
; DI const float* modp(const Frame& F, int l, int mr, int which) { return (const float*)(F.ws + WS_MOD) + ((size_t)(l * 9 + mr) * 6 + which) * 1024; }
; DI void ln_row_v(const Frame& F, f32x4 (&v)[4], float* xout, const float* g, const float* b, const float* sh, const float* sc, bf16_t* hout, const float* slab, const float* gres, float* stat = nullptr) {
;     ...
;         float s = 0.f, s2 = 0.f;
; #pragma unroll
;         for (int j = 0; j < 4; ++j) { s += (v[j][0] + v[j][1]) + (v[j][2] + v[j][3]); s2 += (v[j][0] * v[j][0] + v[j][1] * v[j][1]) + (v[j][2] * v[j][2] + v[j][3] * v[j][3]); }
;         wave_sum2(s, s2, F.lane);
;         const float mean = s * (1.f / D); const float rstd = 1.f / sqrtf(fmaxf(s2 * (1.f / D) - mean * mean, 0.f) + EPS);
; #pragma unroll
;         for (int j = 0; j < 4; ++j) { const f32x4 hh = ((const f32x4*)sh)[F.lane + 64 * j], cc = ((const f32x4*)sc)[F.lane + 64 * j];
;             const f32x4 o = (v[j] - mean) * rstd * (cc + 1.f) + hh; u32x2 wv; wv.x = pk2(o[0], o[1]); wv.y = pk2(o[2], o[3]);
;             ((u32x2*)hout)[F.lane + 64 * j] = wv; }
; DI void ln_phase(const Frame& F, int which) {
;     ...
;     for (int row = gw; row < nrows; row += NGW) {
;         if (row + NGW < nrows) ln_load(F, xrow_ptr(F, row + NGW), vn);
;         const int mr = row < ML ? (row >> 11) : 8;
;         const float* sh = which == 0 ? modp(F, l, mr, 3) : modp(F, l + 1 < NL ? l + 1 : l, mr, 0);
;         const float* sc = which == 0 ? modp(F, l, mr, 4) : modp(F, l + 1 < NL ? l + 1 : l, mr, 1);
	v_sub_f32_e32 v74, v74, v93
	v_sub_f32_e32 v75, v75, v93
	v_sub_f32_e32 v76, v76, v93
	v_sub_f32_e32 v77, v77, v93
	v_sub_f32_e32 v78, v78, v93
	v_sub_f32_e32 v79, v79, v93
	v_sub_f32_e32 v80, v80, v93
	v_sub_f32_e32 v81, v81, v93
	v_sub_f32_e32 v82, v82, v93
	v_sub_f32_e32 v83, v83, v93
	v_sub_f32_e32 v84, v84, v93
	v_sub_f32_e32 v85, v85, v93
	v_sub_f32_e32 v86, v86, v93
	v_sub_f32_e32 v87, v87, v93
	v_sub_f32_e32 v88, v88, v93
	v_sub_f32_e32 v89, v89, v93
	v_add_f32_e32 v130, 1.0, v130
	v_add_f32_e32 v131, 1.0, v131
	v_add_f32_e32 v132, 1.0, v132
	v_add_f32_e32 v133, 1.0, v133
	v_add_f32_e32 v134, 1.0, v134
	v_add_f32_e32 v135, 1.0, v135
	v_add_f32_e32 v136, 1.0, v136
	v_add_f32_e32 v137, 1.0, v137
	v_add_f32_e32 v138, 1.0, v138
	v_add_f32_e32 v139, 1.0, v139
	v_add_f32_e32 v140, 1.0, v140
	v_add_f32_e32 v141, 1.0, v141
	v_add_f32_e32 v142, 1.0, v142
	v_add_f32_e32 v143, 1.0, v143
	v_add_f32_e32 v144, 1.0, v144
	v_add_f32_e32 v145, 1.0, v145
	v_mul_f32_e32 v74, v94, v74
	v_mul_f32_e32 v75, v94, v75
	v_mul_f32_e32 v76, v94, v76
	v_mul_f32_e32 v77, v94, v77
	v_mul_f32_e32 v78, v94, v78
	v_mul_f32_e32 v79, v94, v79
	v_mul_f32_e32 v80, v94, v80
	v_mul_f32_e32 v81, v94, v81
	v_mul_f32_e32 v82, v94, v82
	v_mul_f32_e32 v83, v94, v83
	v_mul_f32_e32 v84, v94, v84
	v_mul_f32_e32 v85, v94, v85
	v_mul_f32_e32 v86, v94, v86
	v_mul_f32_e32 v87, v94, v87
	v_mul_f32_e32 v88, v94, v88
	v_mul_f32_e32 v89, v94, v89
	v_fma_f32 v74, v74, v130, v114
	v_fma_f32 v75, v75, v131, v115
	v_fma_f32 v76, v76, v132, v116
	v_fma_f32 v77, v77, v133, v117
	v_fma_f32 v78, v78, v134, v118
	v_fma_f32 v79, v79, v135, v119
	v_fma_f32 v80, v80, v136, v120
	v_fma_f32 v81, v81, v137, v121
	v_fma_f32 v82, v82, v138, v122
	v_fma_f32 v83, v83, v139, v123
	v_fma_f32 v84, v84, v140, v124
	v_fma_f32 v85, v85, v141, v125
	v_fma_f32 v86, v86, v142, v126
	v_fma_f32 v87, v87, v143, v127
	v_fma_f32 v88, v88, v144, v128
	v_fma_f32 v89, v89, v145, v129
	v_cvt_pk_bf16_f32 v190, v74, v75
	v_cvt_pk_bf16_f32 v191, v76, v77
	v_cvt_pk_bf16_f32 v192, v78, v79
	v_cvt_pk_bf16_f32 v193, v80, v81
	v_cvt_pk_bf16_f32 v194, v82, v83
	v_cvt_pk_bf16_f32 v195, v84, v85
	v_cvt_pk_bf16_f32 v196, v86, v87
	v_cvt_pk_bf16_f32 v197, v88, v89
	s_add_u32 s2, s10, 0x800000
	s_addc_u32 s3, s11, 0
	global_store_dwordx2 v1, v[190:191], s[2:3]
	global_store_dwordx2 v1, v[192:193], s[2:3] offset:512
	global_store_dwordx2 v1, v[194:195], s[2:3] offset:1024
	global_store_dwordx2 v1, v[196:197], s[2:3] offset:1536
	s_add_u32 s2, s8, 0x3000000
	s_addc_u32 s3, s9, 0
	global_load_dwordx4 v[74:77], v0, s[2:3]
	global_load_dwordx4 v[78:81], v0, s[2:3] offset:1024
	global_load_dwordx4 v[82:85], v0, s[2:3] offset:2048
	global_load_dwordx4 v[86:89], v0, s[2:3] offset:3072
	s_add_u32 s2, s14, 0x18000
	s_addc_u32 s3, s15, 0
	global_load_dwordx4 v[114:117], v0, s[2:3]
	global_load_dwordx4 v[118:121], v0, s[2:3] offset:1024
	global_load_dwordx4 v[122:125], v0, s[2:3] offset:2048
	global_load_dwordx4 v[126:129], v0, s[2:3] offset:3072
	s_add_u32 s2, s18, 0x18000
	s_addc_u32 s3, s19, 0
	global_load_dwordx4 v[130:133], v0, s[2:3]
	global_load_dwordx4 v[134:137], v0, s[2:3] offset:1024
	global_load_dwordx4 v[138:141], v0, s[2:3] offset:2048
	global_load_dwordx4 v[142:145], v0, s[2:3] offset:3072
	v_add_f32_e32 v9, v98, v99
	v_add_f32_e32 v91, v100, v101
	v_mul_f32_e32 v90, v98, v98
	v_mul_f32_e32 v92, v99, v99
	v_add_f32_e32 v9, v9, v102
	v_add_f32_e32 v91, v91, v103
	v_add_f32_e32 v9, v9, v104
	v_add_f32_e32 v91, v91, v105
	v_add_f32_e32 v9, v9, v106
	v_add_f32_e32 v91, v91, v107
	v_add_f32_e32 v9, v9, v108
	v_add_f32_e32 v91, v91, v109
	v_add_f32_e32 v9, v9, v110
	v_add_f32_e32 v91, v91, v111
	v_add_f32_e32 v9, v9, v112
	v_add_f32_e32 v91, v91, v113
	v_fmac_f32_e32 v90, v100, v100
	v_fmac_f32_e32 v92, v101, v101
	v_fmac_f32_e32 v90, v102, v102
	v_fmac_f32_e32 v92, v103, v103
	v_fmac_f32_e32 v90, v104, v104
	v_fmac_f32_e32 v92, v105, v105
	v_fmac_f32_e32 v90, v106, v106
	v_fmac_f32_e32 v92, v107, v107
	v_fmac_f32_e32 v90, v108, v108
	v_fmac_f32_e32 v92, v109, v109
	v_fmac_f32_e32 v90, v110, v110
	v_fmac_f32_e32 v92, v111, v111
	v_fmac_f32_e32 v90, v112, v112
	v_fmac_f32_e32 v92, v113, v113
	v_add_f32_e32 v9, v9, v91
	v_add_f32_e32 v90, v90, v92
	ds_bpermute_b32 v91, v3, v9
	ds_bpermute_b32 v92, v3, v90
	s_waitcnt lgkmcnt(0)
	v_add_f32_e32 v9, v9, v91
	v_add_f32_e32 v90, v90, v92
	ds_bpermute_b32 v91, v4, v9
	ds_bpermute_b32 v92, v4, v90
	s_waitcnt lgkmcnt(0)
	v_add_f32_e32 v9, v9, v91
	v_add_f32_e32 v90, v90, v92
	ds_bpermute_b32 v91, v5, v9
	ds_bpermute_b32 v92, v5, v90
	s_waitcnt lgkmcnt(0)
	v_add_f32_e32 v9, v9, v91
	v_add_f32_e32 v90, v90, v92
	ds_bpermute_b32 v91, v6, v9
	ds_bpermute_b32 v92, v6, v90
	s_waitcnt lgkmcnt(0)
	v_add_f32_e32 v9, v9, v91
	v_add_f32_e32 v90, v90, v92
	ds_bpermute_b32 v91, v7, v9
	ds_bpermute_b32 v92, v7, v90
	s_waitcnt lgkmcnt(0)
	v_add_f32_e32 v9, v9, v91
	v_add_f32_e32 v90, v90, v92
	ds_bpermute_b32 v91, v8, v9
	ds_bpermute_b32 v92, v8, v90
	s_waitcnt lgkmcnt(0)
; DI unsigned pk2(float lo, float hi) { f32x2 v = {lo, hi}; bf16x2_t b = __builtin_convertvector(v, bf16x2_t); return __builtin_bit_cast(unsigned, b); }
; DI void ln_row_v(const Frame& F, f32x4 (&v)[4], float* xout, const float* g, const float* b, const float* sh, const float* sc, bf16_t* hout, const float* slab, const float* gres, float* stat = nullptr) {
;     ...
;         float s = 0.f, s2 = 0.f;
; #pragma unroll
;         for (int j = 0; j < 4; ++j) { s += (v[j][0] + v[j][1]) + (v[j][2] + v[j][3]); s2 += (v[j][0] * v[j][0] + v[j][1] * v[j][1]) + (v[j][2] * v[j][2] + v[j][3] * v[j][3]); }
;         wave_sum2(s, s2, F.lane);
;         const float mean = s * (1.f / D); const float rstd = 1.f / sqrtf(fmaxf(s2 * (1.f / D) - mean * mean, 0.f) + EPS);
;         if (stat && F.lane == 0) { f32x2 sv = {mean, rstd}; *(f32x2*)stat = sv; }
; #pragma unroll
;         for (int j = 0; j < 4; ++j) { const f32x4 gg = ((const f32x4*)g)[F.lane + 64 * j], bb = ((const f32x4*)b)[F.lane + 64 * j];
;             v[j] = (v[j] - mean) * rstd * gg + bb; if (xout) ((f32x4*)xout)[F.lane + 64 * j] = v[j]; }
;     }
;     if (hout) {
;         float s = 0.f, s2 = 0.f;
; #pragma unroll
;         for (int j = 0; j < 4; ++j) { s += (v[j][0] + v[j][1]) + (v[j][2] + v[j][3]); s2 += (v[j][0] * v[j][0] + v[j][1] * v[j][1]) + (v[j][2] * v[j][2] + v[j][3] * v[j][3]); }
;         wave_sum2(s, s2, F.lane);
;         const float mean = s * (1.f / D); const float rstd = 1.f / sqrtf(fmaxf(s2 * (1.f / D) - mean * mean, 0.f) + EPS);
; #pragma unroll
;         for (int j = 0; j < 4; ++j) { const f32x4 hh = ((const f32x4*)sh)[F.lane + 64 * j], cc = ((const f32x4*)sc)[F.lane + 64 * j];
;             const f32x4 o = (v[j] - mean) * rstd * (cc + 1.f) + hh; u32x2 wv; wv.x = pk2(o[0], o[1]); wv.y = pk2(o[2], o[3]);
	v_add_f32_e32 v9, v9, v91
	v_add_f32_e32 v90, v90, v92
	v_mul_f32_e32 v93, 0x3a800000, v9
	v_mul_f32_e32 v91, 0x3a800000, v90
	v_fma_f32 v91, -v93, v93, v91
	v_max_f32_e32 v91, 0, v91
	v_add_f32_e32 v91, 0x358637bd, v91
	v_rsq_f32_e32 v94, v91
	v_mul_f32_e32 v91, 0.5, v91
	v_mul_f32_e32 v92, v94, v94
	v_fma_f32 v92, -v91, v92, 0.5
	v_fma_f32 v94, v94, v92, v94
	s_add_u32 s2, s12, 0xc000
	s_addc_u32 s3, s13, 0
	v_mov_b32_e32 v188, v93
	v_mov_b32_e32 v189, v94
	s_mov_b64 exec, 1
	global_store_dwordx2 v97, v[188:189], s[2:3]
	s_mov_b64 exec, -1
	v_sub_f32_e32 v98, v98, v93
	v_sub_f32_e32 v99, v99, v93
	v_sub_f32_e32 v100, v100, v93
	v_sub_f32_e32 v101, v101, v93
	v_sub_f32_e32 v102, v102, v93
	v_sub_f32_e32 v103, v103, v93
	v_sub_f32_e32 v104, v104, v93
	v_sub_f32_e32 v105, v105, v93
	v_sub_f32_e32 v106, v106, v93
	v_sub_f32_e32 v107, v107, v93
	v_sub_f32_e32 v108, v108, v93
	v_sub_f32_e32 v109, v109, v93
	v_sub_f32_e32 v110, v110, v93
	v_sub_f32_e32 v111, v111, v93
	v_sub_f32_e32 v112, v112, v93
	v_sub_f32_e32 v113, v113, v93
	v_mul_f32_e32 v98, v94, v98
	v_mul_f32_e32 v99, v94, v99
	v_mul_f32_e32 v100, v94, v100
	v_mul_f32_e32 v101, v94, v101
	v_mul_f32_e32 v102, v94, v102
	v_mul_f32_e32 v103, v94, v103
	v_mul_f32_e32 v104, v94, v104
	v_mul_f32_e32 v105, v94, v105
	v_mul_f32_e32 v106, v94, v106
	v_mul_f32_e32 v107, v94, v107
	v_mul_f32_e32 v108, v94, v108
	v_mul_f32_e32 v109, v94, v109
	v_mul_f32_e32 v110, v94, v110
	v_mul_f32_e32 v111, v94, v111
	v_mul_f32_e32 v112, v94, v112
	v_mul_f32_e32 v113, v94, v113
	v_fma_f32 v98, v98, v10, v26
	v_fma_f32 v99, v99, v11, v27
	v_fma_f32 v100, v100, v12, v28
	v_fma_f32 v101, v101, v13, v29
	v_fma_f32 v102, v102, v14, v30
	v_fma_f32 v103, v103, v15, v31
	v_fma_f32 v104, v104, v16, v32
	v_fma_f32 v105, v105, v17, v33
	v_fma_f32 v106, v106, v18, v34
	v_fma_f32 v107, v107, v19, v35
	v_fma_f32 v108, v108, v20, v36
	v_fma_f32 v109, v109, v21, v37
	v_fma_f32 v110, v110, v22, v38
	v_fma_f32 v111, v111, v23, v39
	v_fma_f32 v112, v112, v24, v40
	v_fma_f32 v113, v113, v25, v41
	v_add_f32_e32 v9, v98, v99
	v_add_f32_e32 v91, v100, v101
	v_mul_f32_e32 v90, v98, v98
	v_mul_f32_e32 v92, v99, v99
	v_add_f32_e32 v9, v9, v102
	v_add_f32_e32 v91, v91, v103
	v_add_f32_e32 v9, v9, v104
	v_add_f32_e32 v91, v91, v105
	v_add_f32_e32 v9, v9, v106
	v_add_f32_e32 v91, v91, v107
	v_add_f32_e32 v9, v9, v108
	v_add_f32_e32 v91, v91, v109
	v_add_f32_e32 v9, v9, v110
	v_add_f32_e32 v91, v91, v111
	v_add_f32_e32 v9, v9, v112
	v_add_f32_e32 v91, v91, v113
	v_fmac_f32_e32 v90, v100, v100
	v_fmac_f32_e32 v92, v101, v101
	v_fmac_f32_e32 v90, v102, v102
	v_fmac_f32_e32 v92, v103, v103
	v_fmac_f32_e32 v90, v104, v104
	v_fmac_f32_e32 v92, v105, v105
	v_fmac_f32_e32 v90, v106, v106
	v_fmac_f32_e32 v92, v107, v107
	v_fmac_f32_e32 v90, v108, v108
	v_fmac_f32_e32 v92, v109, v109
	v_fmac_f32_e32 v90, v110, v110
	v_fmac_f32_e32 v92, v111, v111
	v_fmac_f32_e32 v90, v112, v112
	v_fmac_f32_e32 v92, v113, v113
	v_add_f32_e32 v9, v9, v91
	v_add_f32_e32 v90, v90, v92
	ds_bpermute_b32 v91, v3, v9
	ds_bpermute_b32 v92, v3, v90
	s_waitcnt lgkmcnt(0)
	v_add_f32_e32 v9, v9, v91
	v_add_f32_e32 v90, v90, v92
	ds_bpermute_b32 v91, v4, v9
	ds_bpermute_b32 v92, v4, v90
	s_waitcnt lgkmcnt(0)
	v_add_f32_e32 v9, v9, v91
	v_add_f32_e32 v90, v90, v92
	ds_bpermute_b32 v91, v5, v9
	ds_bpermute_b32 v92, v5, v90
	s_waitcnt lgkmcnt(0)
	v_add_f32_e32 v9, v9, v91
	v_add_f32_e32 v90, v90, v92
	ds_bpermute_b32 v91, v6, v9
	ds_bpermute_b32 v92, v6, v90
	s_waitcnt lgkmcnt(0)
	v_add_f32_e32 v9, v9, v91
	v_add_f32_e32 v90, v90, v92
	ds_bpermute_b32 v91, v7, v9
	ds_bpermute_b32 v92, v7, v90
	s_waitcnt lgkmcnt(0)
	v_add_f32_e32 v9, v9, v91
	v_add_f32_e32 v90, v90, v92
	ds_bpermute_b32 v91, v8, v9
	ds_bpermute_b32 v92, v8, v90
	s_waitcnt lgkmcnt(0)
	v_add_f32_e32 v9, v9, v91
	v_add_f32_e32 v90, v90, v92
	v_mul_f32_e32 v93, 0x3a800000, v9
	v_mul_f32_e32 v91, 0x3a800000, v90
	v_fma_f32 v91, -v93, v93, v91
	v_max_f32_e32 v91, 0, v91
	v_add_f32_e32 v91, 0x358637bd, v91
	v_rsq_f32_e32 v94, v91
	v_mul_f32_e32 v91, 0.5, v91
	v_mul_f32_e32 v92, v94, v94
	v_fma_f32 v92, -v91, v92, 0.5
	v_fma_f32 v94, v94, v92, v94
	s_waitcnt vmcnt(18)
	v_sub_f32_e32 v98, v98, v93
	v_sub_f32_e32 v99, v99, v93
	v_sub_f32_e32 v100, v100, v93
	v_sub_f32_e32 v101, v101, v93
	v_sub_f32_e32 v102, v102, v93
	v_sub_f32_e32 v103, v103, v93
	v_sub_f32_e32 v104, v104, v93
	v_sub_f32_e32 v105, v105, v93
	v_sub_f32_e32 v106, v106, v93
	v_sub_f32_e32 v107, v107, v93
	v_sub_f32_e32 v108, v108, v93
	v_sub_f32_e32 v109, v109, v93
	v_sub_f32_e32 v110, v110, v93
	v_sub_f32_e32 v111, v111, v93
	v_sub_f32_e32 v112, v112, v93
	v_sub_f32_e32 v113, v113, v93
	v_add_f32_e32 v162, 1.0, v162
	v_add_f32_e32 v163, 1.0, v163
	v_add_f32_e32 v164, 1.0, v164
	v_add_f32_e32 v165, 1.0, v165
	v_add_f32_e32 v166, 1.0, v166
	v_add_f32_e32 v167, 1.0, v167
	v_add_f32_e32 v168, 1.0, v168
	v_add_f32_e32 v169, 1.0, v169
	v_add_f32_e32 v170, 1.0, v170
	v_add_f32_e32 v171, 1.0, v171
	v_add_f32_e32 v172, 1.0, v172
	v_add_f32_e32 v173, 1.0, v173
	v_add_f32_e32 v174, 1.0, v174
	v_add_f32_e32 v175, 1.0, v175
	v_add_f32_e32 v176, 1.0, v176
	v_add_f32_e32 v177, 1.0, v177
	v_mul_f32_e32 v98, v94, v98
	v_mul_f32_e32 v99, v94, v99
	v_mul_f32_e32 v100, v94, v100
	v_mul_f32_e32 v101, v94, v101
	v_mul_f32_e32 v102, v94, v102
	v_mul_f32_e32 v103, v94, v103
	v_mul_f32_e32 v104, v94, v104
	v_mul_f32_e32 v105, v94, v105
	v_mul_f32_e32 v106, v94, v106
	v_mul_f32_e32 v107, v94, v107
	v_mul_f32_e32 v108, v94, v108
	v_mul_f32_e32 v109, v94, v109
	v_mul_f32_e32 v110, v94, v110
	v_mul_f32_e32 v111, v94, v111
	v_mul_f32_e32 v112, v94, v112
	v_mul_f32_e32 v113, v94, v113
; DI unsigned pk2(float lo, float hi) { f32x2 v = {lo, hi}; bf16x2_t b = __builtin_convertvector(v, bf16x2_t); return __builtin_bit_cast(unsigned, b); }
; DI void ln_row_v(const Frame& F, f32x4 (&v)[4], float* xout, const float* g, const float* b, const float* sh, const float* sc, bf16_t* hout, const float* slab, const float* gres, float* stat = nullptr) {
;     ...
;         float s = 0.f, s2 = 0.f;
; #pragma unroll
;         for (int j = 0; j < 4; ++j) { s += (v[j][0] + v[j][1]) + (v[j][2] + v[j][3]); s2 += (v[j][0] * v[j][0] + v[j][1] * v[j][1]) + (v[j][2] * v[j][2] + v[j][3] * v[j][3]); }
;         wave_sum2(s, s2, F.lane);
;         const float mean = s * (1.f / D); const float rstd = 1.f / sqrtf(fmaxf(s2 * (1.f / D) - mean * mean, 0.f) + EPS);
;         if (stat && F.lane == 0) { f32x2 sv = {mean, rstd}; *(f32x2*)stat = sv; }
; #pragma unroll
;         for (int j = 0; j < 4; ++j) { const f32x4 gg = ((const f32x4*)g)[F.lane + 64 * j], bb = ((const f32x4*)b)[F.lane + 64 * j];
;             v[j] = (v[j] - mean) * rstd * gg + bb; if (xout) ((f32x4*)xout)[F.lane + 64 * j] = v[j]; }
;     ...
;         for (int j = 0; j < 4; ++j) { const f32x4 hh = ((const f32x4*)sh)[F.lane + 64 * j], cc = ((const f32x4*)sc)[F.lane + 64 * j];
;             const f32x4 o = (v[j] - mean) * rstd * (cc + 1.f) + hh; u32x2 wv; wv.x = pk2(o[0], o[1]); wv.y = pk2(o[2], o[3]);
;             ((u32x2*)hout)[F.lane + 64 * j] = wv; }
	v_fma_f32 v98, v98, v162, v146
	v_fma_f32 v99, v99, v163, v147
	v_fma_f32 v100, v100, v164, v148
	v_fma_f32 v101, v101, v165, v149
	v_fma_f32 v102, v102, v166, v150
	v_fma_f32 v103, v103, v167, v151
	v_fma_f32 v104, v104, v168, v152
	v_fma_f32 v105, v105, v169, v153
	v_fma_f32 v106, v106, v170, v154
	v_fma_f32 v107, v107, v171, v155
	v_fma_f32 v108, v108, v172, v156
	v_fma_f32 v109, v109, v173, v157
	v_fma_f32 v110, v110, v174, v158
	v_fma_f32 v111, v111, v175, v159
	v_fma_f32 v112, v112, v176, v160
	v_fma_f32 v113, v113, v177, v161
	v_cvt_pk_bf16_f32 v190, v98, v99
	v_cvt_pk_bf16_f32 v191, v100, v101
	v_cvt_pk_bf16_f32 v192, v102, v103
	v_cvt_pk_bf16_f32 v193, v104, v105
	v_cvt_pk_bf16_f32 v194, v106, v107
	v_cvt_pk_bf16_f32 v195, v108, v109
	v_cvt_pk_bf16_f32 v196, v110, v111
	v_cvt_pk_bf16_f32 v197, v112, v113
	s_add_u32 s2, s10, 0xc00000
	s_addc_u32 s3, s11, 0
	global_store_dwordx2 v1, v[190:191], s[2:3]
	global_store_dwordx2 v1, v[192:193], s[2:3] offset:512
	global_store_dwordx2 v1, v[194:195], s[2:3] offset:1024
	global_store_dwordx2 v1, v[196:197], s[2:3] offset:1536
	s_add_u32 s2, s8, 0x3800000
	s_addc_u32 s3, s9, 0
	global_load_dwordx4 v[98:101], v0, s[2:3]
	global_load_dwordx4 v[102:105], v0, s[2:3] offset:1024
	global_load_dwordx4 v[106:109], v0, s[2:3] offset:2048
	global_load_dwordx4 v[110:113], v0, s[2:3] offset:3072
	s_add_u32 s2, s14, 0x1e000
	s_addc_u32 s3, s15, 0
	global_load_dwordx4 v[146:149], v0, s[2:3]
	global_load_dwordx4 v[150:153], v0, s[2:3] offset:1024
	global_load_dwordx4 v[154:157], v0, s[2:3] offset:2048
	global_load_dwordx4 v[158:161], v0, s[2:3] offset:3072
	s_add_u32 s2, s18, 0x1e000
	s_addc_u32 s3, s19, 0
	global_load_dwordx4 v[162:165], v0, s[2:3]
	global_load_dwordx4 v[166:169], v0, s[2:3] offset:1024
	global_load_dwordx4 v[170:173], v0, s[2:3] offset:2048
	global_load_dwordx4 v[174:177], v0, s[2:3] offset:3072
	v_add_f32_e32 v9, v42, v43
	v_add_f32_e32 v91, v44, v45
	v_mul_f32_e32 v90, v42, v42
	v_mul_f32_e32 v92, v43, v43
	v_add_f32_e32 v9, v9, v46
	v_add_f32_e32 v91, v91, v47
	v_add_f32_e32 v9, v9, v48
	v_add_f32_e32 v91, v91, v49
	v_add_f32_e32 v9, v9, v50
	v_add_f32_e32 v91, v91, v51
	v_add_f32_e32 v9, v9, v52
	v_add_f32_e32 v91, v91, v53
	v_add_f32_e32 v9, v9, v54
	v_add_f32_e32 v91, v91, v55
	v_add_f32_e32 v9, v9, v56
	v_add_f32_e32 v91, v91, v57
	v_fmac_f32_e32 v90, v44, v44
	v_fmac_f32_e32 v92, v45, v45
	v_fmac_f32_e32 v90, v46, v46
	v_fmac_f32_e32 v92, v47, v47
	v_fmac_f32_e32 v90, v48, v48
	v_fmac_f32_e32 v92, v49, v49
	v_fmac_f32_e32 v90, v50, v50
	v_fmac_f32_e32 v92, v51, v51
	v_fmac_f32_e32 v90, v52, v52
	v_fmac_f32_e32 v92, v53, v53
	v_fmac_f32_e32 v90, v54, v54
	v_fmac_f32_e32 v92, v55, v55
	v_fmac_f32_e32 v90, v56, v56
	v_fmac_f32_e32 v92, v57, v57
	v_add_f32_e32 v9, v9, v91
	v_add_f32_e32 v90, v90, v92
	ds_bpermute_b32 v91, v3, v9
	ds_bpermute_b32 v92, v3, v90
	s_waitcnt lgkmcnt(0)
	v_add_f32_e32 v9, v9, v91
	v_add_f32_e32 v90, v90, v92
	ds_bpermute_b32 v91, v4, v9
	ds_bpermute_b32 v92, v4, v90
	s_waitcnt lgkmcnt(0)
	v_add_f32_e32 v9, v9, v91
	v_add_f32_e32 v90, v90, v92
	ds_bpermute_b32 v91, v5, v9
	ds_bpermute_b32 v92, v5, v90
	s_waitcnt lgkmcnt(0)
	v_add_f32_e32 v9, v9, v91
	v_add_f32_e32 v90, v90, v92
	ds_bpermute_b32 v91, v6, v9
	ds_bpermute_b32 v92, v6, v90
	s_waitcnt lgkmcnt(0)
	v_add_f32_e32 v9, v9, v91
	v_add_f32_e32 v90, v90, v92
	ds_bpermute_b32 v91, v7, v9
	ds_bpermute_b32 v92, v7, v90
	s_waitcnt lgkmcnt(0)
	v_add_f32_e32 v9, v9, v91
	v_add_f32_e32 v90, v90, v92
	ds_bpermute_b32 v91, v8, v9
	ds_bpermute_b32 v92, v8, v90
	s_waitcnt lgkmcnt(0)
	v_add_f32_e32 v9, v9, v91
	v_add_f32_e32 v90, v90, v92
	v_mul_f32_e32 v93, 0x3a800000, v9
	v_mul_f32_e32 v91, 0x3a800000, v90
	v_fma_f32 v91, -v93, v93, v91
	v_max_f32_e32 v91, 0, v91
	v_add_f32_e32 v91, 0x358637bd, v91
	v_rsq_f32_e32 v94, v91
	v_mul_f32_e32 v91, 0.5, v91
	v_mul_f32_e32 v92, v94, v94
	v_fma_f32 v92, -v91, v92, 0.5
	v_fma_f32 v94, v94, v92, v94
	s_add_u32 s2, s12, 0x10000
	s_addc_u32 s3, s13, 0
	v_mov_b32_e32 v188, v93
	v_mov_b32_e32 v189, v94
	s_mov_b64 exec, 1
	global_store_dwordx2 v97, v[188:189], s[2:3]
	s_mov_b64 exec, -1
	v_sub_f32_e32 v42, v42, v93
	v_sub_f32_e32 v43, v43, v93
	v_sub_f32_e32 v44, v44, v93
	v_sub_f32_e32 v45, v45, v93
	v_sub_f32_e32 v46, v46, v93
	v_sub_f32_e32 v47, v47, v93
	v_sub_f32_e32 v48, v48, v93
	v_sub_f32_e32 v49, v49, v93
	v_sub_f32_e32 v50, v50, v93
	v_sub_f32_e32 v51, v51, v93
	v_sub_f32_e32 v52, v52, v93
	v_sub_f32_e32 v53, v53, v93
	v_sub_f32_e32 v54, v54, v93
	v_sub_f32_e32 v55, v55, v93
	v_sub_f32_e32 v56, v56, v93
	v_sub_f32_e32 v57, v57, v93
	v_mul_f32_e32 v42, v94, v42
	v_mul_f32_e32 v43, v94, v43
	v_mul_f32_e32 v44, v94, v44
	v_mul_f32_e32 v45, v94, v45
	v_mul_f32_e32 v46, v94, v46
	v_mul_f32_e32 v47, v94, v47
	v_mul_f32_e32 v48, v94, v48
	v_mul_f32_e32 v49, v94, v49
	v_mul_f32_e32 v50, v94, v50
	v_mul_f32_e32 v51, v94, v51
	v_mul_f32_e32 v52, v94, v52
	v_mul_f32_e32 v53, v94, v53
	v_mul_f32_e32 v54, v94, v54
	v_mul_f32_e32 v55, v94, v55
	v_mul_f32_e32 v56, v94, v56
	v_mul_f32_e32 v57, v94, v57
	v_fma_f32 v42, v42, v10, v26
	v_fma_f32 v43, v43, v11, v27
	v_fma_f32 v44, v44, v12, v28
	v_fma_f32 v45, v45, v13, v29
	v_fma_f32 v46, v46, v14, v30
	v_fma_f32 v47, v47, v15, v31
	v_fma_f32 v48, v48, v16, v32
	v_fma_f32 v49, v49, v17, v33
	v_fma_f32 v50, v50, v18, v34
	v_fma_f32 v51, v51, v19, v35
	v_fma_f32 v52, v52, v20, v36
	v_fma_f32 v53, v53, v21, v37
	v_fma_f32 v54, v54, v22, v38
	v_fma_f32 v55, v55, v23, v39
	v_fma_f32 v56, v56, v24, v40
	v_fma_f32 v57, v57, v25, v41
	v_add_f32_e32 v9, v42, v43
	v_add_f32_e32 v91, v44, v45
	v_mul_f32_e32 v90, v42, v42
	v_mul_f32_e32 v92, v43, v43
	v_add_f32_e32 v9, v9, v46
	v_add_f32_e32 v91, v91, v47
	v_add_f32_e32 v9, v9, v48
	v_add_f32_e32 v91, v91, v49
	v_add_f32_e32 v9, v9, v50
	v_add_f32_e32 v91, v91, v51
	v_add_f32_e32 v9, v9, v52
	v_add_f32_e32 v91, v91, v53
	v_add_f32_e32 v9, v9, v54
	v_add_f32_e32 v91, v91, v55
	v_add_f32_e32 v9, v9, v56
	v_add_f32_e32 v91, v91, v57
	v_fmac_f32_e32 v90, v44, v44
	v_fmac_f32_e32 v92, v45, v45
	v_fmac_f32_e32 v90, v46, v46
	v_fmac_f32_e32 v92, v47, v47
	v_fmac_f32_e32 v90, v48, v48
	v_fmac_f32_e32 v92, v49, v49
	v_fmac_f32_e32 v90, v50, v50
	v_fmac_f32_e32 v92, v51, v51
	v_fmac_f32_e32 v90, v52, v52
	v_fmac_f32_e32 v92, v53, v53
	v_fmac_f32_e32 v90, v54, v54
	v_fmac_f32_e32 v92, v55, v55
	v_fmac_f32_e32 v90, v56, v56
	v_fmac_f32_e32 v92, v57, v57
	v_add_f32_e32 v9, v9, v91
	v_add_f32_e32 v90, v90, v92
	ds_bpermute_b32 v91, v3, v9
	ds_bpermute_b32 v92, v3, v90
	s_waitcnt lgkmcnt(0)
; DI unsigned pk2(float lo, float hi) { f32x2 v = {lo, hi}; bf16x2_t b = __builtin_convertvector(v, bf16x2_t); return __builtin_bit_cast(unsigned, b); }
; DI const float* modp(const Frame& F, int l, int mr, int which) { return (const float*)(F.ws + WS_MOD) + ((size_t)(l * 9 + mr) * 6 + which) * 1024; }
; DI void ln_row_v(const Frame& F, f32x4 (&v)[4], float* xout, const float* g, const float* b, const float* sh, const float* sc, bf16_t* hout, const float* slab, const float* gres, float* stat = nullptr) {
;     ...
;         float s = 0.f, s2 = 0.f;
; #pragma unroll
;         for (int j = 0; j < 4; ++j) { s += (v[j][0] + v[j][1]) + (v[j][2] + v[j][3]); s2 += (v[j][0] * v[j][0] + v[j][1] * v[j][1]) + (v[j][2] * v[j][2] + v[j][3] * v[j][3]); }
;         wave_sum2(s, s2, F.lane);
;         const float mean = s * (1.f / D); const float rstd = 1.f / sqrtf(fmaxf(s2 * (1.f / D) - mean * mean, 0.f) + EPS);
; #pragma unroll
;         for (int j = 0; j < 4; ++j) { const f32x4 hh = ((const f32x4*)sh)[F.lane + 64 * j], cc = ((const f32x4*)sc)[F.lane + 64 * j];
;             const f32x4 o = (v[j] - mean) * rstd * (cc + 1.f) + hh; u32x2 wv; wv.x = pk2(o[0], o[1]); wv.y = pk2(o[2], o[3]);
;             ((u32x2*)hout)[F.lane + 64 * j] = wv; }
; DI void ln_phase(const Frame& F, int which) {
;     ...
;     for (int row = gw; row < nrows; row += NGW) {
;         if (row + NGW < nrows) ln_load(F, xrow_ptr(F, row + NGW), vn);
;         const int mr = row < ML ? (row >> 11) : 8;
;         const float* sh = which == 0 ? modp(F, l, mr, 3) : modp(F, l + 1 < NL ? l + 1 : l, mr, 0);
;         const float* sc = which == 0 ? modp(F, l, mr, 4) : modp(F, l + 1 < NL ? l + 1 : l, mr, 1);
	v_add_f32_e32 v9, v9, v91
	v_add_f32_e32 v90, v90, v92
	ds_bpermute_b32 v91, v4, v9
	ds_bpermute_b32 v92, v4, v90
	s_waitcnt lgkmcnt(0)
	v_add_f32_e32 v9, v9, v91
	v_add_f32_e32 v90, v90, v92
	ds_bpermute_b32 v91, v5, v9
	ds_bpermute_b32 v92, v5, v90
	s_waitcnt lgkmcnt(0)
	v_add_f32_e32 v9, v9, v91
	v_add_f32_e32 v90, v90, v92
	ds_bpermute_b32 v91, v6, v9
	ds_bpermute_b32 v92, v6, v90
	s_waitcnt lgkmcnt(0)
	v_add_f32_e32 v9, v9, v91
	v_add_f32_e32 v90, v90, v92
	ds_bpermute_b32 v91, v7, v9
	ds_bpermute_b32 v92, v7, v90
	s_waitcnt lgkmcnt(0)
	v_add_f32_e32 v9, v9, v91
	v_add_f32_e32 v90, v90, v92
	ds_bpermute_b32 v91, v8, v9
	ds_bpermute_b32 v92, v8, v90
	s_waitcnt lgkmcnt(0)
	v_add_f32_e32 v9, v9, v91
	v_add_f32_e32 v90, v90, v92
	v_mul_f32_e32 v93, 0x3a800000, v9
	v_mul_f32_e32 v91, 0x3a800000, v90
	v_fma_f32 v91, -v93, v93, v91
	v_max_f32_e32 v91, 0, v91
	v_add_f32_e32 v91, 0x358637bd, v91
	v_rsq_f32_e32 v94, v91
	v_mul_f32_e32 v91, 0.5, v91
	v_mul_f32_e32 v92, v94, v94
	v_fma_f32 v92, -v91, v92, 0.5
	v_fma_f32 v94, v94, v92, v94
	s_waitcnt vmcnt(18)
	v_sub_f32_e32 v42, v42, v93
	v_sub_f32_e32 v43, v43, v93
	v_sub_f32_e32 v44, v44, v93
	v_sub_f32_e32 v45, v45, v93
	v_sub_f32_e32 v46, v46, v93
	v_sub_f32_e32 v47, v47, v93
	v_sub_f32_e32 v48, v48, v93
	v_sub_f32_e32 v49, v49, v93
	v_sub_f32_e32 v50, v50, v93
	v_sub_f32_e32 v51, v51, v93
	v_sub_f32_e32 v52, v52, v93
	v_sub_f32_e32 v53, v53, v93
	v_sub_f32_e32 v54, v54, v93
	v_sub_f32_e32 v55, v55, v93
	v_sub_f32_e32 v56, v56, v93
	v_sub_f32_e32 v57, v57, v93
	v_add_f32_e32 v130, 1.0, v130
	v_add_f32_e32 v131, 1.0, v131
	v_add_f32_e32 v132, 1.0, v132
	v_add_f32_e32 v133, 1.0, v133
	v_add_f32_e32 v134, 1.0, v134
	v_add_f32_e32 v135, 1.0, v135
	v_add_f32_e32 v136, 1.0, v136
	v_add_f32_e32 v137, 1.0, v137
	v_add_f32_e32 v138, 1.0, v138
	v_add_f32_e32 v139, 1.0, v139
	v_add_f32_e32 v140, 1.0, v140
	v_add_f32_e32 v141, 1.0, v141
	v_add_f32_e32 v142, 1.0, v142
	v_add_f32_e32 v143, 1.0, v143
	v_add_f32_e32 v144, 1.0, v144
	v_add_f32_e32 v145, 1.0, v145
	v_mul_f32_e32 v42, v94, v42
	v_mul_f32_e32 v43, v94, v43
	v_mul_f32_e32 v44, v94, v44
	v_mul_f32_e32 v45, v94, v45
	v_mul_f32_e32 v46, v94, v46
	v_mul_f32_e32 v47, v94, v47
	v_mul_f32_e32 v48, v94, v48
	v_mul_f32_e32 v49, v94, v49
	v_mul_f32_e32 v50, v94, v50
	v_mul_f32_e32 v51, v94, v51
	v_mul_f32_e32 v52, v94, v52
	v_mul_f32_e32 v53, v94, v53
	v_mul_f32_e32 v54, v94, v54
	v_mul_f32_e32 v55, v94, v55
	v_mul_f32_e32 v56, v94, v56
	v_mul_f32_e32 v57, v94, v57
	v_fma_f32 v42, v42, v130, v114
	v_fma_f32 v43, v43, v131, v115
	v_fma_f32 v44, v44, v132, v116
	v_fma_f32 v45, v45, v133, v117
	v_fma_f32 v46, v46, v134, v118
	v_fma_f32 v47, v47, v135, v119
	v_fma_f32 v48, v48, v136, v120
	v_fma_f32 v49, v49, v137, v121
	v_fma_f32 v50, v50, v138, v122
	v_fma_f32 v51, v51, v139, v123
	v_fma_f32 v52, v52, v140, v124
	v_fma_f32 v53, v53, v141, v125
	v_fma_f32 v54, v54, v142, v126
	v_fma_f32 v55, v55, v143, v127
	v_fma_f32 v56, v56, v144, v128
	v_fma_f32 v57, v57, v145, v129
	v_cvt_pk_bf16_f32 v190, v42, v43
	v_cvt_pk_bf16_f32 v191, v44, v45
	v_cvt_pk_bf16_f32 v192, v46, v47
	v_cvt_pk_bf16_f32 v193, v48, v49
	v_cvt_pk_bf16_f32 v194, v50, v51
	v_cvt_pk_bf16_f32 v195, v52, v53
	v_cvt_pk_bf16_f32 v196, v54, v55
	v_cvt_pk_bf16_f32 v197, v56, v57
	s_add_u32 s2, s10, 0x1000000
	s_addc_u32 s3, s11, 0
	global_store_dwordx2 v1, v[190:191], s[2:3]
	global_store_dwordx2 v1, v[192:193], s[2:3] offset:512
	global_store_dwordx2 v1, v[194:195], s[2:3] offset:1024
	global_store_dwordx2 v1, v[196:197], s[2:3] offset:1536
	s_add_u32 s2, s14, 0x24000
	s_addc_u32 s3, s15, 0
	global_load_dwordx4 v[114:117], v0, s[2:3]
	global_load_dwordx4 v[118:121], v0, s[2:3] offset:1024
	global_load_dwordx4 v[122:125], v0, s[2:3] offset:2048
	global_load_dwordx4 v[126:129], v0, s[2:3] offset:3072
	s_add_u32 s2, s18, 0x24000
	s_addc_u32 s3, s19, 0
	global_load_dwordx4 v[130:133], v0, s[2:3]
	global_load_dwordx4 v[134:137], v0, s[2:3] offset:1024
	global_load_dwordx4 v[138:141], v0, s[2:3] offset:2048
	global_load_dwordx4 v[142:145], v0, s[2:3] offset:3072
	v_add_f32_e32 v9, v58, v59
	v_add_f32_e32 v91, v60, v61
	v_mul_f32_e32 v90, v58, v58
	v_mul_f32_e32 v92, v59, v59
	v_add_f32_e32 v9, v9, v62
	v_add_f32_e32 v91, v91, v63
	v_add_f32_e32 v9, v9, v64
	v_add_f32_e32 v91, v91, v65
	v_add_f32_e32 v9, v9, v66
	v_add_f32_e32 v91, v91, v67
	v_add_f32_e32 v9, v9, v68
	v_add_f32_e32 v91, v91, v69
	v_add_f32_e32 v9, v9, v70
	v_add_f32_e32 v91, v91, v71
	v_add_f32_e32 v9, v9, v72
	v_add_f32_e32 v91, v91, v73
	v_fmac_f32_e32 v90, v60, v60
	v_fmac_f32_e32 v92, v61, v61
	v_fmac_f32_e32 v90, v62, v62
	v_fmac_f32_e32 v92, v63, v63
	v_fmac_f32_e32 v90, v64, v64
	v_fmac_f32_e32 v92, v65, v65
	v_fmac_f32_e32 v90, v66, v66
	v_fmac_f32_e32 v92, v67, v67
	v_fmac_f32_e32 v90, v68, v68
	v_fmac_f32_e32 v92, v69, v69
	v_fmac_f32_e32 v90, v70, v70
	v_fmac_f32_e32 v92, v71, v71
	v_fmac_f32_e32 v90, v72, v72
	v_fmac_f32_e32 v92, v73, v73
	v_add_f32_e32 v9, v9, v91
	v_add_f32_e32 v90, v90, v92
	ds_bpermute_b32 v91, v3, v9
	ds_bpermute_b32 v92, v3, v90
	s_waitcnt lgkmcnt(0)
	v_add_f32_e32 v9, v9, v91
	v_add_f32_e32 v90, v90, v92
	ds_bpermute_b32 v91, v4, v9
	ds_bpermute_b32 v92, v4, v90
	s_waitcnt lgkmcnt(0)
	v_add_f32_e32 v9, v9, v91
	v_add_f32_e32 v90, v90, v92
	ds_bpermute_b32 v91, v5, v9
	ds_bpermute_b32 v92, v5, v90
	s_waitcnt lgkmcnt(0)
	v_add_f32_e32 v9, v9, v91
	v_add_f32_e32 v90, v90, v92
	ds_bpermute_b32 v91, v6, v9
	ds_bpermute_b32 v92, v6, v90
	s_waitcnt lgkmcnt(0)
	v_add_f32_e32 v9, v9, v91
	v_add_f32_e32 v90, v90, v92
	ds_bpermute_b32 v91, v7, v9
	ds_bpermute_b32 v92, v7, v90
	s_waitcnt lgkmcnt(0)
; DI unsigned pk2(float lo, float hi) { f32x2 v = {lo, hi}; bf16x2_t b = __builtin_convertvector(v, bf16x2_t); return __builtin_bit_cast(unsigned, b); }
; DI void ln_row_v(const Frame& F, f32x4 (&v)[4], float* xout, const float* g, const float* b, const float* sh, const float* sc, bf16_t* hout, const float* slab, const float* gres, float* stat = nullptr) {
;     ...
;         float s = 0.f, s2 = 0.f;
; #pragma unroll
;         for (int j = 0; j < 4; ++j) { s += (v[j][0] + v[j][1]) + (v[j][2] + v[j][3]); s2 += (v[j][0] * v[j][0] + v[j][1] * v[j][1]) + (v[j][2] * v[j][2] + v[j][3] * v[j][3]); }
;         wave_sum2(s, s2, F.lane);
;         const float mean = s * (1.f / D); const float rstd = 1.f / sqrtf(fmaxf(s2 * (1.f / D) - mean * mean, 0.f) + EPS);
;         if (stat && F.lane == 0) { f32x2 sv = {mean, rstd}; *(f32x2*)stat = sv; }
; #pragma unroll
;         for (int j = 0; j < 4; ++j) { const f32x4 gg = ((const f32x4*)g)[F.lane + 64 * j], bb = ((const f32x4*)b)[F.lane + 64 * j];
;             v[j] = (v[j] - mean) * rstd * gg + bb; if (xout) ((f32x4*)xout)[F.lane + 64 * j] = v[j]; }
;     }
;     if (hout) {
;         float s = 0.f, s2 = 0.f;
; #pragma unroll
;         for (int j = 0; j < 4; ++j) { s += (v[j][0] + v[j][1]) + (v[j][2] + v[j][3]); s2 += (v[j][0] * v[j][0] + v[j][1] * v[j][1]) + (v[j][2] * v[j][2] + v[j][3] * v[j][3]); }
;         wave_sum2(s, s2, F.lane);
;         const float mean = s * (1.f / D); const float rstd = 1.f / sqrtf(fmaxf(s2 * (1.f / D) - mean * mean, 0.f) + EPS);
; #pragma unroll
;         for (int j = 0; j < 4; ++j) { const f32x4 hh = ((const f32x4*)sh)[F.lane + 64 * j], cc = ((const f32x4*)sc)[F.lane + 64 * j];
;             const f32x4 o = (v[j] - mean) * rstd * (cc + 1.f) + hh; u32x2 wv; wv.x = pk2(o[0], o[1]); wv.y = pk2(o[2], o[3]);
	v_add_f32_e32 v9, v9, v91
	v_add_f32_e32 v90, v90, v92
	ds_bpermute_b32 v91, v8, v9
	ds_bpermute_b32 v92, v8, v90
	s_waitcnt lgkmcnt(0)
	v_add_f32_e32 v9, v9, v91
	v_add_f32_e32 v90, v90, v92
	v_mul_f32_e32 v93, 0x3a800000, v9
	v_mul_f32_e32 v91, 0x3a800000, v90
	v_fma_f32 v91, -v93, v93, v91
	v_max_f32_e32 v91, 0, v91
	v_add_f32_e32 v91, 0x358637bd, v91
	v_rsq_f32_e32 v94, v91
	v_mul_f32_e32 v91, 0.5, v91
	v_mul_f32_e32 v92, v94, v94
	v_fma_f32 v92, -v91, v92, 0.5
	v_fma_f32 v94, v94, v92, v94
	s_add_u32 s2, s12, 0x14000
	s_addc_u32 s3, s13, 0
	v_mov_b32_e32 v188, v93
	v_mov_b32_e32 v189, v94
	s_mov_b64 exec, 1
	global_store_dwordx2 v97, v[188:189], s[2:3]
	s_mov_b64 exec, -1
	v_sub_f32_e32 v58, v58, v93
	v_sub_f32_e32 v59, v59, v93
	v_sub_f32_e32 v60, v60, v93
	v_sub_f32_e32 v61, v61, v93
	v_sub_f32_e32 v62, v62, v93
	v_sub_f32_e32 v63, v63, v93
	v_sub_f32_e32 v64, v64, v93
	v_sub_f32_e32 v65, v65, v93
	v_sub_f32_e32 v66, v66, v93
	v_sub_f32_e32 v67, v67, v93
	v_sub_f32_e32 v68, v68, v93
	v_sub_f32_e32 v69, v69, v93
	v_sub_f32_e32 v70, v70, v93
	v_sub_f32_e32 v71, v71, v93
	v_sub_f32_e32 v72, v72, v93
	v_sub_f32_e32 v73, v73, v93
	v_mul_f32_e32 v58, v94, v58
	v_mul_f32_e32 v59, v94, v59
	v_mul_f32_e32 v60, v94, v60
	v_mul_f32_e32 v61, v94, v61
	v_mul_f32_e32 v62, v94, v62
	v_mul_f32_e32 v63, v94, v63
	v_mul_f32_e32 v64, v94, v64
	v_mul_f32_e32 v65, v94, v65
	v_mul_f32_e32 v66, v94, v66
	v_mul_f32_e32 v67, v94, v67
	v_mul_f32_e32 v68, v94, v68
	v_mul_f32_e32 v69, v94, v69
	v_mul_f32_e32 v70, v94, v70
	v_mul_f32_e32 v71, v94, v71
	v_mul_f32_e32 v72, v94, v72
	v_mul_f32_e32 v73, v94, v73
	v_fma_f32 v58, v58, v10, v26
	v_fma_f32 v59, v59, v11, v27
	v_fma_f32 v60, v60, v12, v28
	v_fma_f32 v61, v61, v13, v29
	v_fma_f32 v62, v62, v14, v30
	v_fma_f32 v63, v63, v15, v31
	v_fma_f32 v64, v64, v16, v32
	v_fma_f32 v65, v65, v17, v33
	v_fma_f32 v66, v66, v18, v34
	v_fma_f32 v67, v67, v19, v35
	v_fma_f32 v68, v68, v20, v36
	v_fma_f32 v69, v69, v21, v37
	v_fma_f32 v70, v70, v22, v38
	v_fma_f32 v71, v71, v23, v39
	v_fma_f32 v72, v72, v24, v40
	v_fma_f32 v73, v73, v25, v41
	v_add_f32_e32 v9, v58, v59
	v_add_f32_e32 v91, v60, v61
	v_mul_f32_e32 v90, v58, v58
	v_mul_f32_e32 v92, v59, v59
	v_add_f32_e32 v9, v9, v62
	v_add_f32_e32 v91, v91, v63
	v_add_f32_e32 v9, v9, v64
	v_add_f32_e32 v91, v91, v65
	v_add_f32_e32 v9, v9, v66
	v_add_f32_e32 v91, v91, v67
	v_add_f32_e32 v9, v9, v68
	v_add_f32_e32 v91, v91, v69
	v_add_f32_e32 v9, v9, v70
	v_add_f32_e32 v91, v91, v71
	v_add_f32_e32 v9, v9, v72
	v_add_f32_e32 v91, v91, v73
	v_fmac_f32_e32 v90, v60, v60
	v_fmac_f32_e32 v92, v61, v61
	v_fmac_f32_e32 v90, v62, v62
	v_fmac_f32_e32 v92, v63, v63
	v_fmac_f32_e32 v90, v64, v64
	v_fmac_f32_e32 v92, v65, v65
	v_fmac_f32_e32 v90, v66, v66
	v_fmac_f32_e32 v92, v67, v67
	v_fmac_f32_e32 v90, v68, v68
	v_fmac_f32_e32 v92, v69, v69
	v_fmac_f32_e32 v90, v70, v70
	v_fmac_f32_e32 v92, v71, v71
	v_fmac_f32_e32 v90, v72, v72
	v_fmac_f32_e32 v92, v73, v73
	v_add_f32_e32 v9, v9, v91
	v_add_f32_e32 v90, v90, v92
	ds_bpermute_b32 v91, v3, v9
	ds_bpermute_b32 v92, v3, v90
	s_waitcnt lgkmcnt(0)
	v_add_f32_e32 v9, v9, v91
	v_add_f32_e32 v90, v90, v92
	ds_bpermute_b32 v91, v4, v9
	ds_bpermute_b32 v92, v4, v90
	s_waitcnt lgkmcnt(0)
	v_add_f32_e32 v9, v9, v91
	v_add_f32_e32 v90, v90, v92
	ds_bpermute_b32 v91, v5, v9
	ds_bpermute_b32 v92, v5, v90
	s_waitcnt lgkmcnt(0)
	v_add_f32_e32 v9, v9, v91
	v_add_f32_e32 v90, v90, v92
	ds_bpermute_b32 v91, v6, v9
	ds_bpermute_b32 v92, v6, v90
	s_waitcnt lgkmcnt(0)
	v_add_f32_e32 v9, v9, v91
	v_add_f32_e32 v90, v90, v92
	ds_bpermute_b32 v91, v7, v9
	ds_bpermute_b32 v92, v7, v90
	s_waitcnt lgkmcnt(0)
	v_add_f32_e32 v9, v9, v91
	v_add_f32_e32 v90, v90, v92
	ds_bpermute_b32 v91, v8, v9
	ds_bpermute_b32 v92, v8, v90
	s_waitcnt lgkmcnt(0)
	v_add_f32_e32 v9, v9, v91
	v_add_f32_e32 v90, v90, v92
	v_mul_f32_e32 v93, 0x3a800000, v9
	v_mul_f32_e32 v91, 0x3a800000, v90
	v_fma_f32 v91, -v93, v93, v91
	v_max_f32_e32 v91, 0, v91
	v_add_f32_e32 v91, 0x358637bd, v91
	v_rsq_f32_e32 v94, v91
	v_mul_f32_e32 v91, 0.5, v91
	v_mul_f32_e32 v92, v94, v94
	v_fma_f32 v92, -v91, v92, 0.5
	v_fma_f32 v94, v94, v92, v94
	s_waitcnt vmcnt(14)
	v_sub_f32_e32 v58, v58, v93
	v_sub_f32_e32 v59, v59, v93
	v_sub_f32_e32 v60, v60, v93
	v_sub_f32_e32 v61, v61, v93
	v_sub_f32_e32 v62, v62, v93
	v_sub_f32_e32 v63, v63, v93
	v_sub_f32_e32 v64, v64, v93
	v_sub_f32_e32 v65, v65, v93
	v_sub_f32_e32 v66, v66, v93
	v_sub_f32_e32 v67, v67, v93
	v_sub_f32_e32 v68, v68, v93
	v_sub_f32_e32 v69, v69, v93
	v_sub_f32_e32 v70, v70, v93
	v_sub_f32_e32 v71, v71, v93
	v_sub_f32_e32 v72, v72, v93
	v_sub_f32_e32 v73, v73, v93
	v_add_f32_e32 v162, 1.0, v162
	v_add_f32_e32 v163, 1.0, v163
	v_add_f32_e32 v164, 1.0, v164
	v_add_f32_e32 v165, 1.0, v165
	v_add_f32_e32 v166, 1.0, v166
	v_add_f32_e32 v167, 1.0, v167
	v_add_f32_e32 v168, 1.0, v168
	v_add_f32_e32 v169, 1.0, v169
	v_add_f32_e32 v170, 1.0, v170
	v_add_f32_e32 v171, 1.0, v171
	v_add_f32_e32 v172, 1.0, v172
	v_add_f32_e32 v173, 1.0, v173
	v_add_f32_e32 v174, 1.0, v174
	v_add_f32_e32 v175, 1.0, v175
	v_add_f32_e32 v176, 1.0, v176
	v_add_f32_e32 v177, 1.0, v177
	v_mul_f32_e32 v58, v94, v58
	v_mul_f32_e32 v59, v94, v59
	v_mul_f32_e32 v60, v94, v60
	v_mul_f32_e32 v61, v94, v61
	v_mul_f32_e32 v62, v94, v62
	v_mul_f32_e32 v63, v94, v63
	v_mul_f32_e32 v64, v94, v64
	v_mul_f32_e32 v65, v94, v65
	v_mul_f32_e32 v66, v94, v66
	v_mul_f32_e32 v67, v94, v67
	v_mul_f32_e32 v68, v94, v68
	v_mul_f32_e32 v69, v94, v69
	v_mul_f32_e32 v70, v94, v70
	v_mul_f32_e32 v71, v94, v71
	v_mul_f32_e32 v72, v94, v72
	v_mul_f32_e32 v73, v94, v73
	v_fma_f32 v58, v58, v162, v146
; DI unsigned pk2(float lo, float hi) { f32x2 v = {lo, hi}; bf16x2_t b = __builtin_convertvector(v, bf16x2_t); return __builtin_bit_cast(unsigned, b); }
; DI void ln_row_v(const Frame& F, f32x4 (&v)[4], float* xout, const float* g, const float* b, const float* sh, const float* sc, bf16_t* hout, const float* slab, const float* gres, float* stat = nullptr) {
;     ...
;         float s = 0.f, s2 = 0.f;
; #pragma unroll
;         for (int j = 0; j < 4; ++j) { s += (v[j][0] + v[j][1]) + (v[j][2] + v[j][3]); s2 += (v[j][0] * v[j][0] + v[j][1] * v[j][1]) + (v[j][2] * v[j][2] + v[j][3] * v[j][3]); }
;         wave_sum2(s, s2, F.lane);
;         const float mean = s * (1.f / D); const float rstd = 1.f / sqrtf(fmaxf(s2 * (1.f / D) - mean * mean, 0.f) + EPS);
;         if (stat && F.lane == 0) { f32x2 sv = {mean, rstd}; *(f32x2*)stat = sv; }
; #pragma unroll
;         for (int j = 0; j < 4; ++j) { const f32x4 gg = ((const f32x4*)g)[F.lane + 64 * j], bb = ((const f32x4*)b)[F.lane + 64 * j];
;             v[j] = (v[j] - mean) * rstd * gg + bb; if (xout) ((f32x4*)xout)[F.lane + 64 * j] = v[j]; }
;     ...
;         for (int j = 0; j < 4; ++j) { const f32x4 hh = ((const f32x4*)sh)[F.lane + 64 * j], cc = ((const f32x4*)sc)[F.lane + 64 * j];
;             const f32x4 o = (v[j] - mean) * rstd * (cc + 1.f) + hh; u32x2 wv; wv.x = pk2(o[0], o[1]); wv.y = pk2(o[2], o[3]);
;             ((u32x2*)hout)[F.lane + 64 * j] = wv; }
	v_fma_f32 v59, v59, v163, v147
	v_fma_f32 v60, v60, v164, v148
	v_fma_f32 v61, v61, v165, v149
	v_fma_f32 v62, v62, v166, v150
	v_fma_f32 v63, v63, v167, v151
	v_fma_f32 v64, v64, v168, v152
	v_fma_f32 v65, v65, v169, v153
	v_fma_f32 v66, v66, v170, v154
	v_fma_f32 v67, v67, v171, v155
	v_fma_f32 v68, v68, v172, v156
	v_fma_f32 v69, v69, v173, v157
	v_fma_f32 v70, v70, v174, v158
	v_fma_f32 v71, v71, v175, v159
	v_fma_f32 v72, v72, v176, v160
	v_fma_f32 v73, v73, v177, v161
	v_cvt_pk_bf16_f32 v190, v58, v59
	v_cvt_pk_bf16_f32 v191, v60, v61
	v_cvt_pk_bf16_f32 v192, v62, v63
	v_cvt_pk_bf16_f32 v193, v64, v65
	v_cvt_pk_bf16_f32 v194, v66, v67
	v_cvt_pk_bf16_f32 v195, v68, v69
	v_cvt_pk_bf16_f32 v196, v70, v71
	v_cvt_pk_bf16_f32 v197, v72, v73
	s_add_u32 s2, s10, 0x1400000
	s_addc_u32 s3, s11, 0
	global_store_dwordx2 v1, v[190:191], s[2:3]
	global_store_dwordx2 v1, v[192:193], s[2:3] offset:512
	global_store_dwordx2 v1, v[194:195], s[2:3] offset:1024
	global_store_dwordx2 v1, v[196:197], s[2:3] offset:1536
	s_add_u32 s2, s14, 0x2a000
	s_addc_u32 s3, s15, 0
	global_load_dwordx4 v[146:149], v0, s[2:3]
	global_load_dwordx4 v[150:153], v0, s[2:3] offset:1024
	global_load_dwordx4 v[154:157], v0, s[2:3] offset:2048
	global_load_dwordx4 v[158:161], v0, s[2:3] offset:3072
	s_add_u32 s2, s18, 0x2a000
	s_addc_u32 s3, s19, 0
	global_load_dwordx4 v[162:165], v0, s[2:3]
	global_load_dwordx4 v[166:169], v0, s[2:3] offset:1024
	global_load_dwordx4 v[170:173], v0, s[2:3] offset:2048
	global_load_dwordx4 v[174:177], v0, s[2:3] offset:3072
	v_add_f32_e32 v9, v74, v75
	v_add_f32_e32 v91, v76, v77
	v_mul_f32_e32 v90, v74, v74
	v_mul_f32_e32 v92, v75, v75
	v_add_f32_e32 v9, v9, v78
	v_add_f32_e32 v91, v91, v79
	v_add_f32_e32 v9, v9, v80
	v_add_f32_e32 v91, v91, v81
	v_add_f32_e32 v9, v9, v82
	v_add_f32_e32 v91, v91, v83
	v_add_f32_e32 v9, v9, v84
	v_add_f32_e32 v91, v91, v85
	v_add_f32_e32 v9, v9, v86
	v_add_f32_e32 v91, v91, v87
	v_add_f32_e32 v9, v9, v88
	v_add_f32_e32 v91, v91, v89
	v_fmac_f32_e32 v90, v76, v76
	v_fmac_f32_e32 v92, v77, v77
	v_fmac_f32_e32 v90, v78, v78
	v_fmac_f32_e32 v92, v79, v79
	v_fmac_f32_e32 v90, v80, v80
	v_fmac_f32_e32 v92, v81, v81
	v_fmac_f32_e32 v90, v82, v82
	v_fmac_f32_e32 v92, v83, v83
	v_fmac_f32_e32 v90, v84, v84
	v_fmac_f32_e32 v92, v85, v85
	v_fmac_f32_e32 v90, v86, v86
	v_fmac_f32_e32 v92, v87, v87
	v_fmac_f32_e32 v90, v88, v88
	v_fmac_f32_e32 v92, v89, v89
	v_add_f32_e32 v9, v9, v91
	v_add_f32_e32 v90, v90, v92
	ds_bpermute_b32 v91, v3, v9
	ds_bpermute_b32 v92, v3, v90
	s_waitcnt lgkmcnt(0)
	v_add_f32_e32 v9, v9, v91
	v_add_f32_e32 v90, v90, v92
	ds_bpermute_b32 v91, v4, v9
	ds_bpermute_b32 v92, v4, v90
	s_waitcnt lgkmcnt(0)
	v_add_f32_e32 v9, v9, v91
	v_add_f32_e32 v90, v90, v92
	ds_bpermute_b32 v91, v5, v9
	ds_bpermute_b32 v92, v5, v90
	s_waitcnt lgkmcnt(0)
	v_add_f32_e32 v9, v9, v91
	v_add_f32_e32 v90, v90, v92
	ds_bpermute_b32 v91, v6, v9
	ds_bpermute_b32 v92, v6, v90
	s_waitcnt lgkmcnt(0)
	v_add_f32_e32 v9, v9, v91
	v_add_f32_e32 v90, v90, v92
	ds_bpermute_b32 v91, v7, v9
	ds_bpermute_b32 v92, v7, v90
	s_waitcnt lgkmcnt(0)
	v_add_f32_e32 v9, v9, v91
	v_add_f32_e32 v90, v90, v92
	ds_bpermute_b32 v91, v8, v9
	ds_bpermute_b32 v92, v8, v90
	s_waitcnt lgkmcnt(0)
	v_add_f32_e32 v9, v9, v91
	v_add_f32_e32 v90, v90, v92
	v_mul_f32_e32 v93, 0x3a800000, v9
	v_mul_f32_e32 v91, 0x3a800000, v90
	v_fma_f32 v91, -v93, v93, v91
	v_max_f32_e32 v91, 0, v91
	v_add_f32_e32 v91, 0x358637bd, v91
	v_rsq_f32_e32 v94, v91
	v_mul_f32_e32 v91, 0.5, v91
	v_mul_f32_e32 v92, v94, v94
	v_fma_f32 v92, -v91, v92, 0.5
	v_fma_f32 v94, v94, v92, v94
	s_add_u32 s2, s12, 0x18000
	s_addc_u32 s3, s13, 0
	v_mov_b32_e32 v188, v93
	v_mov_b32_e32 v189, v94
	s_mov_b64 exec, 1
	global_store_dwordx2 v97, v[188:189], s[2:3]
	s_mov_b64 exec, -1
	v_sub_f32_e32 v74, v74, v93
	v_sub_f32_e32 v75, v75, v93
	v_sub_f32_e32 v76, v76, v93
	v_sub_f32_e32 v77, v77, v93
	v_sub_f32_e32 v78, v78, v93
	v_sub_f32_e32 v79, v79, v93
	v_sub_f32_e32 v80, v80, v93
	v_sub_f32_e32 v81, v81, v93
	v_sub_f32_e32 v82, v82, v93
	v_sub_f32_e32 v83, v83, v93
	v_sub_f32_e32 v84, v84, v93
	v_sub_f32_e32 v85, v85, v93
	v_sub_f32_e32 v86, v86, v93
	v_sub_f32_e32 v87, v87, v93
	v_sub_f32_e32 v88, v88, v93
	v_sub_f32_e32 v89, v89, v93
	v_mul_f32_e32 v74, v94, v74
	v_mul_f32_e32 v75, v94, v75
	v_mul_f32_e32 v76, v94, v76
	v_mul_f32_e32 v77, v94, v77
	v_mul_f32_e32 v78, v94, v78
	v_mul_f32_e32 v79, v94, v79
	v_mul_f32_e32 v80, v94, v80
	v_mul_f32_e32 v81, v94, v81
	v_mul_f32_e32 v82, v94, v82
	v_mul_f32_e32 v83, v94, v83
	v_mul_f32_e32 v84, v94, v84
	v_mul_f32_e32 v85, v94, v85
	v_mul_f32_e32 v86, v94, v86
	v_mul_f32_e32 v87, v94, v87
	v_mul_f32_e32 v88, v94, v88
	v_mul_f32_e32 v89, v94, v89
	v_fma_f32 v74, v74, v10, v26
	v_fma_f32 v75, v75, v11, v27
	v_fma_f32 v76, v76, v12, v28
	v_fma_f32 v77, v77, v13, v29
	v_fma_f32 v78, v78, v14, v30
	v_fma_f32 v79, v79, v15, v31
	v_fma_f32 v80, v80, v16, v32
	v_fma_f32 v81, v81, v17, v33
	v_fma_f32 v82, v82, v18, v34
	v_fma_f32 v83, v83, v19, v35
	v_fma_f32 v84, v84, v20, v36
	v_fma_f32 v85, v85, v21, v37
	v_fma_f32 v86, v86, v22, v38
	v_fma_f32 v87, v87, v23, v39
	v_fma_f32 v88, v88, v24, v40
	v_fma_f32 v89, v89, v25, v41
	v_add_f32_e32 v9, v74, v75
	v_add_f32_e32 v91, v76, v77
	v_mul_f32_e32 v90, v74, v74
	v_mul_f32_e32 v92, v75, v75
	v_add_f32_e32 v9, v9, v78
	v_add_f32_e32 v91, v91, v79
	v_add_f32_e32 v9, v9, v80
	v_add_f32_e32 v91, v91, v81
	v_add_f32_e32 v9, v9, v82
	v_add_f32_e32 v91, v91, v83
	v_add_f32_e32 v9, v9, v84
	v_add_f32_e32 v91, v91, v85
	v_add_f32_e32 v9, v9, v86
	v_add_f32_e32 v91, v91, v87
	v_add_f32_e32 v9, v9, v88
	v_add_f32_e32 v91, v91, v89
	v_fmac_f32_e32 v90, v76, v76
	v_fmac_f32_e32 v92, v77, v77
	v_fmac_f32_e32 v90, v78, v78
	v_fmac_f32_e32 v92, v79, v79
	v_fmac_f32_e32 v90, v80, v80
	v_fmac_f32_e32 v92, v81, v81
	v_fmac_f32_e32 v90, v82, v82
	v_fmac_f32_e32 v92, v83, v83
	v_fmac_f32_e32 v90, v84, v84
	v_fmac_f32_e32 v92, v85, v85
	v_fmac_f32_e32 v90, v86, v86
	v_fmac_f32_e32 v92, v87, v87
	v_fmac_f32_e32 v90, v88, v88
	v_fmac_f32_e32 v92, v89, v89
	v_add_f32_e32 v9, v9, v91
	v_add_f32_e32 v90, v90, v92
	ds_bpermute_b32 v91, v3, v9
	ds_bpermute_b32 v92, v3, v90
	s_waitcnt lgkmcnt(0)
; DI unsigned pk2(float lo, float hi) { f32x2 v = {lo, hi}; bf16x2_t b = __builtin_convertvector(v, bf16x2_t); return __builtin_bit_cast(unsigned, b); }
; DI void ln_row_v(const Frame& F, f32x4 (&v)[4], float* xout, const float* g, const float* b, const float* sh, const float* sc, bf16_t* hout, const float* slab, const float* gres, float* stat = nullptr) {
;     ...
;         float s = 0.f, s2 = 0.f;
; #pragma unroll
;         for (int j = 0; j < 4; ++j) { s += (v[j][0] + v[j][1]) + (v[j][2] + v[j][3]); s2 += (v[j][0] * v[j][0] + v[j][1] * v[j][1]) + (v[j][2] * v[j][2] + v[j][3] * v[j][3]); }
;         wave_sum2(s, s2, F.lane);
;     ...
;         float s = 0.f, s2 = 0.f;
; #pragma unroll
;         for (int j = 0; j < 4; ++j) { s += (v[j][0] + v[j][1]) + (v[j][2] + v[j][3]); s2 += (v[j][0] * v[j][0] + v[j][1] * v[j][1]) + (v[j][2] * v[j][2] + v[j][3] * v[j][3]); }
;         wave_sum2(s, s2, F.lane);
;         const float mean = s * (1.f / D); const float rstd = 1.f / sqrtf(fmaxf(s2 * (1.f / D) - mean * mean, 0.f) + EPS);
; #pragma unroll
;         for (int j = 0; j < 4; ++j) { const f32x4 hh = ((const f32x4*)sh)[F.lane + 64 * j], cc = ((const f32x4*)sc)[F.lane + 64 * j];
;             const f32x4 o = (v[j] - mean) * rstd * (cc + 1.f) + hh; u32x2 wv; wv.x = pk2(o[0], o[1]); wv.y = pk2(o[2], o[3]);
;             ((u32x2*)hout)[F.lane + 64 * j] = wv; }
	v_add_f32_e32 v9, v9, v91
	v_add_f32_e32 v90, v90, v92
	ds_bpermute_b32 v91, v4, v9
	ds_bpermute_b32 v92, v4, v90
	s_waitcnt lgkmcnt(0)
	v_add_f32_e32 v9, v9, v91
	v_add_f32_e32 v90, v90, v92
	ds_bpermute_b32 v91, v5, v9
	ds_bpermute_b32 v92, v5, v90
	s_waitcnt lgkmcnt(0)
	v_add_f32_e32 v9, v9, v91
	v_add_f32_e32 v90, v90, v92
	ds_bpermute_b32 v91, v6, v9
	ds_bpermute_b32 v92, v6, v90
	s_waitcnt lgkmcnt(0)
	v_add_f32_e32 v9, v9, v91
	v_add_f32_e32 v90, v90, v92
	ds_bpermute_b32 v91, v7, v9
	ds_bpermute_b32 v92, v7, v90
	s_waitcnt lgkmcnt(0)
	v_add_f32_e32 v9, v9, v91
	v_add_f32_e32 v90, v90, v92
	ds_bpermute_b32 v91, v8, v9
	ds_bpermute_b32 v92, v8, v90
	s_waitcnt lgkmcnt(0)
	v_add_f32_e32 v9, v9, v91
	v_add_f32_e32 v90, v90, v92
	v_mul_f32_e32 v93, 0x3a800000, v9
	v_mul_f32_e32 v91, 0x3a800000, v90
	v_fma_f32 v91, -v93, v93, v91
	v_max_f32_e32 v91, 0, v91
	v_add_f32_e32 v91, 0x358637bd, v91
	v_rsq_f32_e32 v94, v91
	v_mul_f32_e32 v91, 0.5, v91
	v_mul_f32_e32 v92, v94, v94
	v_fma_f32 v92, -v91, v92, 0.5
	v_fma_f32 v94, v94, v92, v94
	s_waitcnt vmcnt(14)
	v_sub_f32_e32 v74, v74, v93
	v_sub_f32_e32 v75, v75, v93
	v_sub_f32_e32 v76, v76, v93
	v_sub_f32_e32 v77, v77, v93
	v_sub_f32_e32 v78, v78, v93
	v_sub_f32_e32 v79, v79, v93
	v_sub_f32_e32 v80, v80, v93
	v_sub_f32_e32 v81, v81, v93
	v_sub_f32_e32 v82, v82, v93
	v_sub_f32_e32 v83, v83, v93
	v_sub_f32_e32 v84, v84, v93
	v_sub_f32_e32 v85, v85, v93
	v_sub_f32_e32 v86, v86, v93
	v_sub_f32_e32 v87, v87, v93
	v_sub_f32_e32 v88, v88, v93
	v_sub_f32_e32 v89, v89, v93
	v_add_f32_e32 v130, 1.0, v130
	v_add_f32_e32 v131, 1.0, v131
	v_add_f32_e32 v132, 1.0, v132
	v_add_f32_e32 v133, 1.0, v133
	v_add_f32_e32 v134, 1.0, v134
	v_add_f32_e32 v135, 1.0, v135
	v_add_f32_e32 v136, 1.0, v136
	v_add_f32_e32 v137, 1.0, v137
	v_add_f32_e32 v138, 1.0, v138
	v_add_f32_e32 v139, 1.0, v139
	v_add_f32_e32 v140, 1.0, v140
	v_add_f32_e32 v141, 1.0, v141
	v_add_f32_e32 v142, 1.0, v142
	v_add_f32_e32 v143, 1.0, v143
	v_add_f32_e32 v144, 1.0, v144
	v_add_f32_e32 v145, 1.0, v145
	v_mul_f32_e32 v74, v94, v74
	v_mul_f32_e32 v75, v94, v75
	v_mul_f32_e32 v76, v94, v76
	v_mul_f32_e32 v77, v94, v77
	v_mul_f32_e32 v78, v94, v78
	v_mul_f32_e32 v79, v94, v79
	v_mul_f32_e32 v80, v94, v80
	v_mul_f32_e32 v81, v94, v81
	v_mul_f32_e32 v82, v94, v82
	v_mul_f32_e32 v83, v94, v83
	v_mul_f32_e32 v84, v94, v84
	v_mul_f32_e32 v85, v94, v85
	v_mul_f32_e32 v86, v94, v86
	v_mul_f32_e32 v87, v94, v87
	v_mul_f32_e32 v88, v94, v88
	v_mul_f32_e32 v89, v94, v89
	v_fma_f32 v74, v74, v130, v114
	v_fma_f32 v75, v75, v131, v115
	v_fma_f32 v76, v76, v132, v116
	v_fma_f32 v77, v77, v133, v117
	v_fma_f32 v78, v78, v134, v118
	v_fma_f32 v79, v79, v135, v119
	v_fma_f32 v80, v80, v136, v120
	v_fma_f32 v81, v81, v137, v121
	v_fma_f32 v82, v82, v138, v122
	v_fma_f32 v83, v83, v139, v123
	v_fma_f32 v84, v84, v140, v124
	v_fma_f32 v85, v85, v141, v125
	v_fma_f32 v86, v86, v142, v126
	v_fma_f32 v87, v87, v143, v127
	v_fma_f32 v88, v88, v144, v128
	v_fma_f32 v89, v89, v145, v129
	v_cvt_pk_bf16_f32 v190, v74, v75
	v_cvt_pk_bf16_f32 v191, v76, v77
	v_cvt_pk_bf16_f32 v192, v78, v79
	v_cvt_pk_bf16_f32 v193, v80, v81
	v_cvt_pk_bf16_f32 v194, v82, v83
	v_cvt_pk_bf16_f32 v195, v84, v85
	v_cvt_pk_bf16_f32 v196, v86, v87
	v_cvt_pk_bf16_f32 v197, v88, v89
	s_add_u32 s2, s10, 0x1800000
	s_addc_u32 s3, s11, 0
	global_store_dwordx2 v1, v[190:191], s[2:3]
	global_store_dwordx2 v1, v[192:193], s[2:3] offset:512
	global_store_dwordx2 v1, v[194:195], s[2:3] offset:1024
	global_store_dwordx2 v1, v[196:197], s[2:3] offset:1536
	v_add_f32_e32 v9, v98, v99
	v_add_f32_e32 v91, v100, v101
	v_mul_f32_e32 v90, v98, v98
	v_mul_f32_e32 v92, v99, v99
	v_add_f32_e32 v9, v9, v102
	v_add_f32_e32 v91, v91, v103
	v_add_f32_e32 v9, v9, v104
	v_add_f32_e32 v91, v91, v105
	v_add_f32_e32 v9, v9, v106
	v_add_f32_e32 v91, v91, v107
	v_add_f32_e32 v9, v9, v108
	v_add_f32_e32 v91, v91, v109
	v_add_f32_e32 v9, v9, v110
	v_add_f32_e32 v91, v91, v111
	v_add_f32_e32 v9, v9, v112
	v_add_f32_e32 v91, v91, v113
	v_fmac_f32_e32 v90, v100, v100
	v_fmac_f32_e32 v92, v101, v101
	v_fmac_f32_e32 v90, v102, v102
	v_fmac_f32_e32 v92, v103, v103
	v_fmac_f32_e32 v90, v104, v104
	v_fmac_f32_e32 v92, v105, v105
	v_fmac_f32_e32 v90, v106, v106
	v_fmac_f32_e32 v92, v107, v107
	v_fmac_f32_e32 v90, v108, v108
	v_fmac_f32_e32 v92, v109, v109
	v_fmac_f32_e32 v90, v110, v110
	v_fmac_f32_e32 v92, v111, v111
	v_fmac_f32_e32 v90, v112, v112
	v_fmac_f32_e32 v92, v113, v113
	v_add_f32_e32 v9, v9, v91
	v_add_f32_e32 v90, v90, v92
	ds_bpermute_b32 v91, v3, v9
	ds_bpermute_b32 v92, v3, v90
	s_waitcnt lgkmcnt(0)
	v_add_f32_e32 v9, v9, v91
	v_add_f32_e32 v90, v90, v92
	ds_bpermute_b32 v91, v4, v9
	ds_bpermute_b32 v92, v4, v90
	s_waitcnt lgkmcnt(0)
	v_add_f32_e32 v9, v9, v91
	v_add_f32_e32 v90, v90, v92
	ds_bpermute_b32 v91, v5, v9
	ds_bpermute_b32 v92, v5, v90
	s_waitcnt lgkmcnt(0)
	v_add_f32_e32 v9, v9, v91
	v_add_f32_e32 v90, v90, v92
	ds_bpermute_b32 v91, v6, v9
	ds_bpermute_b32 v92, v6, v90
	s_waitcnt lgkmcnt(0)
	v_add_f32_e32 v9, v9, v91
	v_add_f32_e32 v90, v90, v92
	ds_bpermute_b32 v91, v7, v9
	ds_bpermute_b32 v92, v7, v90
	s_waitcnt lgkmcnt(0)
	v_add_f32_e32 v9, v9, v91
	v_add_f32_e32 v90, v90, v92
	ds_bpermute_b32 v91, v8, v9
	ds_bpermute_b32 v92, v8, v90
	s_waitcnt lgkmcnt(0)
; DI unsigned pk2(float lo, float hi) { f32x2 v = {lo, hi}; bf16x2_t b = __builtin_convertvector(v, bf16x2_t); return __builtin_bit_cast(unsigned, b); }
; DI void ln_row_v(const Frame& F, f32x4 (&v)[4], float* xout, const float* g, const float* b, const float* sh, const float* sc, bf16_t* hout, const float* slab, const float* gres, float* stat = nullptr) {
;     ...
;         float s = 0.f, s2 = 0.f;
; #pragma unroll
;         for (int j = 0; j < 4; ++j) { s += (v[j][0] + v[j][1]) + (v[j][2] + v[j][3]); s2 += (v[j][0] * v[j][0] + v[j][1] * v[j][1]) + (v[j][2] * v[j][2] + v[j][3] * v[j][3]); }
;         wave_sum2(s, s2, F.lane);
;         const float mean = s * (1.f / D); const float rstd = 1.f / sqrtf(fmaxf(s2 * (1.f / D) - mean * mean, 0.f) + EPS);
;         if (stat && F.lane == 0) { f32x2 sv = {mean, rstd}; *(f32x2*)stat = sv; }
; #pragma unroll
;         for (int j = 0; j < 4; ++j) { const f32x4 gg = ((const f32x4*)g)[F.lane + 64 * j], bb = ((const f32x4*)b)[F.lane + 64 * j];
;             v[j] = (v[j] - mean) * rstd * gg + bb; if (xout) ((f32x4*)xout)[F.lane + 64 * j] = v[j]; }
;     }
;     if (hout) {
;         float s = 0.f, s2 = 0.f;
; #pragma unroll
;         for (int j = 0; j < 4; ++j) { s += (v[j][0] + v[j][1]) + (v[j][2] + v[j][3]); s2 += (v[j][0] * v[j][0] + v[j][1] * v[j][1]) + (v[j][2] * v[j][2] + v[j][3] * v[j][3]); }
;         wave_sum2(s, s2, F.lane);
;         const float mean = s * (1.f / D); const float rstd = 1.f / sqrtf(fmaxf(s2 * (1.f / D) - mean * mean, 0.f) + EPS);
; #pragma unroll
;         for (int j = 0; j < 4; ++j) { const f32x4 hh = ((const f32x4*)sh)[F.lane + 64 * j], cc = ((const f32x4*)sc)[F.lane + 64 * j];
;             const f32x4 o = (v[j] - mean) * rstd * (cc + 1.f) + hh; u32x2 wv; wv.x = pk2(o[0], o[1]); wv.y = pk2(o[2], o[3]);
;             ((u32x2*)hout)[F.lane + 64 * j] = wv; }
	v_add_f32_e32 v9, v9, v91
	v_add_f32_e32 v90, v90, v92
	v_mul_f32_e32 v93, 0x3a800000, v9
	v_mul_f32_e32 v91, 0x3a800000, v90
	v_fma_f32 v91, -v93, v93, v91
	v_max_f32_e32 v91, 0, v91
	v_add_f32_e32 v91, 0x358637bd, v91
	v_rsq_f32_e32 v94, v91
	v_mul_f32_e32 v91, 0.5, v91
	v_mul_f32_e32 v92, v94, v94
	v_fma_f32 v92, -v91, v92, 0.5
	v_fma_f32 v94, v94, v92, v94
	s_add_u32 s2, s12, 0x1c000
	s_addc_u32 s3, s13, 0
	v_mov_b32_e32 v188, v93
	v_mov_b32_e32 v189, v94
	s_mov_b64 exec, 1
	global_store_dwordx2 v97, v[188:189], s[2:3]
	s_mov_b64 exec, -1
	v_sub_f32_e32 v98, v98, v93
	v_sub_f32_e32 v99, v99, v93
	v_sub_f32_e32 v100, v100, v93
	v_sub_f32_e32 v101, v101, v93
	v_sub_f32_e32 v102, v102, v93
	v_sub_f32_e32 v103, v103, v93
	v_sub_f32_e32 v104, v104, v93
	v_sub_f32_e32 v105, v105, v93
	v_sub_f32_e32 v106, v106, v93
	v_sub_f32_e32 v107, v107, v93
	v_sub_f32_e32 v108, v108, v93
	v_sub_f32_e32 v109, v109, v93
	v_sub_f32_e32 v110, v110, v93
	v_sub_f32_e32 v111, v111, v93
	v_sub_f32_e32 v112, v112, v93
	v_sub_f32_e32 v113, v113, v93
	v_mul_f32_e32 v98, v94, v98
	v_mul_f32_e32 v99, v94, v99
	v_mul_f32_e32 v100, v94, v100
	v_mul_f32_e32 v101, v94, v101
	v_mul_f32_e32 v102, v94, v102
	v_mul_f32_e32 v103, v94, v103
	v_mul_f32_e32 v104, v94, v104
	v_mul_f32_e32 v105, v94, v105
	v_mul_f32_e32 v106, v94, v106
	v_mul_f32_e32 v107, v94, v107
	v_mul_f32_e32 v108, v94, v108
	v_mul_f32_e32 v109, v94, v109
	v_mul_f32_e32 v110, v94, v110
	v_mul_f32_e32 v111, v94, v111
	v_mul_f32_e32 v112, v94, v112
	v_mul_f32_e32 v113, v94, v113
	v_fma_f32 v98, v98, v10, v26
	v_fma_f32 v99, v99, v11, v27
	v_fma_f32 v100, v100, v12, v28
	v_fma_f32 v101, v101, v13, v29
	v_fma_f32 v102, v102, v14, v30
	v_fma_f32 v103, v103, v15, v31
	v_fma_f32 v104, v104, v16, v32
	v_fma_f32 v105, v105, v17, v33
	v_fma_f32 v106, v106, v18, v34
	v_fma_f32 v107, v107, v19, v35
	v_fma_f32 v108, v108, v20, v36
	v_fma_f32 v109, v109, v21, v37
	v_fma_f32 v110, v110, v22, v38
	v_fma_f32 v111, v111, v23, v39
	v_fma_f32 v112, v112, v24, v40
	v_fma_f32 v113, v113, v25, v41
	v_add_f32_e32 v9, v98, v99
	v_add_f32_e32 v91, v100, v101
	v_mul_f32_e32 v90, v98, v98
	v_mul_f32_e32 v92, v99, v99
	v_add_f32_e32 v9, v9, v102
	v_add_f32_e32 v91, v91, v103
	v_add_f32_e32 v9, v9, v104
	v_add_f32_e32 v91, v91, v105
	v_add_f32_e32 v9, v9, v106
	v_add_f32_e32 v91, v91, v107
	v_add_f32_e32 v9, v9, v108
	v_add_f32_e32 v91, v91, v109
	v_add_f32_e32 v9, v9, v110
	v_add_f32_e32 v91, v91, v111
	v_add_f32_e32 v9, v9, v112
	v_add_f32_e32 v91, v91, v113
	v_fmac_f32_e32 v90, v100, v100
	v_fmac_f32_e32 v92, v101, v101
	v_fmac_f32_e32 v90, v102, v102
	v_fmac_f32_e32 v92, v103, v103
	v_fmac_f32_e32 v90, v104, v104
	v_fmac_f32_e32 v92, v105, v105
	v_fmac_f32_e32 v90, v106, v106
	v_fmac_f32_e32 v92, v107, v107
	v_fmac_f32_e32 v90, v108, v108
	v_fmac_f32_e32 v92, v109, v109
	v_fmac_f32_e32 v90, v110, v110
	v_fmac_f32_e32 v92, v111, v111
	v_fmac_f32_e32 v90, v112, v112
	v_fmac_f32_e32 v92, v113, v113
	v_add_f32_e32 v9, v9, v91
	v_add_f32_e32 v90, v90, v92
	ds_bpermute_b32 v91, v3, v9
	ds_bpermute_b32 v92, v3, v90
	s_waitcnt lgkmcnt(0)
	v_add_f32_e32 v9, v9, v91
	v_add_f32_e32 v90, v90, v92
	ds_bpermute_b32 v91, v4, v9
	ds_bpermute_b32 v92, v4, v90
	s_waitcnt lgkmcnt(0)
	v_add_f32_e32 v9, v9, v91
	v_add_f32_e32 v90, v90, v92
	ds_bpermute_b32 v91, v5, v9
	ds_bpermute_b32 v92, v5, v90
	s_waitcnt lgkmcnt(0)
	v_add_f32_e32 v9, v9, v91
	v_add_f32_e32 v90, v90, v92
	ds_bpermute_b32 v91, v6, v9
	ds_bpermute_b32 v92, v6, v90
	s_waitcnt lgkmcnt(0)
	v_add_f32_e32 v9, v9, v91
	v_add_f32_e32 v90, v90, v92
	ds_bpermute_b32 v91, v7, v9
	ds_bpermute_b32 v92, v7, v90
	s_waitcnt lgkmcnt(0)
	v_add_f32_e32 v9, v9, v91
	v_add_f32_e32 v90, v90, v92
	ds_bpermute_b32 v91, v8, v9
	ds_bpermute_b32 v92, v8, v90
	s_waitcnt lgkmcnt(0)
	v_add_f32_e32 v9, v9, v91
	v_add_f32_e32 v90, v90, v92
	v_mul_f32_e32 v93, 0x3a800000, v9
	v_mul_f32_e32 v91, 0x3a800000, v90
	v_fma_f32 v91, -v93, v93, v91
	v_max_f32_e32 v91, 0, v91
	v_add_f32_e32 v91, 0x358637bd, v91
	v_rsq_f32_e32 v94, v91
	v_mul_f32_e32 v91, 0.5, v91
	v_mul_f32_e32 v92, v94, v94
	v_fma_f32 v92, -v91, v92, 0.5
	v_fma_f32 v94, v94, v92, v94
	s_waitcnt vmcnt(6)
	v_sub_f32_e32 v98, v98, v93
	v_sub_f32_e32 v99, v99, v93
	v_sub_f32_e32 v100, v100, v93
	v_sub_f32_e32 v101, v101, v93
	v_sub_f32_e32 v102, v102, v93
	v_sub_f32_e32 v103, v103, v93
	v_sub_f32_e32 v104, v104, v93
	v_sub_f32_e32 v105, v105, v93
	v_sub_f32_e32 v106, v106, v93
	v_sub_f32_e32 v107, v107, v93
	v_sub_f32_e32 v108, v108, v93
	v_sub_f32_e32 v109, v109, v93
	v_sub_f32_e32 v110, v110, v93
	v_sub_f32_e32 v111, v111, v93
	v_sub_f32_e32 v112, v112, v93
	v_sub_f32_e32 v113, v113, v93
	v_add_f32_e32 v162, 1.0, v162
	v_add_f32_e32 v163, 1.0, v163
	v_add_f32_e32 v164, 1.0, v164
	v_add_f32_e32 v165, 1.0, v165
	v_add_f32_e32 v166, 1.0, v166
	v_add_f32_e32 v167, 1.0, v167
	v_add_f32_e32 v168, 1.0, v168
	v_add_f32_e32 v169, 1.0, v169
	v_add_f32_e32 v170, 1.0, v170
	v_add_f32_e32 v171, 1.0, v171
	v_add_f32_e32 v172, 1.0, v172
	v_add_f32_e32 v173, 1.0, v173
	v_add_f32_e32 v174, 1.0, v174
	v_add_f32_e32 v175, 1.0, v175
	v_add_f32_e32 v176, 1.0, v176
	v_add_f32_e32 v177, 1.0, v177
	v_mul_f32_e32 v98, v94, v98
	v_mul_f32_e32 v99, v94, v99
	v_mul_f32_e32 v100, v94, v100
	v_mul_f32_e32 v101, v94, v101
	v_mul_f32_e32 v102, v94, v102
	v_mul_f32_e32 v103, v94, v103
	v_mul_f32_e32 v104, v94, v104
	v_mul_f32_e32 v105, v94, v105
	v_mul_f32_e32 v106, v94, v106
	v_mul_f32_e32 v107, v94, v107
	v_mul_f32_e32 v108, v94, v108
	v_mul_f32_e32 v109, v94, v109
	v_mul_f32_e32 v110, v94, v110
	v_mul_f32_e32 v111, v94, v111
	v_mul_f32_e32 v112, v94, v112
	v_mul_f32_e32 v113, v94, v113
	v_fma_f32 v98, v98, v162, v146
	v_fma_f32 v99, v99, v163, v147
	v_fma_f32 v100, v100, v164, v148
	v_fma_f32 v101, v101, v165, v149
	v_fma_f32 v102, v102, v166, v150
	v_fma_f32 v103, v103, v167, v151
	v_fma_f32 v104, v104, v168, v152
	v_fma_f32 v105, v105, v169, v153
	v_fma_f32 v106, v106, v170, v154
	v_fma_f32 v107, v107, v171, v155
	v_fma_f32 v108, v108, v172, v156
	v_fma_f32 v109, v109, v173, v157
	v_fma_f32 v110, v110, v174, v158
	v_fma_f32 v111, v111, v175, v159
	v_fma_f32 v112, v112, v176, v160
	v_fma_f32 v113, v113, v177, v161
	v_cvt_pk_bf16_f32 v190, v98, v99
	v_cvt_pk_bf16_f32 v191, v100, v101
	v_cvt_pk_bf16_f32 v192, v102, v103
	v_cvt_pk_bf16_f32 v193, v104, v105
	v_cvt_pk_bf16_f32 v194, v106, v107
	v_cvt_pk_bf16_f32 v195, v108, v109
	v_cvt_pk_bf16_f32 v196, v110, v111
	v_cvt_pk_bf16_f32 v197, v112, v113
	s_add_u32 s2, s10, 0x1c00000
	s_addc_u32 s3, s11, 0
	global_store_dwordx2 v1, v[190:191], s[2:3]
	global_store_dwordx2 v1, v[192:193], s[2:3] offset:512
	global_store_dwordx2 v1, v[194:195], s[2:3] offset:1024
	global_store_dwordx2 v1, v[196:197], s[2:3] offset:1536
	s_waitcnt vmcnt(0)
	s_branch .Lln_b_done
; DI void ln_row_v(const Frame& F, f32x4 (&v)[4], float* xout, const float* g, const float* b, const float* sh, const float* sc, bf16_t* hout, const float* slab, const float* gres, float* stat = nullptr) {
;     ...
;         float s = 0.f, s2 = 0.f;
; #pragma unroll
;         for (int j = 0; j < 4; ++j) { s += (v[j][0] + v[j][1]) + (v[j][2] + v[j][3]); s2 += (v[j][0] * v[j][0] + v[j][1] * v[j][1]) + (v[j][2] * v[j][2] + v[j][3] * v[j][3]); }
;         wave_sum2(s, s2, F.lane);
;         const float mean = s * (1.f / D); const float rstd = 1.f / sqrtf(fmaxf(s2 * (1.f / D) - mean * mean, 0.f) + EPS);
;         if (stat && F.lane == 0) { f32x2 sv = {mean, rstd}; *(f32x2*)stat = sv; }
; #pragma unroll
;         for (int j = 0; j < 4; ++j) { const f32x4 gg = ((const f32x4*)g)[F.lane + 64 * j], bb = ((const f32x4*)b)[F.lane + 64 * j];
;             v[j] = (v[j] - mean) * rstd * gg + bb; if (xout) ((f32x4*)xout)[F.lane + 64 * j] = v[j]; }
; DI void ln_phase(const Frame& F, int which) {
;     const int gw = F.vcu * 8 + F.wave, NGW = F.G * 8; const int l = F.l;
;     const int nrows = (l == NL - 1) ? ML : MT;
;     bf16_t* H = (bf16_t*)(F.ws + WS_HB);
;     const float* g = pin(F, which == 0 ? I_LN1G : I_LN2G) + l * 1024; const float* b = pin(F, which == 0 ? I_LN1B : I_LN2B) + l * 1024;
;     const bool wh = !(which == 1 && l == NL - 1);
;     f32x4 vc[4], vn[4];
;     if (gw < nrows) ln_load(F, xrow_ptr(F, gw), vc);
;     for (int row = gw; row < nrows; row += NGW) {
;         if (row + NGW < nrows) ln_load(F, xrow_ptr(F, row + NGW), vn);
;         const int mr = row < ML ? (row >> 11) : 8;
;         const float* sh = which == 0 ? modp(F, l, mr, 3) : modp(F, l + 1 < NL ? l + 1 : l, mr, 0);
;         const float* sc = which == 0 ? modp(F, l, mr, 4) : modp(F, l + 1 < NL ? l + 1 : l, mr, 1);
;         const bool sl = (which == 1 && row >= ML);
;         const bool st_only = row < ML && !(which == 1 && l == NL - 1);
;         float* stp = st_only ? (float*)(F.ws + (which == 0 ? WS_ST1 : WS_ST2)) + 2 * (size_t)row : nullptr;
;         ln_row_v(F, vc, st_only ? nullptr : xrow_ptr(F, row), g, b, sh, sc, wh ? H + (size_t)row * D : nullptr, sl ? (const float*)(F.ws + WS_KN) + (size_t)(row - ML) * 1024 : nullptr, modp(F, l, mr, 5), stp);
.Lln_b_final:
	global_load_dwordx4 v[10:13], v0, s[4:5]
	global_load_dwordx4 v[14:17], v0, s[4:5] offset:1024
	global_load_dwordx4 v[18:21], v0, s[4:5] offset:2048
	global_load_dwordx4 v[22:25], v0, s[4:5] offset:3072
	global_load_dwordx4 v[26:29], v0, s[6:7]
	global_load_dwordx4 v[30:33], v0, s[6:7] offset:1024
	global_load_dwordx4 v[34:37], v0, s[6:7] offset:2048
	global_load_dwordx4 v[38:41], v0, s[6:7] offset:3072
	s_add_u32 s2, s8, 0x0
	s_addc_u32 s3, s9, 0
	global_load_dwordx4 v[42:45], v0, s[2:3]
	global_load_dwordx4 v[46:49], v0, s[2:3] offset:1024
	global_load_dwordx4 v[50:53], v0, s[2:3] offset:2048
	global_load_dwordx4 v[54:57], v0, s[2:3] offset:3072
	s_add_u32 s2, s8, 0x800000
	s_addc_u32 s3, s9, 0
	global_load_dwordx4 v[58:61], v0, s[2:3]
	global_load_dwordx4 v[62:65], v0, s[2:3] offset:1024
	global_load_dwordx4 v[66:69], v0, s[2:3] offset:2048
	global_load_dwordx4 v[70:73], v0, s[2:3] offset:3072
	s_add_u32 s2, s8, 0x1000000
	s_addc_u32 s3, s9, 0
	global_load_dwordx4 v[74:77], v0, s[2:3]
	global_load_dwordx4 v[78:81], v0, s[2:3] offset:1024
	global_load_dwordx4 v[82:85], v0, s[2:3] offset:2048
	global_load_dwordx4 v[86:89], v0, s[2:3] offset:3072
	s_add_u32 s2, s8, 0x1800000
	s_addc_u32 s3, s9, 0
	global_load_dwordx4 v[98:101], v0, s[2:3]
	global_load_dwordx4 v[102:105], v0, s[2:3] offset:1024
	global_load_dwordx4 v[106:109], v0, s[2:3] offset:2048
	global_load_dwordx4 v[110:113], v0, s[2:3] offset:3072
	s_waitcnt vmcnt(12)
	v_add_f32_e32 v9, v42, v43
	v_add_f32_e32 v91, v44, v45
	v_mul_f32_e32 v90, v42, v42
	v_mul_f32_e32 v92, v43, v43
	v_add_f32_e32 v9, v9, v46
	v_add_f32_e32 v91, v91, v47
	v_add_f32_e32 v9, v9, v48
	v_add_f32_e32 v91, v91, v49
	v_add_f32_e32 v9, v9, v50
	v_add_f32_e32 v91, v91, v51
	v_add_f32_e32 v9, v9, v52
	v_add_f32_e32 v91, v91, v53
	v_add_f32_e32 v9, v9, v54
	v_add_f32_e32 v91, v91, v55
	v_add_f32_e32 v9, v9, v56
	v_add_f32_e32 v91, v91, v57
	v_fmac_f32_e32 v90, v44, v44
	v_fmac_f32_e32 v92, v45, v45
	v_fmac_f32_e32 v90, v46, v46
	v_fmac_f32_e32 v92, v47, v47
	v_fmac_f32_e32 v90, v48, v48
	v_fmac_f32_e32 v92, v49, v49
	v_fmac_f32_e32 v90, v50, v50
	v_fmac_f32_e32 v92, v51, v51
	v_fmac_f32_e32 v90, v52, v52
	v_fmac_f32_e32 v92, v53, v53
	v_fmac_f32_e32 v90, v54, v54
	v_fmac_f32_e32 v92, v55, v55
	v_fmac_f32_e32 v90, v56, v56
	v_fmac_f32_e32 v92, v57, v57
	v_add_f32_e32 v9, v9, v91
	v_add_f32_e32 v90, v90, v92
	ds_bpermute_b32 v91, v3, v9
	ds_bpermute_b32 v92, v3, v90
	s_waitcnt lgkmcnt(0)
	v_add_f32_e32 v9, v9, v91
	v_add_f32_e32 v90, v90, v92
	ds_bpermute_b32 v91, v4, v9
	ds_bpermute_b32 v92, v4, v90
	s_waitcnt lgkmcnt(0)
	v_add_f32_e32 v9, v9, v91
	v_add_f32_e32 v90, v90, v92
	ds_bpermute_b32 v91, v5, v9
	ds_bpermute_b32 v92, v5, v90
	s_waitcnt lgkmcnt(0)
	v_add_f32_e32 v9, v9, v91
	v_add_f32_e32 v90, v90, v92
	ds_bpermute_b32 v91, v6, v9
	ds_bpermute_b32 v92, v6, v90
	s_waitcnt lgkmcnt(0)
	v_add_f32_e32 v9, v9, v91
	v_add_f32_e32 v90, v90, v92
	ds_bpermute_b32 v91, v7, v9
	ds_bpermute_b32 v92, v7, v90
	s_waitcnt lgkmcnt(0)
	v_add_f32_e32 v9, v9, v91
	v_add_f32_e32 v90, v90, v92
	ds_bpermute_b32 v91, v8, v9
	ds_bpermute_b32 v92, v8, v90
	s_waitcnt lgkmcnt(0)
	v_add_f32_e32 v9, v9, v91
	v_add_f32_e32 v90, v90, v92
	v_mul_f32_e32 v93, 0x3a800000, v9
	v_mul_f32_e32 v91, 0x3a800000, v90
	v_fma_f32 v91, -v93, v93, v91
	v_max_f32_e32 v91, 0, v91
	v_add_f32_e32 v91, 0x358637bd, v91
	v_rsq_f32_e32 v94, v91
	v_mul_f32_e32 v91, 0.5, v91
	v_mul_f32_e32 v92, v94, v94
	v_fma_f32 v92, -v91, v92, 0.5
	v_fma_f32 v94, v94, v92, v94
	v_sub_f32_e32 v42, v42, v93
	v_sub_f32_e32 v43, v43, v93
	v_sub_f32_e32 v44, v44, v93
	v_sub_f32_e32 v45, v45, v93
	v_sub_f32_e32 v46, v46, v93
	v_sub_f32_e32 v47, v47, v93
	v_sub_f32_e32 v48, v48, v93
	v_sub_f32_e32 v49, v49, v93
	v_sub_f32_e32 v50, v50, v93
	v_sub_f32_e32 v51, v51, v93
	v_sub_f32_e32 v52, v52, v93
	v_sub_f32_e32 v53, v53, v93
	v_sub_f32_e32 v54, v54, v93
	v_sub_f32_e32 v55, v55, v93
	v_sub_f32_e32 v56, v56, v93
	v_sub_f32_e32 v57, v57, v93
	v_mul_f32_e32 v42, v94, v42
	v_mul_f32_e32 v43, v94, v43
	v_mul_f32_e32 v44, v94, v44
	v_mul_f32_e32 v45, v94, v45
	v_mul_f32_e32 v46, v94, v46
	v_mul_f32_e32 v47, v94, v47
	v_mul_f32_e32 v48, v94, v48
	v_mul_f32_e32 v49, v94, v49
	v_mul_f32_e32 v50, v94, v50
	v_mul_f32_e32 v51, v94, v51
	v_mul_f32_e32 v52, v94, v52
	v_mul_f32_e32 v53, v94, v53
	v_mul_f32_e32 v54, v94, v54
	v_mul_f32_e32 v55, v94, v55
	v_mul_f32_e32 v56, v94, v56
	v_mul_f32_e32 v57, v94, v57
	v_fma_f32 v42, v42, v10, v26
	v_fma_f32 v43, v43, v11, v27
	v_fma_f32 v44, v44, v12, v28
	v_fma_f32 v45, v45, v13, v29
	v_fma_f32 v46, v46, v14, v30
	v_fma_f32 v47, v47, v15, v31
	v_fma_f32 v48, v48, v16, v32
	v_fma_f32 v49, v49, v17, v33
	v_fma_f32 v50, v50, v18, v34
	v_fma_f32 v51, v51, v19, v35
	v_fma_f32 v52, v52, v20, v36
	v_fma_f32 v53, v53, v21, v37
	v_fma_f32 v54, v54, v22, v38
	v_fma_f32 v55, v55, v23, v39
	v_fma_f32 v56, v56, v24, v40
	v_fma_f32 v57, v57, v25, v41
	s_add_u32 s2, s8, 0x0
	s_addc_u32 s3, s9, 0
	global_store_dwordx4 v0, v[42:45], s[2:3]
	global_store_dwordx4 v0, v[46:49], s[2:3] offset:1024
	global_store_dwordx4 v0, v[50:53], s[2:3] offset:2048
	global_store_dwordx4 v0, v[54:57], s[2:3] offset:3072
	s_add_u32 s2, s8, 0x2000000
	s_addc_u32 s3, s9, 0
	global_load_dwordx4 v[42:45], v0, s[2:3]
	global_load_dwordx4 v[46:49], v0, s[2:3] offset:1024
	global_load_dwordx4 v[50:53], v0, s[2:3] offset:2048
	global_load_dwordx4 v[54:57], v0, s[2:3] offset:3072
	s_waitcnt vmcnt(16)
; DI void ln_row_v(const Frame& F, f32x4 (&v)[4], float* xout, const float* g, const float* b, const float* sh, const float* sc, bf16_t* hout, const float* slab, const float* gres, float* stat = nullptr) {
;     ...
;         float s = 0.f, s2 = 0.f;
; #pragma unroll
;         for (int j = 0; j < 4; ++j) { s += (v[j][0] + v[j][1]) + (v[j][2] + v[j][3]); s2 += (v[j][0] * v[j][0] + v[j][1] * v[j][1]) + (v[j][2] * v[j][2] + v[j][3] * v[j][3]); }
;         wave_sum2(s, s2, F.lane);
;         const float mean = s * (1.f / D); const float rstd = 1.f / sqrtf(fmaxf(s2 * (1.f / D) - mean * mean, 0.f) + EPS);
;         if (stat && F.lane == 0) { f32x2 sv = {mean, rstd}; *(f32x2*)stat = sv; }
; #pragma unroll
;         for (int j = 0; j < 4; ++j) { const f32x4 gg = ((const f32x4*)g)[F.lane + 64 * j], bb = ((const f32x4*)b)[F.lane + 64 * j];
;             v[j] = (v[j] - mean) * rstd * gg + bb; if (xout) ((f32x4*)xout)[F.lane + 64 * j] = v[j]; }
; DI void ln_phase(const Frame& F, int which) {
;     ...
;     for (int row = gw; row < nrows; row += NGW) {
;         if (row + NGW < nrows) ln_load(F, xrow_ptr(F, row + NGW), vn);
	v_add_f32_e32 v9, v58, v59
	v_add_f32_e32 v91, v60, v61
	v_mul_f32_e32 v90, v58, v58
	v_mul_f32_e32 v92, v59, v59
	v_add_f32_e32 v9, v9, v62
	v_add_f32_e32 v91, v91, v63
	v_add_f32_e32 v9, v9, v64
	v_add_f32_e32 v91, v91, v65
	v_add_f32_e32 v9, v9, v66
	v_add_f32_e32 v91, v91, v67
	v_add_f32_e32 v9, v9, v68
	v_add_f32_e32 v91, v91, v69
	v_add_f32_e32 v9, v9, v70
	v_add_f32_e32 v91, v91, v71
	v_add_f32_e32 v9, v9, v72
	v_add_f32_e32 v91, v91, v73
	v_fmac_f32_e32 v90, v60, v60
	v_fmac_f32_e32 v92, v61, v61
	v_fmac_f32_e32 v90, v62, v62
	v_fmac_f32_e32 v92, v63, v63
	v_fmac_f32_e32 v90, v64, v64
	v_fmac_f32_e32 v92, v65, v65
	v_fmac_f32_e32 v90, v66, v66
	v_fmac_f32_e32 v92, v67, v67
	v_fmac_f32_e32 v90, v68, v68
	v_fmac_f32_e32 v92, v69, v69
	v_fmac_f32_e32 v90, v70, v70
	v_fmac_f32_e32 v92, v71, v71
	v_fmac_f32_e32 v90, v72, v72
	v_fmac_f32_e32 v92, v73, v73
	v_add_f32_e32 v9, v9, v91
	v_add_f32_e32 v90, v90, v92
	ds_bpermute_b32 v91, v3, v9
	ds_bpermute_b32 v92, v3, v90
	s_waitcnt lgkmcnt(0)
	v_add_f32_e32 v9, v9, v91
	v_add_f32_e32 v90, v90, v92
	ds_bpermute_b32 v91, v4, v9
	ds_bpermute_b32 v92, v4, v90
	s_waitcnt lgkmcnt(0)
	v_add_f32_e32 v9, v9, v91
	v_add_f32_e32 v90, v90, v92
	ds_bpermute_b32 v91, v5, v9
	ds_bpermute_b32 v92, v5, v90
	s_waitcnt lgkmcnt(0)
	v_add_f32_e32 v9, v9, v91
	v_add_f32_e32 v90, v90, v92
	ds_bpermute_b32 v91, v6, v9
	ds_bpermute_b32 v92, v6, v90
	s_waitcnt lgkmcnt(0)
	v_add_f32_e32 v9, v9, v91
	v_add_f32_e32 v90, v90, v92
	ds_bpermute_b32 v91, v7, v9
	ds_bpermute_b32 v92, v7, v90
	s_waitcnt lgkmcnt(0)
	v_add_f32_e32 v9, v9, v91
	v_add_f32_e32 v90, v90, v92
	ds_bpermute_b32 v91, v8, v9
	ds_bpermute_b32 v92, v8, v90
	s_waitcnt lgkmcnt(0)
	v_add_f32_e32 v9, v9, v91
	v_add_f32_e32 v90, v90, v92
	v_mul_f32_e32 v93, 0x3a800000, v9
	v_mul_f32_e32 v91, 0x3a800000, v90
	v_fma_f32 v91, -v93, v93, v91
	v_max_f32_e32 v91, 0, v91
	v_add_f32_e32 v91, 0x358637bd, v91
	v_rsq_f32_e32 v94, v91
	v_mul_f32_e32 v91, 0.5, v91
	v_mul_f32_e32 v92, v94, v94
	v_fma_f32 v92, -v91, v92, 0.5
	v_fma_f32 v94, v94, v92, v94
	v_sub_f32_e32 v58, v58, v93
	v_sub_f32_e32 v59, v59, v93
	v_sub_f32_e32 v60, v60, v93
	v_sub_f32_e32 v61, v61, v93
	v_sub_f32_e32 v62, v62, v93
	v_sub_f32_e32 v63, v63, v93
	v_sub_f32_e32 v64, v64, v93
	v_sub_f32_e32 v65, v65, v93
	v_sub_f32_e32 v66, v66, v93
	v_sub_f32_e32 v67, v67, v93
	v_sub_f32_e32 v68, v68, v93
	v_sub_f32_e32 v69, v69, v93
	v_sub_f32_e32 v70, v70, v93
	v_sub_f32_e32 v71, v71, v93
	v_sub_f32_e32 v72, v72, v93
	v_sub_f32_e32 v73, v73, v93
	v_mul_f32_e32 v58, v94, v58
	v_mul_f32_e32 v59, v94, v59
	v_mul_f32_e32 v60, v94, v60
	v_mul_f32_e32 v61, v94, v61
	v_mul_f32_e32 v62, v94, v62
	v_mul_f32_e32 v63, v94, v63
	v_mul_f32_e32 v64, v94, v64
	v_mul_f32_e32 v65, v94, v65
	v_mul_f32_e32 v66, v94, v66
	v_mul_f32_e32 v67, v94, v67
	v_mul_f32_e32 v68, v94, v68
	v_mul_f32_e32 v69, v94, v69
	v_mul_f32_e32 v70, v94, v70
	v_mul_f32_e32 v71, v94, v71
	v_mul_f32_e32 v72, v94, v72
	v_mul_f32_e32 v73, v94, v73
	v_fma_f32 v58, v58, v10, v26
	v_fma_f32 v59, v59, v11, v27
	v_fma_f32 v60, v60, v12, v28
	v_fma_f32 v61, v61, v13, v29
	v_fma_f32 v62, v62, v14, v30
	v_fma_f32 v63, v63, v15, v31
	v_fma_f32 v64, v64, v16, v32
	v_fma_f32 v65, v65, v17, v33
	v_fma_f32 v66, v66, v18, v34
	v_fma_f32 v67, v67, v19, v35
	v_fma_f32 v68, v68, v20, v36
	v_fma_f32 v69, v69, v21, v37
	v_fma_f32 v70, v70, v22, v38
	v_fma_f32 v71, v71, v23, v39
	v_fma_f32 v72, v72, v24, v40
	v_fma_f32 v73, v73, v25, v41
	s_add_u32 s2, s8, 0x800000
	s_addc_u32 s3, s9, 0
	global_store_dwordx4 v0, v[58:61], s[2:3]
	global_store_dwordx4 v0, v[62:65], s[2:3] offset:1024
	global_store_dwordx4 v0, v[66:69], s[2:3] offset:2048
	global_store_dwordx4 v0, v[70:73], s[2:3] offset:3072
	s_add_u32 s2, s8, 0x2800000
	s_addc_u32 s3, s9, 0
	global_load_dwordx4 v[58:61], v0, s[2:3]
	global_load_dwordx4 v[62:65], v0, s[2:3] offset:1024
	global_load_dwordx4 v[66:69], v0, s[2:3] offset:2048
	global_load_dwordx4 v[70:73], v0, s[2:3] offset:3072
	s_waitcnt vmcnt(20)
	v_add_f32_e32 v9, v74, v75
	v_add_f32_e32 v91, v76, v77
	v_mul_f32_e32 v90, v74, v74
	v_mul_f32_e32 v92, v75, v75
	v_add_f32_e32 v9, v9, v78
	v_add_f32_e32 v91, v91, v79
	v_add_f32_e32 v9, v9, v80
	v_add_f32_e32 v91, v91, v81
	v_add_f32_e32 v9, v9, v82
	v_add_f32_e32 v91, v91, v83
	v_add_f32_e32 v9, v9, v84
	v_add_f32_e32 v91, v91, v85
	v_add_f32_e32 v9, v9, v86
	v_add_f32_e32 v91, v91, v87
	v_add_f32_e32 v9, v9, v88
	v_add_f32_e32 v91, v91, v89
	v_fmac_f32_e32 v90, v76, v76
	v_fmac_f32_e32 v92, v77, v77
	v_fmac_f32_e32 v90, v78, v78
	v_fmac_f32_e32 v92, v79, v79
	v_fmac_f32_e32 v90, v80, v80
	v_fmac_f32_e32 v92, v81, v81
	v_fmac_f32_e32 v90, v82, v82
	v_fmac_f32_e32 v92, v83, v83
	v_fmac_f32_e32 v90, v84, v84
	v_fmac_f32_e32 v92, v85, v85
	v_fmac_f32_e32 v90, v86, v86
	v_fmac_f32_e32 v92, v87, v87
	v_fmac_f32_e32 v90, v88, v88
	v_fmac_f32_e32 v92, v89, v89
	v_add_f32_e32 v9, v9, v91
	v_add_f32_e32 v90, v90, v92
	ds_bpermute_b32 v91, v3, v9
	ds_bpermute_b32 v92, v3, v90
	s_waitcnt lgkmcnt(0)
	v_add_f32_e32 v9, v9, v91
	v_add_f32_e32 v90, v90, v92
	ds_bpermute_b32 v91, v4, v9
	ds_bpermute_b32 v92, v4, v90
	s_waitcnt lgkmcnt(0)
	v_add_f32_e32 v9, v9, v91
	v_add_f32_e32 v90, v90, v92
	ds_bpermute_b32 v91, v5, v9
	ds_bpermute_b32 v92, v5, v90
	s_waitcnt lgkmcnt(0)
	v_add_f32_e32 v9, v9, v91
	v_add_f32_e32 v90, v90, v92
	ds_bpermute_b32 v91, v6, v9
	ds_bpermute_b32 v92, v6, v90
	s_waitcnt lgkmcnt(0)
	v_add_f32_e32 v9, v9, v91
	v_add_f32_e32 v90, v90, v92
	ds_bpermute_b32 v91, v7, v9
	ds_bpermute_b32 v92, v7, v90
	s_waitcnt lgkmcnt(0)
	v_add_f32_e32 v9, v9, v91
	v_add_f32_e32 v90, v90, v92
	ds_bpermute_b32 v91, v8, v9
	ds_bpermute_b32 v92, v8, v90
	s_waitcnt lgkmcnt(0)
; DI void ln_row_v(const Frame& F, f32x4 (&v)[4], float* xout, const float* g, const float* b, const float* sh, const float* sc, bf16_t* hout, const float* slab, const float* gres, float* stat = nullptr) {
;     ...
;         float s = 0.f, s2 = 0.f;
; #pragma unroll
;         for (int j = 0; j < 4; ++j) { s += (v[j][0] + v[j][1]) + (v[j][2] + v[j][3]); s2 += (v[j][0] * v[j][0] + v[j][1] * v[j][1]) + (v[j][2] * v[j][2] + v[j][3] * v[j][3]); }
;         wave_sum2(s, s2, F.lane);
;         const float mean = s * (1.f / D); const float rstd = 1.f / sqrtf(fmaxf(s2 * (1.f / D) - mean * mean, 0.f) + EPS);
;         if (stat && F.lane == 0) { f32x2 sv = {mean, rstd}; *(f32x2*)stat = sv; }
; #pragma unroll
;         for (int j = 0; j < 4; ++j) { const f32x4 gg = ((const f32x4*)g)[F.lane + 64 * j], bb = ((const f32x4*)b)[F.lane + 64 * j];
;             v[j] = (v[j] - mean) * rstd * gg + bb; if (xout) ((f32x4*)xout)[F.lane + 64 * j] = v[j]; }
; DI void ln_phase(const Frame& F, int which) {
;     ...
;     for (int row = gw; row < nrows; row += NGW) {
;         if (row + NGW < nrows) ln_load(F, xrow_ptr(F, row + NGW), vn);
	v_add_f32_e32 v9, v9, v91
	v_add_f32_e32 v90, v90, v92
	v_mul_f32_e32 v93, 0x3a800000, v9
	v_mul_f32_e32 v91, 0x3a800000, v90
	v_fma_f32 v91, -v93, v93, v91
	v_max_f32_e32 v91, 0, v91
	v_add_f32_e32 v91, 0x358637bd, v91
	v_rsq_f32_e32 v94, v91
	v_mul_f32_e32 v91, 0.5, v91
	v_mul_f32_e32 v92, v94, v94
	v_fma_f32 v92, -v91, v92, 0.5
	v_fma_f32 v94, v94, v92, v94
	v_sub_f32_e32 v74, v74, v93
	v_sub_f32_e32 v75, v75, v93
	v_sub_f32_e32 v76, v76, v93
	v_sub_f32_e32 v77, v77, v93
	v_sub_f32_e32 v78, v78, v93
	v_sub_f32_e32 v79, v79, v93
	v_sub_f32_e32 v80, v80, v93
	v_sub_f32_e32 v81, v81, v93
	v_sub_f32_e32 v82, v82, v93
	v_sub_f32_e32 v83, v83, v93
	v_sub_f32_e32 v84, v84, v93
	v_sub_f32_e32 v85, v85, v93
	v_sub_f32_e32 v86, v86, v93
	v_sub_f32_e32 v87, v87, v93
	v_sub_f32_e32 v88, v88, v93
	v_sub_f32_e32 v89, v89, v93
	v_mul_f32_e32 v74, v94, v74
	v_mul_f32_e32 v75, v94, v75
	v_mul_f32_e32 v76, v94, v76
	v_mul_f32_e32 v77, v94, v77
	v_mul_f32_e32 v78, v94, v78
	v_mul_f32_e32 v79, v94, v79
	v_mul_f32_e32 v80, v94, v80
	v_mul_f32_e32 v81, v94, v81
	v_mul_f32_e32 v82, v94, v82
	v_mul_f32_e32 v83, v94, v83
	v_mul_f32_e32 v84, v94, v84
	v_mul_f32_e32 v85, v94, v85
	v_mul_f32_e32 v86, v94, v86
	v_mul_f32_e32 v87, v94, v87
	v_mul_f32_e32 v88, v94, v88
	v_mul_f32_e32 v89, v94, v89
	v_fma_f32 v74, v74, v10, v26
	v_fma_f32 v75, v75, v11, v27
	v_fma_f32 v76, v76, v12, v28
	v_fma_f32 v77, v77, v13, v29
	v_fma_f32 v78, v78, v14, v30
	v_fma_f32 v79, v79, v15, v31
	v_fma_f32 v80, v80, v16, v32
	v_fma_f32 v81, v81, v17, v33
	v_fma_f32 v82, v82, v18, v34
	v_fma_f32 v83, v83, v19, v35
	v_fma_f32 v84, v84, v20, v36
	v_fma_f32 v85, v85, v21, v37
	v_fma_f32 v86, v86, v22, v38
	v_fma_f32 v87, v87, v23, v39
	v_fma_f32 v88, v88, v24, v40
	v_fma_f32 v89, v89, v25, v41
	s_add_u32 s2, s8, 0x1000000
	s_addc_u32 s3, s9, 0
	global_store_dwordx4 v0, v[74:77], s[2:3]
	global_store_dwordx4 v0, v[78:81], s[2:3] offset:1024
	global_store_dwordx4 v0, v[82:85], s[2:3] offset:2048
	global_store_dwordx4 v0, v[86:89], s[2:3] offset:3072
	s_add_u32 s2, s8, 0x3000000
	s_addc_u32 s3, s9, 0
	global_load_dwordx4 v[74:77], v0, s[2:3]
	global_load_dwordx4 v[78:81], v0, s[2:3] offset:1024
	global_load_dwordx4 v[82:85], v0, s[2:3] offset:2048
	global_load_dwordx4 v[86:89], v0, s[2:3] offset:3072
	s_waitcnt vmcnt(24)
	v_add_f32_e32 v9, v98, v99
	v_add_f32_e32 v91, v100, v101
	v_mul_f32_e32 v90, v98, v98
	v_mul_f32_e32 v92, v99, v99
	v_add_f32_e32 v9, v9, v102
	v_add_f32_e32 v91, v91, v103
	v_add_f32_e32 v9, v9, v104
	v_add_f32_e32 v91, v91, v105
	v_add_f32_e32 v9, v9, v106
	v_add_f32_e32 v91, v91, v107
	v_add_f32_e32 v9, v9, v108
	v_add_f32_e32 v91, v91, v109
	v_add_f32_e32 v9, v9, v110
	v_add_f32_e32 v91, v91, v111
	v_add_f32_e32 v9, v9, v112
	v_add_f32_e32 v91, v91, v113
	v_fmac_f32_e32 v90, v100, v100
	v_fmac_f32_e32 v92, v101, v101
	v_fmac_f32_e32 v90, v102, v102
	v_fmac_f32_e32 v92, v103, v103
	v_fmac_f32_e32 v90, v104, v104
	v_fmac_f32_e32 v92, v105, v105
	v_fmac_f32_e32 v90, v106, v106
	v_fmac_f32_e32 v92, v107, v107
	v_fmac_f32_e32 v90, v108, v108
	v_fmac_f32_e32 v92, v109, v109
	v_fmac_f32_e32 v90, v110, v110
	v_fmac_f32_e32 v92, v111, v111
	v_fmac_f32_e32 v90, v112, v112
	v_fmac_f32_e32 v92, v113, v113
	v_add_f32_e32 v9, v9, v91
	v_add_f32_e32 v90, v90, v92
	ds_bpermute_b32 v91, v3, v9
	ds_bpermute_b32 v92, v3, v90
	s_waitcnt lgkmcnt(0)
	v_add_f32_e32 v9, v9, v91
	v_add_f32_e32 v90, v90, v92
	ds_bpermute_b32 v91, v4, v9
	ds_bpermute_b32 v92, v4, v90
	s_waitcnt lgkmcnt(0)
	v_add_f32_e32 v9, v9, v91
	v_add_f32_e32 v90, v90, v92
	ds_bpermute_b32 v91, v5, v9
	ds_bpermute_b32 v92, v5, v90
	s_waitcnt lgkmcnt(0)
	v_add_f32_e32 v9, v9, v91
	v_add_f32_e32 v90, v90, v92
	ds_bpermute_b32 v91, v6, v9
	ds_bpermute_b32 v92, v6, v90
	s_waitcnt lgkmcnt(0)
	v_add_f32_e32 v9, v9, v91
	v_add_f32_e32 v90, v90, v92
	ds_bpermute_b32 v91, v7, v9
	ds_bpermute_b32 v92, v7, v90
	s_waitcnt lgkmcnt(0)
	v_add_f32_e32 v9, v9, v91
	v_add_f32_e32 v90, v90, v92
	ds_bpermute_b32 v91, v8, v9
	ds_bpermute_b32 v92, v8, v90
	s_waitcnt lgkmcnt(0)
	v_add_f32_e32 v9, v9, v91
	v_add_f32_e32 v90, v90, v92
	v_mul_f32_e32 v93, 0x3a800000, v9
	v_mul_f32_e32 v91, 0x3a800000, v90
	v_fma_f32 v91, -v93, v93, v91
	v_max_f32_e32 v91, 0, v91
	v_add_f32_e32 v91, 0x358637bd, v91
	v_rsq_f32_e32 v94, v91
	v_mul_f32_e32 v91, 0.5, v91
	v_mul_f32_e32 v92, v94, v94
	v_fma_f32 v92, -v91, v92, 0.5
	v_fma_f32 v94, v94, v92, v94
	v_sub_f32_e32 v98, v98, v93
	v_sub_f32_e32 v99, v99, v93
	v_sub_f32_e32 v100, v100, v93
	v_sub_f32_e32 v101, v101, v93
	v_sub_f32_e32 v102, v102, v93
	v_sub_f32_e32 v103, v103, v93
	v_sub_f32_e32 v104, v104, v93
	v_sub_f32_e32 v105, v105, v93
	v_sub_f32_e32 v106, v106, v93
	v_sub_f32_e32 v107, v107, v93
	v_sub_f32_e32 v108, v108, v93
	v_sub_f32_e32 v109, v109, v93
	v_sub_f32_e32 v110, v110, v93
	v_sub_f32_e32 v111, v111, v93
	v_sub_f32_e32 v112, v112, v93
	v_sub_f32_e32 v113, v113, v93
	v_mul_f32_e32 v98, v94, v98
	v_mul_f32_e32 v99, v94, v99
	v_mul_f32_e32 v100, v94, v100
	v_mul_f32_e32 v101, v94, v101
	v_mul_f32_e32 v102, v94, v102
	v_mul_f32_e32 v103, v94, v103
	v_mul_f32_e32 v104, v94, v104
	v_mul_f32_e32 v105, v94, v105
	v_mul_f32_e32 v106, v94, v106
	v_mul_f32_e32 v107, v94, v107
	v_mul_f32_e32 v108, v94, v108
	v_mul_f32_e32 v109, v94, v109
	v_mul_f32_e32 v110, v94, v110
	v_mul_f32_e32 v111, v94, v111
	v_mul_f32_e32 v112, v94, v112
	v_mul_f32_e32 v113, v94, v113
	v_fma_f32 v98, v98, v10, v26
	v_fma_f32 v99, v99, v11, v27
	v_fma_f32 v100, v100, v12, v28
	v_fma_f32 v101, v101, v13, v29
	v_fma_f32 v102, v102, v14, v30
	v_fma_f32 v103, v103, v15, v31
	v_fma_f32 v104, v104, v16, v32
	v_fma_f32 v105, v105, v17, v33
	v_fma_f32 v106, v106, v18, v34
	v_fma_f32 v107, v107, v19, v35
	v_fma_f32 v108, v108, v20, v36
	v_fma_f32 v109, v109, v21, v37
	v_fma_f32 v110, v110, v22, v38
	v_fma_f32 v111, v111, v23, v39
	v_fma_f32 v112, v112, v24, v40
	v_fma_f32 v113, v113, v25, v41
	s_add_u32 s2, s8, 0x1800000
	s_addc_u32 s3, s9, 0
	global_store_dwordx4 v0, v[98:101], s[2:3]
	global_store_dwordx4 v0, v[102:105], s[2:3] offset:1024
	global_store_dwordx4 v0, v[106:109], s[2:3] offset:2048
	global_store_dwordx4 v0, v[110:113], s[2:3] offset:3072
	s_add_u32 s2, s8, 0x3800000
	s_addc_u32 s3, s9, 0
	global_load_dwordx4 v[98:101], v0, s[2:3]
	global_load_dwordx4 v[102:105], v0, s[2:3] offset:1024
	global_load_dwordx4 v[106:109], v0, s[2:3] offset:2048
	global_load_dwordx4 v[110:113], v0, s[2:3] offset:3072
	s_waitcnt vmcnt(24)
; DI void ln_row_v(const Frame& F, f32x4 (&v)[4], float* xout, const float* g, const float* b, const float* sh, const float* sc, bf16_t* hout, const float* slab, const float* gres, float* stat = nullptr) {
;     ...
;         float s = 0.f, s2 = 0.f;
; #pragma unroll
;         for (int j = 0; j < 4; ++j) { s += (v[j][0] + v[j][1]) + (v[j][2] + v[j][3]); s2 += (v[j][0] * v[j][0] + v[j][1] * v[j][1]) + (v[j][2] * v[j][2] + v[j][3] * v[j][3]); }
;         wave_sum2(s, s2, F.lane);
;         const float mean = s * (1.f / D); const float rstd = 1.f / sqrtf(fmaxf(s2 * (1.f / D) - mean * mean, 0.f) + EPS);
;         if (stat && F.lane == 0) { f32x2 sv = {mean, rstd}; *(f32x2*)stat = sv; }
; #pragma unroll
;         for (int j = 0; j < 4; ++j) { const f32x4 gg = ((const f32x4*)g)[F.lane + 64 * j], bb = ((const f32x4*)b)[F.lane + 64 * j];
;             v[j] = (v[j] - mean) * rstd * gg + bb; if (xout) ((f32x4*)xout)[F.lane + 64 * j] = v[j]; }
	v_add_f32_e32 v9, v42, v43
	v_add_f32_e32 v91, v44, v45
	v_mul_f32_e32 v90, v42, v42
	v_mul_f32_e32 v92, v43, v43
	v_add_f32_e32 v9, v9, v46
	v_add_f32_e32 v91, v91, v47
	v_add_f32_e32 v9, v9, v48
	v_add_f32_e32 v91, v91, v49
	v_add_f32_e32 v9, v9, v50
	v_add_f32_e32 v91, v91, v51
	v_add_f32_e32 v9, v9, v52
	v_add_f32_e32 v91, v91, v53
	v_add_f32_e32 v9, v9, v54
	v_add_f32_e32 v91, v91, v55
	v_add_f32_e32 v9, v9, v56
	v_add_f32_e32 v91, v91, v57
	v_fmac_f32_e32 v90, v44, v44
	v_fmac_f32_e32 v92, v45, v45
	v_fmac_f32_e32 v90, v46, v46
	v_fmac_f32_e32 v92, v47, v47
	v_fmac_f32_e32 v90, v48, v48
	v_fmac_f32_e32 v92, v49, v49
	v_fmac_f32_e32 v90, v50, v50
	v_fmac_f32_e32 v92, v51, v51
	v_fmac_f32_e32 v90, v52, v52
	v_fmac_f32_e32 v92, v53, v53
	v_fmac_f32_e32 v90, v54, v54
	v_fmac_f32_e32 v92, v55, v55
	v_fmac_f32_e32 v90, v56, v56
	v_fmac_f32_e32 v92, v57, v57
	v_add_f32_e32 v9, v9, v91
	v_add_f32_e32 v90, v90, v92
	ds_bpermute_b32 v91, v3, v9
	ds_bpermute_b32 v92, v3, v90
	s_waitcnt lgkmcnt(0)
	v_add_f32_e32 v9, v9, v91
	v_add_f32_e32 v90, v90, v92
	ds_bpermute_b32 v91, v4, v9
	ds_bpermute_b32 v92, v4, v90
	s_waitcnt lgkmcnt(0)
	v_add_f32_e32 v9, v9, v91
	v_add_f32_e32 v90, v90, v92
	ds_bpermute_b32 v91, v5, v9
	ds_bpermute_b32 v92, v5, v90
	s_waitcnt lgkmcnt(0)
	v_add_f32_e32 v9, v9, v91
	v_add_f32_e32 v90, v90, v92
	ds_bpermute_b32 v91, v6, v9
	ds_bpermute_b32 v92, v6, v90
	s_waitcnt lgkmcnt(0)
	v_add_f32_e32 v9, v9, v91
	v_add_f32_e32 v90, v90, v92
	ds_bpermute_b32 v91, v7, v9
	ds_bpermute_b32 v92, v7, v90
	s_waitcnt lgkmcnt(0)
	v_add_f32_e32 v9, v9, v91
	v_add_f32_e32 v90, v90, v92
	ds_bpermute_b32 v91, v8, v9
	ds_bpermute_b32 v92, v8, v90
	s_waitcnt lgkmcnt(0)
	v_add_f32_e32 v9, v9, v91
	v_add_f32_e32 v90, v90, v92
	v_mul_f32_e32 v93, 0x3a800000, v9
	v_mul_f32_e32 v91, 0x3a800000, v90
	v_fma_f32 v91, -v93, v93, v91
	v_max_f32_e32 v91, 0, v91
	v_add_f32_e32 v91, 0x358637bd, v91
	v_rsq_f32_e32 v94, v91
	v_mul_f32_e32 v91, 0.5, v91
	v_mul_f32_e32 v92, v94, v94
	v_fma_f32 v92, -v91, v92, 0.5
	v_fma_f32 v94, v94, v92, v94
	v_sub_f32_e32 v42, v42, v93
	v_sub_f32_e32 v43, v43, v93
	v_sub_f32_e32 v44, v44, v93
	v_sub_f32_e32 v45, v45, v93
	v_sub_f32_e32 v46, v46, v93
	v_sub_f32_e32 v47, v47, v93
	v_sub_f32_e32 v48, v48, v93
	v_sub_f32_e32 v49, v49, v93
	v_sub_f32_e32 v50, v50, v93
	v_sub_f32_e32 v51, v51, v93
	v_sub_f32_e32 v52, v52, v93
	v_sub_f32_e32 v53, v53, v93
	v_sub_f32_e32 v54, v54, v93
	v_sub_f32_e32 v55, v55, v93
	v_sub_f32_e32 v56, v56, v93
	v_sub_f32_e32 v57, v57, v93
	v_mul_f32_e32 v42, v94, v42
	v_mul_f32_e32 v43, v94, v43
	v_mul_f32_e32 v44, v94, v44
	v_mul_f32_e32 v45, v94, v45
	v_mul_f32_e32 v46, v94, v46
	v_mul_f32_e32 v47, v94, v47
	v_mul_f32_e32 v48, v94, v48
	v_mul_f32_e32 v49, v94, v49
	v_mul_f32_e32 v50, v94, v50
	v_mul_f32_e32 v51, v94, v51
	v_mul_f32_e32 v52, v94, v52
	v_mul_f32_e32 v53, v94, v53
	v_mul_f32_e32 v54, v94, v54
	v_mul_f32_e32 v55, v94, v55
	v_mul_f32_e32 v56, v94, v56
	v_mul_f32_e32 v57, v94, v57
	v_fma_f32 v42, v42, v10, v26
	v_fma_f32 v43, v43, v11, v27
	v_fma_f32 v44, v44, v12, v28
	v_fma_f32 v45, v45, v13, v29
	v_fma_f32 v46, v46, v14, v30
	v_fma_f32 v47, v47, v15, v31
	v_fma_f32 v48, v48, v16, v32
	v_fma_f32 v49, v49, v17, v33
	v_fma_f32 v50, v50, v18, v34
	v_fma_f32 v51, v51, v19, v35
	v_fma_f32 v52, v52, v20, v36
	v_fma_f32 v53, v53, v21, v37
	v_fma_f32 v54, v54, v22, v38
	v_fma_f32 v55, v55, v23, v39
	v_fma_f32 v56, v56, v24, v40
	v_fma_f32 v57, v57, v25, v41
	s_add_u32 s2, s8, 0x2000000
	s_addc_u32 s3, s9, 0
	global_store_dwordx4 v0, v[42:45], s[2:3]
	global_store_dwordx4 v0, v[46:49], s[2:3] offset:1024
	global_store_dwordx4 v0, v[50:53], s[2:3] offset:2048
	global_store_dwordx4 v0, v[54:57], s[2:3] offset:3072
	s_waitcnt vmcnt(20)
	v_add_f32_e32 v9, v58, v59
	v_add_f32_e32 v91, v60, v61
	v_mul_f32_e32 v90, v58, v58
	v_mul_f32_e32 v92, v59, v59
	v_add_f32_e32 v9, v9, v62
	v_add_f32_e32 v91, v91, v63
	v_add_f32_e32 v9, v9, v64
	v_add_f32_e32 v91, v91, v65
	v_add_f32_e32 v9, v9, v66
	v_add_f32_e32 v91, v91, v67
	v_add_f32_e32 v9, v9, v68
	v_add_f32_e32 v91, v91, v69
	v_add_f32_e32 v9, v9, v70
	v_add_f32_e32 v91, v91, v71
	v_add_f32_e32 v9, v9, v72
	v_add_f32_e32 v91, v91, v73
	v_fmac_f32_e32 v90, v60, v60
	v_fmac_f32_e32 v92, v61, v61
	v_fmac_f32_e32 v90, v62, v62
	v_fmac_f32_e32 v92, v63, v63
	v_fmac_f32_e32 v90, v64, v64
	v_fmac_f32_e32 v92, v65, v65
	v_fmac_f32_e32 v90, v66, v66
	v_fmac_f32_e32 v92, v67, v67
	v_fmac_f32_e32 v90, v68, v68
	v_fmac_f32_e32 v92, v69, v69
	v_fmac_f32_e32 v90, v70, v70
	v_fmac_f32_e32 v92, v71, v71
	v_fmac_f32_e32 v90, v72, v72
	v_fmac_f32_e32 v92, v73, v73
	v_add_f32_e32 v9, v9, v91
	v_add_f32_e32 v90, v90, v92
	ds_bpermute_b32 v91, v3, v9
	ds_bpermute_b32 v92, v3, v90
	s_waitcnt lgkmcnt(0)
	v_add_f32_e32 v9, v9, v91
	v_add_f32_e32 v90, v90, v92
	ds_bpermute_b32 v91, v4, v9
	ds_bpermute_b32 v92, v4, v90
	s_waitcnt lgkmcnt(0)
	v_add_f32_e32 v9, v9, v91
	v_add_f32_e32 v90, v90, v92
	ds_bpermute_b32 v91, v5, v9
	ds_bpermute_b32 v92, v5, v90
	s_waitcnt lgkmcnt(0)
	v_add_f32_e32 v9, v9, v91
	v_add_f32_e32 v90, v90, v92
	ds_bpermute_b32 v91, v6, v9
	ds_bpermute_b32 v92, v6, v90
	s_waitcnt lgkmcnt(0)
	v_add_f32_e32 v9, v9, v91
	v_add_f32_e32 v90, v90, v92
	ds_bpermute_b32 v91, v7, v9
	ds_bpermute_b32 v92, v7, v90
	s_waitcnt lgkmcnt(0)
	v_add_f32_e32 v9, v9, v91
	v_add_f32_e32 v90, v90, v92
	ds_bpermute_b32 v91, v8, v9
	ds_bpermute_b32 v92, v8, v90
	s_waitcnt lgkmcnt(0)
; DI void ln_row_v(const Frame& F, f32x4 (&v)[4], float* xout, const float* g, const float* b, const float* sh, const float* sc, bf16_t* hout, const float* slab, const float* gres, float* stat = nullptr) {
;     ...
;         float s = 0.f, s2 = 0.f;
; #pragma unroll
;         for (int j = 0; j < 4; ++j) { s += (v[j][0] + v[j][1]) + (v[j][2] + v[j][3]); s2 += (v[j][0] * v[j][0] + v[j][1] * v[j][1]) + (v[j][2] * v[j][2] + v[j][3] * v[j][3]); }
;         wave_sum2(s, s2, F.lane);
;         const float mean = s * (1.f / D); const float rstd = 1.f / sqrtf(fmaxf(s2 * (1.f / D) - mean * mean, 0.f) + EPS);
;         if (stat && F.lane == 0) { f32x2 sv = {mean, rstd}; *(f32x2*)stat = sv; }
; #pragma unroll
;         for (int j = 0; j < 4; ++j) { const f32x4 gg = ((const f32x4*)g)[F.lane + 64 * j], bb = ((const f32x4*)b)[F.lane + 64 * j];
;             v[j] = (v[j] - mean) * rstd * gg + bb; if (xout) ((f32x4*)xout)[F.lane + 64 * j] = v[j]; }
	v_add_f32_e32 v9, v9, v91
	v_add_f32_e32 v90, v90, v92
	v_mul_f32_e32 v93, 0x3a800000, v9
	v_mul_f32_e32 v91, 0x3a800000, v90
	v_fma_f32 v91, -v93, v93, v91
	v_max_f32_e32 v91, 0, v91
	v_add_f32_e32 v91, 0x358637bd, v91
	v_rsq_f32_e32 v94, v91
	v_mul_f32_e32 v91, 0.5, v91
	v_mul_f32_e32 v92, v94, v94
	v_fma_f32 v92, -v91, v92, 0.5
	v_fma_f32 v94, v94, v92, v94
	v_sub_f32_e32 v58, v58, v93
	v_sub_f32_e32 v59, v59, v93
	v_sub_f32_e32 v60, v60, v93
	v_sub_f32_e32 v61, v61, v93
	v_sub_f32_e32 v62, v62, v93
	v_sub_f32_e32 v63, v63, v93
	v_sub_f32_e32 v64, v64, v93
	v_sub_f32_e32 v65, v65, v93
	v_sub_f32_e32 v66, v66, v93
	v_sub_f32_e32 v67, v67, v93
	v_sub_f32_e32 v68, v68, v93
	v_sub_f32_e32 v69, v69, v93
	v_sub_f32_e32 v70, v70, v93
	v_sub_f32_e32 v71, v71, v93
	v_sub_f32_e32 v72, v72, v93
	v_sub_f32_e32 v73, v73, v93
	v_mul_f32_e32 v58, v94, v58
	v_mul_f32_e32 v59, v94, v59
	v_mul_f32_e32 v60, v94, v60
	v_mul_f32_e32 v61, v94, v61
	v_mul_f32_e32 v62, v94, v62
	v_mul_f32_e32 v63, v94, v63
	v_mul_f32_e32 v64, v94, v64
	v_mul_f32_e32 v65, v94, v65
	v_mul_f32_e32 v66, v94, v66
	v_mul_f32_e32 v67, v94, v67
	v_mul_f32_e32 v68, v94, v68
	v_mul_f32_e32 v69, v94, v69
	v_mul_f32_e32 v70, v94, v70
	v_mul_f32_e32 v71, v94, v71
	v_mul_f32_e32 v72, v94, v72
	v_mul_f32_e32 v73, v94, v73
	v_fma_f32 v58, v58, v10, v26
	v_fma_f32 v59, v59, v11, v27
	v_fma_f32 v60, v60, v12, v28
	v_fma_f32 v61, v61, v13, v29
	v_fma_f32 v62, v62, v14, v30
	v_fma_f32 v63, v63, v15, v31
	v_fma_f32 v64, v64, v16, v32
	v_fma_f32 v65, v65, v17, v33
	v_fma_f32 v66, v66, v18, v34
	v_fma_f32 v67, v67, v19, v35
	v_fma_f32 v68, v68, v20, v36
	v_fma_f32 v69, v69, v21, v37
	v_fma_f32 v70, v70, v22, v38
	v_fma_f32 v71, v71, v23, v39
	v_fma_f32 v72, v72, v24, v40
	v_fma_f32 v73, v73, v25, v41
	s_add_u32 s2, s8, 0x2800000
	s_addc_u32 s3, s9, 0
	global_store_dwordx4 v0, v[58:61], s[2:3]
	global_store_dwordx4 v0, v[62:65], s[2:3] offset:1024
	global_store_dwordx4 v0, v[66:69], s[2:3] offset:2048
	global_store_dwordx4 v0, v[70:73], s[2:3] offset:3072
	s_waitcnt vmcnt(16)
	v_add_f32_e32 v9, v74, v75
	v_add_f32_e32 v91, v76, v77
	v_mul_f32_e32 v90, v74, v74
	v_mul_f32_e32 v92, v75, v75
	v_add_f32_e32 v9, v9, v78
	v_add_f32_e32 v91, v91, v79
	v_add_f32_e32 v9, v9, v80
	v_add_f32_e32 v91, v91, v81
	v_add_f32_e32 v9, v9, v82
	v_add_f32_e32 v91, v91, v83
	v_add_f32_e32 v9, v9, v84
	v_add_f32_e32 v91, v91, v85
	v_add_f32_e32 v9, v9, v86
	v_add_f32_e32 v91, v91, v87
	v_add_f32_e32 v9, v9, v88
	v_add_f32_e32 v91, v91, v89
	v_fmac_f32_e32 v90, v76, v76
	v_fmac_f32_e32 v92, v77, v77
	v_fmac_f32_e32 v90, v78, v78
	v_fmac_f32_e32 v92, v79, v79
	v_fmac_f32_e32 v90, v80, v80
	v_fmac_f32_e32 v92, v81, v81
	v_fmac_f32_e32 v90, v82, v82
	v_fmac_f32_e32 v92, v83, v83
	v_fmac_f32_e32 v90, v84, v84
	v_fmac_f32_e32 v92, v85, v85
	v_fmac_f32_e32 v90, v86, v86
	v_fmac_f32_e32 v92, v87, v87
	v_fmac_f32_e32 v90, v88, v88
	v_fmac_f32_e32 v92, v89, v89
	v_add_f32_e32 v9, v9, v91
	v_add_f32_e32 v90, v90, v92
	ds_bpermute_b32 v91, v3, v9
	ds_bpermute_b32 v92, v3, v90
	s_waitcnt lgkmcnt(0)
	v_add_f32_e32 v9, v9, v91
	v_add_f32_e32 v90, v90, v92
	ds_bpermute_b32 v91, v4, v9
	ds_bpermute_b32 v92, v4, v90
	s_waitcnt lgkmcnt(0)
	v_add_f32_e32 v9, v9, v91
	v_add_f32_e32 v90, v90, v92
	ds_bpermute_b32 v91, v5, v9
	ds_bpermute_b32 v92, v5, v90
	s_waitcnt lgkmcnt(0)
	v_add_f32_e32 v9, v9, v91
	v_add_f32_e32 v90, v90, v92
	ds_bpermute_b32 v91, v6, v9
	ds_bpermute_b32 v92, v6, v90
	s_waitcnt lgkmcnt(0)
	v_add_f32_e32 v9, v9, v91
	v_add_f32_e32 v90, v90, v92
	ds_bpermute_b32 v91, v7, v9
	ds_bpermute_b32 v92, v7, v90
	s_waitcnt lgkmcnt(0)
	v_add_f32_e32 v9, v9, v91
	v_add_f32_e32 v90, v90, v92
	ds_bpermute_b32 v91, v8, v9
	ds_bpermute_b32 v92, v8, v90
	s_waitcnt lgkmcnt(0)
	v_add_f32_e32 v9, v9, v91
	v_add_f32_e32 v90, v90, v92
	v_mul_f32_e32 v93, 0x3a800000, v9
	v_mul_f32_e32 v91, 0x3a800000, v90
	v_fma_f32 v91, -v93, v93, v91
	v_max_f32_e32 v91, 0, v91
	v_add_f32_e32 v91, 0x358637bd, v91
	v_rsq_f32_e32 v94, v91
	v_mul_f32_e32 v91, 0.5, v91
	v_mul_f32_e32 v92, v94, v94
	v_fma_f32 v92, -v91, v92, 0.5
	v_fma_f32 v94, v94, v92, v94
	v_sub_f32_e32 v74, v74, v93
	v_sub_f32_e32 v75, v75, v93
	v_sub_f32_e32 v76, v76, v93
	v_sub_f32_e32 v77, v77, v93
	v_sub_f32_e32 v78, v78, v93
	v_sub_f32_e32 v79, v79, v93
	v_sub_f32_e32 v80, v80, v93
	v_sub_f32_e32 v81, v81, v93
	v_sub_f32_e32 v82, v82, v93
	v_sub_f32_e32 v83, v83, v93
	v_sub_f32_e32 v84, v84, v93
	v_sub_f32_e32 v85, v85, v93
	v_sub_f32_e32 v86, v86, v93
	v_sub_f32_e32 v87, v87, v93
	v_sub_f32_e32 v88, v88, v93
	v_sub_f32_e32 v89, v89, v93
	v_mul_f32_e32 v74, v94, v74
	v_mul_f32_e32 v75, v94, v75
	v_mul_f32_e32 v76, v94, v76
	v_mul_f32_e32 v77, v94, v77
	v_mul_f32_e32 v78, v94, v78
	v_mul_f32_e32 v79, v94, v79
	v_mul_f32_e32 v80, v94, v80
	v_mul_f32_e32 v81, v94, v81
	v_mul_f32_e32 v82, v94, v82
	v_mul_f32_e32 v83, v94, v83
	v_mul_f32_e32 v84, v94, v84
	v_mul_f32_e32 v85, v94, v85
	v_mul_f32_e32 v86, v94, v86
	v_mul_f32_e32 v87, v94, v87
	v_mul_f32_e32 v88, v94, v88
	v_mul_f32_e32 v89, v94, v89
	v_fma_f32 v74, v74, v10, v26
	v_fma_f32 v75, v75, v11, v27
	v_fma_f32 v76, v76, v12, v28
	v_fma_f32 v77, v77, v13, v29
	v_fma_f32 v78, v78, v14, v30
	v_fma_f32 v79, v79, v15, v31
	v_fma_f32 v80, v80, v16, v32
	v_fma_f32 v81, v81, v17, v33
	v_fma_f32 v82, v82, v18, v34
	v_fma_f32 v83, v83, v19, v35
	v_fma_f32 v84, v84, v20, v36
	v_fma_f32 v85, v85, v21, v37
	v_fma_f32 v86, v86, v22, v38
	v_fma_f32 v87, v87, v23, v39
	v_fma_f32 v88, v88, v24, v40
	v_fma_f32 v89, v89, v25, v41
	s_add_u32 s2, s8, 0x3000000
	s_addc_u32 s3, s9, 0
	global_store_dwordx4 v0, v[74:77], s[2:3]
	global_store_dwordx4 v0, v[78:81], s[2:3] offset:1024
	global_store_dwordx4 v0, v[82:85], s[2:3] offset:2048
	global_store_dwordx4 v0, v[86:89], s[2:3] offset:3072
	s_waitcnt vmcnt(12)
; DI void ln_row_v(const Frame& F, f32x4 (&v)[4], float* xout, const float* g, const float* b, const float* sh, const float* sc, bf16_t* hout, const float* slab, const float* gres, float* stat = nullptr) {
;     ...
;         float s = 0.f, s2 = 0.f;
; #pragma unroll
;         for (int j = 0; j < 4; ++j) { s += (v[j][0] + v[j][1]) + (v[j][2] + v[j][3]); s2 += (v[j][0] * v[j][0] + v[j][1] * v[j][1]) + (v[j][2] * v[j][2] + v[j][3] * v[j][3]); }
;         wave_sum2(s, s2, F.lane);
;         const float mean = s * (1.f / D); const float rstd = 1.f / sqrtf(fmaxf(s2 * (1.f / D) - mean * mean, 0.f) + EPS);
;         if (stat && F.lane == 0) { f32x2 sv = {mean, rstd}; *(f32x2*)stat = sv; }
; #pragma unroll
;         for (int j = 0; j < 4; ++j) { const f32x4 gg = ((const f32x4*)g)[F.lane + 64 * j], bb = ((const f32x4*)b)[F.lane + 64 * j];
;             v[j] = (v[j] - mean) * rstd * gg + bb; if (xout) ((f32x4*)xout)[F.lane + 64 * j] = v[j]; }
	v_add_f32_e32 v9, v98, v99
	v_add_f32_e32 v91, v100, v101
	v_mul_f32_e32 v90, v98, v98
	v_mul_f32_e32 v92, v99, v99
	v_add_f32_e32 v9, v9, v102
	v_add_f32_e32 v91, v91, v103
	v_add_f32_e32 v9, v9, v104
	v_add_f32_e32 v91, v91, v105
	v_add_f32_e32 v9, v9, v106
	v_add_f32_e32 v91, v91, v107
	v_add_f32_e32 v9, v9, v108
	v_add_f32_e32 v91, v91, v109
	v_add_f32_e32 v9, v9, v110
	v_add_f32_e32 v91, v91, v111
	v_add_f32_e32 v9, v9, v112
	v_add_f32_e32 v91, v91, v113
	v_fmac_f32_e32 v90, v100, v100
	v_fmac_f32_e32 v92, v101, v101
	v_fmac_f32_e32 v90, v102, v102
	v_fmac_f32_e32 v92, v103, v103
	v_fmac_f32_e32 v90, v104, v104
	v_fmac_f32_e32 v92, v105, v105
	v_fmac_f32_e32 v90, v106, v106
	v_fmac_f32_e32 v92, v107, v107
	v_fmac_f32_e32 v90, v108, v108
	v_fmac_f32_e32 v92, v109, v109
	v_fmac_f32_e32 v90, v110, v110
	v_fmac_f32_e32 v92, v111, v111
	v_fmac_f32_e32 v90, v112, v112
	v_fmac_f32_e32 v92, v113, v113
	v_add_f32_e32 v9, v9, v91
	v_add_f32_e32 v90, v90, v92
	ds_bpermute_b32 v91, v3, v9
	ds_bpermute_b32 v92, v3, v90
	s_waitcnt lgkmcnt(0)
	v_add_f32_e32 v9, v9, v91
	v_add_f32_e32 v90, v90, v92
	ds_bpermute_b32 v91, v4, v9
	ds_bpermute_b32 v92, v4, v90
	s_waitcnt lgkmcnt(0)
	v_add_f32_e32 v9, v9, v91
	v_add_f32_e32 v90, v90, v92
	ds_bpermute_b32 v91, v5, v9
	ds_bpermute_b32 v92, v5, v90
	s_waitcnt lgkmcnt(0)
	v_add_f32_e32 v9, v9, v91
	v_add_f32_e32 v90, v90, v92
	ds_bpermute_b32 v91, v6, v9
	ds_bpermute_b32 v92, v6, v90
	s_waitcnt lgkmcnt(0)
	v_add_f32_e32 v9, v9, v91
	v_add_f32_e32 v90, v90, v92
	ds_bpermute_b32 v91, v7, v9
	ds_bpermute_b32 v92, v7, v90
	s_waitcnt lgkmcnt(0)
	v_add_f32_e32 v9, v9, v91
	v_add_f32_e32 v90, v90, v92
	ds_bpermute_b32 v91, v8, v9
	ds_bpermute_b32 v92, v8, v90
	s_waitcnt lgkmcnt(0)
	v_add_f32_e32 v9, v9, v91
	v_add_f32_e32 v90, v90, v92
	v_mul_f32_e32 v93, 0x3a800000, v9
	v_mul_f32_e32 v91, 0x3a800000, v90
	v_fma_f32 v91, -v93, v93, v91
	v_max_f32_e32 v91, 0, v91
	v_add_f32_e32 v91, 0x358637bd, v91
	v_rsq_f32_e32 v94, v91
	v_mul_f32_e32 v91, 0.5, v91
	v_mul_f32_e32 v92, v94, v94
	v_fma_f32 v92, -v91, v92, 0.5
	v_fma_f32 v94, v94, v92, v94
	v_sub_f32_e32 v98, v98, v93
	v_sub_f32_e32 v99, v99, v93
	v_sub_f32_e32 v100, v100, v93
	v_sub_f32_e32 v101, v101, v93
	v_sub_f32_e32 v102, v102, v93
	v_sub_f32_e32 v103, v103, v93
	v_sub_f32_e32 v104, v104, v93
	v_sub_f32_e32 v105, v105, v93
	v_sub_f32_e32 v106, v106, v93
	v_sub_f32_e32 v107, v107, v93
	v_sub_f32_e32 v108, v108, v93
	v_sub_f32_e32 v109, v109, v93
	v_sub_f32_e32 v110, v110, v93
	v_sub_f32_e32 v111, v111, v93
	v_sub_f32_e32 v112, v112, v93
	v_sub_f32_e32 v113, v113, v93
	v_mul_f32_e32 v98, v94, v98
	v_mul_f32_e32 v99, v94, v99
	v_mul_f32_e32 v100, v94, v100
	v_mul_f32_e32 v101, v94, v101
	v_mul_f32_e32 v102, v94, v102
	v_mul_f32_e32 v103, v94, v103
	v_mul_f32_e32 v104, v94, v104
	v_mul_f32_e32 v105, v94, v105
	v_mul_f32_e32 v106, v94, v106
	v_mul_f32_e32 v107, v94, v107
	v_mul_f32_e32 v108, v94, v108
	v_mul_f32_e32 v109, v94, v109
	v_mul_f32_e32 v110, v94, v110
	v_mul_f32_e32 v111, v94, v111
	v_mul_f32_e32 v112, v94, v112
	v_mul_f32_e32 v113, v94, v113
	v_fma_f32 v98, v98, v10, v26
	v_fma_f32 v99, v99, v11, v27
	v_fma_f32 v100, v100, v12, v28
	v_fma_f32 v101, v101, v13, v29
	v_fma_f32 v102, v102, v14, v30
	v_fma_f32 v103, v103, v15, v31
	v_fma_f32 v104, v104, v16, v32
	v_fma_f32 v105, v105, v17, v33
	v_fma_f32 v106, v106, v18, v34
	v_fma_f32 v107, v107, v19, v35
	v_fma_f32 v108, v108, v20, v36
	v_fma_f32 v109, v109, v21, v37
	v_fma_f32 v110, v110, v22, v38
	v_fma_f32 v111, v111, v23, v39
	v_fma_f32 v112, v112, v24, v40
	v_fma_f32 v113, v113, v25, v41
	s_add_u32 s2, s8, 0x3800000
	s_addc_u32 s3, s9, 0
	global_store_dwordx4 v0, v[98:101], s[2:3]
	global_store_dwordx4 v0, v[102:105], s[2:3] offset:1024
	global_store_dwordx4 v0, v[106:109], s[2:3] offset:2048
	global_store_dwordx4 v0, v[110:113], s[2:3] offset:3072
	s_waitcnt vmcnt(0)
; DI void ln_phase(const Frame& F, int which) {
;     const int gw = F.vcu * 8 + F.wave, NGW = F.G * 8; const int l = F.l;
;     const int nrows = (l == NL - 1) ? ML : MT;
;     bf16_t* H = (bf16_t*)(F.ws + WS_HB);
;     const float* g = pin(F, which == 0 ? I_LN1G : I_LN2G) + l * 1024; const float* b = pin(F, which == 0 ? I_LN1B : I_LN2B) + l * 1024;
;     const bool wh = !(which == 1 && l == NL - 1);
;     f32x4 vc[4], vn[4];
;     if (gw < nrows) ln_load(F, xrow_ptr(F, gw), vc);
;     for (int row = gw; row < nrows; row += NGW) {
;         if (row + NGW < nrows) ln_load(F, xrow_ptr(F, row + NGW), vn);
.Lln_b_done:
	s_add_i32 s16, s16, 0x4000
	s_add_i32 s2, s70, 0xffe5
	s_and_b32 s2, s2, 0xff
	s_cmp_gt_u32 s2, 8
	s_cselect_b64 s[8:9], -1, 0
	s_cmp_lt_u32 s2, 9
	s_cselect_b64 s[12:13], -1, 0
	s_and_b64 s[2:3], s[12:13], exec
	s_movk_i32 s2, 0x4800
	s_cselect_b32 s28, 0x4000, s2
	s_cmp_ge_u32 s16, s28
	s_cbranch_scc1 .LBB0_536
	s_lshl_b64 s[2:3], s[44:45], 3
	s_add_u32 s2, s62, s2
	s_addc_u32 s3, s63, s3
	s_load_dwordx4 s[4:7], s[2:3], 0xb8
	v_readlane_b32 s18, v255, 35
	s_lshl_b32 s2, s18, 12
	v_mov_b32_e32 v0, s16
	v_sub_co_u32_e32 v1, vcc, s16, v217
	s_waitcnt lgkmcnt(0)
	s_add_u32 s10, s6, s2
	s_addc_u32 s11, s7, 0
	s_add_u32 s14, s4, s2
	s_addc_u32 s15, s5, 0
	s_add_u32 s29, s94, 0x3600000
	s_addc_u32 s30, s95, 0
	v_readlane_b32 s20, v255, 17
	v_cndmask_b32_e32 v0, v1, v0, vcc
	v_mov_b32_e32 v1, v97
	s_and_b64 s[2:3], vcc, exec
	v_readlane_b32 s21, v255, 18
	s_cselect_b32 s3, s21, s30
	s_cselect_b32 s2, s20, s29
	v_lshlrev_b64 v[0:1], 12, v[0:1]
	v_lshl_add_u64 v[0:1], s[2:3], 0, v[0:1]
	v_lshlrev_b32_e32 v12, 4, v186
	v_readfirstlane_b32 s2, v0
	v_readfirstlane_b32 s3, v1
	s_nop 4
	global_load_dwordx4 v[16:19], v12, s[2:3]
	global_load_dwordx4 v[8:11], v12, s[2:3] offset:1024
	global_load_dwordx4 v[4:7], v12, s[2:3] offset:2048
	global_load_dwordx4 v[0:3], v12, s[2:3] offset:3072
	v_readlane_b32 s2, v255, 34
	s_cmp_lt_u32 s2, 27
	s_cselect_b64 s[2:3], -1, 0
	s_cmp_lg_u64 s[2:3], 0
	v_mov_b32_e32 v13, v97
	s_addc_u32 s31, s18, 0
	s_cmp_lg_u64 s[4:5], 0
	v_lshl_add_u64 v[32:33], s[14:15], 0, v[12:13]
	v_lshl_add_u64 v[34:35], s[10:11], 0, v[12:13]
	v_lshl_add_u64 v[12:13], s[94:95], 0, v[12:13]
	s_mov_b64 s[4:5], 0x9100000
	v_lshl_add_u64 v[36:37], v[12:13], 0, s[4:5]
	s_mov_b64 s[4:5], 0x105000
	v_lshl_add_u64 v[38:39], v[12:13], 0, s[4:5]
	s_mov_b64 s[4:5], 0x100000
	v_lshl_add_u64 v[40:41], v[12:13], 0, s[4:5]
	s_mov_b64 s[4:5], 0x101000
	s_cselect_b64 s[6:7], -1, 0
	v_lshl_add_u64 v[42:43], v[12:13], 0, s[4:5]
	s_lshl_b32 s34, s93, 3
	s_lshl_b32 s4, s16, 3
	s_add_u32 s4, s4, s44
	s_addc_u32 s5, 0, s45
	v_readlane_b32 s10, v255, 16
	s_add_u32 s14, s10, s4
	v_readlane_b32 s4, v255, 21
	s_addc_u32 s15, s4, s5
	s_lshl_b32 s35, s93, 6
	s_lshl_b64 s[4:5], s[16:17], 11
	v_readlane_b32 s10, v255, 6
	s_add_u32 s10, s10, s44
	v_readlane_b32 s11, v255, 7
	s_addc_u32 s11, s11, s45
	s_add_u32 s4, s10, s4
	v_lshlrev_b32_e32 v12, 3, v186
	v_mov_b32_e32 v13, v97
	s_addc_u32 s5, s11, s5
	v_lshlrev_b32_e32 v14, 2, v186
	v_lshl_add_u64 v[44:45], s[4:5], 0, v[12:13]
	v_mov_b32_e32 v12, 0
	s_mul_i32 s31, s31, 9
	v_xor_b32_e32 v52, 4, v14
	v_xor_b32_e32 v53, 8, v14
	v_xor_b32_e32 v54, 16, v14
	v_xor_b32_e32 v55, 32, v14
	v_xor_b32_e32 v56, 64, v14
	v_xor_b32_e32 v57, 0x80, v14
	v_cmp_ne_u32_e64 s[2:3], 0, v186
	s_lshl_b32 s18, s93, 14
	s_mov_b32 s19, s17
	s_mov_b64 s[4:5], s[16:17]
	v_mov_b32_e32 v13, v12
	v_mov_b32_e32 v14, v12
	v_mov_b32_e32 v15, v12
	v_mov_b32_e32 v20, v12
	v_mov_b32_e32 v21, v12
	v_mov_b32_e32 v22, v12
	v_mov_b32_e32 v23, v12
	v_mov_b32_e32 v24, v12
	v_mov_b32_e32 v25, v12
	v_mov_b32_e32 v26, v12
	v_mov_b32_e32 v27, v12
	v_mov_b32_e32 v28, v12
	v_mov_b32_e32 v29, v12
	v_mov_b32_e32 v30, v12
	v_mov_b32_e32 v31, v12
	v_readlane_b32 s22, v255, 19
	v_readlane_b32 s23, v255, 20
	s_branch .LBB0_517

; #define MFMA32(a, b, c) __builtin_amdgcn_mfma_f32_32x32x16_bf16((a), (b), (c), 0, 0, 0)
; DI void krope_phase(const Frame& F, int crank, int ncu) {
;     ...
;         const bf16_t* hp = H + (size_t)(row0 + r32) * 1024 + 8 * h5 + 128 * w; const bf16_t* wp = Wk + (size_t)r32 * 1024 + 8 * h5 + 128 * w;
;         bf16x8 a[8], b[8];
; #pragma unroll
;         for (int q = 0; q < 8; ++q) { a[q] = *(const bf16x8*)(wp + 16 * q); b[q] = *(const bf16x8*)(hp + 16 * q); }
; #pragma unroll
;         for (int q = 0; q < 8; ++q) acc = MFMA32(a[q], b[q], acc);
;         __syncthreads();
; #pragma unroll
;         for (int i = 0; i < 16; ++i) part[(w * 16 + i) * 64 + F.lane] = acc[i];
;         __syncthreads();
.LBB0_542:
	v_lshlrev_b64 v[4:5], 11, v[96:97]
	v_lshl_add_u64 v[38:39], v[16:17], 0, v[4:5]
	global_load_dwordx4 v[100:103], v[18:19], off
	global_load_dwordx4 v[132:135], v[38:39], off
	global_load_dwordx4 v[104:107], v[18:19], off offset:32
	global_load_dwordx4 v[136:139], v[38:39], off offset:32
	global_load_dwordx4 v[108:111], v[18:19], off offset:64
	global_load_dwordx4 v[140:143], v[38:39], off offset:64
	global_load_dwordx4 v[112:115], v[18:19], off offset:96
	global_load_dwordx4 v[144:147], v[38:39], off offset:96
	global_load_dwordx4 v[116:119], v[18:19], off offset:128
	global_load_dwordx4 v[148:151], v[38:39], off offset:128
	global_load_dwordx4 v[120:123], v[18:19], off offset:160
	global_load_dwordx4 v[152:155], v[38:39], off offset:160
	global_load_dwordx4 v[124:127], v[18:19], off offset:192
	global_load_dwordx4 v[156:159], v[38:39], off offset:192
	global_load_dwordx4 v[128:131], v[18:19], off offset:224
	global_load_dwordx4 v[160:163], v[38:39], off offset:224
	s_andn2_b64 vcc, exec, s[8:9]
	s_waitcnt vmcnt(14)
	v_mfma_f32_32x32x16_bf16 v[0:15], v[100:103], v[132:135], 0
	s_waitcnt vmcnt(12)
	v_mfma_f32_32x32x16_bf16 v[0:15], v[104:107], v[136:139], v[0:15]
	s_waitcnt vmcnt(10)
	v_mfma_f32_32x32x16_bf16 v[0:15], v[108:111], v[140:143], v[0:15]
	s_waitcnt vmcnt(8)
	v_mfma_f32_32x32x16_bf16 v[0:15], v[112:115], v[144:147], v[0:15]
	s_waitcnt vmcnt(6)
	v_mfma_f32_32x32x16_bf16 v[0:15], v[116:119], v[148:151], v[0:15]
	s_waitcnt vmcnt(4)
	v_mfma_f32_32x32x16_bf16 v[0:15], v[120:123], v[152:155], v[0:15]
	s_waitcnt vmcnt(2)
	v_mfma_f32_32x32x16_bf16 v[0:15], v[124:127], v[156:159], v[0:15]
	s_waitcnt vmcnt(0)
	v_mfma_f32_32x32x16_bf16 v[0:15], v[128:131], v[160:163], v[0:15]
	s_waitcnt lgkmcnt(0)
	s_barrier
	s_nop 11
	ds_write2st64_b32 v22, v0, v1 offset1:1
	ds_write2st64_b32 v22, v2, v3 offset0:2 offset1:3
	ds_write2st64_b32 v22, v4, v5 offset0:4 offset1:5
	ds_write2st64_b32 v22, v6, v7 offset0:6 offset1:7
	ds_write2st64_b32 v22, v8, v9 offset0:8 offset1:9
	ds_write2st64_b32 v22, v10, v11 offset0:10 offset1:11
	ds_write2st64_b32 v22, v12, v13 offset0:12 offset1:13
	ds_write2st64_b32 v22, v14, v15 offset0:14 offset1:15
	s_waitcnt lgkmcnt(0)
	s_barrier
	s_cbranch_vccnz .LBB0_541
	ds_read2st64_b32 v[0:1], v23 offset1:1
	ds_read2st64_b32 v[2:3], v23 offset0:16 offset1:17
	ds_read2st64_b32 v[4:5], v23 offset0:2 offset1:3
	ds_read2st64_b32 v[6:7], v23 offset0:4 offset1:5
	ds_read2st64_b32 v[8:9], v23 offset0:6 offset1:7
	s_waitcnt lgkmcnt(4)
	v_add_f32_e32 v0, 0, v0
	ds_read2st64_b32 v[10:11], v23 offset0:18 offset1:19
	ds_read2st64_b32 v[12:13], v23 offset0:20 offset1:21
	ds_read2st64_b32 v[14:15], v23 offset0:22 offset1:23
	s_waitcnt lgkmcnt(6)
	v_add_f32_e32 v0, v0, v2
	ds_read2st64_b32 v[26:27], v23 offset0:32 offset1:33
	ds_read2st64_b32 v[28:29], v23 offset0:48 offset1:49
	ds_read2st64_b32 v[30:31], v23 offset0:34 offset1:35
	ds_read2st64_b32 v[32:33], v23 offset0:36 offset1:37
	ds_read2st64_b32 v[34:35], v23 offset0:38 offset1:39
	s_waitcnt lgkmcnt(4)
	v_add_f32_e32 v0, v0, v26
	ds_read2st64_b32 v[36:37], v23 offset0:50 offset1:51
	ds_read2st64_b32 v[38:39], v23 offset0:52 offset1:53
	ds_read2st64_b32 v[40:41], v23 offset0:54 offset1:55
	s_waitcnt lgkmcnt(6)
	v_add_f32_e32 v0, v0, v28
	ds_read2st64_b32 v[42:43], v23 offset0:64 offset1:65
	ds_read2st64_b32 v[44:45], v23 offset0:80 offset1:81
	ds_read2st64_b32 v[46:47], v23 offset0:66 offset1:67
	ds_read2st64_b32 v[48:49], v23 offset0:68 offset1:69
	ds_read2st64_b32 v[50:51], v23 offset0:70 offset1:71
	s_waitcnt lgkmcnt(4)
	v_add_f32_e32 v0, v0, v42
	ds_read2st64_b32 v[52:53], v23 offset0:82 offset1:83
	ds_read2st64_b32 v[54:55], v23 offset0:84 offset1:85
	ds_read2st64_b32 v[56:57], v23 offset0:86 offset1:87
	s_waitcnt lgkmcnt(6)
	v_add_f32_e32 v0, v0, v44
	ds_read2st64_b32 v[58:59], v23 offset0:96 offset1:97
	ds_read2st64_b32 v[60:61], v23 offset0:112 offset1:113
	ds_read2st64_b32 v[62:63], v23 offset0:98 offset1:99
	ds_read2st64_b32 v[64:65], v23 offset0:100 offset1:101
	ds_read2st64_b32 v[66:67], v23 offset0:102 offset1:103
	s_waitcnt lgkmcnt(4)
	v_add_f32_e32 v0, v0, v58
	s_waitcnt lgkmcnt(3)
	v_add_f32_e32 v2, v0, v60
	v_add_f32_e32 v0, 0, v1
	v_add_f32_e32 v0, v0, v3
	v_add_f32_e32 v0, v0, v27
	v_add_f32_e32 v0, v0, v29
	v_add_f32_e32 v0, v0, v43
	v_add_f32_e32 v0, v0, v45
	v_add_f32_e32 v0, v0, v59
	v_add_f32_e32 v3, v0, v61
	v_add_f32_e32 v0, 0, v4
	v_add_f32_e32 v0, v0, v10
	v_add_f32_e32 v0, v0, v30
	v_add_f32_e32 v0, v0, v36
	ds_read2st64_b32 v[68:69], v23 offset0:114 offset1:115
	ds_read2st64_b32 v[70:71], v23 offset0:116 offset1:117
	ds_read2st64_b32 v[72:73], v23 offset0:118 offset1:119
	v_add_f32_e32 v0, v0, v46
	v_add_f32_e32 v0, v0, v52
	s_waitcnt lgkmcnt(5)
	v_add_f32_e32 v0, v0, v62
	s_waitcnt lgkmcnt(2)
	v_add_f32_e32 v4, v0, v68
	v_add_f32_e32 v0, 0, v5
	v_add_f32_e32 v0, v0, v11
	v_add_f32_e32 v0, v0, v31
	v_add_f32_e32 v0, v0, v37
	v_add_f32_e32 v0, v0, v47
	v_add_f32_e32 v0, v0, v53
	v_add_f32_e32 v0, v0, v63
	v_add_f32_e32 v5, v0, v69
	v_add_f32_e32 v0, 0, v6
	v_add_f32_e32 v0, v0, v12
	v_add_f32_e32 v0, v0, v32
	v_add_f32_e32 v0, v0, v38
	v_add_f32_e32 v0, v0, v48
	v_add_f32_e32 v0, v0, v54
	v_add_f32_e32 v0, v0, v64
	s_waitcnt lgkmcnt(1)
; DI float shx(float v, int m, int lane) { return __int_as_float(__builtin_amdgcn_ds_bpermute((lane ^ m) << 2, __float_as_int(v))); }
; DI void krope_phase(const Frame& F, int crank, int ncu) {
;     ...
;         if (w == 0) {
; #pragma unroll
;             for (int i = 0; i < 16; ++i) { float sacc = 0.f;
; #pragma unroll
;                 for (int q = 0; q < 8; ++q) sacc += part[(q * 16 + i) * 64 + F.lane];
;                 acc[i] = sacc; }
;             const int row = row0 + r32;
;             f32x16 oth;
; #pragma unroll
;             for (int i = 0; i < 16; ++i) oth[i] = shx(acc[i], 32, F.lane);
;             u32x2 wv[4];
; #pragma unroll
;             for (int g = 0; g < 4; ++g) { float o[4];
; #pragma unroll
;                 for (int e = 0; e < 4; ++e) { const int i = 4 * g + e; float x1 = h5 ? oth[i] : acc[i], x2 = h5 ? acc[i] : oth[i]; float cs = 1.f, sn = 0.f;
;                     if (row < ML) { cs = rm[(size_t)(row & 2047) * 32 + i]; sn = rm[(size_t)(row & 2047) * 32 + 16 + i]; }
	v_add_f32_e32 v6, v0, v70
	v_add_f32_e32 v0, 0, v7
	v_add_f32_e32 v0, v0, v13
	v_add_f32_e32 v0, v0, v33
	v_add_f32_e32 v0, v0, v39
	v_add_f32_e32 v0, v0, v49
	v_add_f32_e32 v0, v0, v55
	v_add_f32_e32 v0, v0, v65
	v_add_f32_e32 v7, v0, v71
	v_add_f32_e32 v0, 0, v8
	v_add_f32_e32 v0, v0, v14
	v_add_f32_e32 v0, v0, v34
	v_add_f32_e32 v0, v0, v40
	v_add_f32_e32 v0, v0, v50
	v_add_f32_e32 v0, v0, v56
	v_add_f32_e32 v0, v0, v66
	s_waitcnt lgkmcnt(0)
	v_add_f32_e32 v8, v0, v72
	v_add_f32_e32 v0, 0, v9
	v_add_f32_e32 v0, v0, v15
	v_add_f32_e32 v0, v0, v35
	v_add_f32_e32 v0, v0, v41
	v_add_f32_e32 v0, v0, v51
	v_add_f32_e32 v0, v0, v57
	v_add_f32_e32 v0, v0, v67
	v_add_f32_e32 v9, v0, v73
	ds_read2st64_b32 v[0:1], v23 offset0:8 offset1:9
	ds_read2st64_b32 v[10:11], v23 offset0:24 offset1:25
	ds_read2st64_b32 v[26:27], v23 offset0:10 offset1:11
	ds_read2st64_b32 v[28:29], v23 offset0:12 offset1:13
	ds_read2st64_b32 v[30:31], v23 offset0:14 offset1:15
	s_waitcnt lgkmcnt(4)
	v_add_f32_e32 v0, 0, v0
	ds_read2st64_b32 v[34:35], v23 offset0:26 offset1:27
	ds_read2st64_b32 v[36:37], v23 offset0:28 offset1:29
	ds_read2st64_b32 v[38:39], v23 offset0:30 offset1:31
	s_waitcnt lgkmcnt(6)
	v_add_f32_e32 v0, v0, v10
	ds_read2st64_b32 v[14:15], v23 offset0:40 offset1:41
	ds_read2st64_b32 v[32:33], v23 offset0:56 offset1:57
	ds_read2st64_b32 v[40:41], v23 offset0:42 offset1:43
	ds_read2st64_b32 v[42:43], v23 offset0:44 offset1:45
	ds_read2st64_b32 v[44:45], v23 offset0:46 offset1:47
	s_waitcnt lgkmcnt(4)
	v_add_f32_e32 v0, v0, v14
	ds_read2st64_b32 v[46:47], v23 offset0:58 offset1:59
	ds_read2st64_b32 v[48:49], v23 offset0:60 offset1:61
	ds_read2st64_b32 v[50:51], v23 offset0:62 offset1:63
	s_waitcnt lgkmcnt(6)
	v_add_f32_e32 v0, v0, v32
	ds_read2st64_b32 v[52:53], v23 offset0:72 offset1:73
	ds_read2st64_b32 v[54:55], v23 offset0:88 offset1:89
	ds_read2st64_b32 v[56:57], v23 offset0:74 offset1:75
	ds_read2st64_b32 v[58:59], v23 offset0:76 offset1:77
	ds_read2st64_b32 v[60:61], v23 offset0:78 offset1:79
	s_waitcnt lgkmcnt(4)
	v_add_f32_e32 v0, v0, v52
	ds_read2st64_b32 v[62:63], v23 offset0:90 offset1:91
	ds_read2st64_b32 v[64:65], v23 offset0:92 offset1:93
	ds_read2st64_b32 v[66:67], v23 offset0:94 offset1:95
	s_waitcnt lgkmcnt(6)
	v_add_f32_e32 v0, v0, v54
	ds_read2st64_b32 v[68:69], v23 offset0:104 offset1:105
	ds_read2st64_b32 v[70:71], v23 offset0:120 offset1:121
	ds_read2st64_b32 v[72:73], v23 offset0:106 offset1:107
	ds_read2st64_b32 v[74:75], v23 offset0:108 offset1:109
	ds_read2st64_b32 v[76:77], v23 offset0:110 offset1:111
	s_waitcnt lgkmcnt(4)
	v_add_f32_e32 v0, v0, v68
	s_waitcnt lgkmcnt(3)
	v_add_f32_e32 v13, v0, v70
	v_add_f32_e32 v0, 0, v1
	v_add_f32_e32 v0, v0, v11
	v_add_f32_e32 v0, v0, v15
	v_add_f32_e32 v0, v0, v33
	v_add_f32_e32 v0, v0, v53
	v_add_f32_e32 v0, v0, v55
	v_add_f32_e32 v0, v0, v69
	v_add_f32_e32 v14, v0, v71
	v_add_f32_e32 v0, 0, v26
	v_add_f32_e32 v0, v0, v34
	v_add_f32_e32 v0, v0, v40
	v_add_f32_e32 v0, v0, v46
	ds_read2st64_b32 v[78:79], v23 offset0:122 offset1:123
	ds_read2st64_b32 v[80:81], v23 offset0:124 offset1:125
	ds_read2st64_b32 v[82:83], v23 offset0:126 offset1:127
	v_add_f32_e32 v0, v0, v56
	v_add_f32_e32 v0, v0, v62
	s_waitcnt lgkmcnt(5)
	v_add_f32_e32 v0, v0, v72
	s_waitcnt lgkmcnt(2)
	v_add_f32_e32 v33, v0, v78
	v_add_f32_e32 v0, 0, v27
	v_add_f32_e32 v0, v0, v35
	v_add_f32_e32 v0, v0, v41
	v_add_f32_e32 v0, v0, v47
	v_add_f32_e32 v0, v0, v57
	v_add_f32_e32 v0, v0, v63
	v_add_f32_e32 v0, v0, v73
	v_add_f32_e32 v34, v0, v79
	v_add_f32_e32 v0, 0, v28
	v_add_f32_e32 v0, v0, v36
	v_add_f32_e32 v0, v0, v42
	v_add_f32_e32 v0, v0, v48
	v_add_f32_e32 v0, v0, v58
	v_add_f32_e32 v0, v0, v64
	v_add_f32_e32 v0, v0, v74
	s_waitcnt lgkmcnt(1)
	v_add_f32_e32 v40, v0, v80
	v_add_f32_e32 v0, 0, v29
	v_add_f32_e32 v0, v0, v37
	v_add_f32_e32 v0, v0, v43
	v_add_f32_e32 v0, v0, v49
	v_add_f32_e32 v0, v0, v59
	v_add_f32_e32 v0, v0, v65
	v_add_f32_e32 v0, v0, v75
	v_add_f32_e32 v41, v0, v81
	v_add_f32_e32 v0, 0, v30
	v_add_f32_e32 v0, v0, v38
	v_add_f32_e32 v0, v0, v44
	v_add_f32_e32 v0, v0, v50
	v_add_f32_e32 v0, v0, v60
	v_add_f32_e32 v0, v0, v66
	v_add_f32_e32 v0, v0, v76
	s_waitcnt lgkmcnt(0)
	v_add_f32_e32 v46, v0, v82
	v_add_f32_e32 v0, 0, v31
	v_add_f32_e32 v0, v0, v39
	v_add_f32_e32 v0, v0, v45
	v_add_f32_e32 v0, v0, v51
	v_add_f32_e32 v0, v0, v61
	v_add_f32_e32 v0, v0, v67
	v_add_f32_e32 v0, v0, v77
	v_add_f32_e32 v47, v0, v83
	ds_bpermute_b32 v11, v24, v2
	ds_bpermute_b32 v10, v24, v3
	ds_bpermute_b32 v15, v24, v4
	ds_bpermute_b32 v12, v24, v5
	ds_bpermute_b32 v35, v24, v6
	ds_bpermute_b32 v29, v24, v7
	ds_bpermute_b32 v37, v24, v8
	ds_bpermute_b32 v36, v24, v9
	ds_bpermute_b32 v43, v24, v13
	ds_bpermute_b32 v42, v24, v14
	ds_bpermute_b32 v45, v24, v33
	ds_bpermute_b32 v44, v24, v34
	ds_bpermute_b32 v51, v24, v40
	ds_bpermute_b32 v48, v24, v41
	ds_bpermute_b32 v54, v24, v46
	ds_bpermute_b32 v52, v24, v47
	v_and_b32_e32 v0, 0xffe0, v25
	s_cmpk_lt_u32 s14, 0x200
	v_lshlrev_b32_e32 v0, 2, v0
	v_mov_b32_e32 v1, v97
	s_cselect_b64 s[10:11], -1, 0
	s_cmpk_gt_u32 s14, 0x1ff
	v_lshl_add_u64 v[0:1], s[6:7], 0, v[0:1]
	v_mov_b32_e32 v30, 0
	v_mov_b32_e32 v26, 1.0
	v_mov_b32_e32 v27, 1.0
	v_mov_b32_e32 v28, 0
	s_cbranch_scc1 .LBB0_545
	global_load_dword v27, v[0:1], off
	global_load_dword v28, v[0:1], off offset:64
